# v41
# baseline (speedup 1.0000x reference)
; #define PG8_STAGE(bufoff, gbase, voff) do { _Pragma("unroll") for (int _i = 0; _i < 2; ++_i) \
;         __builtin_amdgcn_global_load_lds((const unsigned*)((const char*)(gbase) + (voff)[_i]), (PG8_LAS unsigned*)(lds + (bufoff) + ldsw + _i * 8192), 16, 0, 0); } while (0)
; #define PG8_LDA(dst, b, h) do { _Pragma("unroll") for (int m = 0; m < 4; ++m) _Pragma("unroll") for (int k = 0; k < 2; ++k) dst[m][k] = *(const PG8_LAS bf16x8*)(lds + PG8_SA(b, h) + aoff + m * 2048 + k * 1024); } while (0)
; #define PG8_LDB(dst, b, h) do { _Pragma("unroll") for (int n = 0; n < 2; ++n) _Pragma("unroll") for (int k = 0; k < 2; ++k) dst[n][k] = *(const PG8_LAS bf16x8*)(lds + PG8_SB(b, h) + boff + n * 2048 + k * 1024); } while (0)
; #define PG8_MMA(ai, bj, At, Bt) do { __builtin_amdgcn_s_setprio(1); _Pragma("unroll") for (int m = 0; m < 4; ++m) _Pragma("unroll") for (int n = 0; n < 2; ++n) _Pragma("unroll") for (int k = 0; k < 2; ++k) \
;         acc[ai][bj][m][n] = __builtin_amdgcn_mfma_f32_16x16x32_bf16(Bt[n][k], At[m][k], acc[ai][bj][m][n], 0, 0, 0); __builtin_amdgcn_s_setprio(0); } while (0)
; #define PG8_BAR __builtin_amdgcn_s_barrier()
; template <class Epi, class Sched, bool ALIGN_EPI = false, bool SP2 = false>
; __device__ __forceinline__ void gemm_phase(PG8_LAS unsigned char* lds, const Gemm g, const Sched& S, const Epi& E) {
;     ...
;         const bool has_next = S.next(ui + 1, nxt);
;         const char* nA = has_next ? (const char*)g.A + (size_t)nxt.pm * tstep : cA; const char* nB = has_next ? (const char*)g.Bt + (size_t)nxt.pn * tstep : cB;
;         for (int t = 0; t < nt; t += 2) {
;             const bool last = (t == nt - 2);
;             const char* a1 = cA + (size_t)(t + 1) * kstep;
;             const char* a2 = last ? nA : cA + (size_t)(t + 2) * kstep; const char* b2 = last ? nB : cB + (size_t)(t + 2) * kstep;
;             const char* a3 = a2 + kstep; const char* b3 = b2 + kstep;
;             if (last && has_next) S.a_ready(nxt);
;             if constexpr (SP2) {
;             PG8_LDB(B0, 0, 0); PG8_LDB(B1, 0, 1); PG8_SCHED; PG8_LDA(At, 0, 0); PG8_STAGE(PG8_SA(1, 1), a1 + hstep, voffA);
;             PG8_WAIT_V(8); PG8_WAIT_L(0); PG8_BAR; PG8_MMA(0, 0, At, B0); PG8_MMA(0, 1, At, B1); PG8_BAR; PG8_SCHED;
;             PG8_LDA(At, 0, 1); PG8_STAGE(PG8_SB(0, 0), b2, voffB); PG8_STAGE(PG8_SB(0, 1), b2 + hstep, voffB); PG8_STAGE(PG8_SA(0, 0), a2, voffA);
.LBB0_168:
	s_ashr_i32 s29, s28, 31
	v_cmp_lt_i64_e32 vcc, s[30:31], v[140:141]
	s_lshl_b64 s[30:31], s[28:29], 20
	s_add_u32 s30, s6, s30
	s_addc_u32 s31, s7, s31
	s_and_b64 s[34:35], vcc, exec
	s_cselect_b32 s29, s31, s39
	s_cselect_b32 s57, s30, s38
	s_ashr_i32 s27, s26, 31
	s_lshl_b64 s[34:35], s[26:27], 20
	s_add_u32 s34, s22, s34
	s_addc_u32 s35, s23, s35
	s_and_b64 s[42:43], vcc, exec
	s_cselect_b32 s27, s35, s41
	s_cselect_b32 s58, s34, s40
	s_add_u32 s38, s38, 0x80080
	s_addc_u32 s39, s39, 0
	s_add_u32 s59, s40, 0x100
	s_addc_u32 s60, s41, 0
	s_mov_b32 s61, -2
	ds_read_b128 v[152:155], v149
	ds_read_b128 v[156:159], v149 offset:1024
	ds_read_b128 v[160:163], v149 offset:2048
	ds_read_b128 v[164:167], v149 offset:3072
	ds_read_b128 v[168:171], v150
	ds_read_b128 v[172:175], v150 offset:1024
	ds_read_b128 v[176:179], v150 offset:2048
	ds_read_b128 v[180:183], v150 offset:3072
	s_add_u32 s40, s38, 0xfff80080
	s_addc_u32 s41, s39, -1
	s_cmp_eq_u32 s61, 28
	s_cselect_b32 s43, s29, s41
	s_cselect_b32 s42, s57, s40
	s_cselect_b32 s41, s27, s60
	s_cselect_b32 s40, s58, s59
	s_add_i32 m0, s37, 0xc000
	ds_read_b128 v[184:187], v151
	ds_read_b128 v[188:191], v151 offset:1024
	ds_read_b128 v[192:195], v151 offset:2048
	ds_read_b128 v[196:199], v151 offset:3072
	ds_read_b128 v[200:203], v151 offset:4096
	ds_read_b128 v[204:207], v151 offset:5120
	ds_read_b128 v[208:211], v151 offset:6144
	ds_read_b128 v[214:217], v151 offset:7168
	global_load_lds_dwordx4 v136, s[38:39]
	s_add_i32 m0, s37, 0xe000
	s_nop 0
	global_load_lds_dwordx4 v138, s[38:39]
	s_waitcnt vmcnt(8)
	s_waitcnt lgkmcnt(0)
	s_barrier
	s_waitcnt lgkmcnt(0)
	v_mfma_f32_16x16x32_bf16 v[124:127], v[152:155], v[184:187], 0
	v_mfma_f32_16x16x32_bf16 v[120:123], v[160:163], v[184:187], 0
	v_mfma_f32_16x16x32_bf16 v[108:111], v[152:155], v[192:195], 0
	v_mfma_f32_16x16x32_bf16 v[104:107], v[160:163], v[192:195], 0
	v_mfma_f32_16x16x32_bf16 v[92:95], v[152:155], v[200:203], 0
	v_mfma_f32_16x16x32_bf16 v[88:91], v[160:163], v[200:203], 0
	v_mfma_f32_16x16x32_bf16 v[76:79], v[152:155], v[208:211], 0
	v_mfma_f32_16x16x32_bf16 v[72:75], v[160:163], v[208:211], 0
	v_mfma_f32_16x16x32_bf16 v[124:127], v[156:159], v[188:191], v[124:127]
	v_mfma_f32_16x16x32_bf16 v[120:123], v[164:167], v[188:191], v[120:123]
	v_mfma_f32_16x16x32_bf16 v[108:111], v[156:159], v[196:199], v[108:111]
	v_mfma_f32_16x16x32_bf16 v[104:107], v[164:167], v[196:199], v[104:107]
	v_mfma_f32_16x16x32_bf16 v[92:95], v[156:159], v[204:207], v[92:95]
	v_mfma_f32_16x16x32_bf16 v[88:91], v[164:167], v[204:207], v[88:91]
	v_mfma_f32_16x16x32_bf16 v[76:79], v[156:159], v[214:217], v[76:79]
	v_mfma_f32_16x16x32_bf16 v[72:75], v[164:167], v[214:217], v[72:75]
	v_mfma_f32_16x16x32_bf16 v[116:119], v[168:171], v[184:187], 0
	v_mfma_f32_16x16x32_bf16 v[112:115], v[176:179], v[184:187], 0
	v_mfma_f32_16x16x32_bf16 v[100:103], v[168:171], v[192:195], 0
	v_mfma_f32_16x16x32_bf16 v[96:99], v[176:179], v[192:195], 0
	v_mfma_f32_16x16x32_bf16 v[84:87], v[168:171], v[200:203], 0
	v_mfma_f32_16x16x32_bf16 v[80:83], v[176:179], v[200:203], 0
	v_mfma_f32_16x16x32_bf16 v[68:71], v[168:171], v[208:211], 0
	v_mfma_f32_16x16x32_bf16 v[64:67], v[176:179], v[208:211], 0
	v_mfma_f32_16x16x32_bf16 v[116:119], v[172:175], v[188:191], v[116:119]
	v_mfma_f32_16x16x32_bf16 v[112:115], v[180:183], v[188:191], v[112:115]
	v_mfma_f32_16x16x32_bf16 v[100:103], v[172:175], v[196:199], v[100:103]
	v_mfma_f32_16x16x32_bf16 v[96:99], v[180:183], v[196:199], v[96:99]
	v_mfma_f32_16x16x32_bf16 v[84:87], v[172:175], v[204:207], v[84:87]
	v_mfma_f32_16x16x32_bf16 v[80:83], v[180:183], v[204:207], v[80:83]
	v_mfma_f32_16x16x32_bf16 v[68:71], v[172:175], v[214:217], v[68:71]
	v_mfma_f32_16x16x32_bf16 v[64:67], v[180:183], v[214:217], v[64:67]
	s_barrier
	s_add_i32 s62, s53, s24
	s_mov_b32 m0, s62
	ds_read_b128 v[184:187], v151 offset:16384
	ds_read_b128 v[188:191], v151 offset:17408
	ds_read_b128 v[192:195], v151 offset:18432
	ds_read_b128 v[196:199], v151 offset:19456
	ds_read_b128 v[200:203], v151 offset:20480
	ds_read_b128 v[204:207], v151 offset:21504
	ds_read_b128 v[208:211], v151 offset:22528
	ds_read_b128 v[214:217], v151 offset:23552
	global_load_lds_dwordx4 v132, s[40:41]
	s_add_i32 m0, s62, 0x2000
	s_add_u32 s62, s40, 0x80000
	s_addc_u32 s63, s41, 0
	s_add_i32 s64, s54, s24
	global_load_lds_dwordx4 v128, s[40:41]
	s_mov_b32 m0, s64
	s_nop 0
	global_load_lds_dwordx4 v132, s[62:63]
	s_add_i32 m0, s64, 0x2000
	s_nop 0
	global_load_lds_dwordx4 v128, s[62:63]
	s_mov_b32 m0, s37
	s_nop 0
	global_load_lds_dwordx4 v134, s[42:43]
	s_mov_b32 m0, s45
	s_nop 0
	global_load_lds_dwordx4 v130, s[42:43]
	s_waitcnt vmcnt(8)
	s_waitcnt lgkmcnt(0)
	s_barrier
; #define PG8_STAGE(bufoff, gbase, voff) do { _Pragma("unroll") for (int _i = 0; _i < 2; ++_i) \
;         __builtin_amdgcn_global_load_lds((const unsigned*)((const char*)(gbase) + (voff)[_i]), (PG8_LAS unsigned*)(lds + (bufoff) + ldsw + _i * 8192), 16, 0, 0); } while (0)
; #define PG8_LDA(dst, b, h) do { _Pragma("unroll") for (int m = 0; m < 4; ++m) _Pragma("unroll") for (int k = 0; k < 2; ++k) dst[m][k] = *(const PG8_LAS bf16x8*)(lds + PG8_SA(b, h) + aoff + m * 2048 + k * 1024); } while (0)
; #define PG8_LDB(dst, b, h) do { _Pragma("unroll") for (int n = 0; n < 2; ++n) _Pragma("unroll") for (int k = 0; k < 2; ++k) dst[n][k] = *(const PG8_LAS bf16x8*)(lds + PG8_SB(b, h) + boff + n * 2048 + k * 1024); } while (0)
; #define PG8_MMA(ai, bj, At, Bt) do { __builtin_amdgcn_s_setprio(1); _Pragma("unroll") for (int m = 0; m < 4; ++m) _Pragma("unroll") for (int n = 0; n < 2; ++n) _Pragma("unroll") for (int k = 0; k < 2; ++k) \
;         acc[ai][bj][m][n] = __builtin_amdgcn_mfma_f32_16x16x32_bf16(Bt[n][k], At[m][k], acc[ai][bj][m][n], 0, 0, 0); __builtin_amdgcn_s_setprio(0); } while (0)
; #define PG8_WAIT_V(n) asm volatile("s_waitcnt vmcnt(" #n ")" ::: "memory")
; #define PG8_WAIT_L(n) asm volatile("s_waitcnt lgkmcnt(" #n ")" ::: "memory")
; #define PG8_BAR __builtin_amdgcn_s_barrier()
; #define PG8_SCHED __builtin_amdgcn_sched_barrier(0)
; template <class Epi, class Sched, bool ALIGN_EPI = false, bool SP2 = false>
; __device__ __forceinline__ void gemm_phase(PG8_LAS unsigned char* lds, const Gemm g, const Sched& S, const Epi& E) {
;     ...
;             PG8_WAIT_V(8); PG8_WAIT_L(0); PG8_BAR; PG8_MMA(0, 0, At, B0); PG8_MMA(0, 1, At, B1); PG8_BAR; PG8_SCHED;
;             PG8_LDA(At, 0, 1); PG8_STAGE(PG8_SB(0, 0), b2, voffB); PG8_STAGE(PG8_SB(0, 1), b2 + hstep, voffB); PG8_STAGE(PG8_SA(0, 0), a2, voffA);
;             PG8_WAIT_V(8); PG8_WAIT_L(0); PG8_BAR; PG8_MMA(1, 0, At, B0); PG8_MMA(1, 1, At, B1); PG8_BAR; PG8_SCHED;
;             PG8_LDB(B0, 1, 0); PG8_LDB(B1, 1, 1); PG8_SCHED; PG8_LDA(At, 1, 0); PG8_STAGE(PG8_SA(0, 1), a2 + hstep, voffA);
;             PG8_WAIT_V(8); PG8_WAIT_L(0); PG8_BAR; PG8_MMA(0, 0, At, B0); PG8_MMA(0, 1, At, B1); PG8_BAR; PG8_SCHED;
	s_waitcnt lgkmcnt(0)
	v_mfma_f32_16x16x32_bf16 v[60:63], v[152:155], v[184:187], 0
	v_mfma_f32_16x16x32_bf16 v[56:59], v[160:163], v[184:187], 0
	v_mfma_f32_16x16x32_bf16 v[44:47], v[152:155], v[192:195], 0
	v_mfma_f32_16x16x32_bf16 v[40:43], v[160:163], v[192:195], 0
	v_mfma_f32_16x16x32_bf16 v[28:31], v[152:155], v[200:203], 0
	v_mfma_f32_16x16x32_bf16 v[24:27], v[160:163], v[200:203], 0
	v_mfma_f32_16x16x32_bf16 v[12:15], v[152:155], v[208:211], 0
	v_mfma_f32_16x16x32_bf16 v[8:11], v[160:163], v[208:211], 0
	v_mfma_f32_16x16x32_bf16 v[60:63], v[156:159], v[188:191], v[60:63]
	v_mfma_f32_16x16x32_bf16 v[56:59], v[164:167], v[188:191], v[56:59]
	v_mfma_f32_16x16x32_bf16 v[44:47], v[156:159], v[196:199], v[44:47]
	v_mfma_f32_16x16x32_bf16 v[40:43], v[164:167], v[196:199], v[40:43]
	v_mfma_f32_16x16x32_bf16 v[28:31], v[156:159], v[204:207], v[28:31]
	v_mfma_f32_16x16x32_bf16 v[24:27], v[164:167], v[204:207], v[24:27]
	v_mfma_f32_16x16x32_bf16 v[12:15], v[156:159], v[214:217], v[12:15]
	v_mfma_f32_16x16x32_bf16 v[8:11], v[164:167], v[214:217], v[8:11]
	v_mfma_f32_16x16x32_bf16 v[52:55], v[168:171], v[184:187], 0
	v_mfma_f32_16x16x32_bf16 v[48:51], v[176:179], v[184:187], 0
	v_mfma_f32_16x16x32_bf16 v[36:39], v[168:171], v[192:195], 0
	v_mfma_f32_16x16x32_bf16 v[32:35], v[176:179], v[192:195], 0
	v_mfma_f32_16x16x32_bf16 v[20:23], v[168:171], v[200:203], 0
	v_mfma_f32_16x16x32_bf16 v[16:19], v[176:179], v[200:203], 0
	v_mfma_f32_16x16x32_bf16 v[4:7], v[168:171], v[208:211], 0
	v_mfma_f32_16x16x32_bf16 v[0:3], v[176:179], v[208:211], 0
	v_mfma_f32_16x16x32_bf16 v[52:55], v[172:175], v[188:191], v[52:55]
	v_mfma_f32_16x16x32_bf16 v[48:51], v[180:183], v[188:191], v[48:51]
	v_mfma_f32_16x16x32_bf16 v[36:39], v[172:175], v[196:199], v[36:39]
	v_mfma_f32_16x16x32_bf16 v[32:35], v[180:183], v[196:199], v[32:35]
	v_mfma_f32_16x16x32_bf16 v[20:23], v[172:175], v[204:207], v[20:23]
	v_mfma_f32_16x16x32_bf16 v[16:19], v[180:183], v[204:207], v[16:19]
	v_mfma_f32_16x16x32_bf16 v[4:7], v[172:175], v[214:217], v[4:7]
	v_mfma_f32_16x16x32_bf16 v[0:3], v[180:183], v[214:217], v[0:3]
	s_barrier
	s_add_i32 s62, 0, 0x18000
	s_add_i32 s63, 0, 0x1c000
	v_add_u32_e32 v164, s62, v147
	v_add_u32_e32 v180, s63, v147
	ds_read_b128 v[152:155], v164
	ds_read_b128 v[156:159], v164 offset:1024
	ds_read_b128 v[160:163], v164 offset:2048
	ds_read_b128 v[164:167], v164 offset:3072
	ds_read_b128 v[168:171], v180
	ds_read_b128 v[172:175], v180 offset:1024
	ds_read_b128 v[176:179], v180 offset:2048
	ds_read_b128 v[180:183], v180 offset:3072
	s_add_u32 s84, s42, 0x80
	s_addc_u32 s85, s43, 0
	s_add_u32 s42, s42, 0x80000
	s_addc_u32 s43, s43, 0
	s_mov_b32 m0, s46
	ds_read_b128 v[184:187], v151 offset:32768
	ds_read_b128 v[188:191], v151 offset:33792
	ds_read_b128 v[192:195], v151 offset:34816
	ds_read_b128 v[196:199], v151 offset:35840
	ds_read_b128 v[200:203], v151 offset:36864
	ds_read_b128 v[204:207], v151 offset:37888
	ds_read_b128 v[208:211], v151 offset:38912
	ds_read_b128 v[214:217], v151 offset:39936
	global_load_lds_dwordx4 v134, s[42:43]
	s_mov_b32 m0, s47
	s_nop 0
	global_load_lds_dwordx4 v130, s[42:43]
	s_waitcnt vmcnt(8)
	s_waitcnt lgkmcnt(0)
	s_barrier
	s_waitcnt lgkmcnt(0)
	v_mfma_f32_16x16x32_bf16 v[124:127], v[152:155], v[184:187], v[124:127]
	v_mfma_f32_16x16x32_bf16 v[120:123], v[160:163], v[184:187], v[120:123]
	v_mfma_f32_16x16x32_bf16 v[108:111], v[152:155], v[192:195], v[108:111]
	v_mfma_f32_16x16x32_bf16 v[104:107], v[160:163], v[192:195], v[104:107]
	v_mfma_f32_16x16x32_bf16 v[92:95], v[152:155], v[200:203], v[92:95]
	v_mfma_f32_16x16x32_bf16 v[88:91], v[160:163], v[200:203], v[88:91]
	v_mfma_f32_16x16x32_bf16 v[76:79], v[152:155], v[208:211], v[76:79]
	v_mfma_f32_16x16x32_bf16 v[72:75], v[160:163], v[208:211], v[72:75]
	v_mfma_f32_16x16x32_bf16 v[124:127], v[156:159], v[188:191], v[124:127]
	v_mfma_f32_16x16x32_bf16 v[120:123], v[164:167], v[188:191], v[120:123]
	v_mfma_f32_16x16x32_bf16 v[108:111], v[156:159], v[196:199], v[108:111]
	v_mfma_f32_16x16x32_bf16 v[104:107], v[164:167], v[196:199], v[104:107]
	v_mfma_f32_16x16x32_bf16 v[92:95], v[156:159], v[204:207], v[92:95]
	v_mfma_f32_16x16x32_bf16 v[88:91], v[164:167], v[204:207], v[88:91]
	v_mfma_f32_16x16x32_bf16 v[76:79], v[156:159], v[214:217], v[76:79]
	v_mfma_f32_16x16x32_bf16 v[72:75], v[164:167], v[214:217], v[72:75]
	v_mfma_f32_16x16x32_bf16 v[116:119], v[168:171], v[184:187], v[116:119]
	v_mfma_f32_16x16x32_bf16 v[112:115], v[176:179], v[184:187], v[112:115]
	v_mfma_f32_16x16x32_bf16 v[100:103], v[168:171], v[192:195], v[100:103]
	v_mfma_f32_16x16x32_bf16 v[96:99], v[176:179], v[192:195], v[96:99]
	v_mfma_f32_16x16x32_bf16 v[84:87], v[168:171], v[200:203], v[84:87]
	v_mfma_f32_16x16x32_bf16 v[80:83], v[176:179], v[200:203], v[80:83]
	v_mfma_f32_16x16x32_bf16 v[68:71], v[168:171], v[208:211], v[68:71]
	v_mfma_f32_16x16x32_bf16 v[64:67], v[176:179], v[208:211], v[64:67]
	v_mfma_f32_16x16x32_bf16 v[116:119], v[172:175], v[188:191], v[116:119]
	v_mfma_f32_16x16x32_bf16 v[112:115], v[180:183], v[188:191], v[112:115]
	v_mfma_f32_16x16x32_bf16 v[100:103], v[172:175], v[196:199], v[100:103]
	v_mfma_f32_16x16x32_bf16 v[96:99], v[180:183], v[196:199], v[96:99]
	v_mfma_f32_16x16x32_bf16 v[84:87], v[172:175], v[204:207], v[84:87]
	v_mfma_f32_16x16x32_bf16 v[80:83], v[180:183], v[204:207], v[80:83]
	v_mfma_f32_16x16x32_bf16 v[68:71], v[172:175], v[214:217], v[68:71]
	v_mfma_f32_16x16x32_bf16 v[64:67], v[180:183], v[214:217], v[64:67]
	s_barrier
; #define PG8_STAGE(bufoff, gbase, voff) do { _Pragma("unroll") for (int _i = 0; _i < 2; ++_i) \
;         __builtin_amdgcn_global_load_lds((const unsigned*)((const char*)(gbase) + (voff)[_i]), (PG8_LAS unsigned*)(lds + (bufoff) + ldsw + _i * 8192), 16, 0, 0); } while (0)
; #define PG8_LDA(dst, b, h) do { _Pragma("unroll") for (int m = 0; m < 4; ++m) _Pragma("unroll") for (int k = 0; k < 2; ++k) dst[m][k] = *(const PG8_LAS bf16x8*)(lds + PG8_SA(b, h) + aoff + m * 2048 + k * 1024); } while (0)
; #define PG8_LDB(dst, b, h) do { _Pragma("unroll") for (int n = 0; n < 2; ++n) _Pragma("unroll") for (int k = 0; k < 2; ++k) dst[n][k] = *(const PG8_LAS bf16x8*)(lds + PG8_SB(b, h) + boff + n * 2048 + k * 1024); } while (0)
; #define PG8_MMA(ai, bj, At, Bt) do { __builtin_amdgcn_s_setprio(1); _Pragma("unroll") for (int m = 0; m < 4; ++m) _Pragma("unroll") for (int n = 0; n < 2; ++n) _Pragma("unroll") for (int k = 0; k < 2; ++k) \
;         acc[ai][bj][m][n] = __builtin_amdgcn_mfma_f32_16x16x32_bf16(Bt[n][k], At[m][k], acc[ai][bj][m][n], 0, 0, 0); __builtin_amdgcn_s_setprio(0); } while (0)
; #define PG8_WAIT_V(n) asm volatile("s_waitcnt vmcnt(" #n ")" ::: "memory")
; #define PG8_WAIT_L(n) asm volatile("s_waitcnt lgkmcnt(" #n ")" ::: "memory")
; #define PG8_BAR __builtin_amdgcn_s_barrier()
; #define PG8_SCHED __builtin_amdgcn_sched_barrier(0)
; template <class Epi, class Sched, bool ALIGN_EPI = false, bool SP2 = false>
; __device__ __forceinline__ void gemm_phase(PG8_LAS unsigned char* lds, const Gemm g, const Sched& S, const Epi& E) {
;     ...
;             PG8_LDB(B0, 0, 0); PG8_LDB(B1, 0, 1); PG8_SCHED; PG8_LDA(At, 0, 0); PG8_STAGE(PG8_SA(1, 1), a1 + hstep, voffA);
;             PG8_WAIT_V(8); PG8_WAIT_L(0); PG8_BAR; PG8_MMA(0, 0, At, B0); PG8_MMA(0, 1, At, B1); PG8_BAR; PG8_SCHED;
;     ...
;             PG8_LDA(At, 1, 1); PG8_STAGE(PG8_SB(1, 0), b3, voffB); PG8_STAGE(PG8_SB(1, 1), b3 + hstep, voffB); PG8_STAGE(PG8_SA(1, 0), a3, voffA);
;             PG8_WAIT_V(8); PG8_WAIT_L(0); PG8_BAR; PG8_MMA(1, 0, At, B0); PG8_MMA(1, 1, At, B1); PG8_BAR; PG8_SCHED;
	s_add_i32 s42, s62, s24
	s_add_u32 s86, s40, 0x80
	s_addc_u32 s87, s41, 0
	s_mov_b32 m0, s42
	ds_read_b128 v[184:187], v151 offset:49152
	ds_read_b128 v[188:191], v151 offset:50176
	ds_read_b128 v[192:195], v151 offset:51200
	ds_read_b128 v[196:199], v151 offset:52224
	ds_read_b128 v[200:203], v151 offset:53248
	ds_read_b128 v[204:207], v151 offset:54272
	ds_read_b128 v[208:211], v151 offset:55296
	ds_read_b128 v[214:217], v151 offset:56320
	global_load_lds_dwordx4 v132, s[86:87]
	s_add_i32 m0, s42, 0x2000
	s_add_u32 s40, s40, 0x80080
	s_addc_u32 s41, s41, 0
	s_add_i32 s42, s63, s24
	global_load_lds_dwordx4 v128, s[86:87]
	s_mov_b32 m0, s42
	s_nop 0
	global_load_lds_dwordx4 v132, s[40:41]
	s_add_i32 m0, s42, 0x2000
	s_nop 0
	global_load_lds_dwordx4 v128, s[40:41]
	s_mov_b32 m0, s49
	s_nop 0
	global_load_lds_dwordx4 v134, s[84:85]
	s_mov_b32 m0, s50
	s_nop 0
	global_load_lds_dwordx4 v130, s[84:85]
	s_waitcnt vmcnt(8)
	s_waitcnt lgkmcnt(0)
	s_barrier
	s_waitcnt lgkmcnt(0)
	v_mfma_f32_16x16x32_bf16 v[60:63], v[152:155], v[184:187], v[60:63]
	v_mfma_f32_16x16x32_bf16 v[56:59], v[160:163], v[184:187], v[56:59]
	v_mfma_f32_16x16x32_bf16 v[44:47], v[152:155], v[192:195], v[44:47]
	v_mfma_f32_16x16x32_bf16 v[40:43], v[160:163], v[192:195], v[40:43]
	v_mfma_f32_16x16x32_bf16 v[28:31], v[152:155], v[200:203], v[28:31]
	v_mfma_f32_16x16x32_bf16 v[24:27], v[160:163], v[200:203], v[24:27]
	v_mfma_f32_16x16x32_bf16 v[12:15], v[152:155], v[208:211], v[12:15]
	v_mfma_f32_16x16x32_bf16 v[8:11], v[160:163], v[208:211], v[8:11]
	v_mfma_f32_16x16x32_bf16 v[60:63], v[156:159], v[188:191], v[60:63]
	v_mfma_f32_16x16x32_bf16 v[56:59], v[164:167], v[188:191], v[56:59]
	v_mfma_f32_16x16x32_bf16 v[44:47], v[156:159], v[196:199], v[44:47]
	v_mfma_f32_16x16x32_bf16 v[40:43], v[164:167], v[196:199], v[40:43]
	v_mfma_f32_16x16x32_bf16 v[28:31], v[156:159], v[204:207], v[28:31]
	v_mfma_f32_16x16x32_bf16 v[24:27], v[164:167], v[204:207], v[24:27]
	v_mfma_f32_16x16x32_bf16 v[12:15], v[156:159], v[214:217], v[12:15]
	v_mfma_f32_16x16x32_bf16 v[8:11], v[164:167], v[214:217], v[8:11]
	v_mfma_f32_16x16x32_bf16 v[52:55], v[168:171], v[184:187], v[52:55]
	v_mfma_f32_16x16x32_bf16 v[48:51], v[176:179], v[184:187], v[48:51]
	v_mfma_f32_16x16x32_bf16 v[36:39], v[168:171], v[192:195], v[36:39]
	v_mfma_f32_16x16x32_bf16 v[32:35], v[176:179], v[192:195], v[32:35]
	v_mfma_f32_16x16x32_bf16 v[20:23], v[168:171], v[200:203], v[20:23]
	v_mfma_f32_16x16x32_bf16 v[16:19], v[176:179], v[200:203], v[16:19]
	v_mfma_f32_16x16x32_bf16 v[4:7], v[168:171], v[208:211], v[4:7]
	v_mfma_f32_16x16x32_bf16 v[0:3], v[176:179], v[208:211], v[0:3]
	v_mfma_f32_16x16x32_bf16 v[52:55], v[172:175], v[188:191], v[52:55]
	v_mfma_f32_16x16x32_bf16 v[48:51], v[180:183], v[188:191], v[48:51]
	v_mfma_f32_16x16x32_bf16 v[36:39], v[172:175], v[196:199], v[36:39]
	v_mfma_f32_16x16x32_bf16 v[32:35], v[180:183], v[196:199], v[32:35]
	v_mfma_f32_16x16x32_bf16 v[20:23], v[172:175], v[204:207], v[20:23]
	v_mfma_f32_16x16x32_bf16 v[16:19], v[180:183], v[204:207], v[16:19]
	v_mfma_f32_16x16x32_bf16 v[4:7], v[172:175], v[214:217], v[4:7]
	v_mfma_f32_16x16x32_bf16 v[0:3], v[180:183], v[214:217], v[0:3]
	s_add_i32 s61, s61, 2
	s_add_u32 s38, s38, 0x100
	s_addc_u32 s39, s39, 0
	s_add_u32 s59, s59, 0x100
	s_addc_u32 s60, s60, 0
	s_cmp_gt_u32 s61, 29
	s_barrier
.LBB0_169:
	ds_read_b128 v[152:155], v149
	ds_read_b128 v[156:159], v149 offset:1024
	ds_read_b128 v[160:163], v149 offset:2048
	ds_read_b128 v[164:167], v149 offset:3072
	ds_read_b128 v[168:171], v150
	ds_read_b128 v[172:175], v150 offset:1024
	ds_read_b128 v[176:179], v150 offset:2048
	ds_read_b128 v[180:183], v150 offset:3072
	s_add_u32 s40, s38, 0xfff80080
	s_addc_u32 s41, s39, -1
	s_cmp_eq_u32 s61, 28
	s_cselect_b32 s43, s29, s41
	s_cselect_b32 s42, s57, s40
	s_cselect_b32 s41, s27, s60
	s_cselect_b32 s40, s58, s59
	s_add_i32 m0, s37, 0xc000
	ds_read_b128 v[184:187], v151
	ds_read_b128 v[188:191], v151 offset:1024
	ds_read_b128 v[192:195], v151 offset:2048
	ds_read_b128 v[196:199], v151 offset:3072
	ds_read_b128 v[200:203], v151 offset:4096
	ds_read_b128 v[204:207], v151 offset:5120
	ds_read_b128 v[208:211], v151 offset:6144
	ds_read_b128 v[214:217], v151 offset:7168
	global_load_lds_dwordx4 v136, s[38:39]
	s_add_i32 m0, s37, 0xe000
	s_nop 0
	global_load_lds_dwordx4 v138, s[38:39]
	s_waitcnt vmcnt(8)
	s_waitcnt lgkmcnt(0)
	s_barrier
	s_waitcnt lgkmcnt(0)
	v_mfma_f32_16x16x32_bf16 v[124:127], v[152:155], v[184:187], v[124:127]
	v_mfma_f32_16x16x32_bf16 v[120:123], v[160:163], v[184:187], v[120:123]
	v_mfma_f32_16x16x32_bf16 v[108:111], v[152:155], v[192:195], v[108:111]
	v_mfma_f32_16x16x32_bf16 v[104:107], v[160:163], v[192:195], v[104:107]
	v_mfma_f32_16x16x32_bf16 v[92:95], v[152:155], v[200:203], v[92:95]
	v_mfma_f32_16x16x32_bf16 v[88:91], v[160:163], v[200:203], v[88:91]
	v_mfma_f32_16x16x32_bf16 v[76:79], v[152:155], v[208:211], v[76:79]
	v_mfma_f32_16x16x32_bf16 v[72:75], v[160:163], v[208:211], v[72:75]
	v_mfma_f32_16x16x32_bf16 v[124:127], v[156:159], v[188:191], v[124:127]
	v_mfma_f32_16x16x32_bf16 v[120:123], v[164:167], v[188:191], v[120:123]
	v_mfma_f32_16x16x32_bf16 v[108:111], v[156:159], v[196:199], v[108:111]
	v_mfma_f32_16x16x32_bf16 v[104:107], v[164:167], v[196:199], v[104:107]
	v_mfma_f32_16x16x32_bf16 v[92:95], v[156:159], v[204:207], v[92:95]
	v_mfma_f32_16x16x32_bf16 v[88:91], v[164:167], v[204:207], v[88:91]
	v_mfma_f32_16x16x32_bf16 v[76:79], v[156:159], v[214:217], v[76:79]
	v_mfma_f32_16x16x32_bf16 v[72:75], v[164:167], v[214:217], v[72:75]
	v_mfma_f32_16x16x32_bf16 v[116:119], v[168:171], v[184:187], v[116:119]
	v_mfma_f32_16x16x32_bf16 v[112:115], v[176:179], v[184:187], v[112:115]
	v_mfma_f32_16x16x32_bf16 v[100:103], v[168:171], v[192:195], v[100:103]
	v_mfma_f32_16x16x32_bf16 v[96:99], v[176:179], v[192:195], v[96:99]
	v_mfma_f32_16x16x32_bf16 v[84:87], v[168:171], v[200:203], v[84:87]
	v_mfma_f32_16x16x32_bf16 v[80:83], v[176:179], v[200:203], v[80:83]
	v_mfma_f32_16x16x32_bf16 v[68:71], v[168:171], v[208:211], v[68:71]
	v_mfma_f32_16x16x32_bf16 v[64:67], v[176:179], v[208:211], v[64:67]
	v_mfma_f32_16x16x32_bf16 v[116:119], v[172:175], v[188:191], v[116:119]
	v_mfma_f32_16x16x32_bf16 v[112:115], v[180:183], v[188:191], v[112:115]
	v_mfma_f32_16x16x32_bf16 v[100:103], v[172:175], v[196:199], v[100:103]
	v_mfma_f32_16x16x32_bf16 v[96:99], v[180:183], v[196:199], v[96:99]
	v_mfma_f32_16x16x32_bf16 v[84:87], v[172:175], v[204:207], v[84:87]
	v_mfma_f32_16x16x32_bf16 v[80:83], v[180:183], v[204:207], v[80:83]
	v_mfma_f32_16x16x32_bf16 v[68:71], v[172:175], v[214:217], v[68:71]
	v_mfma_f32_16x16x32_bf16 v[64:67], v[180:183], v[214:217], v[64:67]
	s_barrier
; #define PG8_STAGE(bufoff, gbase, voff) do { _Pragma("unroll") for (int _i = 0; _i < 2; ++_i) \
;         __builtin_amdgcn_global_load_lds((const unsigned*)((const char*)(gbase) + (voff)[_i]), (PG8_LAS unsigned*)(lds + (bufoff) + ldsw + _i * 8192), 16, 0, 0); } while (0)
; #define PG8_LDA(dst, b, h) do { _Pragma("unroll") for (int m = 0; m < 4; ++m) _Pragma("unroll") for (int k = 0; k < 2; ++k) dst[m][k] = *(const PG8_LAS bf16x8*)(lds + PG8_SA(b, h) + aoff + m * 2048 + k * 1024); } while (0)
; #define PG8_LDB(dst, b, h) do { _Pragma("unroll") for (int n = 0; n < 2; ++n) _Pragma("unroll") for (int k = 0; k < 2; ++k) dst[n][k] = *(const PG8_LAS bf16x8*)(lds + PG8_SB(b, h) + boff + n * 2048 + k * 1024); } while (0)
; #define PG8_MMA(ai, bj, At, Bt) do { __builtin_amdgcn_s_setprio(1); _Pragma("unroll") for (int m = 0; m < 4; ++m) _Pragma("unroll") for (int n = 0; n < 2; ++n) _Pragma("unroll") for (int k = 0; k < 2; ++k) \
;         acc[ai][bj][m][n] = __builtin_amdgcn_mfma_f32_16x16x32_bf16(Bt[n][k], At[m][k], acc[ai][bj][m][n], 0, 0, 0); __builtin_amdgcn_s_setprio(0); } while (0)
; #define PG8_WAIT_V(n) asm volatile("s_waitcnt vmcnt(" #n ")" ::: "memory")
; #define PG8_WAIT_L(n) asm volatile("s_waitcnt lgkmcnt(" #n ")" ::: "memory")
; #define PG8_BAR __builtin_amdgcn_s_barrier()
; #define PG8_SCHED __builtin_amdgcn_sched_barrier(0)
; template <class Epi, class Sched, bool ALIGN_EPI = false, bool SP2 = false>
; __device__ __forceinline__ void gemm_phase(PG8_LAS unsigned char* lds, const Gemm g, const Sched& S, const Epi& E) {
;     ...
;             PG8_LDA(At, 0, 1); PG8_STAGE(PG8_SB(0, 0), b2, voffB); PG8_STAGE(PG8_SB(0, 1), b2 + hstep, voffB); PG8_STAGE(PG8_SA(0, 0), a2, voffA);
;             PG8_WAIT_V(8); PG8_WAIT_L(0); PG8_BAR; PG8_MMA(1, 0, At, B0); PG8_MMA(1, 1, At, B1); PG8_BAR; PG8_SCHED;
;             PG8_LDB(B0, 1, 0); PG8_LDB(B1, 1, 1); PG8_SCHED; PG8_LDA(At, 1, 0); PG8_STAGE(PG8_SA(0, 1), a2 + hstep, voffA);
;             PG8_WAIT_V(8); PG8_WAIT_L(0); PG8_BAR; PG8_MMA(0, 0, At, B0); PG8_MMA(0, 1, At, B1); PG8_BAR; PG8_SCHED;
	s_add_i32 s62, s53, s24
	s_mov_b32 m0, s62
	ds_read_b128 v[184:187], v151 offset:16384
	ds_read_b128 v[188:191], v151 offset:17408
	ds_read_b128 v[192:195], v151 offset:18432
	ds_read_b128 v[196:199], v151 offset:19456
	ds_read_b128 v[200:203], v151 offset:20480
	ds_read_b128 v[204:207], v151 offset:21504
	ds_read_b128 v[208:211], v151 offset:22528
	ds_read_b128 v[214:217], v151 offset:23552
	global_load_lds_dwordx4 v132, s[40:41]
	s_add_i32 m0, s62, 0x2000
	s_add_u32 s62, s40, 0x80000
	s_addc_u32 s63, s41, 0
	s_add_i32 s64, s54, s24
	global_load_lds_dwordx4 v128, s[40:41]
	s_mov_b32 m0, s64
	s_nop 0
	global_load_lds_dwordx4 v132, s[62:63]
	s_add_i32 m0, s64, 0x2000
	s_nop 0
	global_load_lds_dwordx4 v128, s[62:63]
	s_mov_b32 m0, s37
	s_nop 0
	global_load_lds_dwordx4 v134, s[42:43]
	s_mov_b32 m0, s45
	s_nop 0
	global_load_lds_dwordx4 v130, s[42:43]
	s_waitcnt vmcnt(8)
	s_waitcnt lgkmcnt(0)
	s_barrier
	s_waitcnt lgkmcnt(0)
	v_mfma_f32_16x16x32_bf16 v[60:63], v[152:155], v[184:187], v[60:63]
	v_mfma_f32_16x16x32_bf16 v[56:59], v[160:163], v[184:187], v[56:59]
	v_mfma_f32_16x16x32_bf16 v[44:47], v[152:155], v[192:195], v[44:47]
	v_mfma_f32_16x16x32_bf16 v[40:43], v[160:163], v[192:195], v[40:43]
	v_mfma_f32_16x16x32_bf16 v[28:31], v[152:155], v[200:203], v[28:31]
	v_mfma_f32_16x16x32_bf16 v[24:27], v[160:163], v[200:203], v[24:27]
	v_mfma_f32_16x16x32_bf16 v[12:15], v[152:155], v[208:211], v[12:15]
	v_mfma_f32_16x16x32_bf16 v[8:11], v[160:163], v[208:211], v[8:11]
	v_mfma_f32_16x16x32_bf16 v[60:63], v[156:159], v[188:191], v[60:63]
	v_mfma_f32_16x16x32_bf16 v[56:59], v[164:167], v[188:191], v[56:59]
	v_mfma_f32_16x16x32_bf16 v[44:47], v[156:159], v[196:199], v[44:47]
	v_mfma_f32_16x16x32_bf16 v[40:43], v[164:167], v[196:199], v[40:43]
	v_mfma_f32_16x16x32_bf16 v[28:31], v[156:159], v[204:207], v[28:31]
	v_mfma_f32_16x16x32_bf16 v[24:27], v[164:167], v[204:207], v[24:27]
	v_mfma_f32_16x16x32_bf16 v[12:15], v[156:159], v[214:217], v[12:15]
	v_mfma_f32_16x16x32_bf16 v[8:11], v[164:167], v[214:217], v[8:11]
	v_mfma_f32_16x16x32_bf16 v[52:55], v[168:171], v[184:187], v[52:55]
	v_mfma_f32_16x16x32_bf16 v[48:51], v[176:179], v[184:187], v[48:51]
	v_mfma_f32_16x16x32_bf16 v[36:39], v[168:171], v[192:195], v[36:39]
	v_mfma_f32_16x16x32_bf16 v[32:35], v[176:179], v[192:195], v[32:35]
	v_mfma_f32_16x16x32_bf16 v[20:23], v[168:171], v[200:203], v[20:23]
	v_mfma_f32_16x16x32_bf16 v[16:19], v[176:179], v[200:203], v[16:19]
	v_mfma_f32_16x16x32_bf16 v[4:7], v[168:171], v[208:211], v[4:7]
	v_mfma_f32_16x16x32_bf16 v[0:3], v[176:179], v[208:211], v[0:3]
	v_mfma_f32_16x16x32_bf16 v[52:55], v[172:175], v[188:191], v[52:55]
	v_mfma_f32_16x16x32_bf16 v[48:51], v[180:183], v[188:191], v[48:51]
	v_mfma_f32_16x16x32_bf16 v[36:39], v[172:175], v[196:199], v[36:39]
	v_mfma_f32_16x16x32_bf16 v[32:35], v[180:183], v[196:199], v[32:35]
	v_mfma_f32_16x16x32_bf16 v[20:23], v[172:175], v[204:207], v[20:23]
	v_mfma_f32_16x16x32_bf16 v[16:19], v[180:183], v[204:207], v[16:19]
	v_mfma_f32_16x16x32_bf16 v[4:7], v[172:175], v[214:217], v[4:7]
	v_mfma_f32_16x16x32_bf16 v[0:3], v[180:183], v[214:217], v[0:3]
	s_barrier
	s_add_i32 s62, 0, 0x18000
	s_add_i32 s63, 0, 0x1c000
	v_add_u32_e32 v164, s62, v147
	v_add_u32_e32 v180, s63, v147
	ds_read_b128 v[152:155], v164
	ds_read_b128 v[156:159], v164 offset:1024
	ds_read_b128 v[160:163], v164 offset:2048
	ds_read_b128 v[164:167], v164 offset:3072
	ds_read_b128 v[168:171], v180
	ds_read_b128 v[172:175], v180 offset:1024
	ds_read_b128 v[176:179], v180 offset:2048
	ds_read_b128 v[180:183], v180 offset:3072
	s_add_u32 s84, s42, 0x80
	s_addc_u32 s85, s43, 0
	s_add_u32 s42, s42, 0x80000
	s_addc_u32 s43, s43, 0
	s_mov_b32 m0, s46
	ds_read_b128 v[184:187], v151 offset:32768
	ds_read_b128 v[188:191], v151 offset:33792
	ds_read_b128 v[192:195], v151 offset:34816
	ds_read_b128 v[196:199], v151 offset:35840
	ds_read_b128 v[200:203], v151 offset:36864
	ds_read_b128 v[204:207], v151 offset:37888
	ds_read_b128 v[208:211], v151 offset:38912
	ds_read_b128 v[214:217], v151 offset:39936
	global_load_lds_dwordx4 v134, s[42:43]
	s_mov_b32 m0, s47
	s_nop 0
	global_load_lds_dwordx4 v130, s[42:43]
	s_waitcnt vmcnt(8)
	s_waitcnt lgkmcnt(0)
	s_barrier
	s_waitcnt lgkmcnt(0)
	v_mfma_f32_16x16x32_bf16 v[124:127], v[152:155], v[184:187], v[124:127]
	v_mfma_f32_16x16x32_bf16 v[120:123], v[160:163], v[184:187], v[120:123]
	v_mfma_f32_16x16x32_bf16 v[108:111], v[152:155], v[192:195], v[108:111]
	v_mfma_f32_16x16x32_bf16 v[104:107], v[160:163], v[192:195], v[104:107]
	v_mfma_f32_16x16x32_bf16 v[92:95], v[152:155], v[200:203], v[92:95]
	v_mfma_f32_16x16x32_bf16 v[88:91], v[160:163], v[200:203], v[88:91]
	v_mfma_f32_16x16x32_bf16 v[76:79], v[152:155], v[208:211], v[76:79]
	v_mfma_f32_16x16x32_bf16 v[72:75], v[160:163], v[208:211], v[72:75]
	v_mfma_f32_16x16x32_bf16 v[124:127], v[156:159], v[188:191], v[124:127]
	v_mfma_f32_16x16x32_bf16 v[120:123], v[164:167], v[188:191], v[120:123]
	v_mfma_f32_16x16x32_bf16 v[108:111], v[156:159], v[196:199], v[108:111]
	v_mfma_f32_16x16x32_bf16 v[104:107], v[164:167], v[196:199], v[104:107]
	v_mfma_f32_16x16x32_bf16 v[92:95], v[156:159], v[204:207], v[92:95]
	v_mfma_f32_16x16x32_bf16 v[88:91], v[164:167], v[204:207], v[88:91]
	v_mfma_f32_16x16x32_bf16 v[76:79], v[156:159], v[214:217], v[76:79]
	v_mfma_f32_16x16x32_bf16 v[72:75], v[164:167], v[214:217], v[72:75]
	v_mfma_f32_16x16x32_bf16 v[116:119], v[168:171], v[184:187], v[116:119]
	v_mfma_f32_16x16x32_bf16 v[112:115], v[176:179], v[184:187], v[112:115]
	v_mfma_f32_16x16x32_bf16 v[100:103], v[168:171], v[192:195], v[100:103]
	v_mfma_f32_16x16x32_bf16 v[96:99], v[176:179], v[192:195], v[96:99]
	v_mfma_f32_16x16x32_bf16 v[84:87], v[168:171], v[200:203], v[84:87]
	v_mfma_f32_16x16x32_bf16 v[80:83], v[176:179], v[200:203], v[80:83]
	v_mfma_f32_16x16x32_bf16 v[68:71], v[168:171], v[208:211], v[68:71]
	v_mfma_f32_16x16x32_bf16 v[64:67], v[176:179], v[208:211], v[64:67]
	v_mfma_f32_16x16x32_bf16 v[116:119], v[172:175], v[188:191], v[116:119]
	v_mfma_f32_16x16x32_bf16 v[112:115], v[180:183], v[188:191], v[112:115]
	v_mfma_f32_16x16x32_bf16 v[100:103], v[172:175], v[196:199], v[100:103]
	v_mfma_f32_16x16x32_bf16 v[96:99], v[180:183], v[196:199], v[96:99]
	v_mfma_f32_16x16x32_bf16 v[84:87], v[172:175], v[204:207], v[84:87]
	v_mfma_f32_16x16x32_bf16 v[80:83], v[180:183], v[204:207], v[80:83]
	v_mfma_f32_16x16x32_bf16 v[68:71], v[172:175], v[214:217], v[68:71]
	v_mfma_f32_16x16x32_bf16 v[64:67], v[180:183], v[214:217], v[64:67]
	s_barrier
; __device__ __forceinline__ float fsilu(float v) { return v * fsigmoid(v); }
; __device__ __forceinline__ u32x4 pack8(const f32x4 a, const f32x4 b) { u32x4 w; w.x = cvt_pk_bf16(a[0], a[1]); w.y = cvt_pk_bf16(a[2], a[3]); w.z = cvt_pk_bf16(b[0], b[1]); w.w = cvt_pk_bf16(b[2], b[3]); return w; }
; #define PG8_STAGE(bufoff, gbase, voff) do { _Pragma("unroll") for (int _i = 0; _i < 2; ++_i) \
;         __builtin_amdgcn_global_load_lds((const unsigned*)((const char*)(gbase) + (voff)[_i]), (PG8_LAS unsigned*)(lds + (bufoff) + ldsw + _i * 8192), 16, 0, 0); } while (0)
; #define PG8_LDA(dst, b, h) do { _Pragma("unroll") for (int m = 0; m < 4; ++m) _Pragma("unroll") for (int k = 0; k < 2; ++k) dst[m][k] = *(const PG8_LAS bf16x8*)(lds + PG8_SA(b, h) + aoff + m * 2048 + k * 1024); } while (0)
; #define PG8_MMA(ai, bj, At, Bt) do { __builtin_amdgcn_s_setprio(1); _Pragma("unroll") for (int m = 0; m < 4; ++m) _Pragma("unroll") for (int n = 0; n < 2; ++n) _Pragma("unroll") for (int k = 0; k < 2; ++k) \
;         acc[ai][bj][m][n] = __builtin_amdgcn_mfma_f32_16x16x32_bf16(Bt[n][k], At[m][k], acc[ai][bj][m][n], 0, 0, 0); __builtin_amdgcn_s_setprio(0); } while (0)
; #define PG8_BAR __builtin_amdgcn_s_barrier()
;     __device__ __forceinline__ void operator()(const f32x4 (&acc)[2][2][4][2], const Unit& u, int wr, int wc, int fr, int fq) const {
;         const int row0 = u.pm * BM + wr * 64 + fr, col0 = u.pn * 128 + wc * 32 + 8 * fq;
; #pragma unroll
;         for (int ai = 0; ai < 2; ++ai)
; #pragma unroll
;             for (int m = 0; m < 4; ++m) {
;                 bf16_t* rowp = O + (size_t)(row0 + ai * HALF + m * 16) * ldc + col0;
;                 f32x4 h0, h1;
; #pragma unroll
;                 for (int j = 0; j < 4; ++j) { h0[j] = fsilu(acc[ai][0][m][0][j]) * acc[ai][1][m][0][j]; h1[j] = fsilu(acc[ai][0][m][1][j]) * acc[ai][1][m][1][j]; }
;                 *(u32x4*)rowp = pack8(h0, h1);
; template <class Epi, class Sched, bool ALIGN_EPI = false, bool SP2 = false>
; __device__ __forceinline__ void gemm_phase(PG8_LAS unsigned char* lds, const Gemm g, const Sched& S, const Epi& E) {
;     ...
;             PG8_LDA(At, 1, 1); PG8_STAGE(PG8_SB(1, 0), b3, voffB); PG8_STAGE(PG8_SB(1, 1), b3 + hstep, voffB); PG8_STAGE(PG8_SA(1, 0), a3, voffA);
;             PG8_WAIT_V(8); PG8_WAIT_L(0); PG8_BAR; PG8_MMA(1, 0, At, B0); PG8_MMA(1, 1, At, B1); PG8_BAR; PG8_SCHED;
	s_add_i32 s42, s62, s24
	s_add_u32 s86, s40, 0x80
	s_addc_u32 s87, s41, 0
	s_mov_b32 m0, s42
	ds_read_b128 v[184:187], v151 offset:49152
	ds_read_b128 v[188:191], v151 offset:50176
	ds_read_b128 v[192:195], v151 offset:51200
	ds_read_b128 v[196:199], v151 offset:52224
	ds_read_b128 v[200:203], v151 offset:53248
	ds_read_b128 v[204:207], v151 offset:54272
	ds_read_b128 v[208:211], v151 offset:55296
	ds_read_b128 v[214:217], v151 offset:56320
	global_load_lds_dwordx4 v132, s[86:87]
	s_add_i32 m0, s42, 0x2000
	s_add_u32 s40, s40, 0x80080
	s_addc_u32 s41, s41, 0
	s_add_i32 s42, s63, s24
	global_load_lds_dwordx4 v128, s[86:87]
	s_mov_b32 m0, s42
	s_nop 0
	global_load_lds_dwordx4 v132, s[40:41]
	s_add_i32 m0, s42, 0x2000
	s_nop 0
	global_load_lds_dwordx4 v128, s[40:41]
	s_mov_b32 m0, s49
	s_nop 0
	global_load_lds_dwordx4 v134, s[84:85]
	s_mov_b32 m0, s50
	s_nop 0
	global_load_lds_dwordx4 v130, s[84:85]
	s_waitcnt vmcnt(8)
	s_waitcnt lgkmcnt(0)
	s_barrier
	s_waitcnt lgkmcnt(0)
	v_mfma_f32_16x16x32_bf16 v[60:63], v[152:155], v[184:187], v[60:63]
	v_mfma_f32_16x16x32_bf16 v[56:59], v[160:163], v[184:187], v[56:59]
	v_mfma_f32_16x16x32_bf16 v[44:47], v[152:155], v[192:195], v[44:47]
	v_mfma_f32_16x16x32_bf16 v[40:43], v[160:163], v[192:195], v[40:43]
	v_mfma_f32_16x16x32_bf16 v[28:31], v[152:155], v[200:203], v[28:31]
	v_mfma_f32_16x16x32_bf16 v[24:27], v[160:163], v[200:203], v[24:27]
	v_mfma_f32_16x16x32_bf16 v[12:15], v[152:155], v[208:211], v[12:15]
	v_mfma_f32_16x16x32_bf16 v[8:11], v[160:163], v[208:211], v[8:11]
	v_mfma_f32_16x16x32_bf16 v[60:63], v[156:159], v[188:191], v[60:63]
	v_mfma_f32_16x16x32_bf16 v[56:59], v[164:167], v[188:191], v[56:59]
	v_mfma_f32_16x16x32_bf16 v[44:47], v[156:159], v[196:199], v[44:47]
	v_mfma_f32_16x16x32_bf16 v[40:43], v[164:167], v[196:199], v[40:43]
	v_mfma_f32_16x16x32_bf16 v[28:31], v[156:159], v[204:207], v[28:31]
	v_mfma_f32_16x16x32_bf16 v[24:27], v[164:167], v[204:207], v[24:27]
	v_mfma_f32_16x16x32_bf16 v[12:15], v[156:159], v[214:217], v[12:15]
	v_mfma_f32_16x16x32_bf16 v[8:11], v[164:167], v[214:217], v[8:11]
	v_mfma_f32_16x16x32_bf16 v[52:55], v[168:171], v[184:187], v[52:55]
	v_mfma_f32_16x16x32_bf16 v[48:51], v[176:179], v[184:187], v[48:51]
	v_mfma_f32_16x16x32_bf16 v[36:39], v[168:171], v[192:195], v[36:39]
	v_mfma_f32_16x16x32_bf16 v[32:35], v[176:179], v[192:195], v[32:35]
	v_mfma_f32_16x16x32_bf16 v[20:23], v[168:171], v[200:203], v[20:23]
	v_mfma_f32_16x16x32_bf16 v[16:19], v[176:179], v[200:203], v[16:19]
	v_mfma_f32_16x16x32_bf16 v[4:7], v[168:171], v[208:211], v[4:7]
	v_mfma_f32_16x16x32_bf16 v[0:3], v[176:179], v[208:211], v[0:3]
	v_mfma_f32_16x16x32_bf16 v[52:55], v[172:175], v[188:191], v[52:55]
	v_mfma_f32_16x16x32_bf16 v[48:51], v[180:183], v[188:191], v[48:51]
	v_mfma_f32_16x16x32_bf16 v[36:39], v[172:175], v[196:199], v[36:39]
	v_mfma_f32_16x16x32_bf16 v[32:35], v[180:183], v[196:199], v[32:35]
	v_mfma_f32_16x16x32_bf16 v[20:23], v[172:175], v[204:207], v[20:23]
	v_mfma_f32_16x16x32_bf16 v[16:19], v[180:183], v[204:207], v[16:19]
	v_mfma_f32_16x16x32_bf16 v[4:7], v[172:175], v[214:217], v[4:7]
	v_mfma_f32_16x16x32_bf16 v[0:3], v[180:183], v[214:217], v[0:3]
	s_add_i32 s61, s61, 2
	s_add_u32 s38, s38, 0x100
	s_addc_u32 s39, s39, 0
	s_add_u32 s59, s59, 0x100
	s_addc_u32 s60, s60, 0
	s_cmp_gt_u32 s61, 29
	s_barrier
	s_cbranch_scc0 .LBB0_169
	v_mul_f32_e32 v153, 0xbfb8aa3b, v124
	v_mul_f32_e32 v158, 0xbfb8aa3b, v120
	v_exp_f32_e32 v153, v153
	v_exp_f32_e32 v159, v158
	v_mul_f32_e32 v158, 0xbfb8aa3b, v125
	v_exp_f32_e32 v160, v158
	v_add_f32_e32 v153, 1.0, v153
	v_rcp_f32_e32 v158, v153
	v_add_f32_e32 v153, 1.0, v159
	v_add_f32_e32 v159, 1.0, v160
	v_rcp_f32_e32 v159, v159
	v_mul_f32_e32 v160, 0xbfb8aa3b, v121
	v_exp_f32_e32 v161, v160
	v_rcp_f32_e32 v160, v153
	v_pk_mul_f32 v[124:125], v[124:125], v[158:159]
	v_mul_f32_e32 v153, 0xbfb8aa3b, v127
	v_pk_mul_f32 v[116:117], v[124:125], v[116:117]
	v_add_f32_e32 v124, 1.0, v161
	v_mul_f32_e32 v125, 0xbfb8aa3b, v122
	v_rcp_f32_e32 v161, v124
	v_mul_f32_e32 v124, 0xbfb8aa3b, v126
	v_exp_f32_e32 v125, v125
	v_exp_f32_e32 v124, v124
	v_exp_f32_e32 v153, v153
	v_mul_f32_e32 v158, 0xbfb8aa3b, v123
	v_exp_f32_e32 v159, v158
	v_add_f32_e32 v125, 1.0, v125
	v_add_f32_e32 v124, 1.0, v124
	v_rcp_f32_e32 v158, v125
	v_add_f32_e32 v125, 1.0, v153
	v_rcp_f32_e32 v124, v124
	v_rcp_f32_e32 v125, v125
	v_add_f32_e32 v153, 1.0, v159
	v_rcp_f32_e32 v159, v153
	v_pk_mul_f32 v[120:121], v[120:121], v[160:161]
	v_lshl_or_b32 v154, s56, 7, v148
	v_pk_mul_f32 v[120:121], v[120:121], v[112:113]
	v_pk_mul_f32 v[112:113], v[126:127], v[124:125]
	v_lshl_add_u32 v152, s36, 8, v146
	v_ashrrev_i32_e32 v155, 31, v154
	v_mov_b64_e32 v[144:145], s[10:11]
	v_pk_mul_f32 v[118:119], v[112:113], v[118:119]
	v_pk_mul_f32 v[112:113], v[122:123], v[158:159]
	v_mad_i64_i32 v[156:157], s[38:39], v152, s55, v[144:145]
	v_pk_mul_f32 v[122:123], v[112:113], v[114:115]
	v_lshlrev_b64 v[112:113], 1, v[154:155]
	v_lshl_add_u64 v[124:125], v[156:157], 0, v[112:113]
	v_cvt_pk_bf16_f32 v114, v116, v117
	v_cvt_pk_bf16_f32 v115, v118, v119
	v_cvt_pk_bf16_f32 v116, v120, v121
	v_cvt_pk_bf16_f32 v117, v122, v123
	global_store_dwordx4 v[124:125], v[114:117], off
	v_mul_f32_e32 v118, 0xbfb8aa3b, v109
	v_exp_f32_e32 v118, v118
	v_mul_f32_e32 v116, 0xbfb8aa3b, v108
	v_mul_f32_e32 v117, 0xbfb8aa3b, v104
	v_exp_f32_e32 v116, v116
	v_exp_f32_e32 v117, v117
	v_or_b32_e32 v114, 16, v152
	v_mad_i64_i32 v[114:115], s[38:39], v114, s55, v[144:145]
	v_add_f32_e32 v116, 1.0, v116
	v_add_f32_e32 v119, 1.0, v117
	v_add_f32_e32 v117, 1.0, v118
	v_rcp_f32_e32 v116, v116
	v_rcp_f32_e32 v117, v117
; __device__ __forceinline__ float fsilu(float v) { return v * fsigmoid(v); }
; __device__ __forceinline__ u32x4 pack8(const f32x4 a, const f32x4 b) { u32x4 w; w.x = cvt_pk_bf16(a[0], a[1]); w.y = cvt_pk_bf16(a[2], a[3]); w.z = cvt_pk_bf16(b[0], b[1]); w.w = cvt_pk_bf16(b[2], b[3]); return w; }
;     __device__ __forceinline__ void operator()(const f32x4 (&acc)[2][2][4][2], const Unit& u, int wr, int wc, int fr, int fq) const {
;         const int row0 = u.pm * BM + wr * 64 + fr, col0 = u.pn * 128 + wc * 32 + 8 * fq;
; #pragma unroll
;         for (int ai = 0; ai < 2; ++ai)
; #pragma unroll
;             for (int m = 0; m < 4; ++m) {
;                 bf16_t* rowp = O + (size_t)(row0 + ai * HALF + m * 16) * ldc + col0;
;                 f32x4 h0, h1;
; #pragma unroll
;                 for (int j = 0; j < 4; ++j) { h0[j] = fsilu(acc[ai][0][m][0][j]) * acc[ai][1][m][0][j]; h1[j] = fsilu(acc[ai][0][m][1][j]) * acc[ai][1][m][1][j]; }
;                 *(u32x4*)rowp = pack8(h0, h1);
	v_mul_f32_e32 v118, 0xbfb8aa3b, v105
	v_exp_f32_e32 v120, v118
	v_rcp_f32_e32 v118, v119
	v_pk_mul_f32 v[108:109], v[108:109], v[116:117]
	v_mul_f32_e32 v116, 0xbfb8aa3b, v111
	v_pk_mul_f32 v[100:101], v[108:109], v[100:101]
	v_add_f32_e32 v108, 1.0, v120
	v_rcp_f32_e32 v119, v108
	v_mul_f32_e32 v109, 0xbfb8aa3b, v106
	v_mul_f32_e32 v108, 0xbfb8aa3b, v110
	v_exp_f32_e32 v109, v109
	v_exp_f32_e32 v108, v108
	v_exp_f32_e32 v117, v116
	v_mul_f32_e32 v116, 0xbfb8aa3b, v107
	v_pk_mul_f32 v[104:105], v[104:105], v[118:119]
	v_exp_f32_e32 v118, v116
	v_add_f32_e32 v109, 1.0, v109
	v_add_f32_e32 v108, 1.0, v108
	v_rcp_f32_e32 v116, v109
	v_add_f32_e32 v109, 1.0, v117
	v_rcp_f32_e32 v108, v108
	v_rcp_f32_e32 v109, v109
	v_add_f32_e32 v117, 1.0, v118
	v_rcp_f32_e32 v117, v117
	v_pk_mul_f32 v[104:105], v[104:105], v[96:97]
	v_pk_mul_f32 v[96:97], v[110:111], v[108:109]
	v_lshl_add_u64 v[108:109], v[114:115], 0, v[112:113]
	v_pk_mul_f32 v[102:103], v[96:97], v[102:103]
	v_pk_mul_f32 v[96:97], v[106:107], v[116:117]
	s_and_b64 vcc, exec, s[8:9]
	v_pk_mul_f32 v[106:107], v[96:97], v[98:99]
	v_cvt_pk_bf16_f32 v96, v100, v101
	v_cvt_pk_bf16_f32 v97, v102, v103
	v_cvt_pk_bf16_f32 v98, v104, v105
	v_cvt_pk_bf16_f32 v99, v106, v107
	global_store_dwordx4 v[108:109], v[96:99], off
	v_mul_f32_e32 v100, 0xbfb8aa3b, v93
	v_exp_f32_e32 v100, v100
	v_mul_f32_e32 v98, 0xbfb8aa3b, v92
	v_mul_f32_e32 v99, 0xbfb8aa3b, v88
	v_exp_f32_e32 v98, v98
	v_exp_f32_e32 v99, v99
	v_or_b32_e32 v96, 32, v152
	v_mad_i64_i32 v[96:97], s[38:39], v96, s55, v[144:145]
	v_add_f32_e32 v98, 1.0, v98
	v_add_f32_e32 v101, 1.0, v99
	v_add_f32_e32 v99, 1.0, v100
	v_rcp_f32_e32 v98, v98
	v_rcp_f32_e32 v99, v99
	v_mul_f32_e32 v100, 0xbfb8aa3b, v89
	v_exp_f32_e32 v102, v100
	v_rcp_f32_e32 v100, v101
	v_pk_mul_f32 v[92:93], v[92:93], v[98:99]
	v_mul_f32_e32 v98, 0xbfb8aa3b, v95
	v_pk_mul_f32 v[84:85], v[92:93], v[84:85]
	v_add_f32_e32 v92, 1.0, v102
	v_rcp_f32_e32 v101, v92
	v_mul_f32_e32 v93, 0xbfb8aa3b, v90
	v_mul_f32_e32 v92, 0xbfb8aa3b, v94
	v_exp_f32_e32 v93, v93
	v_exp_f32_e32 v92, v92
	v_exp_f32_e32 v99, v98
	v_mul_f32_e32 v98, 0xbfb8aa3b, v91
	v_pk_mul_f32 v[88:89], v[88:89], v[100:101]
	v_exp_f32_e32 v100, v98
	v_add_f32_e32 v93, 1.0, v93
	v_add_f32_e32 v92, 1.0, v92
	v_rcp_f32_e32 v98, v93
	v_add_f32_e32 v93, 1.0, v99
	v_rcp_f32_e32 v92, v92
	v_rcp_f32_e32 v93, v93
	v_add_f32_e32 v99, 1.0, v100
	v_rcp_f32_e32 v99, v99
	v_pk_mul_f32 v[88:89], v[88:89], v[80:81]
	v_pk_mul_f32 v[80:81], v[94:95], v[92:93]
	v_lshl_add_u64 v[92:93], v[96:97], 0, v[112:113]
	v_pk_mul_f32 v[86:87], v[80:81], v[86:87]
	v_pk_mul_f32 v[80:81], v[90:91], v[98:99]
	s_mov_b32 s56, s26
	v_pk_mul_f32 v[90:91], v[80:81], v[82:83]
	v_cvt_pk_bf16_f32 v80, v84, v85
	v_cvt_pk_bf16_f32 v81, v86, v87
	v_cvt_pk_bf16_f32 v82, v88, v89
	v_cvt_pk_bf16_f32 v83, v90, v91
	global_store_dwordx4 v[92:93], v[80:83], off
	v_mul_f32_e32 v84, 0xbfb8aa3b, v77
	v_exp_f32_e32 v84, v84
	v_mul_f32_e32 v82, 0xbfb8aa3b, v76
	v_mul_f32_e32 v83, 0xbfb8aa3b, v72
	v_exp_f32_e32 v82, v82
	v_exp_f32_e32 v83, v83
	v_or_b32_e32 v80, 48, v152
	v_mad_i64_i32 v[80:81], s[38:39], v80, s55, v[144:145]
	v_add_f32_e32 v82, 1.0, v82
	v_add_f32_e32 v85, 1.0, v83
	v_add_f32_e32 v83, 1.0, v84
	v_rcp_f32_e32 v82, v82
	v_rcp_f32_e32 v83, v83
	v_mul_f32_e32 v84, 0xbfb8aa3b, v73
	v_exp_f32_e32 v86, v84
	v_rcp_f32_e32 v84, v85
	v_pk_mul_f32 v[76:77], v[76:77], v[82:83]
	v_mul_f32_e32 v82, 0xbfb8aa3b, v79
	v_pk_mul_f32 v[68:69], v[76:77], v[68:69]
	v_add_f32_e32 v76, 1.0, v86
	v_rcp_f32_e32 v85, v76
	v_mul_f32_e32 v77, 0xbfb8aa3b, v74
	v_mul_f32_e32 v76, 0xbfb8aa3b, v78
	v_exp_f32_e32 v77, v77
	v_exp_f32_e32 v76, v76
	v_exp_f32_e32 v83, v82
	v_mul_f32_e32 v82, 0xbfb8aa3b, v75
	v_pk_mul_f32 v[72:73], v[72:73], v[84:85]
	v_exp_f32_e32 v84, v82
	v_add_f32_e32 v77, 1.0, v77
	v_add_f32_e32 v76, 1.0, v76
	v_rcp_f32_e32 v82, v77
	v_add_f32_e32 v77, 1.0, v83
	v_rcp_f32_e32 v76, v76
	v_rcp_f32_e32 v77, v77
	v_add_f32_e32 v83, 1.0, v84
	v_rcp_f32_e32 v83, v83
	v_pk_mul_f32 v[72:73], v[72:73], v[64:65]
	v_pk_mul_f32 v[64:65], v[78:79], v[76:77]
	v_lshl_add_u64 v[76:77], v[80:81], 0, v[112:113]
	v_pk_mul_f32 v[70:71], v[64:65], v[70:71]
	v_pk_mul_f32 v[64:65], v[74:75], v[82:83]
	s_mov_b32 s36, s28
	v_pk_mul_f32 v[74:75], v[64:65], v[66:67]
	v_cvt_pk_bf16_f32 v64, v68, v69
	v_cvt_pk_bf16_f32 v65, v70, v71
	v_cvt_pk_bf16_f32 v66, v72, v73
	v_cvt_pk_bf16_f32 v67, v74, v75
	global_store_dwordx4 v[76:77], v[64:67], off
	v_mul_f32_e32 v68, 0xbfb8aa3b, v61
	v_exp_f32_e32 v68, v68
	v_mul_f32_e32 v66, 0xbfb8aa3b, v60
	v_mul_f32_e32 v67, 0xbfb8aa3b, v56
	v_exp_f32_e32 v66, v66
	v_exp_f32_e32 v67, v67
	v_add_u32_e32 v64, 0x80, v152
	v_mad_i64_i32 v[64:65], s[38:39], v64, s55, v[144:145]
	v_add_f32_e32 v66, 1.0, v66
	v_add_f32_e32 v69, 1.0, v67
	v_add_f32_e32 v67, 1.0, v68
	v_rcp_f32_e32 v66, v66
	v_rcp_f32_e32 v67, v67
	v_mul_f32_e32 v68, 0xbfb8aa3b, v57
	v_exp_f32_e32 v70, v68
	v_rcp_f32_e32 v68, v69
	v_pk_mul_f32 v[60:61], v[60:61], v[66:67]
	v_mul_f32_e32 v66, 0xbfb8aa3b, v63
	v_pk_mul_f32 v[52:53], v[60:61], v[52:53]
	v_add_f32_e32 v60, 1.0, v70
	v_rcp_f32_e32 v69, v60
	v_mul_f32_e32 v61, 0xbfb8aa3b, v58
	v_mul_f32_e32 v60, 0xbfb8aa3b, v62
	v_exp_f32_e32 v61, v61
	v_exp_f32_e32 v60, v60
	v_exp_f32_e32 v67, v66
	v_mul_f32_e32 v66, 0xbfb8aa3b, v59
	v_pk_mul_f32 v[56:57], v[56:57], v[68:69]
	v_exp_f32_e32 v68, v66
	v_add_f32_e32 v61, 1.0, v61
	v_add_f32_e32 v60, 1.0, v60
; __device__ __forceinline__ float fsilu(float v) { return v * fsigmoid(v); }
; __device__ __forceinline__ u32x4 pack8(const f32x4 a, const f32x4 b) { u32x4 w; w.x = cvt_pk_bf16(a[0], a[1]); w.y = cvt_pk_bf16(a[2], a[3]); w.z = cvt_pk_bf16(b[0], b[1]); w.w = cvt_pk_bf16(b[2], b[3]); return w; }
; #define PG8_WAIT_V(n) asm volatile("s_waitcnt vmcnt(" #n ")" ::: "memory")
; #define PG8_BAR __builtin_amdgcn_s_barrier()
;     __device__ __forceinline__ void operator()(const f32x4 (&acc)[2][2][4][2], const Unit& u, int wr, int wc, int fr, int fq) const {
;         const int row0 = u.pm * BM + wr * 64 + fr, col0 = u.pn * 128 + wc * 32 + 8 * fq;
; #pragma unroll
;         for (int ai = 0; ai < 2; ++ai)
; #pragma unroll
;             for (int m = 0; m < 4; ++m) {
;                 bf16_t* rowp = O + (size_t)(row0 + ai * HALF + m * 16) * ldc + col0;
;                 f32x4 h0, h1;
; #pragma unroll
;                 for (int j = 0; j < 4; ++j) { h0[j] = fsilu(acc[ai][0][m][0][j]) * acc[ai][1][m][0][j]; h1[j] = fsilu(acc[ai][0][m][1][j]) * acc[ai][1][m][1][j]; }
;                 *(u32x4*)rowp = pack8(h0, h1);
; template <class Epi, class Sched, bool ALIGN_EPI = false, bool SP2 = false>
; __device__ __forceinline__ void gemm_phase(PG8_LAS unsigned char* lds, const Gemm g, const Sched& S, const Epi& E) {
;     ...
;         if (!has_next) break;
; #pragma unroll
;         for (int a = 0; a < 2; ++a)
; #pragma unroll
;             for (int b = 0; b < 2; ++b)
; #pragma unroll
;                 for (int m = 0; m < 4; ++m)
; #pragma unroll
;                     for (int n = 0; n < 2; ++n) acc[a][b][m][n] = (f32x4){0.f, 0.f, 0.f, 0.f};
;         cur = nxt; cA = nA; cB = nB; ++ui;
;         if constexpr (ALIGN_EPI) { if (wr == 1) PG8_BAR; }
;     }
;     PG8_WAIT_V(0);
;     if constexpr (!ALIGN_EPI) { if (wr == 0) PG8_BAR; }
;     PG8_BAR;
	v_rcp_f32_e32 v66, v61
	v_add_f32_e32 v61, 1.0, v67
	v_rcp_f32_e32 v60, v60
	v_rcp_f32_e32 v61, v61
	v_add_f32_e32 v67, 1.0, v68
	v_rcp_f32_e32 v67, v67
	v_pk_mul_f32 v[56:57], v[56:57], v[48:49]
	v_pk_mul_f32 v[48:49], v[62:63], v[60:61]
	v_lshl_add_u64 v[60:61], v[64:65], 0, v[112:113]
	v_pk_mul_f32 v[54:55], v[48:49], v[54:55]
	v_pk_mul_f32 v[48:49], v[58:59], v[66:67]
	s_mov_b64 s[40:41], s[34:35]
	v_pk_mul_f32 v[58:59], v[48:49], v[50:51]
	v_cvt_pk_bf16_f32 v48, v52, v53
	v_cvt_pk_bf16_f32 v49, v54, v55
	v_cvt_pk_bf16_f32 v50, v56, v57
	v_cvt_pk_bf16_f32 v51, v58, v59
	global_store_dwordx4 v[60:61], v[48:51], off
	v_mul_f32_e32 v52, 0xbfb8aa3b, v45
	v_exp_f32_e32 v52, v52
	v_mul_f32_e32 v50, 0xbfb8aa3b, v44
	v_mul_f32_e32 v51, 0xbfb8aa3b, v40
	v_exp_f32_e32 v50, v50
	v_exp_f32_e32 v51, v51
	v_add_u32_e32 v48, 0x90, v152
	v_mad_i64_i32 v[48:49], s[38:39], v48, s55, v[144:145]
	v_add_f32_e32 v50, 1.0, v50
	v_add_f32_e32 v53, 1.0, v51
	v_add_f32_e32 v51, 1.0, v52
	v_rcp_f32_e32 v50, v50
	v_rcp_f32_e32 v51, v51
	v_mul_f32_e32 v52, 0xbfb8aa3b, v41
	v_exp_f32_e32 v54, v52
	v_rcp_f32_e32 v52, v53
	v_pk_mul_f32 v[44:45], v[44:45], v[50:51]
	v_mul_f32_e32 v50, 0xbfb8aa3b, v47
	v_pk_mul_f32 v[36:37], v[44:45], v[36:37]
	v_add_f32_e32 v44, 1.0, v54
	v_rcp_f32_e32 v53, v44
	v_mul_f32_e32 v45, 0xbfb8aa3b, v42
	v_mul_f32_e32 v44, 0xbfb8aa3b, v46
	v_exp_f32_e32 v45, v45
	v_exp_f32_e32 v44, v44
	v_exp_f32_e32 v51, v50
	v_mul_f32_e32 v50, 0xbfb8aa3b, v43
	v_pk_mul_f32 v[40:41], v[40:41], v[52:53]
	v_exp_f32_e32 v52, v50
	v_add_f32_e32 v45, 1.0, v45
	v_add_f32_e32 v44, 1.0, v44
	v_rcp_f32_e32 v50, v45
	v_add_f32_e32 v45, 1.0, v51
	v_rcp_f32_e32 v44, v44
	v_rcp_f32_e32 v45, v45
	v_add_f32_e32 v51, 1.0, v52
	v_rcp_f32_e32 v51, v51
	v_pk_mul_f32 v[40:41], v[40:41], v[32:33]
	v_pk_mul_f32 v[32:33], v[46:47], v[44:45]
	v_lshl_add_u64 v[44:45], v[48:49], 0, v[112:113]
	v_pk_mul_f32 v[38:39], v[32:33], v[38:39]
	v_pk_mul_f32 v[32:33], v[42:43], v[50:51]
	s_nop 0
	v_pk_mul_f32 v[42:43], v[32:33], v[34:35]
	v_cvt_pk_bf16_f32 v32, v36, v37
	v_cvt_pk_bf16_f32 v33, v38, v39
	v_cvt_pk_bf16_f32 v34, v40, v41
	v_cvt_pk_bf16_f32 v35, v42, v43
	global_store_dwordx4 v[44:45], v[32:35], off
	v_mul_f32_e32 v36, 0xbfb8aa3b, v29
	v_exp_f32_e32 v36, v36
	v_mul_f32_e32 v34, 0xbfb8aa3b, v28
	v_mul_f32_e32 v35, 0xbfb8aa3b, v24
	v_exp_f32_e32 v34, v34
	v_exp_f32_e32 v35, v35
	v_add_u32_e32 v32, 0xa0, v152
	v_mad_i64_i32 v[32:33], s[38:39], v32, s55, v[144:145]
	v_add_f32_e32 v34, 1.0, v34
	v_add_f32_e32 v37, 1.0, v35
	v_add_f32_e32 v35, 1.0, v36
	v_rcp_f32_e32 v34, v34
	v_rcp_f32_e32 v35, v35
	v_mul_f32_e32 v36, 0xbfb8aa3b, v25
	v_exp_f32_e32 v38, v36
	v_rcp_f32_e32 v36, v37
	v_pk_mul_f32 v[28:29], v[28:29], v[34:35]
	v_mul_f32_e32 v34, 0xbfb8aa3b, v31
	v_pk_mul_f32 v[20:21], v[28:29], v[20:21]
	v_add_f32_e32 v28, 1.0, v38
	v_rcp_f32_e32 v37, v28
	v_mul_f32_e32 v29, 0xbfb8aa3b, v26
	v_mul_f32_e32 v28, 0xbfb8aa3b, v30
	v_exp_f32_e32 v29, v29
	v_exp_f32_e32 v28, v28
	v_exp_f32_e32 v35, v34
	v_mul_f32_e32 v34, 0xbfb8aa3b, v27
	v_pk_mul_f32 v[24:25], v[24:25], v[36:37]
	v_exp_f32_e32 v36, v34
	v_add_f32_e32 v29, 1.0, v29
	v_add_f32_e32 v28, 1.0, v28
	v_rcp_f32_e32 v34, v29
	v_add_f32_e32 v29, 1.0, v35
	v_rcp_f32_e32 v28, v28
	v_rcp_f32_e32 v29, v29
	v_add_f32_e32 v35, 1.0, v36
	v_rcp_f32_e32 v35, v35
	v_pk_mul_f32 v[24:25], v[24:25], v[16:17]
	v_pk_mul_f32 v[16:17], v[30:31], v[28:29]
	v_lshl_add_u64 v[28:29], v[32:33], 0, v[112:113]
	v_pk_mul_f32 v[22:23], v[16:17], v[22:23]
	v_pk_mul_f32 v[16:17], v[26:27], v[34:35]
	s_nop 0
	v_pk_mul_f32 v[26:27], v[16:17], v[18:19]
	v_cvt_pk_bf16_f32 v16, v20, v21
	v_cvt_pk_bf16_f32 v17, v22, v23
	v_cvt_pk_bf16_f32 v18, v24, v25
	v_cvt_pk_bf16_f32 v19, v26, v27
	global_store_dwordx4 v[28:29], v[16:19], off
	v_mul_f32_e32 v20, 0xbfb8aa3b, v13
	v_exp_f32_e32 v20, v20
	v_mul_f32_e32 v18, 0xbfb8aa3b, v12
	v_mul_f32_e32 v19, 0xbfb8aa3b, v8
	v_exp_f32_e32 v18, v18
	v_exp_f32_e32 v19, v19
	v_add_u32_e32 v16, 0xb0, v152
	v_mad_i64_i32 v[16:17], s[38:39], v16, s55, v[144:145]
	v_add_f32_e32 v18, 1.0, v18
	v_add_f32_e32 v21, 1.0, v19
	v_add_f32_e32 v19, 1.0, v20
	v_rcp_f32_e32 v18, v18
	v_rcp_f32_e32 v19, v19
	v_mul_f32_e32 v20, 0xbfb8aa3b, v9
	v_exp_f32_e32 v22, v20
	v_rcp_f32_e32 v20, v21
	v_pk_mul_f32 v[12:13], v[12:13], v[18:19]
	v_mul_f32_e32 v18, 0xbfb8aa3b, v15
	v_pk_mul_f32 v[4:5], v[12:13], v[4:5]
	v_add_f32_e32 v12, 1.0, v22
	v_rcp_f32_e32 v21, v12
	v_mul_f32_e32 v13, 0xbfb8aa3b, v10
	v_mul_f32_e32 v12, 0xbfb8aa3b, v14
	v_exp_f32_e32 v13, v13
	v_exp_f32_e32 v12, v12
	v_exp_f32_e32 v19, v18
	v_mul_f32_e32 v18, 0xbfb8aa3b, v11
	v_pk_mul_f32 v[8:9], v[8:9], v[20:21]
	v_exp_f32_e32 v20, v18
	v_add_f32_e32 v13, 1.0, v13
	v_add_f32_e32 v12, 1.0, v12
	v_rcp_f32_e32 v18, v13
	v_add_f32_e32 v13, 1.0, v19
	v_rcp_f32_e32 v12, v12
	v_rcp_f32_e32 v13, v13
	v_add_f32_e32 v19, 1.0, v20
	v_rcp_f32_e32 v19, v19
	v_pk_mul_f32 v[8:9], v[8:9], v[0:1]
	v_pk_mul_f32 v[0:1], v[14:15], v[12:13]
	v_lshl_add_u64 v[12:13], v[16:17], 0, v[112:113]
	v_pk_mul_f32 v[6:7], v[0:1], v[6:7]
	v_pk_mul_f32 v[0:1], v[10:11], v[18:19]
	s_mov_b64 s[38:39], s[30:31]
	v_pk_mul_f32 v[10:11], v[0:1], v[2:3]
	v_cvt_pk_bf16_f32 v0, v4, v5
	v_cvt_pk_bf16_f32 v1, v6, v7
	v_cvt_pk_bf16_f32 v2, v8, v9
	v_cvt_pk_bf16_f32 v3, v10, v11
	global_store_dwordx4 v[12:13], v[0:3], off
	s_cbranch_vccz .LBB0_166
	s_waitcnt vmcnt(0)
	s_cmpk_gt_u32 s3, 0xff
	s_cbranch_scc1 .LBB0_173
	s_barrier

; #define PG8_STAGE(bufoff, gbase, voff) do { _Pragma("unroll") for (int _i = 0; _i < 2; ++_i) \
;         __builtin_amdgcn_global_load_lds((const unsigned*)((const char*)(gbase) + (voff)[_i]), (PG8_LAS unsigned*)(lds + (bufoff) + ldsw + _i * 8192), 16, 0, 0); } while (0)
; #define PG8_LDA(dst, b, h) do { _Pragma("unroll") for (int m = 0; m < 4; ++m) _Pragma("unroll") for (int k = 0; k < 2; ++k) dst[m][k] = *(const PG8_LAS bf16x8*)(lds + PG8_SA(b, h) + aoff + m * 2048 + k * 1024); } while (0)
; #define PG8_LDB(dst, b, h) do { _Pragma("unroll") for (int n = 0; n < 2; ++n) _Pragma("unroll") for (int k = 0; k < 2; ++k) dst[n][k] = *(const PG8_LAS bf16x8*)(lds + PG8_SB(b, h) + boff + n * 2048 + k * 1024); } while (0)
; #define PG8_MMA(ai, bj, At, Bt) do { __builtin_amdgcn_s_setprio(1); _Pragma("unroll") for (int m = 0; m < 4; ++m) _Pragma("unroll") for (int n = 0; n < 2; ++n) _Pragma("unroll") for (int k = 0; k < 2; ++k) \
;         acc[ai][bj][m][n] = __builtin_amdgcn_mfma_f32_16x16x32_bf16(Bt[n][k], At[m][k], acc[ai][bj][m][n], 0, 0, 0); __builtin_amdgcn_s_setprio(0); } while (0)
; #define PG8_BAR __builtin_amdgcn_s_barrier()
; template <class Epi, class Sched, bool ALIGN_EPI = false, bool SP2 = false>
; __device__ __forceinline__ void gemm_phase(PG8_LAS unsigned char* lds, const Gemm g, const Sched& S, const Epi& E) {
;     ...
;         const bool has_next = S.next(ui + 1, nxt);
;         const char* nA = has_next ? (const char*)g.A + (size_t)nxt.pm * tstep : cA; const char* nB = has_next ? (const char*)g.Bt + (size_t)nxt.pn * tstep : cB;
;         for (int t = 0; t < nt; t += 2) {
;             const bool last = (t == nt - 2);
;             const char* a1 = cA + (size_t)(t + 1) * kstep;
;             const char* a2 = last ? nA : cA + (size_t)(t + 2) * kstep; const char* b2 = last ? nB : cB + (size_t)(t + 2) * kstep;
;             const char* a3 = a2 + kstep; const char* b3 = b2 + kstep;
;             if (last && has_next) S.a_ready(nxt);
;             if constexpr (SP2) {
;             PG8_LDB(B0, 0, 0); PG8_LDB(B1, 0, 1); PG8_SCHED; PG8_LDA(At, 0, 0); PG8_STAGE(PG8_SA(1, 1), a1 + hstep, voffA);
;             PG8_WAIT_V(8); PG8_WAIT_L(0); PG8_BAR; PG8_MMA(0, 0, At, B0); PG8_MMA(0, 1, At, B1); PG8_BAR; PG8_SCHED;
;             PG8_LDA(At, 0, 1); PG8_STAGE(PG8_SB(0, 0), b2, voffB); PG8_STAGE(PG8_SB(0, 1), b2 + hstep, voffB); PG8_STAGE(PG8_SA(0, 0), a2, voffA);
.LBB0_244:
	s_add_u32 s67, s46, 0x100
	v_mov_b32_e32 v220, v251
	s_addc_u32 s68, s47, 0
	s_mov_b32 s69, -2
	ds_read_b128 v[140:143], v169
	ds_read_b128 v[144:147], v169 offset:1024
	ds_read_b128 v[148:151], v169 offset:2048
	ds_read_b128 v[152:155], v169 offset:3072
	ds_read_b128 v[156:159], v170
	ds_read_b128 v[160:163], v170 offset:1024
	ds_read_b128 v[172:175], v170 offset:2048
	ds_read_b128 v[176:179], v170 offset:3072
	s_add_u32 s46, s44, 0x100
	s_addc_u32 s47, s45, 0
	s_cmpk_eq_i32 s69, 0x54
	s_cselect_b32 s51, s11, s47
	s_cselect_b32 s50, s10, s46
	s_cselect_b32 s49, s13, s68
	s_cselect_b32 s48, s12, s67
	s_add_i32 m0, s26, 0xc000
	ds_read_b128 v[180:183], v171
	ds_read_b128 v[184:187], v171 offset:1024
	ds_read_b128 v[188:191], v171 offset:2048
	ds_read_b128 v[192:195], v171 offset:3072
	ds_read_b128 v[196:199], v171 offset:4096
	ds_read_b128 v[200:203], v171 offset:5120
	ds_read_b128 v[204:207], v171 offset:6144
	ds_read_b128 v[208:211], v171 offset:7168
	global_load_lds_dwordx4 v136, s[44:45]
	s_add_i32 m0, s26, 0xe000
	s_nop 0
	global_load_lds_dwordx4 v138, s[44:45]
	s_waitcnt vmcnt(8)
	s_waitcnt lgkmcnt(0)
	s_barrier
	s_waitcnt lgkmcnt(0)
	v_mfma_f32_16x16x32_bf16 v[124:127], v[140:143], v[180:183], 0
	v_mfma_f32_16x16x32_bf16 v[120:123], v[148:151], v[180:183], 0
	v_mfma_f32_16x16x32_bf16 v[116:119], v[140:143], v[188:191], 0
	v_mfma_f32_16x16x32_bf16 v[112:115], v[148:151], v[188:191], 0
	v_mfma_f32_16x16x32_bf16 v[108:111], v[140:143], v[196:199], 0
	v_mfma_f32_16x16x32_bf16 v[96:99], v[148:151], v[196:199], 0
	v_mfma_f32_16x16x32_bf16 v[84:87], v[140:143], v[204:207], 0
	v_mfma_f32_16x16x32_bf16 v[76:79], v[148:151], v[204:207], 0
	v_mfma_f32_16x16x32_bf16 v[124:127], v[144:147], v[184:187], v[124:127]
	v_mfma_f32_16x16x32_bf16 v[120:123], v[152:155], v[184:187], v[120:123]
	v_mfma_f32_16x16x32_bf16 v[116:119], v[144:147], v[192:195], v[116:119]
	v_mfma_f32_16x16x32_bf16 v[112:115], v[152:155], v[192:195], v[112:115]
	v_mfma_f32_16x16x32_bf16 v[108:111], v[144:147], v[200:203], v[108:111]
	v_mfma_f32_16x16x32_bf16 v[96:99], v[152:155], v[200:203], v[96:99]
	v_mfma_f32_16x16x32_bf16 v[84:87], v[144:147], v[208:211], v[84:87]
	v_mfma_f32_16x16x32_bf16 v[76:79], v[152:155], v[208:211], v[76:79]
	v_mfma_f32_16x16x32_bf16 v[104:107], v[156:159], v[180:183], 0
	v_mfma_f32_16x16x32_bf16 v[100:103], v[172:175], v[180:183], 0
	v_mfma_f32_16x16x32_bf16 v[92:95], v[156:159], v[188:191], 0
	v_mfma_f32_16x16x32_bf16 v[88:91], v[172:175], v[188:191], 0
	v_mfma_f32_16x16x32_bf16 v[80:83], v[156:159], v[196:199], 0
	v_mfma_f32_16x16x32_bf16 v[72:75], v[172:175], v[196:199], 0
	v_mfma_f32_16x16x32_bf16 v[68:71], v[156:159], v[204:207], 0
	v_mfma_f32_16x16x32_bf16 v[64:67], v[172:175], v[204:207], 0
	v_mfma_f32_16x16x32_bf16 v[104:107], v[160:163], v[184:187], v[104:107]
	v_mfma_f32_16x16x32_bf16 v[100:103], v[176:179], v[184:187], v[100:103]
	v_mfma_f32_16x16x32_bf16 v[92:95], v[160:163], v[192:195], v[92:95]
	v_mfma_f32_16x16x32_bf16 v[88:91], v[176:179], v[192:195], v[88:91]
	v_mfma_f32_16x16x32_bf16 v[80:83], v[160:163], v[200:203], v[80:83]
	v_mfma_f32_16x16x32_bf16 v[72:75], v[176:179], v[200:203], v[72:75]
	v_mfma_f32_16x16x32_bf16 v[68:71], v[160:163], v[208:211], v[68:71]
	v_mfma_f32_16x16x32_bf16 v[64:67], v[176:179], v[208:211], v[64:67]
	s_barrier
	s_add_i32 s44, s61, s25
	s_mov_b32 m0, s44
	ds_read_b128 v[180:183], v171 offset:16384
	ds_read_b128 v[184:187], v171 offset:17408
	ds_read_b128 v[188:191], v171 offset:18432
	ds_read_b128 v[192:195], v171 offset:19456
	ds_read_b128 v[196:199], v171 offset:20480
	ds_read_b128 v[200:203], v171 offset:21504
	ds_read_b128 v[204:207], v171 offset:22528
	ds_read_b128 v[208:211], v171 offset:23552
	global_load_lds_dwordx4 v130, s[48:49]
	s_add_i32 m0, s44, 0x2000
	s_add_u32 s44, s48, 0x160000
	s_addc_u32 s45, s49, 0
	s_add_i32 s70, s62, s25
	global_load_lds_dwordx4 v134, s[48:49]
	s_mov_b32 m0, s70
	s_nop 0
	global_load_lds_dwordx4 v130, s[44:45]
	s_add_i32 m0, s70, 0x2000
	s_nop 0
	global_load_lds_dwordx4 v134, s[44:45]
	s_mov_b32 m0, s26
	s_nop 0
	global_load_lds_dwordx4 v128, s[50:51]
	s_mov_b32 m0, s27
	s_nop 0
	global_load_lds_dwordx4 v132, s[50:51]
	s_waitcnt vmcnt(8)
	s_waitcnt lgkmcnt(0)
	s_barrier
	s_waitcnt lgkmcnt(0)
	v_mfma_f32_16x16x32_bf16 v[60:63], v[140:143], v[180:183], 0
	v_mfma_f32_16x16x32_bf16 v[56:59], v[148:151], v[180:183], 0
	v_mfma_f32_16x16x32_bf16 v[52:55], v[140:143], v[188:191], 0
	v_mfma_f32_16x16x32_bf16 v[48:51], v[148:151], v[188:191], 0
	v_mfma_f32_16x16x32_bf16 v[44:47], v[140:143], v[196:199], 0
	v_mfma_f32_16x16x32_bf16 v[32:35], v[148:151], v[196:199], 0
	v_mfma_f32_16x16x32_bf16 v[20:23], v[140:143], v[204:207], 0
	v_mfma_f32_16x16x32_bf16 v[12:15], v[148:151], v[204:207], 0
	v_mfma_f32_16x16x32_bf16 v[60:63], v[144:147], v[184:187], v[60:63]
	v_mfma_f32_16x16x32_bf16 v[56:59], v[152:155], v[184:187], v[56:59]
	v_mfma_f32_16x16x32_bf16 v[52:55], v[144:147], v[192:195], v[52:55]
	v_mfma_f32_16x16x32_bf16 v[48:51], v[152:155], v[192:195], v[48:51]
	v_mfma_f32_16x16x32_bf16 v[44:47], v[144:147], v[200:203], v[44:47]
	v_mfma_f32_16x16x32_bf16 v[32:35], v[152:155], v[200:203], v[32:35]
	v_mfma_f32_16x16x32_bf16 v[20:23], v[144:147], v[208:211], v[20:23]
	v_mfma_f32_16x16x32_bf16 v[12:15], v[152:155], v[208:211], v[12:15]
	v_mfma_f32_16x16x32_bf16 v[40:43], v[156:159], v[180:183], 0
	v_mfma_f32_16x16x32_bf16 v[36:39], v[172:175], v[180:183], 0
	v_mfma_f32_16x16x32_bf16 v[28:31], v[156:159], v[188:191], 0
	v_mfma_f32_16x16x32_bf16 v[24:27], v[172:175], v[188:191], 0
	v_mfma_f32_16x16x32_bf16 v[16:19], v[156:159], v[196:199], 0
	v_mfma_f32_16x16x32_bf16 v[8:11], v[172:175], v[196:199], 0
	v_mfma_f32_16x16x32_bf16 v[4:7], v[156:159], v[204:207], 0
	v_mfma_f32_16x16x32_bf16 v[0:3], v[172:175], v[204:207], 0
	v_mfma_f32_16x16x32_bf16 v[40:43], v[160:163], v[184:187], v[40:43]
	v_mfma_f32_16x16x32_bf16 v[36:39], v[176:179], v[184:187], v[36:39]
	v_mfma_f32_16x16x32_bf16 v[28:31], v[160:163], v[192:195], v[28:31]
	v_mfma_f32_16x16x32_bf16 v[24:27], v[176:179], v[192:195], v[24:27]
	v_mfma_f32_16x16x32_bf16 v[16:19], v[160:163], v[200:203], v[16:19]
	v_mfma_f32_16x16x32_bf16 v[8:11], v[176:179], v[200:203], v[8:11]
	v_mfma_f32_16x16x32_bf16 v[4:7], v[160:163], v[208:211], v[4:7]
	v_mfma_f32_16x16x32_bf16 v[0:3], v[176:179], v[208:211], v[0:3]
	s_barrier
; #define PG8_STAGE(bufoff, gbase, voff) do { _Pragma("unroll") for (int _i = 0; _i < 2; ++_i) \
;         __builtin_amdgcn_global_load_lds((const unsigned*)((const char*)(gbase) + (voff)[_i]), (PG8_LAS unsigned*)(lds + (bufoff) + ldsw + _i * 8192), 16, 0, 0); } while (0)
; #define PG8_LDA(dst, b, h) do { _Pragma("unroll") for (int m = 0; m < 4; ++m) _Pragma("unroll") for (int k = 0; k < 2; ++k) dst[m][k] = *(const PG8_LAS bf16x8*)(lds + PG8_SA(b, h) + aoff + m * 2048 + k * 1024); } while (0)
; #define PG8_LDB(dst, b, h) do { _Pragma("unroll") for (int n = 0; n < 2; ++n) _Pragma("unroll") for (int k = 0; k < 2; ++k) dst[n][k] = *(const PG8_LAS bf16x8*)(lds + PG8_SB(b, h) + boff + n * 2048 + k * 1024); } while (0)
; #define PG8_MMA(ai, bj, At, Bt) do { __builtin_amdgcn_s_setprio(1); _Pragma("unroll") for (int m = 0; m < 4; ++m) _Pragma("unroll") for (int n = 0; n < 2; ++n) _Pragma("unroll") for (int k = 0; k < 2; ++k) \
;         acc[ai][bj][m][n] = __builtin_amdgcn_mfma_f32_16x16x32_bf16(Bt[n][k], At[m][k], acc[ai][bj][m][n], 0, 0, 0); __builtin_amdgcn_s_setprio(0); } while (0)
; #define PG8_WAIT_V(n) asm volatile("s_waitcnt vmcnt(" #n ")" ::: "memory")
; #define PG8_WAIT_L(n) asm volatile("s_waitcnt lgkmcnt(" #n ")" ::: "memory")
; #define PG8_BAR __builtin_amdgcn_s_barrier()
; #define PG8_SCHED __builtin_amdgcn_sched_barrier(0)
; template <class Epi, class Sched, bool ALIGN_EPI = false, bool SP2 = false>
; __device__ __forceinline__ void gemm_phase(PG8_LAS unsigned char* lds, const Gemm g, const Sched& S, const Epi& E) {
;     ...
;             PG8_LDB(B0, 1, 0); PG8_LDB(B1, 1, 1); PG8_SCHED; PG8_LDA(At, 1, 0); PG8_STAGE(PG8_SA(0, 1), a2 + hstep, voffA);
;             PG8_WAIT_V(8); PG8_WAIT_L(0); PG8_BAR; PG8_MMA(0, 0, At, B0); PG8_MMA(0, 1, At, B1); PG8_BAR; PG8_SCHED;
;             PG8_LDA(At, 1, 1); PG8_STAGE(PG8_SB(1, 0), b3, voffB); PG8_STAGE(PG8_SB(1, 1), b3 + hstep, voffB); PG8_STAGE(PG8_SA(1, 0), a3, voffA);
;             PG8_WAIT_V(8); PG8_WAIT_L(0); PG8_BAR; PG8_MMA(1, 0, At, B0); PG8_MMA(1, 1, At, B1); PG8_BAR; PG8_SCHED;
	s_add_i32 s70, 0, 0x18000
	s_add_i32 s71, 0, 0x1c000
	v_add_u32_e32 v152, s70, v167
	v_add_u32_e32 v176, s71, v167
	ds_read_b128 v[140:143], v152
	ds_read_b128 v[144:147], v152 offset:1024
	ds_read_b128 v[148:151], v152 offset:2048
	ds_read_b128 v[152:155], v152 offset:3072
	ds_read_b128 v[156:159], v176
	ds_read_b128 v[160:163], v176 offset:1024
	ds_read_b128 v[172:175], v176 offset:2048
	ds_read_b128 v[176:179], v176 offset:3072
	s_add_u32 s44, s50, 0x160000
	s_addc_u32 s45, s51, 0
	s_mov_b32 m0, s52
	ds_read_b128 v[180:183], v171 offset:32768
	ds_read_b128 v[184:187], v171 offset:33792
	ds_read_b128 v[188:191], v171 offset:34816
	ds_read_b128 v[192:195], v171 offset:35840
	ds_read_b128 v[196:199], v171 offset:36864
	ds_read_b128 v[200:203], v171 offset:37888
	ds_read_b128 v[204:207], v171 offset:38912
	ds_read_b128 v[208:211], v171 offset:39936
	global_load_lds_dwordx4 v128, s[44:45]
	s_mov_b32 m0, s53
	s_nop 0
	global_load_lds_dwordx4 v132, s[44:45]
	s_waitcnt vmcnt(8)
	s_waitcnt lgkmcnt(0)
	s_barrier
	s_waitcnt lgkmcnt(0)
	v_mfma_f32_16x16x32_bf16 v[124:127], v[140:143], v[180:183], v[124:127]
	v_mfma_f32_16x16x32_bf16 v[120:123], v[148:151], v[180:183], v[120:123]
	v_mfma_f32_16x16x32_bf16 v[116:119], v[140:143], v[188:191], v[116:119]
	v_mfma_f32_16x16x32_bf16 v[112:115], v[148:151], v[188:191], v[112:115]
	v_mfma_f32_16x16x32_bf16 v[108:111], v[140:143], v[196:199], v[108:111]
	v_mfma_f32_16x16x32_bf16 v[96:99], v[148:151], v[196:199], v[96:99]
	v_mfma_f32_16x16x32_bf16 v[84:87], v[140:143], v[204:207], v[84:87]
	v_mfma_f32_16x16x32_bf16 v[76:79], v[148:151], v[204:207], v[76:79]
	v_mfma_f32_16x16x32_bf16 v[124:127], v[144:147], v[184:187], v[124:127]
	v_mfma_f32_16x16x32_bf16 v[120:123], v[152:155], v[184:187], v[120:123]
	v_mfma_f32_16x16x32_bf16 v[116:119], v[144:147], v[192:195], v[116:119]
	v_mfma_f32_16x16x32_bf16 v[112:115], v[152:155], v[192:195], v[112:115]
	v_mfma_f32_16x16x32_bf16 v[108:111], v[144:147], v[200:203], v[108:111]
	v_mfma_f32_16x16x32_bf16 v[96:99], v[152:155], v[200:203], v[96:99]
	v_mfma_f32_16x16x32_bf16 v[84:87], v[144:147], v[208:211], v[84:87]
	v_mfma_f32_16x16x32_bf16 v[76:79], v[152:155], v[208:211], v[76:79]
	v_mfma_f32_16x16x32_bf16 v[104:107], v[156:159], v[180:183], v[104:107]
	v_mfma_f32_16x16x32_bf16 v[100:103], v[172:175], v[180:183], v[100:103]
	v_mfma_f32_16x16x32_bf16 v[92:95], v[156:159], v[188:191], v[92:95]
	v_mfma_f32_16x16x32_bf16 v[88:91], v[172:175], v[188:191], v[88:91]
	v_mfma_f32_16x16x32_bf16 v[80:83], v[156:159], v[196:199], v[80:83]
	v_mfma_f32_16x16x32_bf16 v[72:75], v[172:175], v[196:199], v[72:75]
	v_mfma_f32_16x16x32_bf16 v[68:71], v[156:159], v[204:207], v[68:71]
	v_mfma_f32_16x16x32_bf16 v[64:67], v[172:175], v[204:207], v[64:67]
	v_mfma_f32_16x16x32_bf16 v[104:107], v[160:163], v[184:187], v[104:107]
	v_mfma_f32_16x16x32_bf16 v[100:103], v[176:179], v[184:187], v[100:103]
	v_mfma_f32_16x16x32_bf16 v[92:95], v[160:163], v[192:195], v[92:95]
	v_mfma_f32_16x16x32_bf16 v[88:91], v[176:179], v[192:195], v[88:91]
	v_mfma_f32_16x16x32_bf16 v[80:83], v[160:163], v[200:203], v[80:83]
	v_mfma_f32_16x16x32_bf16 v[72:75], v[176:179], v[200:203], v[72:75]
	v_mfma_f32_16x16x32_bf16 v[68:71], v[160:163], v[208:211], v[68:71]
	v_mfma_f32_16x16x32_bf16 v[64:67], v[176:179], v[208:211], v[64:67]
	s_barrier
	s_add_i32 s44, s70, s25
	s_add_u32 s86, s48, 0x80
	s_addc_u32 s87, s49, 0
	s_mov_b32 m0, s44
	ds_read_b128 v[180:183], v171 offset:49152
	ds_read_b128 v[184:187], v171 offset:50176
	ds_read_b128 v[188:191], v171 offset:51200
	ds_read_b128 v[192:195], v171 offset:52224
	ds_read_b128 v[196:199], v171 offset:53248
	ds_read_b128 v[200:203], v171 offset:54272
	ds_read_b128 v[204:207], v171 offset:55296
	ds_read_b128 v[208:211], v171 offset:56320
	global_load_lds_dwordx4 v130, s[86:87]
	s_add_i32 m0, s44, 0x2000
	s_add_u32 s44, s48, 0x160080
	s_addc_u32 s45, s49, 0
	s_add_i32 s48, s71, s25
	global_load_lds_dwordx4 v134, s[86:87]
	s_mov_b32 m0, s48
	s_nop 0
	global_load_lds_dwordx4 v130, s[44:45]
	s_add_i32 m0, s48, 0x2000
	s_nop 0
	global_load_lds_dwordx4 v134, s[44:45]
	s_add_u32 s84, s50, 0x80
	s_addc_u32 s85, s51, 0
	s_mov_b32 m0, s57
	s_nop 0
	global_load_lds_dwordx4 v128, s[84:85]
	s_mov_b32 m0, s58
	s_nop 0
	global_load_lds_dwordx4 v132, s[84:85]
	s_waitcnt vmcnt(8)
	s_waitcnt lgkmcnt(0)
	s_barrier
	s_waitcnt lgkmcnt(0)
	v_mfma_f32_16x16x32_bf16 v[60:63], v[140:143], v[180:183], v[60:63]
	v_mfma_f32_16x16x32_bf16 v[56:59], v[148:151], v[180:183], v[56:59]
	v_mfma_f32_16x16x32_bf16 v[52:55], v[140:143], v[188:191], v[52:55]
	v_mfma_f32_16x16x32_bf16 v[48:51], v[148:151], v[188:191], v[48:51]
	v_mfma_f32_16x16x32_bf16 v[44:47], v[140:143], v[196:199], v[44:47]
	v_mfma_f32_16x16x32_bf16 v[32:35], v[148:151], v[196:199], v[32:35]
	v_mfma_f32_16x16x32_bf16 v[20:23], v[140:143], v[204:207], v[20:23]
	v_mfma_f32_16x16x32_bf16 v[12:15], v[148:151], v[204:207], v[12:15]
	v_mfma_f32_16x16x32_bf16 v[60:63], v[144:147], v[184:187], v[60:63]
	v_mfma_f32_16x16x32_bf16 v[56:59], v[152:155], v[184:187], v[56:59]
	v_mfma_f32_16x16x32_bf16 v[52:55], v[144:147], v[192:195], v[52:55]
	v_mfma_f32_16x16x32_bf16 v[48:51], v[152:155], v[192:195], v[48:51]
	v_mfma_f32_16x16x32_bf16 v[44:47], v[144:147], v[200:203], v[44:47]
	v_mfma_f32_16x16x32_bf16 v[32:35], v[152:155], v[200:203], v[32:35]
	v_mfma_f32_16x16x32_bf16 v[20:23], v[144:147], v[208:211], v[20:23]
	v_mfma_f32_16x16x32_bf16 v[12:15], v[152:155], v[208:211], v[12:15]
	v_mfma_f32_16x16x32_bf16 v[40:43], v[156:159], v[180:183], v[40:43]
	v_mfma_f32_16x16x32_bf16 v[36:39], v[172:175], v[180:183], v[36:39]
	v_mfma_f32_16x16x32_bf16 v[28:31], v[156:159], v[188:191], v[28:31]
	v_mfma_f32_16x16x32_bf16 v[24:27], v[172:175], v[188:191], v[24:27]
	v_mfma_f32_16x16x32_bf16 v[16:19], v[156:159], v[196:199], v[16:19]
	v_mfma_f32_16x16x32_bf16 v[8:11], v[172:175], v[196:199], v[8:11]
	v_mfma_f32_16x16x32_bf16 v[4:7], v[156:159], v[204:207], v[4:7]
	v_mfma_f32_16x16x32_bf16 v[0:3], v[172:175], v[204:207], v[0:3]
	v_mfma_f32_16x16x32_bf16 v[40:43], v[160:163], v[184:187], v[40:43]
	v_mfma_f32_16x16x32_bf16 v[36:39], v[176:179], v[184:187], v[36:39]
	v_mfma_f32_16x16x32_bf16 v[28:31], v[160:163], v[192:195], v[28:31]
	v_mfma_f32_16x16x32_bf16 v[24:27], v[176:179], v[192:195], v[24:27]
	v_mfma_f32_16x16x32_bf16 v[16:19], v[160:163], v[200:203], v[16:19]
	v_mfma_f32_16x16x32_bf16 v[8:11], v[176:179], v[200:203], v[8:11]
	v_mfma_f32_16x16x32_bf16 v[4:7], v[160:163], v[208:211], v[4:7]
	v_mfma_f32_16x16x32_bf16 v[0:3], v[176:179], v[208:211], v[0:3]
	s_add_i32 s69, s69, 2
	s_add_u32 s67, s67, 0x100
	s_addc_u32 s68, s68, 0
	s_cmpk_gt_u32 s69, 0x55
	s_mov_b64 s[44:45], s[46:47]
	s_barrier
; #define PG8_STAGE(bufoff, gbase, voff) do { _Pragma("unroll") for (int _i = 0; _i < 2; ++_i) \
;         __builtin_amdgcn_global_load_lds((const unsigned*)((const char*)(gbase) + (voff)[_i]), (PG8_LAS unsigned*)(lds + (bufoff) + ldsw + _i * 8192), 16, 0, 0); } while (0)
; #define PG8_LDA(dst, b, h) do { _Pragma("unroll") for (int m = 0; m < 4; ++m) _Pragma("unroll") for (int k = 0; k < 2; ++k) dst[m][k] = *(const PG8_LAS bf16x8*)(lds + PG8_SA(b, h) + aoff + m * 2048 + k * 1024); } while (0)
; #define PG8_LDB(dst, b, h) do { _Pragma("unroll") for (int n = 0; n < 2; ++n) _Pragma("unroll") for (int k = 0; k < 2; ++k) dst[n][k] = *(const PG8_LAS bf16x8*)(lds + PG8_SB(b, h) + boff + n * 2048 + k * 1024); } while (0)
; #define PG8_MMA(ai, bj, At, Bt) do { __builtin_amdgcn_s_setprio(1); _Pragma("unroll") for (int m = 0; m < 4; ++m) _Pragma("unroll") for (int n = 0; n < 2; ++n) _Pragma("unroll") for (int k = 0; k < 2; ++k) \
;         acc[ai][bj][m][n] = __builtin_amdgcn_mfma_f32_16x16x32_bf16(Bt[n][k], At[m][k], acc[ai][bj][m][n], 0, 0, 0); __builtin_amdgcn_s_setprio(0); } while (0)
; #define PG8_WAIT_V(n) asm volatile("s_waitcnt vmcnt(" #n ")" ::: "memory")
; #define PG8_WAIT_L(n) asm volatile("s_waitcnt lgkmcnt(" #n ")" ::: "memory")
; #define PG8_BAR __builtin_amdgcn_s_barrier()
; #define PG8_SCHED __builtin_amdgcn_sched_barrier(0)
; template <class Epi, class Sched, bool ALIGN_EPI = false, bool SP2 = false>
; __device__ __forceinline__ void gemm_phase(PG8_LAS unsigned char* lds, const Gemm g, const Sched& S, const Epi& E) {
;     ...
;             PG8_LDB(B0, 0, 0); PG8_LDB(B1, 0, 1); PG8_SCHED; PG8_LDA(At, 0, 0); PG8_STAGE(PG8_SA(1, 1), a1 + hstep, voffA);
;             PG8_WAIT_V(8); PG8_WAIT_L(0); PG8_BAR; PG8_MMA(0, 0, At, B0); PG8_MMA(0, 1, At, B1); PG8_BAR; PG8_SCHED;
;             PG8_LDA(At, 0, 1); PG8_STAGE(PG8_SB(0, 0), b2, voffB); PG8_STAGE(PG8_SB(0, 1), b2 + hstep, voffB); PG8_STAGE(PG8_SA(0, 0), a2, voffA);
;             PG8_WAIT_V(8); PG8_WAIT_L(0); PG8_BAR; PG8_MMA(1, 0, At, B0); PG8_MMA(1, 1, At, B1); PG8_BAR; PG8_SCHED;
.LBB0_245:
	ds_read_b128 v[140:143], v169
	ds_read_b128 v[144:147], v169 offset:1024
	ds_read_b128 v[148:151], v169 offset:2048
	ds_read_b128 v[152:155], v169 offset:3072
	ds_read_b128 v[156:159], v170
	ds_read_b128 v[160:163], v170 offset:1024
	ds_read_b128 v[172:175], v170 offset:2048
	ds_read_b128 v[176:179], v170 offset:3072
	s_add_u32 s46, s44, 0x100
	s_addc_u32 s47, s45, 0
	s_cmpk_eq_i32 s69, 0x54
	s_cselect_b32 s51, s11, s47
	s_cselect_b32 s50, s10, s46
	s_cselect_b32 s49, s13, s68
	s_cselect_b32 s48, s12, s67
	s_add_i32 m0, s26, 0xc000
	ds_read_b128 v[180:183], v171
	ds_read_b128 v[184:187], v171 offset:1024
	ds_read_b128 v[188:191], v171 offset:2048
	ds_read_b128 v[192:195], v171 offset:3072
	ds_read_b128 v[196:199], v171 offset:4096
	ds_read_b128 v[200:203], v171 offset:5120
	ds_read_b128 v[204:207], v171 offset:6144
	ds_read_b128 v[208:211], v171 offset:7168
	global_load_lds_dwordx4 v136, s[44:45]
	s_add_i32 m0, s26, 0xe000
	s_nop 0
	global_load_lds_dwordx4 v138, s[44:45]
	s_waitcnt vmcnt(8)
	s_waitcnt lgkmcnt(0)
	s_barrier
	s_waitcnt lgkmcnt(0)
	v_mfma_f32_16x16x32_bf16 v[124:127], v[140:143], v[180:183], v[124:127]
	v_mfma_f32_16x16x32_bf16 v[120:123], v[148:151], v[180:183], v[120:123]
	v_mfma_f32_16x16x32_bf16 v[116:119], v[140:143], v[188:191], v[116:119]
	v_mfma_f32_16x16x32_bf16 v[112:115], v[148:151], v[188:191], v[112:115]
	v_mfma_f32_16x16x32_bf16 v[108:111], v[140:143], v[196:199], v[108:111]
	v_mfma_f32_16x16x32_bf16 v[96:99], v[148:151], v[196:199], v[96:99]
	v_mfma_f32_16x16x32_bf16 v[84:87], v[140:143], v[204:207], v[84:87]
	v_mfma_f32_16x16x32_bf16 v[76:79], v[148:151], v[204:207], v[76:79]
	v_mfma_f32_16x16x32_bf16 v[124:127], v[144:147], v[184:187], v[124:127]
	v_mfma_f32_16x16x32_bf16 v[120:123], v[152:155], v[184:187], v[120:123]
	v_mfma_f32_16x16x32_bf16 v[116:119], v[144:147], v[192:195], v[116:119]
	v_mfma_f32_16x16x32_bf16 v[112:115], v[152:155], v[192:195], v[112:115]
	v_mfma_f32_16x16x32_bf16 v[108:111], v[144:147], v[200:203], v[108:111]
	v_mfma_f32_16x16x32_bf16 v[96:99], v[152:155], v[200:203], v[96:99]
	v_mfma_f32_16x16x32_bf16 v[84:87], v[144:147], v[208:211], v[84:87]
	v_mfma_f32_16x16x32_bf16 v[76:79], v[152:155], v[208:211], v[76:79]
	v_mfma_f32_16x16x32_bf16 v[104:107], v[156:159], v[180:183], v[104:107]
	v_mfma_f32_16x16x32_bf16 v[100:103], v[172:175], v[180:183], v[100:103]
	v_mfma_f32_16x16x32_bf16 v[92:95], v[156:159], v[188:191], v[92:95]
	v_mfma_f32_16x16x32_bf16 v[88:91], v[172:175], v[188:191], v[88:91]
	v_mfma_f32_16x16x32_bf16 v[80:83], v[156:159], v[196:199], v[80:83]
	v_mfma_f32_16x16x32_bf16 v[72:75], v[172:175], v[196:199], v[72:75]
	v_mfma_f32_16x16x32_bf16 v[68:71], v[156:159], v[204:207], v[68:71]
	v_mfma_f32_16x16x32_bf16 v[64:67], v[172:175], v[204:207], v[64:67]
	v_mfma_f32_16x16x32_bf16 v[104:107], v[160:163], v[184:187], v[104:107]
	v_mfma_f32_16x16x32_bf16 v[100:103], v[176:179], v[184:187], v[100:103]
	v_mfma_f32_16x16x32_bf16 v[92:95], v[160:163], v[192:195], v[92:95]
	v_mfma_f32_16x16x32_bf16 v[88:91], v[176:179], v[192:195], v[88:91]
	v_mfma_f32_16x16x32_bf16 v[80:83], v[160:163], v[200:203], v[80:83]
	v_mfma_f32_16x16x32_bf16 v[72:75], v[176:179], v[200:203], v[72:75]
	v_mfma_f32_16x16x32_bf16 v[68:71], v[160:163], v[208:211], v[68:71]
	v_mfma_f32_16x16x32_bf16 v[64:67], v[176:179], v[208:211], v[64:67]
	s_barrier
	s_add_i32 s44, s61, s25
	s_mov_b32 m0, s44
	ds_read_b128 v[180:183], v171 offset:16384
	ds_read_b128 v[184:187], v171 offset:17408
	ds_read_b128 v[188:191], v171 offset:18432
	ds_read_b128 v[192:195], v171 offset:19456
	ds_read_b128 v[196:199], v171 offset:20480
	ds_read_b128 v[200:203], v171 offset:21504
	ds_read_b128 v[204:207], v171 offset:22528
	ds_read_b128 v[208:211], v171 offset:23552
	global_load_lds_dwordx4 v130, s[48:49]
	s_add_i32 m0, s44, 0x2000
	s_add_u32 s44, s48, 0x160000
	s_addc_u32 s45, s49, 0
	s_add_i32 s70, s62, s25
	global_load_lds_dwordx4 v134, s[48:49]
	s_mov_b32 m0, s70
	s_nop 0
	global_load_lds_dwordx4 v130, s[44:45]
	s_add_i32 m0, s70, 0x2000
	s_nop 0
	global_load_lds_dwordx4 v134, s[44:45]
	s_mov_b32 m0, s26
	s_nop 0
	global_load_lds_dwordx4 v128, s[50:51]
	s_mov_b32 m0, s27
	s_nop 0
	global_load_lds_dwordx4 v132, s[50:51]
	s_waitcnt vmcnt(8)
	s_waitcnt lgkmcnt(0)
	s_barrier
	s_waitcnt lgkmcnt(0)
	v_mfma_f32_16x16x32_bf16 v[60:63], v[140:143], v[180:183], v[60:63]
	v_mfma_f32_16x16x32_bf16 v[56:59], v[148:151], v[180:183], v[56:59]
	v_mfma_f32_16x16x32_bf16 v[52:55], v[140:143], v[188:191], v[52:55]
	v_mfma_f32_16x16x32_bf16 v[48:51], v[148:151], v[188:191], v[48:51]
	v_mfma_f32_16x16x32_bf16 v[44:47], v[140:143], v[196:199], v[44:47]
	v_mfma_f32_16x16x32_bf16 v[32:35], v[148:151], v[196:199], v[32:35]
	v_mfma_f32_16x16x32_bf16 v[20:23], v[140:143], v[204:207], v[20:23]
	v_mfma_f32_16x16x32_bf16 v[12:15], v[148:151], v[204:207], v[12:15]
	v_mfma_f32_16x16x32_bf16 v[60:63], v[144:147], v[184:187], v[60:63]
	v_mfma_f32_16x16x32_bf16 v[56:59], v[152:155], v[184:187], v[56:59]
	v_mfma_f32_16x16x32_bf16 v[52:55], v[144:147], v[192:195], v[52:55]
	v_mfma_f32_16x16x32_bf16 v[48:51], v[152:155], v[192:195], v[48:51]
	v_mfma_f32_16x16x32_bf16 v[44:47], v[144:147], v[200:203], v[44:47]
	v_mfma_f32_16x16x32_bf16 v[32:35], v[152:155], v[200:203], v[32:35]
	v_mfma_f32_16x16x32_bf16 v[20:23], v[144:147], v[208:211], v[20:23]
	v_mfma_f32_16x16x32_bf16 v[12:15], v[152:155], v[208:211], v[12:15]
	v_mfma_f32_16x16x32_bf16 v[40:43], v[156:159], v[180:183], v[40:43]
	v_mfma_f32_16x16x32_bf16 v[36:39], v[172:175], v[180:183], v[36:39]
	v_mfma_f32_16x16x32_bf16 v[28:31], v[156:159], v[188:191], v[28:31]
	v_mfma_f32_16x16x32_bf16 v[24:27], v[172:175], v[188:191], v[24:27]
	v_mfma_f32_16x16x32_bf16 v[16:19], v[156:159], v[196:199], v[16:19]
	v_mfma_f32_16x16x32_bf16 v[8:11], v[172:175], v[196:199], v[8:11]
	v_mfma_f32_16x16x32_bf16 v[4:7], v[156:159], v[204:207], v[4:7]
	v_mfma_f32_16x16x32_bf16 v[0:3], v[172:175], v[204:207], v[0:3]
	v_mfma_f32_16x16x32_bf16 v[40:43], v[160:163], v[184:187], v[40:43]
	v_mfma_f32_16x16x32_bf16 v[36:39], v[176:179], v[184:187], v[36:39]
	v_mfma_f32_16x16x32_bf16 v[28:31], v[160:163], v[192:195], v[28:31]
	v_mfma_f32_16x16x32_bf16 v[24:27], v[176:179], v[192:195], v[24:27]
	v_mfma_f32_16x16x32_bf16 v[16:19], v[160:163], v[200:203], v[16:19]
	v_mfma_f32_16x16x32_bf16 v[8:11], v[176:179], v[200:203], v[8:11]
	v_mfma_f32_16x16x32_bf16 v[4:7], v[160:163], v[208:211], v[4:7]
	v_mfma_f32_16x16x32_bf16 v[0:3], v[176:179], v[208:211], v[0:3]
	s_barrier
; #define PG8_STAGE(bufoff, gbase, voff) do { _Pragma("unroll") for (int _i = 0; _i < 2; ++_i) \
;         __builtin_amdgcn_global_load_lds((const unsigned*)((const char*)(gbase) + (voff)[_i]), (PG8_LAS unsigned*)(lds + (bufoff) + ldsw + _i * 8192), 16, 0, 0); } while (0)
; #define PG8_LDA(dst, b, h) do { _Pragma("unroll") for (int m = 0; m < 4; ++m) _Pragma("unroll") for (int k = 0; k < 2; ++k) dst[m][k] = *(const PG8_LAS bf16x8*)(lds + PG8_SA(b, h) + aoff + m * 2048 + k * 1024); } while (0)
; #define PG8_LDB(dst, b, h) do { _Pragma("unroll") for (int n = 0; n < 2; ++n) _Pragma("unroll") for (int k = 0; k < 2; ++k) dst[n][k] = *(const PG8_LAS bf16x8*)(lds + PG8_SB(b, h) + boff + n * 2048 + k * 1024); } while (0)
; #define PG8_MMA(ai, bj, At, Bt) do { __builtin_amdgcn_s_setprio(1); _Pragma("unroll") for (int m = 0; m < 4; ++m) _Pragma("unroll") for (int n = 0; n < 2; ++n) _Pragma("unroll") for (int k = 0; k < 2; ++k) \
;         acc[ai][bj][m][n] = __builtin_amdgcn_mfma_f32_16x16x32_bf16(Bt[n][k], At[m][k], acc[ai][bj][m][n], 0, 0, 0); __builtin_amdgcn_s_setprio(0); } while (0)
; #define PG8_WAIT_V(n) asm volatile("s_waitcnt vmcnt(" #n ")" ::: "memory")
; #define PG8_WAIT_L(n) asm volatile("s_waitcnt lgkmcnt(" #n ")" ::: "memory")
; #define PG8_BAR __builtin_amdgcn_s_barrier()
; #define PG8_SCHED __builtin_amdgcn_sched_barrier(0)
; template <class Epi, class Sched, bool ALIGN_EPI = false, bool SP2 = false>
; __device__ __forceinline__ void gemm_phase(PG8_LAS unsigned char* lds, const Gemm g, const Sched& S, const Epi& E) {
;     ...
;             PG8_LDB(B0, 1, 0); PG8_LDB(B1, 1, 1); PG8_SCHED; PG8_LDA(At, 1, 0); PG8_STAGE(PG8_SA(0, 1), a2 + hstep, voffA);
;             PG8_WAIT_V(8); PG8_WAIT_L(0); PG8_BAR; PG8_MMA(0, 0, At, B0); PG8_MMA(0, 1, At, B1); PG8_BAR; PG8_SCHED;
;             PG8_LDA(At, 1, 1); PG8_STAGE(PG8_SB(1, 0), b3, voffB); PG8_STAGE(PG8_SB(1, 1), b3 + hstep, voffB); PG8_STAGE(PG8_SA(1, 0), a3, voffA);
;             PG8_WAIT_V(8); PG8_WAIT_L(0); PG8_BAR; PG8_MMA(1, 0, At, B0); PG8_MMA(1, 1, At, B1); PG8_BAR; PG8_SCHED;
	s_add_i32 s70, 0, 0x18000
	s_add_i32 s71, 0, 0x1c000
	v_add_u32_e32 v152, s70, v167
	v_add_u32_e32 v176, s71, v167
	ds_read_b128 v[140:143], v152
	ds_read_b128 v[144:147], v152 offset:1024
	ds_read_b128 v[148:151], v152 offset:2048
	ds_read_b128 v[152:155], v152 offset:3072
	ds_read_b128 v[156:159], v176
	ds_read_b128 v[160:163], v176 offset:1024
	ds_read_b128 v[172:175], v176 offset:2048
	ds_read_b128 v[176:179], v176 offset:3072
	s_add_u32 s44, s50, 0x160000
	s_addc_u32 s45, s51, 0
	s_mov_b32 m0, s52
	ds_read_b128 v[180:183], v171 offset:32768
	ds_read_b128 v[184:187], v171 offset:33792
	ds_read_b128 v[188:191], v171 offset:34816
	ds_read_b128 v[192:195], v171 offset:35840
	ds_read_b128 v[196:199], v171 offset:36864
	ds_read_b128 v[200:203], v171 offset:37888
	ds_read_b128 v[204:207], v171 offset:38912
	ds_read_b128 v[208:211], v171 offset:39936
	global_load_lds_dwordx4 v128, s[44:45]
	s_mov_b32 m0, s53
	s_nop 0
	global_load_lds_dwordx4 v132, s[44:45]
	s_waitcnt vmcnt(8)
	s_waitcnt lgkmcnt(0)
	s_barrier
	s_waitcnt lgkmcnt(0)
	v_mfma_f32_16x16x32_bf16 v[124:127], v[140:143], v[180:183], v[124:127]
	v_mfma_f32_16x16x32_bf16 v[120:123], v[148:151], v[180:183], v[120:123]
	v_mfma_f32_16x16x32_bf16 v[116:119], v[140:143], v[188:191], v[116:119]
	v_mfma_f32_16x16x32_bf16 v[112:115], v[148:151], v[188:191], v[112:115]
	v_mfma_f32_16x16x32_bf16 v[108:111], v[140:143], v[196:199], v[108:111]
	v_mfma_f32_16x16x32_bf16 v[96:99], v[148:151], v[196:199], v[96:99]
	v_mfma_f32_16x16x32_bf16 v[84:87], v[140:143], v[204:207], v[84:87]
	v_mfma_f32_16x16x32_bf16 v[76:79], v[148:151], v[204:207], v[76:79]
	v_mfma_f32_16x16x32_bf16 v[124:127], v[144:147], v[184:187], v[124:127]
	v_mfma_f32_16x16x32_bf16 v[120:123], v[152:155], v[184:187], v[120:123]
	v_mfma_f32_16x16x32_bf16 v[116:119], v[144:147], v[192:195], v[116:119]
	v_mfma_f32_16x16x32_bf16 v[112:115], v[152:155], v[192:195], v[112:115]
	v_mfma_f32_16x16x32_bf16 v[108:111], v[144:147], v[200:203], v[108:111]
	v_mfma_f32_16x16x32_bf16 v[96:99], v[152:155], v[200:203], v[96:99]
	v_mfma_f32_16x16x32_bf16 v[84:87], v[144:147], v[208:211], v[84:87]
	v_mfma_f32_16x16x32_bf16 v[76:79], v[152:155], v[208:211], v[76:79]
	v_mfma_f32_16x16x32_bf16 v[104:107], v[156:159], v[180:183], v[104:107]
	v_mfma_f32_16x16x32_bf16 v[100:103], v[172:175], v[180:183], v[100:103]
	v_mfma_f32_16x16x32_bf16 v[92:95], v[156:159], v[188:191], v[92:95]
	v_mfma_f32_16x16x32_bf16 v[88:91], v[172:175], v[188:191], v[88:91]
	v_mfma_f32_16x16x32_bf16 v[80:83], v[156:159], v[196:199], v[80:83]
	v_mfma_f32_16x16x32_bf16 v[72:75], v[172:175], v[196:199], v[72:75]
	v_mfma_f32_16x16x32_bf16 v[68:71], v[156:159], v[204:207], v[68:71]
	v_mfma_f32_16x16x32_bf16 v[64:67], v[172:175], v[204:207], v[64:67]
	v_mfma_f32_16x16x32_bf16 v[104:107], v[160:163], v[184:187], v[104:107]
	v_mfma_f32_16x16x32_bf16 v[100:103], v[176:179], v[184:187], v[100:103]
	v_mfma_f32_16x16x32_bf16 v[92:95], v[160:163], v[192:195], v[92:95]
	v_mfma_f32_16x16x32_bf16 v[88:91], v[176:179], v[192:195], v[88:91]
	v_mfma_f32_16x16x32_bf16 v[80:83], v[160:163], v[200:203], v[80:83]
	v_mfma_f32_16x16x32_bf16 v[72:75], v[176:179], v[200:203], v[72:75]
	v_mfma_f32_16x16x32_bf16 v[68:71], v[160:163], v[208:211], v[68:71]
	v_mfma_f32_16x16x32_bf16 v[64:67], v[176:179], v[208:211], v[64:67]
	s_barrier
	s_add_i32 s44, s70, s25
	s_add_u32 s86, s48, 0x80
	s_addc_u32 s87, s49, 0
	s_mov_b32 m0, s44
	ds_read_b128 v[180:183], v171 offset:49152
	ds_read_b128 v[184:187], v171 offset:50176
	ds_read_b128 v[188:191], v171 offset:51200
	ds_read_b128 v[192:195], v171 offset:52224
	ds_read_b128 v[196:199], v171 offset:53248
	ds_read_b128 v[200:203], v171 offset:54272
	ds_read_b128 v[204:207], v171 offset:55296
	ds_read_b128 v[208:211], v171 offset:56320
	global_load_lds_dwordx4 v130, s[86:87]
	s_add_i32 m0, s44, 0x2000
	s_add_u32 s44, s48, 0x160080
	s_addc_u32 s45, s49, 0
	s_add_i32 s48, s71, s25
	global_load_lds_dwordx4 v134, s[86:87]
	s_mov_b32 m0, s48
	s_nop 0
	global_load_lds_dwordx4 v130, s[44:45]
	s_add_i32 m0, s48, 0x2000
	s_nop 0
	global_load_lds_dwordx4 v134, s[44:45]
	s_add_u32 s84, s50, 0x80
	s_addc_u32 s85, s51, 0
	s_mov_b32 m0, s57
	s_nop 0
	global_load_lds_dwordx4 v128, s[84:85]
	s_mov_b32 m0, s58
	s_nop 0
	global_load_lds_dwordx4 v132, s[84:85]
	s_waitcnt vmcnt(8)
	s_waitcnt lgkmcnt(0)
	s_barrier
	s_waitcnt lgkmcnt(0)
	v_mfma_f32_16x16x32_bf16 v[60:63], v[140:143], v[180:183], v[60:63]
	v_mfma_f32_16x16x32_bf16 v[56:59], v[148:151], v[180:183], v[56:59]
	v_mfma_f32_16x16x32_bf16 v[52:55], v[140:143], v[188:191], v[52:55]
	v_mfma_f32_16x16x32_bf16 v[48:51], v[148:151], v[188:191], v[48:51]
	v_mfma_f32_16x16x32_bf16 v[44:47], v[140:143], v[196:199], v[44:47]
	v_mfma_f32_16x16x32_bf16 v[32:35], v[148:151], v[196:199], v[32:35]
	v_mfma_f32_16x16x32_bf16 v[20:23], v[140:143], v[204:207], v[20:23]
	v_mfma_f32_16x16x32_bf16 v[12:15], v[148:151], v[204:207], v[12:15]
	v_mfma_f32_16x16x32_bf16 v[60:63], v[144:147], v[184:187], v[60:63]
	v_mfma_f32_16x16x32_bf16 v[56:59], v[152:155], v[184:187], v[56:59]
	v_mfma_f32_16x16x32_bf16 v[52:55], v[144:147], v[192:195], v[52:55]
	v_mfma_f32_16x16x32_bf16 v[48:51], v[152:155], v[192:195], v[48:51]
	v_mfma_f32_16x16x32_bf16 v[44:47], v[144:147], v[200:203], v[44:47]
	v_mfma_f32_16x16x32_bf16 v[32:35], v[152:155], v[200:203], v[32:35]
	v_mfma_f32_16x16x32_bf16 v[20:23], v[144:147], v[208:211], v[20:23]
	v_mfma_f32_16x16x32_bf16 v[12:15], v[152:155], v[208:211], v[12:15]
	v_mfma_f32_16x16x32_bf16 v[40:43], v[156:159], v[180:183], v[40:43]
	v_mfma_f32_16x16x32_bf16 v[36:39], v[172:175], v[180:183], v[36:39]
	v_mfma_f32_16x16x32_bf16 v[28:31], v[156:159], v[188:191], v[28:31]
	v_mfma_f32_16x16x32_bf16 v[24:27], v[172:175], v[188:191], v[24:27]
	v_mfma_f32_16x16x32_bf16 v[16:19], v[156:159], v[196:199], v[16:19]
	v_mfma_f32_16x16x32_bf16 v[8:11], v[172:175], v[196:199], v[8:11]
	v_mfma_f32_16x16x32_bf16 v[4:7], v[156:159], v[204:207], v[4:7]
	v_mfma_f32_16x16x32_bf16 v[0:3], v[172:175], v[204:207], v[0:3]
	v_mfma_f32_16x16x32_bf16 v[40:43], v[160:163], v[184:187], v[40:43]
	v_mfma_f32_16x16x32_bf16 v[36:39], v[176:179], v[184:187], v[36:39]
	v_mfma_f32_16x16x32_bf16 v[28:31], v[160:163], v[192:195], v[28:31]
	v_mfma_f32_16x16x32_bf16 v[24:27], v[176:179], v[192:195], v[24:27]
	v_mfma_f32_16x16x32_bf16 v[16:19], v[160:163], v[200:203], v[16:19]
	v_mfma_f32_16x16x32_bf16 v[8:11], v[176:179], v[200:203], v[8:11]
	v_mfma_f32_16x16x32_bf16 v[4:7], v[160:163], v[208:211], v[4:7]
	v_mfma_f32_16x16x32_bf16 v[0:3], v[176:179], v[208:211], v[0:3]
	s_add_i32 s69, s69, 2
	s_add_u32 s67, s67, 0x100
	s_addc_u32 s68, s68, 0
	s_cmpk_gt_u32 s69, 0x55
	s_mov_b64 s[44:45], s[46:47]
	s_barrier
;     __device__ __forceinline__ void operator()(const f32x4 (&acc)[2][2][4][2], const Unit& u, int wr, int wc, int fr, int fq) const {
;         const int row0 = u.pm * BM + wr * 64 + fr, col0 = u.pn * BM + wc * 32 + 8 * fq;
;         const float* gp = gate + (u.pm >> 5) * 18432 + col0;
;         f32x4 gv[2][2];
; #pragma unroll
;         for (int bj = 0; bj < 2; ++bj)
; #pragma unroll
;             for (int n = 0; n < 2; ++n) gv[bj][n] = *(const f32x4*)(gp + bj * HALF + 4 * n) * scale;
; #pragma unroll
;         for (int ai = 0; ai < 2; ++ai) { f32x4 r[4][2][2];
; #pragma unroll
;             for (int m = 0; m < 4; ++m) { const size_t off = (size_t)(row0 + ai * HALF + m * 16) * 2048 + col0;
; #pragma unroll
;                 for (int bj = 0; bj < 2; ++bj)
; #pragma unroll
;                     for (int n = 0; n < 2; ++n) r[m][bj][n] = *(const f32x4*)(res + off + bj * HALF + 4 * n); }
; #pragma unroll
;             for (int m = 0; m < 4; ++m) { const size_t off = (size_t)(row0 + ai * HALF + m * 16) * 2048 + col0;
; #pragma unroll
;                 for (int bj = 0; bj < 2; ++bj)
; #pragma unroll
;                     for (int n = 0; n < 2; ++n) *(f32x4*)(out + off + bj * HALF + 4 * n) = r[m][bj][n] + gv[bj][n] * acc[ai][bj][m][n]; } }
	s_cbranch_scc0 .LBB0_245
	s_lshr_b32 s44, s65, 5
	s_mulk_i32 s44, 0x4800
	s_ashr_i32 s45, s44, 31
	v_lshl_or_b32 v140, s66, 8, v168
	s_lshl_b64 s[44:45], s[44:45], 2
	s_add_u32 s44, s55, s44
	v_ashrrev_i32_e32 v141, 31, v140
	s_addc_u32 s45, s56, s45
	v_lshlrev_b64 v[144:145], 2, v[140:141]
	v_lshl_add_u64 v[140:141], s[44:45], 0, v[144:145]
	global_load_dwordx4 v[146:149], v[140:141], off offset:16
	global_load_dwordx4 v[150:153], v[140:141], off
	global_load_dwordx4 v[172:175], v[140:141], off offset:528
	global_load_dwordx4 v[176:179], v[140:141], off offset:512
	v_lshl_add_u32 v140, s65, 8, v166
	v_ashrrev_i32_e32 v141, 31, v140
	v_lshl_add_u64 v[162:163], s[28:29], 0, v[144:145]
	v_lshlrev_b64 v[164:165], 13, v[140:141]
	v_lshl_add_u64 v[142:143], v[162:163], 0, v[164:165]
	global_load_dwordx4 v[180:183], v[142:143], off
	global_load_dwordx4 v[184:187], v[142:143], off offset:16
	global_load_dwordx4 v[188:191], v[142:143], off offset:528
	global_load_dwordx4 v[192:195], v[142:143], off offset:512
	v_or_b32_e32 v142, 16, v140
	v_ashrrev_i32_e32 v143, 31, v142
	v_lshlrev_b64 v[154:155], 13, v[142:143]
	v_lshl_add_u64 v[142:143], v[162:163], 0, v[154:155]
	global_load_dwordx4 v[196:199], v[142:143], off
	global_load_dwordx4 v[200:203], v[142:143], off offset:16
	global_load_dwordx4 v[204:207], v[142:143], off offset:528
	global_load_dwordx4 v[208:211], v[142:143], off offset:512
	v_or_b32_e32 v142, 32, v140
	v_ashrrev_i32_e32 v143, 31, v142
	v_lshlrev_b64 v[156:157], 13, v[142:143]
	v_or_b32_e32 v140, 48, v140
	v_lshl_add_u64 v[142:143], v[162:163], 0, v[156:157]
	v_ashrrev_i32_e32 v141, 31, v140
	global_load_dwordx4 v[214:217], v[142:143], off
	global_load_dwordx4 v[222:225], v[142:143], off offset:16
	global_load_dwordx4 v[232:235], v[142:143], off offset:512
	global_load_dwordx4 v[236:239], v[142:143], off offset:528
	v_lshlrev_b64 v[212:213], 13, v[140:141]
	v_lshl_add_u64 v[140:141], v[162:163], 0, v[212:213]
	global_load_dwordx4 v[240:243], v[140:141], off
	global_load_dwordx4 v[244:247], v[140:141], off offset:16
	global_load_dwordx4 v[248:251], v[140:141], off offset:512
	s_nop 0
	global_load_dwordx4 v[140:143], v[140:141], off offset:528
	v_lshl_add_u64 v[158:159], s[30:31], 0, v[164:165]
	v_lshl_add_u64 v[230:231], v[158:159], 0, v[144:145]
	v_lshl_add_u64 v[154:155], s[30:31], 0, v[154:155]
	v_lshl_add_u64 v[156:157], s[30:31], 0, v[156:157]
	v_lshl_add_u64 v[218:219], v[154:155], 0, v[144:145]
	v_lshl_add_u64 v[252:253], v[156:157], 0, v[144:145]
	s_and_b64 vcc, exec, s[8:9]
	s_mov_b32 s66, s63
	s_mov_b32 s65, s64
	s_mov_b64 s[46:47], s[12:13]
	s_mov_b64 s[44:45], s[10:11]
	s_waitcnt vmcnt(0)
	v_pk_mul_f32 v[154:155], v[148:149], 0.5 op_sel_hi:[1,0]
	v_pk_mul_f32 v[158:159], v[152:153], 0.5 op_sel_hi:[1,0]
	v_pk_mul_f32 v[160:161], v[150:151], 0.5 op_sel_hi:[1,0]
	v_pk_mul_f32 v[150:151], v[178:179], 0.5 op_sel_hi:[1,0]
	v_pk_mul_f32 v[152:153], v[176:177], 0.5 op_sel_hi:[1,0]
	v_pk_mul_f32 v[156:157], v[146:147], 0.5 op_sel_hi:[1,0]
	v_pk_mul_f32 v[146:147], v[174:175], 0.5 op_sel_hi:[1,0]
	v_pk_mul_f32 v[148:149], v[172:173], 0.5 op_sel_hi:[1,0]
	v_pk_fma_f32 v[126:127], v[126:127], v[158:159], v[182:183]
	v_pk_fma_f32 v[124:125], v[124:125], v[160:161], v[180:181]
	v_pk_fma_f32 v[122:123], v[122:123], v[154:155], v[186:187]
	v_pk_fma_f32 v[120:121], v[120:121], v[156:157], v[184:185]
	v_pk_fma_f32 v[106:107], v[106:107], v[150:151], v[194:195]
	v_pk_fma_f32 v[104:105], v[104:105], v[152:153], v[192:193]
	v_pk_fma_f32 v[102:103], v[102:103], v[146:147], v[190:191]
	v_pk_fma_f32 v[100:101], v[100:101], v[148:149], v[188:189]
	v_pk_fma_f32 v[118:119], v[118:119], v[158:159], v[198:199]
	v_pk_fma_f32 v[116:117], v[116:117], v[160:161], v[196:197]
	v_pk_fma_f32 v[114:115], v[114:115], v[154:155], v[202:203]
	v_pk_fma_f32 v[112:113], v[112:113], v[156:157], v[200:201]
	v_pk_fma_f32 v[82:83], v[82:83], v[150:151], v[234:235]
	v_pk_fma_f32 v[80:81], v[80:81], v[152:153], v[232:233]
	v_pk_fma_f32 v[94:95], v[94:95], v[150:151], v[210:211]
	v_pk_fma_f32 v[92:93], v[92:93], v[152:153], v[208:209]
	v_pk_fma_f32 v[90:91], v[90:91], v[146:147], v[206:207]
	v_pk_fma_f32 v[88:89], v[88:89], v[148:149], v[204:205]
	v_pk_fma_f32 v[110:111], v[110:111], v[158:159], v[216:217]
	v_pk_fma_f32 v[108:109], v[108:109], v[160:161], v[214:215]
	v_pk_fma_f32 v[98:99], v[98:99], v[154:155], v[224:225]
	v_pk_fma_f32 v[96:97], v[96:97], v[156:157], v[222:223]
	global_store_dwordx4 v[230:231], v[124:127], off
	global_store_dwordx4 v[230:231], v[120:123], off offset:16
	global_store_dwordx4 v[230:231], v[104:107], off offset:512
	global_store_dwordx4 v[230:231], v[100:103], off offset:528
	global_store_dwordx4 v[218:219], v[116:119], off
	global_store_dwordx4 v[218:219], v[112:115], off offset:16
	global_store_dwordx4 v[218:219], v[92:95], off offset:512
	global_store_dwordx4 v[218:219], v[88:91], off offset:528
	global_store_dwordx4 v[252:253], v[108:111], off
	global_store_dwordx4 v[252:253], v[96:99], off offset:16
	global_store_dwordx4 v[252:253], v[80:83], off offset:512
	v_pk_fma_f32 v[74:75], v[74:75], v[146:147], v[238:239]
	v_pk_fma_f32 v[72:73], v[72:73], v[148:149], v[236:237]
	v_lshl_add_u64 v[80:81], s[30:31], 0, v[212:213]
	global_store_dwordx4 v[252:253], v[72:75], off offset:528
	v_lshl_add_u64 v[80:81], v[80:81], 0, v[144:145]
; #define PG8_WAIT_V(n) asm volatile("s_waitcnt vmcnt(" #n ")" ::: "memory")
; #define PG8_BAR __builtin_amdgcn_s_barrier()
;     __device__ __forceinline__ void operator()(const f32x4 (&acc)[2][2][4][2], const Unit& u, int wr, int wc, int fr, int fq) const {
;     ...
;         for (int ai = 0; ai < 2; ++ai) { f32x4 r[4][2][2];
; #pragma unroll
;             for (int m = 0; m < 4; ++m) { const size_t off = (size_t)(row0 + ai * HALF + m * 16) * 2048 + col0;
; #pragma unroll
;                 for (int bj = 0; bj < 2; ++bj)
; #pragma unroll
;                     for (int n = 0; n < 2; ++n) r[m][bj][n] = *(const f32x4*)(res + off + bj * HALF + 4 * n); }
; #pragma unroll
;             for (int m = 0; m < 4; ++m) { const size_t off = (size_t)(row0 + ai * HALF + m * 16) * 2048 + col0;
; #pragma unroll
;                 for (int bj = 0; bj < 2; ++bj)
; #pragma unroll
;                     for (int n = 0; n < 2; ++n) *(f32x4*)(out + off + bj * HALF + 4 * n) = r[m][bj][n] + gv[bj][n] * acc[ai][bj][m][n]; } }
; template <class Epi, class Sched, bool ALIGN_EPI = false, bool SP2 = false>
; __device__ __forceinline__ void gemm_phase(PG8_LAS unsigned char* lds, const Gemm g, const Sched& S, const Epi& E) {
;     ...
;         if (!has_next) break;
; #pragma unroll
;         for (int a = 0; a < 2; ++a)
; #pragma unroll
;             for (int b = 0; b < 2; ++b)
; #pragma unroll
;                 for (int m = 0; m < 4; ++m)
; #pragma unroll
;                     for (int n = 0; n < 2; ++n) acc[a][b][m][n] = (f32x4){0.f, 0.f, 0.f, 0.f};
;         cur = nxt; cA = nA; cB = nB; ++ui;
;         if constexpr (ALIGN_EPI) { if (wr == 1) PG8_BAR; }
;     }
;     PG8_WAIT_V(0);
;     if constexpr (!ALIGN_EPI) { if (wr == 0) PG8_BAR; }
;     PG8_BAR;
	v_pk_fma_f32 v[70:71], v[70:71], v[150:151], v[250:251]
	v_pk_fma_f32 v[74:75], v[86:87], v[158:159], v[242:243]
	v_pk_fma_f32 v[72:73], v[84:85], v[160:161], v[240:241]
	global_store_dwordx4 v[80:81], v[72:75], off
	v_pk_fma_f32 v[68:69], v[68:69], v[152:153], v[248:249]
	v_pk_fma_f32 v[66:67], v[66:67], v[146:147], v[142:143]
	v_pk_fma_f32 v[74:75], v[78:79], v[154:155], v[246:247]
	v_pk_fma_f32 v[72:73], v[76:77], v[156:157], v[244:245]
	v_pk_fma_f32 v[64:65], v[64:65], v[148:149], v[140:141]
	v_lshl_add_u64 v[140:141], v[164:165], 0, s[38:39]
	v_lshl_add_u64 v[142:143], v[164:165], 0, s[40:41]
	v_lshl_add_u64 v[172:173], v[164:165], 0, s[42:43]
	global_store_dwordx4 v[80:81], v[72:75], off offset:16
	global_store_dwordx4 v[80:81], v[68:71], off offset:512
	global_store_dwordx4 v[80:81], v[64:67], off offset:528
	v_lshl_add_u64 v[76:77], v[162:163], 0, v[140:141]
	v_lshl_add_u64 v[92:93], v[162:163], 0, v[142:143]
	v_lshl_add_u64 v[108:109], v[162:163], 0, v[172:173]
	global_load_dwordx4 v[64:67], v[76:77], off
	global_load_dwordx4 v[68:71], v[76:77], off offset:16
	global_load_dwordx4 v[72:75], v[76:77], off offset:512
	s_nop 0
	global_load_dwordx4 v[76:79], v[76:77], off offset:528
	s_nop 0
	global_load_dwordx4 v[80:83], v[92:93], off
	global_load_dwordx4 v[84:87], v[92:93], off offset:16
	global_load_dwordx4 v[88:91], v[92:93], off offset:512
	s_nop 0
	global_load_dwordx4 v[92:95], v[92:93], off offset:528
	s_nop 0
	global_load_dwordx4 v[96:99], v[108:109], off
	global_load_dwordx4 v[100:103], v[108:109], off offset:16
	global_load_dwordx4 v[104:107], v[108:109], off offset:512
	s_nop 0
	global_load_dwordx4 v[108:111], v[108:109], off offset:528
	v_lshl_add_u64 v[164:165], v[164:165], 0, s[34:35]
	v_lshl_add_u64 v[124:125], v[162:163], 0, v[164:165]
	global_load_dwordx4 v[112:115], v[124:125], off
	global_load_dwordx4 v[116:119], v[124:125], off offset:16
	global_load_dwordx4 v[120:123], v[124:125], off offset:512
	s_nop 0
	global_load_dwordx4 v[124:127], v[124:125], off offset:528
	v_lshl_add_u64 v[140:141], s[30:31], 0, v[140:141]
	v_lshl_add_u64 v[162:163], s[30:31], 0, v[172:173]
	v_lshl_add_u64 v[142:143], s[30:31], 0, v[142:143]
	v_lshl_add_u64 v[140:141], v[140:141], 0, v[144:145]
	v_lshl_add_u64 v[162:163], v[162:163], 0, v[144:145]
	v_lshl_add_u64 v[142:143], v[142:143], 0, v[144:145]
	v_mov_b32_e32 v251, v220
	s_waitcnt vmcnt(15)
	v_pk_fma_f32 v[62:63], v[62:63], v[158:159], v[66:67]
	v_pk_fma_f32 v[60:61], v[60:61], v[160:161], v[64:65]
	s_waitcnt vmcnt(14)
	v_pk_fma_f32 v[58:59], v[58:59], v[154:155], v[70:71]
	v_pk_fma_f32 v[56:57], v[56:57], v[156:157], v[68:69]
	s_waitcnt vmcnt(5)
	v_pk_fma_f32 v[18:19], v[18:19], v[150:151], v[106:107]
	v_pk_fma_f32 v[16:17], v[16:17], v[152:153], v[104:105]
	v_pk_fma_f32 v[42:43], v[42:43], v[150:151], v[74:75]
	v_pk_fma_f32 v[40:41], v[40:41], v[152:153], v[72:73]
	v_pk_fma_f32 v[38:39], v[38:39], v[146:147], v[78:79]
	v_pk_fma_f32 v[36:37], v[36:37], v[148:149], v[76:77]
	v_pk_fma_f32 v[54:55], v[54:55], v[158:159], v[82:83]
	v_pk_fma_f32 v[52:53], v[52:53], v[160:161], v[80:81]
	v_pk_fma_f32 v[50:51], v[50:51], v[154:155], v[86:87]
	v_pk_fma_f32 v[48:49], v[48:49], v[156:157], v[84:85]
	v_pk_fma_f32 v[30:31], v[30:31], v[150:151], v[90:91]
	v_pk_fma_f32 v[28:29], v[28:29], v[152:153], v[88:89]
	v_pk_fma_f32 v[26:27], v[26:27], v[146:147], v[94:95]
	v_pk_fma_f32 v[24:25], v[24:25], v[148:149], v[92:93]
	v_pk_fma_f32 v[46:47], v[46:47], v[158:159], v[98:99]
	v_pk_fma_f32 v[44:45], v[44:45], v[160:161], v[96:97]
	v_pk_fma_f32 v[34:35], v[34:35], v[154:155], v[102:103]
	v_pk_fma_f32 v[32:33], v[32:33], v[156:157], v[100:101]
	global_store_dwordx4 v[140:141], v[60:63], off
	global_store_dwordx4 v[140:141], v[56:59], off offset:16
	global_store_dwordx4 v[140:141], v[40:43], off offset:512
	global_store_dwordx4 v[140:141], v[36:39], off offset:528
	global_store_dwordx4 v[142:143], v[52:55], off
	global_store_dwordx4 v[142:143], v[48:51], off offset:16
	global_store_dwordx4 v[142:143], v[28:31], off offset:512
	global_store_dwordx4 v[142:143], v[24:27], off offset:528
	global_store_dwordx4 v[162:163], v[44:47], off
	global_store_dwordx4 v[162:163], v[32:35], off offset:16
	global_store_dwordx4 v[162:163], v[16:19], off offset:512
	s_waitcnt vmcnt(15)
	v_pk_fma_f32 v[10:11], v[10:11], v[146:147], v[110:111]
	v_pk_fma_f32 v[8:9], v[8:9], v[148:149], v[108:109]
	v_lshl_add_u64 v[16:17], s[30:31], 0, v[164:165]
	global_store_dwordx4 v[162:163], v[8:11], off offset:528
	v_lshl_add_u64 v[16:17], v[16:17], 0, v[144:145]
	s_waitcnt vmcnt(13)
	v_pk_fma_f32 v[6:7], v[6:7], v[150:151], v[122:123]
	v_pk_fma_f32 v[10:11], v[22:23], v[158:159], v[114:115]
	v_pk_fma_f32 v[8:9], v[20:21], v[160:161], v[112:113]
	global_store_dwordx4 v[16:17], v[8:11], off
	v_pk_fma_f32 v[4:5], v[4:5], v[152:153], v[120:121]
	s_waitcnt vmcnt(13)
	v_pk_fma_f32 v[2:3], v[2:3], v[146:147], v[126:127]
	v_pk_fma_f32 v[10:11], v[14:15], v[154:155], v[118:119]
	v_pk_fma_f32 v[8:9], v[12:13], v[156:157], v[116:117]
	v_pk_fma_f32 v[0:1], v[0:1], v[148:149], v[124:125]
	global_store_dwordx4 v[16:17], v[8:11], off offset:16
	global_store_dwordx4 v[16:17], v[4:7], off offset:512
	global_store_dwordx4 v[16:17], v[0:3], off offset:528
	s_cbranch_vccz .LBB0_234
	s_waitcnt vmcnt(0)
	s_cmpk_gt_u32 s3, 0xff
	s_cbranch_scc1 .LBB0_249
	s_barrier

; #define PG8_STAGE(bufoff, gbase, voff) do { _Pragma("unroll") for (int _i = 0; _i < 2; ++_i) \
;         __builtin_amdgcn_global_load_lds((const unsigned*)((const char*)(gbase) + (voff)[_i]), (PG8_LAS unsigned*)(lds + (bufoff) + ldsw + _i * 8192), 16, 0, 0); } while (0)
; #define PG8_LDA(dst, b, h) do { _Pragma("unroll") for (int m = 0; m < 4; ++m) _Pragma("unroll") for (int k = 0; k < 2; ++k) dst[m][k] = *(const PG8_LAS bf16x8*)(lds + PG8_SA(b, h) + aoff + m * 2048 + k * 1024); } while (0)
; #define PG8_LDB(dst, b, h) do { _Pragma("unroll") for (int n = 0; n < 2; ++n) _Pragma("unroll") for (int k = 0; k < 2; ++k) dst[n][k] = *(const PG8_LAS bf16x8*)(lds + PG8_SB(b, h) + boff + n * 2048 + k * 1024); } while (0)
; #define PG8_MMA(ai, bj, At, Bt) do { __builtin_amdgcn_s_setprio(1); _Pragma("unroll") for (int m = 0; m < 4; ++m) _Pragma("unroll") for (int n = 0; n < 2; ++n) _Pragma("unroll") for (int k = 0; k < 2; ++k) \
;         acc[ai][bj][m][n] = __builtin_amdgcn_mfma_f32_16x16x32_bf16(Bt[n][k], At[m][k], acc[ai][bj][m][n], 0, 0, 0); __builtin_amdgcn_s_setprio(0); } while (0)
; #define PG8_BAR __builtin_amdgcn_s_barrier()
; template <class Epi, class Sched, bool ALIGN_EPI = false, bool SP2 = false>
; __device__ __forceinline__ void gemm_phase(PG8_LAS unsigned char* lds, const Gemm g, const Sched& S, const Epi& E) {
;     ...
;         const bool has_next = S.next(ui + 1, nxt);
;         const char* nA = has_next ? (const char*)g.A + (size_t)nxt.pm * tstep : cA; const char* nB = has_next ? (const char*)g.Bt + (size_t)nxt.pn * tstep : cB;
;         for (int t = 0; t < nt; t += 2) {
;             const bool last = (t == nt - 2);
;             const char* a1 = cA + (size_t)(t + 1) * kstep;
;             const char* a2 = last ? nA : cA + (size_t)(t + 2) * kstep; const char* b2 = last ? nB : cB + (size_t)(t + 2) * kstep;
;             const char* a3 = a2 + kstep; const char* b3 = b2 + kstep;
;             if (last && has_next) S.a_ready(nxt);
;             if constexpr (SP2) {
;             PG8_LDB(B0, 0, 0); PG8_LDB(B1, 0, 1); PG8_SCHED; PG8_LDA(At, 0, 0); PG8_STAGE(PG8_SA(1, 1), a1 + hstep, voffA);
;             PG8_WAIT_V(8); PG8_WAIT_L(0); PG8_BAR; PG8_MMA(0, 0, At, B0); PG8_MMA(0, 1, At, B1); PG8_BAR; PG8_SCHED;
;             PG8_LDA(At, 0, 1); PG8_STAGE(PG8_SB(0, 0), b2, voffB); PG8_STAGE(PG8_SB(0, 1), b2 + hstep, voffB); PG8_STAGE(PG8_SA(0, 0), a2, voffA);
.LBB0_363:
	s_ashr_i32 s77, s76, 31
	s_lshl_b64 s[38:39], s[76:77], 20
	v_cmp_lt_i64_e32 vcc, s[78:79], v[178:179]
	s_add_u32 s78, s73, s38
	s_addc_u32 s79, s96, s39
	s_and_b64 s[38:39], vcc, exec
	s_cselect_b32 s77, s79, s85
	s_cselect_b32 s83, s78, s84
	s_ashr_i32 s75, s74, 31
	s_lshl_b64 s[38:39], s[74:75], 20
	s_add_u32 s80, s97, s38
	s_addc_u32 s81, s90, s39
	s_and_b64 s[38:39], vcc, exec
	s_cselect_b32 s75, s81, s87
	s_cselect_b32 vcc_lo, s80, s86
	s_add_u32 s84, s84, 0x80080
	s_addc_u32 s85, s85, 0
	s_add_u32 vcc_hi, s86, 0x100
	s_addc_u32 s38, s87, 0
	s_mov_b32 s39, -2
	ds_read_b128 v[128:131], v214
	ds_read_b128 v[132:135], v214 offset:1024
	ds_read_b128 v[136:139], v214 offset:2048
	ds_read_b128 v[140:143], v214 offset:3072
	ds_read_b128 v[144:147], v215
	ds_read_b128 v[148:151], v215 offset:1024
	ds_read_b128 v[152:155], v215 offset:2048
	ds_read_b128 v[156:159], v215 offset:3072
	s_add_u32 s58, s84, 0xfff80080
	s_addc_u32 s59, s85, -1
	s_cmp_eq_u32 s39, 28
	s_cselect_b32 s89, s77, s59
	s_cselect_b32 s88, s83, s58
	s_cselect_b32 s87, s75, s38
	s_cselect_b32 s86, vcc_lo, vcc_hi
	s_add_i32 m0, s7, 0xc000
	ds_read_b128 v[160:163], v216
	ds_read_b128 v[182:185], v216 offset:1024
	ds_read_b128 v[186:189], v216 offset:2048
	ds_read_b128 v[190:193], v216 offset:3072
	ds_read_b128 v[222:225], v216 offset:4096
	ds_read_b128 v[232:235], v216 offset:5120
	ds_read_b128 v[236:239], v216 offset:6144
	ds_read_b128 v[240:243], v216 offset:7168
	global_load_lds_dwordx4 v174, s[84:85]
	s_add_i32 m0, s7, 0xe000
	s_nop 0
	global_load_lds_dwordx4 v176, s[84:85]
	s_waitcnt vmcnt(8)
	s_waitcnt lgkmcnt(0)
	s_barrier
	s_waitcnt lgkmcnt(0)
	v_mfma_f32_16x16x32_bf16 v[124:127], v[128:131], v[160:163], 0
	v_mfma_f32_16x16x32_bf16 v[120:123], v[136:139], v[160:163], 0
	v_mfma_f32_16x16x32_bf16 v[116:119], v[128:131], v[186:189], 0
	v_mfma_f32_16x16x32_bf16 v[112:115], v[136:139], v[186:189], 0
	v_mfma_f32_16x16x32_bf16 v[100:103], v[128:131], v[222:225], 0
	v_mfma_f32_16x16x32_bf16 v[96:99], v[136:139], v[222:225], 0
	v_mfma_f32_16x16x32_bf16 v[84:87], v[128:131], v[236:239], 0
	v_mfma_f32_16x16x32_bf16 v[80:83], v[136:139], v[236:239], 0
	v_mfma_f32_16x16x32_bf16 v[124:127], v[132:135], v[182:185], v[124:127]
	v_mfma_f32_16x16x32_bf16 v[120:123], v[140:143], v[182:185], v[120:123]
	v_mfma_f32_16x16x32_bf16 v[116:119], v[132:135], v[190:193], v[116:119]
	v_mfma_f32_16x16x32_bf16 v[112:115], v[140:143], v[190:193], v[112:115]
	v_mfma_f32_16x16x32_bf16 v[100:103], v[132:135], v[232:235], v[100:103]
	v_mfma_f32_16x16x32_bf16 v[96:99], v[140:143], v[232:235], v[96:99]
	v_mfma_f32_16x16x32_bf16 v[84:87], v[132:135], v[240:243], v[84:87]
	v_mfma_f32_16x16x32_bf16 v[80:83], v[140:143], v[240:243], v[80:83]
	v_mfma_f32_16x16x32_bf16 v[108:111], v[144:147], v[160:163], 0
	v_mfma_f32_16x16x32_bf16 v[104:107], v[152:155], v[160:163], 0
	v_mfma_f32_16x16x32_bf16 v[92:95], v[144:147], v[186:189], 0
	v_mfma_f32_16x16x32_bf16 v[88:91], v[152:155], v[186:189], 0
	v_mfma_f32_16x16x32_bf16 v[76:79], v[144:147], v[222:225], 0
	v_mfma_f32_16x16x32_bf16 v[72:75], v[152:155], v[222:225], 0
	v_mfma_f32_16x16x32_bf16 v[68:71], v[144:147], v[236:239], 0
	v_mfma_f32_16x16x32_bf16 v[64:67], v[152:155], v[236:239], 0
	v_mfma_f32_16x16x32_bf16 v[108:111], v[148:151], v[182:185], v[108:111]
	v_mfma_f32_16x16x32_bf16 v[104:107], v[156:159], v[182:185], v[104:107]
	v_mfma_f32_16x16x32_bf16 v[92:95], v[148:151], v[190:193], v[92:95]
	v_mfma_f32_16x16x32_bf16 v[88:91], v[156:159], v[190:193], v[88:91]
	v_mfma_f32_16x16x32_bf16 v[76:79], v[148:151], v[232:235], v[76:79]
	v_mfma_f32_16x16x32_bf16 v[72:75], v[156:159], v[232:235], v[72:75]
	v_mfma_f32_16x16x32_bf16 v[68:71], v[148:151], v[240:243], v[68:71]
	v_mfma_f32_16x16x32_bf16 v[64:67], v[156:159], v[240:243], v[64:67]
	s_barrier
	s_add_i32 s58, s34, s24
	v_lshl_add_u64 v[194:195], s[86:87], 0, v[168:169]
	s_mov_b32 m0, s58
	ds_read_b128 v[160:163], v216 offset:16384
	ds_read_b128 v[182:185], v216 offset:17408
	ds_read_b128 v[186:189], v216 offset:18432
	ds_read_b128 v[190:193], v216 offset:19456
	ds_read_b128 v[222:225], v216 offset:20480
	ds_read_b128 v[232:235], v216 offset:21504
	ds_read_b128 v[236:239], v216 offset:22528
	ds_read_b128 v[240:243], v216 offset:23552
	global_load_lds_dwordx4 v168, s[86:87]
	s_add_i32 m0, s58, 0x2000
	s_add_u32 s58, s86, 0x80000
	v_lshl_add_u64 v[230:231], s[86:87], 0, v[164:165]
	s_addc_u32 s59, s87, 0
	s_add_i32 s48, s35, s24
	global_load_lds_dwordx4 v164, s[86:87]
	s_mov_b32 m0, s48
	v_lshl_add_u64 v[246:247], s[88:89], 0, v[166:167]
	global_load_lds_dwordx4 v168, s[58:59]
	s_add_i32 m0, s48, 0x2000
	s_nop 0
	global_load_lds_dwordx4 v164, s[58:59]
	v_lshl_add_u64 v[244:245], s[88:89], 0, v[170:171]
	s_mov_b32 m0, s7
	s_nop 0
	global_load_lds_dwordx4 v170, s[88:89]
	s_mov_b32 m0, s8
	s_nop 0
	global_load_lds_dwordx4 v166, s[88:89]
	s_waitcnt vmcnt(8)
	s_waitcnt lgkmcnt(0)
	s_barrier
; #define PG8_STAGE(bufoff, gbase, voff) do { _Pragma("unroll") for (int _i = 0; _i < 2; ++_i) \
;         __builtin_amdgcn_global_load_lds((const unsigned*)((const char*)(gbase) + (voff)[_i]), (PG8_LAS unsigned*)(lds + (bufoff) + ldsw + _i * 8192), 16, 0, 0); } while (0)
; #define PG8_LDA(dst, b, h) do { _Pragma("unroll") for (int m = 0; m < 4; ++m) _Pragma("unroll") for (int k = 0; k < 2; ++k) dst[m][k] = *(const PG8_LAS bf16x8*)(lds + PG8_SA(b, h) + aoff + m * 2048 + k * 1024); } while (0)
; #define PG8_LDB(dst, b, h) do { _Pragma("unroll") for (int n = 0; n < 2; ++n) _Pragma("unroll") for (int k = 0; k < 2; ++k) dst[n][k] = *(const PG8_LAS bf16x8*)(lds + PG8_SB(b, h) + boff + n * 2048 + k * 1024); } while (0)
; #define PG8_MMA(ai, bj, At, Bt) do { __builtin_amdgcn_s_setprio(1); _Pragma("unroll") for (int m = 0; m < 4; ++m) _Pragma("unroll") for (int n = 0; n < 2; ++n) _Pragma("unroll") for (int k = 0; k < 2; ++k) \
;         acc[ai][bj][m][n] = __builtin_amdgcn_mfma_f32_16x16x32_bf16(Bt[n][k], At[m][k], acc[ai][bj][m][n], 0, 0, 0); __builtin_amdgcn_s_setprio(0); } while (0)
; #define PG8_WAIT_V(n) asm volatile("s_waitcnt vmcnt(" #n ")" ::: "memory")
; #define PG8_WAIT_L(n) asm volatile("s_waitcnt lgkmcnt(" #n ")" ::: "memory")
; #define PG8_BAR __builtin_amdgcn_s_barrier()
; #define PG8_SCHED __builtin_amdgcn_sched_barrier(0)
; template <class Epi, class Sched, bool ALIGN_EPI = false, bool SP2 = false>
; __device__ __forceinline__ void gemm_phase(PG8_LAS unsigned char* lds, const Gemm g, const Sched& S, const Epi& E) {
;     ...
;             PG8_WAIT_V(8); PG8_WAIT_L(0); PG8_BAR; PG8_MMA(0, 0, At, B0); PG8_MMA(0, 1, At, B1); PG8_BAR; PG8_SCHED;
;             PG8_LDA(At, 0, 1); PG8_STAGE(PG8_SB(0, 0), b2, voffB); PG8_STAGE(PG8_SB(0, 1), b2 + hstep, voffB); PG8_STAGE(PG8_SA(0, 0), a2, voffA);
;             PG8_WAIT_V(8); PG8_WAIT_L(0); PG8_BAR; PG8_MMA(1, 0, At, B0); PG8_MMA(1, 1, At, B1); PG8_BAR; PG8_SCHED;
;             PG8_LDB(B0, 1, 0); PG8_LDB(B1, 1, 1); PG8_SCHED; PG8_LDA(At, 1, 0); PG8_STAGE(PG8_SA(0, 1), a2 + hstep, voffA);
;             PG8_WAIT_V(8); PG8_WAIT_L(0); PG8_BAR; PG8_MMA(0, 0, At, B0); PG8_MMA(0, 1, At, B1); PG8_BAR; PG8_SCHED;
	s_waitcnt lgkmcnt(0)
	v_mfma_f32_16x16x32_bf16 v[60:63], v[128:131], v[160:163], 0
	v_mfma_f32_16x16x32_bf16 v[56:59], v[136:139], v[160:163], 0
	v_mfma_f32_16x16x32_bf16 v[52:55], v[128:131], v[186:189], 0
	v_mfma_f32_16x16x32_bf16 v[48:51], v[136:139], v[186:189], 0
	v_mfma_f32_16x16x32_bf16 v[36:39], v[128:131], v[222:225], 0
	v_mfma_f32_16x16x32_bf16 v[32:35], v[136:139], v[222:225], 0
	v_mfma_f32_16x16x32_bf16 v[20:23], v[128:131], v[236:239], 0
	v_mfma_f32_16x16x32_bf16 v[16:19], v[136:139], v[236:239], 0
	v_mfma_f32_16x16x32_bf16 v[60:63], v[132:135], v[182:185], v[60:63]
	v_mfma_f32_16x16x32_bf16 v[56:59], v[140:143], v[182:185], v[56:59]
	v_mfma_f32_16x16x32_bf16 v[52:55], v[132:135], v[190:193], v[52:55]
	v_mfma_f32_16x16x32_bf16 v[48:51], v[140:143], v[190:193], v[48:51]
	v_mfma_f32_16x16x32_bf16 v[36:39], v[132:135], v[232:235], v[36:39]
	v_mfma_f32_16x16x32_bf16 v[32:35], v[140:143], v[232:235], v[32:35]
	v_mfma_f32_16x16x32_bf16 v[20:23], v[132:135], v[240:243], v[20:23]
	v_mfma_f32_16x16x32_bf16 v[16:19], v[140:143], v[240:243], v[16:19]
	v_mfma_f32_16x16x32_bf16 v[44:47], v[144:147], v[160:163], 0
	v_mfma_f32_16x16x32_bf16 v[40:43], v[152:155], v[160:163], 0
	v_mfma_f32_16x16x32_bf16 v[28:31], v[144:147], v[186:189], 0
	v_mfma_f32_16x16x32_bf16 v[24:27], v[152:155], v[186:189], 0
	v_mfma_f32_16x16x32_bf16 v[12:15], v[144:147], v[222:225], 0
	v_mfma_f32_16x16x32_bf16 v[8:11], v[152:155], v[222:225], 0
	v_mfma_f32_16x16x32_bf16 v[4:7], v[144:147], v[236:239], 0
	v_mfma_f32_16x16x32_bf16 v[0:3], v[152:155], v[236:239], 0
	v_mfma_f32_16x16x32_bf16 v[44:47], v[148:151], v[182:185], v[44:47]
	v_mfma_f32_16x16x32_bf16 v[40:43], v[156:159], v[182:185], v[40:43]
	v_mfma_f32_16x16x32_bf16 v[28:31], v[148:151], v[190:193], v[28:31]
	v_mfma_f32_16x16x32_bf16 v[24:27], v[156:159], v[190:193], v[24:27]
	v_mfma_f32_16x16x32_bf16 v[12:15], v[148:151], v[232:235], v[12:15]
	v_mfma_f32_16x16x32_bf16 v[8:11], v[156:159], v[232:235], v[8:11]
	v_mfma_f32_16x16x32_bf16 v[4:7], v[148:151], v[240:243], v[4:7]
	v_mfma_f32_16x16x32_bf16 v[0:3], v[156:159], v[240:243], v[0:3]
	s_barrier
	s_add_i32 s48, 0, 0x18000
	s_add_i32 s60, 0, 0x1c000
	v_add_u32_e32 v140, s48, v197
	v_add_u32_e32 v156, s60, v197
	ds_read_b128 v[128:131], v140
	ds_read_b128 v[132:135], v140 offset:1024
	ds_read_b128 v[136:139], v140 offset:2048
	ds_read_b128 v[140:143], v140 offset:3072
	ds_read_b128 v[144:147], v156
	ds_read_b128 v[148:151], v156 offset:1024
	ds_read_b128 v[152:155], v156 offset:2048
	ds_read_b128 v[156:159], v156 offset:3072
	s_add_u32 s58, s88, 0x80000
	s_addc_u32 s59, s89, 0
	s_mov_b32 m0, s9
	ds_read_b128 v[160:163], v216 offset:32768
	ds_read_b128 v[182:185], v216 offset:33792
	ds_read_b128 v[186:189], v216 offset:34816
	ds_read_b128 v[190:193], v216 offset:35840
	ds_read_b128 v[222:225], v216 offset:36864
	ds_read_b128 v[232:235], v216 offset:37888
	ds_read_b128 v[236:239], v216 offset:38912
	ds_read_b128 v[240:243], v216 offset:39936
	global_load_lds_dwordx4 v170, s[58:59]
	s_mov_b32 m0, s26
	s_nop 0
	global_load_lds_dwordx4 v166, s[58:59]
	s_waitcnt vmcnt(8)
	s_waitcnt lgkmcnt(0)
	s_barrier
	s_waitcnt lgkmcnt(0)
	v_mfma_f32_16x16x32_bf16 v[124:127], v[128:131], v[160:163], v[124:127]
	v_mfma_f32_16x16x32_bf16 v[120:123], v[136:139], v[160:163], v[120:123]
	v_mfma_f32_16x16x32_bf16 v[116:119], v[128:131], v[186:189], v[116:119]
	v_mfma_f32_16x16x32_bf16 v[112:115], v[136:139], v[186:189], v[112:115]
	v_mfma_f32_16x16x32_bf16 v[100:103], v[128:131], v[222:225], v[100:103]
	v_mfma_f32_16x16x32_bf16 v[96:99], v[136:139], v[222:225], v[96:99]
	v_mfma_f32_16x16x32_bf16 v[84:87], v[128:131], v[236:239], v[84:87]
	v_mfma_f32_16x16x32_bf16 v[80:83], v[136:139], v[236:239], v[80:83]
	v_mfma_f32_16x16x32_bf16 v[124:127], v[132:135], v[182:185], v[124:127]
	v_mfma_f32_16x16x32_bf16 v[120:123], v[140:143], v[182:185], v[120:123]
	v_mfma_f32_16x16x32_bf16 v[116:119], v[132:135], v[190:193], v[116:119]
	v_mfma_f32_16x16x32_bf16 v[112:115], v[140:143], v[190:193], v[112:115]
	v_mfma_f32_16x16x32_bf16 v[100:103], v[132:135], v[232:235], v[100:103]
	v_mfma_f32_16x16x32_bf16 v[96:99], v[140:143], v[232:235], v[96:99]
	v_mfma_f32_16x16x32_bf16 v[84:87], v[132:135], v[240:243], v[84:87]
	v_mfma_f32_16x16x32_bf16 v[80:83], v[140:143], v[240:243], v[80:83]
	v_mfma_f32_16x16x32_bf16 v[108:111], v[144:147], v[160:163], v[108:111]
	v_mfma_f32_16x16x32_bf16 v[104:107], v[152:155], v[160:163], v[104:107]
	v_mfma_f32_16x16x32_bf16 v[92:95], v[144:147], v[186:189], v[92:95]
	v_mfma_f32_16x16x32_bf16 v[88:91], v[152:155], v[186:189], v[88:91]
	v_mfma_f32_16x16x32_bf16 v[76:79], v[144:147], v[222:225], v[76:79]
	v_mfma_f32_16x16x32_bf16 v[72:75], v[152:155], v[222:225], v[72:75]
	v_mfma_f32_16x16x32_bf16 v[68:71], v[144:147], v[236:239], v[68:71]
	v_mfma_f32_16x16x32_bf16 v[64:67], v[152:155], v[236:239], v[64:67]
	v_mfma_f32_16x16x32_bf16 v[108:111], v[148:151], v[182:185], v[108:111]
	v_mfma_f32_16x16x32_bf16 v[104:107], v[156:159], v[182:185], v[104:107]
	v_mfma_f32_16x16x32_bf16 v[92:95], v[148:151], v[190:193], v[92:95]
	v_mfma_f32_16x16x32_bf16 v[88:91], v[156:159], v[190:193], v[88:91]
	v_mfma_f32_16x16x32_bf16 v[76:79], v[148:151], v[232:235], v[76:79]
	v_mfma_f32_16x16x32_bf16 v[72:75], v[156:159], v[232:235], v[72:75]
	v_mfma_f32_16x16x32_bf16 v[68:71], v[148:151], v[240:243], v[68:71]
	v_mfma_f32_16x16x32_bf16 v[64:67], v[156:159], v[240:243], v[64:67]
	s_barrier
; #define PG8_STAGE(bufoff, gbase, voff) do { _Pragma("unroll") for (int _i = 0; _i < 2; ++_i) \
;         __builtin_amdgcn_global_load_lds((const unsigned*)((const char*)(gbase) + (voff)[_i]), (PG8_LAS unsigned*)(lds + (bufoff) + ldsw + _i * 8192), 16, 0, 0); } while (0)
; #define PG8_LDA(dst, b, h) do { _Pragma("unroll") for (int m = 0; m < 4; ++m) _Pragma("unroll") for (int k = 0; k < 2; ++k) dst[m][k] = *(const PG8_LAS bf16x8*)(lds + PG8_SA(b, h) + aoff + m * 2048 + k * 1024); } while (0)
; #define PG8_LDB(dst, b, h) do { _Pragma("unroll") for (int n = 0; n < 2; ++n) _Pragma("unroll") for (int k = 0; k < 2; ++k) dst[n][k] = *(const PG8_LAS bf16x8*)(lds + PG8_SB(b, h) + boff + n * 2048 + k * 1024); } while (0)
; #define PG8_MMA(ai, bj, At, Bt) do { __builtin_amdgcn_s_setprio(1); _Pragma("unroll") for (int m = 0; m < 4; ++m) _Pragma("unroll") for (int n = 0; n < 2; ++n) _Pragma("unroll") for (int k = 0; k < 2; ++k) \
;         acc[ai][bj][m][n] = __builtin_amdgcn_mfma_f32_16x16x32_bf16(Bt[n][k], At[m][k], acc[ai][bj][m][n], 0, 0, 0); __builtin_amdgcn_s_setprio(0); } while (0)
; #define PG8_WAIT_V(n) asm volatile("s_waitcnt vmcnt(" #n ")" ::: "memory")
; #define PG8_WAIT_L(n) asm volatile("s_waitcnt lgkmcnt(" #n ")" ::: "memory")
; #define PG8_BAR __builtin_amdgcn_s_barrier()
; #define PG8_SCHED __builtin_amdgcn_sched_barrier(0)
; template <class Epi, class Sched, bool ALIGN_EPI = false, bool SP2 = false>
; __device__ __forceinline__ void gemm_phase(PG8_LAS unsigned char* lds, const Gemm g, const Sched& S, const Epi& E) {
;     ...
;             PG8_LDB(B0, 0, 0); PG8_LDB(B1, 0, 1); PG8_SCHED; PG8_LDA(At, 0, 0); PG8_STAGE(PG8_SA(1, 1), a1 + hstep, voffA);
;             PG8_WAIT_V(8); PG8_WAIT_L(0); PG8_BAR; PG8_MMA(0, 0, At, B0); PG8_MMA(0, 1, At, B1); PG8_BAR; PG8_SCHED;
;     ...
;             PG8_LDA(At, 1, 1); PG8_STAGE(PG8_SB(1, 0), b3, voffB); PG8_STAGE(PG8_SB(1, 1), b3 + hstep, voffB); PG8_STAGE(PG8_SA(1, 0), a3, voffA);
;             PG8_WAIT_V(8); PG8_WAIT_L(0); PG8_BAR; PG8_MMA(1, 0, At, B0); PG8_MMA(1, 1, At, B1); PG8_BAR; PG8_SCHED;
	s_add_i32 s48, s48, s24
	v_lshl_add_u64 v[194:195], v[194:195], 0, s[54:55]
	s_mov_b32 m0, s48
	ds_read_b128 v[160:163], v216 offset:49152
	ds_read_b128 v[182:185], v216 offset:50176
	ds_read_b128 v[186:189], v216 offset:51200
	ds_read_b128 v[190:193], v216 offset:52224
	ds_read_b128 v[222:225], v216 offset:53248
	ds_read_b128 v[232:235], v216 offset:54272
	ds_read_b128 v[236:239], v216 offset:55296
	ds_read_b128 v[240:243], v216 offset:56320
	global_load_lds_dwordx4 v[194:195], off
	s_add_i32 m0, s48, 0x2000
	s_add_u32 s58, s86, 0x80080
	v_lshl_add_u64 v[194:195], v[230:231], 0, s[54:55]
	s_addc_u32 s59, s87, 0
	s_add_i32 s48, s60, s24
	global_load_lds_dwordx4 v[194:195], off
	s_mov_b32 m0, s48
	s_nop 0
	global_load_lds_dwordx4 v168, s[58:59]
	s_add_i32 m0, s48, 0x2000
	s_nop 0
	global_load_lds_dwordx4 v164, s[58:59]
	v_lshl_add_u64 v[194:195], v[244:245], 0, s[54:55]
	s_mov_b32 m0, s36
	s_nop 0
	global_load_lds_dwordx4 v[194:195], off
	v_lshl_add_u64 v[194:195], v[246:247], 0, s[54:55]
	s_mov_b32 m0, s37
	s_nop 0
	global_load_lds_dwordx4 v[194:195], off
	s_waitcnt vmcnt(8)
	s_waitcnt lgkmcnt(0)
	s_barrier
	s_waitcnt lgkmcnt(0)
	v_mfma_f32_16x16x32_bf16 v[60:63], v[128:131], v[160:163], v[60:63]
	v_mfma_f32_16x16x32_bf16 v[56:59], v[136:139], v[160:163], v[56:59]
	v_mfma_f32_16x16x32_bf16 v[52:55], v[128:131], v[186:189], v[52:55]
	v_mfma_f32_16x16x32_bf16 v[48:51], v[136:139], v[186:189], v[48:51]
	v_mfma_f32_16x16x32_bf16 v[36:39], v[128:131], v[222:225], v[36:39]
	v_mfma_f32_16x16x32_bf16 v[32:35], v[136:139], v[222:225], v[32:35]
	v_mfma_f32_16x16x32_bf16 v[20:23], v[128:131], v[236:239], v[20:23]
	v_mfma_f32_16x16x32_bf16 v[16:19], v[136:139], v[236:239], v[16:19]
	v_mfma_f32_16x16x32_bf16 v[60:63], v[132:135], v[182:185], v[60:63]
	v_mfma_f32_16x16x32_bf16 v[56:59], v[140:143], v[182:185], v[56:59]
	v_mfma_f32_16x16x32_bf16 v[52:55], v[132:135], v[190:193], v[52:55]
	v_mfma_f32_16x16x32_bf16 v[48:51], v[140:143], v[190:193], v[48:51]
	v_mfma_f32_16x16x32_bf16 v[36:39], v[132:135], v[232:235], v[36:39]
	v_mfma_f32_16x16x32_bf16 v[32:35], v[140:143], v[232:235], v[32:35]
	v_mfma_f32_16x16x32_bf16 v[20:23], v[132:135], v[240:243], v[20:23]
	v_mfma_f32_16x16x32_bf16 v[16:19], v[140:143], v[240:243], v[16:19]
	v_mfma_f32_16x16x32_bf16 v[44:47], v[144:147], v[160:163], v[44:47]
	v_mfma_f32_16x16x32_bf16 v[40:43], v[152:155], v[160:163], v[40:43]
	v_mfma_f32_16x16x32_bf16 v[28:31], v[144:147], v[186:189], v[28:31]
	v_mfma_f32_16x16x32_bf16 v[24:27], v[152:155], v[186:189], v[24:27]
	v_mfma_f32_16x16x32_bf16 v[12:15], v[144:147], v[222:225], v[12:15]
	v_mfma_f32_16x16x32_bf16 v[8:11], v[152:155], v[222:225], v[8:11]
	v_mfma_f32_16x16x32_bf16 v[4:7], v[144:147], v[236:239], v[4:7]
	v_mfma_f32_16x16x32_bf16 v[0:3], v[152:155], v[236:239], v[0:3]
	v_mfma_f32_16x16x32_bf16 v[44:47], v[148:151], v[182:185], v[44:47]
	v_mfma_f32_16x16x32_bf16 v[40:43], v[156:159], v[182:185], v[40:43]
	v_mfma_f32_16x16x32_bf16 v[28:31], v[148:151], v[190:193], v[28:31]
	v_mfma_f32_16x16x32_bf16 v[24:27], v[156:159], v[190:193], v[24:27]
	v_mfma_f32_16x16x32_bf16 v[12:15], v[148:151], v[232:235], v[12:15]
	v_mfma_f32_16x16x32_bf16 v[8:11], v[156:159], v[232:235], v[8:11]
	v_mfma_f32_16x16x32_bf16 v[4:7], v[148:151], v[240:243], v[4:7]
	v_mfma_f32_16x16x32_bf16 v[0:3], v[156:159], v[240:243], v[0:3]
	s_add_i32 s39, s39, 2
	s_add_u32 s84, s84, 0x100
	s_addc_u32 s85, s85, 0
	s_add_u32 vcc_hi, vcc_hi, 0x100
	s_addc_u32 s38, s38, 0
	s_cmp_gt_u32 s39, 29
	s_barrier
.LBB0_364:
	ds_read_b128 v[128:131], v214
	ds_read_b128 v[132:135], v214 offset:1024
	ds_read_b128 v[136:139], v214 offset:2048
	ds_read_b128 v[140:143], v214 offset:3072
	ds_read_b128 v[144:147], v215
	ds_read_b128 v[148:151], v215 offset:1024
	ds_read_b128 v[152:155], v215 offset:2048
	ds_read_b128 v[156:159], v215 offset:3072
	s_add_u32 s58, s84, 0xfff80080
	s_addc_u32 s59, s85, -1
	s_cmp_eq_u32 s39, 28
	s_cselect_b32 s89, s77, s59
	s_cselect_b32 s88, s83, s58
	s_cselect_b32 s87, s75, s38
	s_cselect_b32 s86, vcc_lo, vcc_hi
	s_add_i32 m0, s7, 0xc000
	ds_read_b128 v[160:163], v216
	ds_read_b128 v[182:185], v216 offset:1024
	ds_read_b128 v[186:189], v216 offset:2048
	ds_read_b128 v[190:193], v216 offset:3072
	ds_read_b128 v[222:225], v216 offset:4096
	ds_read_b128 v[232:235], v216 offset:5120
	ds_read_b128 v[236:239], v216 offset:6144
	ds_read_b128 v[240:243], v216 offset:7168
	global_load_lds_dwordx4 v174, s[84:85]
	s_add_i32 m0, s7, 0xe000
	s_nop 0
	global_load_lds_dwordx4 v176, s[84:85]
	s_waitcnt vmcnt(8)
	s_waitcnt lgkmcnt(0)
	s_barrier
; #define PG8_STAGE(bufoff, gbase, voff) do { _Pragma("unroll") for (int _i = 0; _i < 2; ++_i) \
;         __builtin_amdgcn_global_load_lds((const unsigned*)((const char*)(gbase) + (voff)[_i]), (PG8_LAS unsigned*)(lds + (bufoff) + ldsw + _i * 8192), 16, 0, 0); } while (0)
; #define PG8_LDA(dst, b, h) do { _Pragma("unroll") for (int m = 0; m < 4; ++m) _Pragma("unroll") for (int k = 0; k < 2; ++k) dst[m][k] = *(const PG8_LAS bf16x8*)(lds + PG8_SA(b, h) + aoff + m * 2048 + k * 1024); } while (0)
; #define PG8_LDB(dst, b, h) do { _Pragma("unroll") for (int n = 0; n < 2; ++n) _Pragma("unroll") for (int k = 0; k < 2; ++k) dst[n][k] = *(const PG8_LAS bf16x8*)(lds + PG8_SB(b, h) + boff + n * 2048 + k * 1024); } while (0)
; #define PG8_MMA(ai, bj, At, Bt) do { __builtin_amdgcn_s_setprio(1); _Pragma("unroll") for (int m = 0; m < 4; ++m) _Pragma("unroll") for (int n = 0; n < 2; ++n) _Pragma("unroll") for (int k = 0; k < 2; ++k) \
;         acc[ai][bj][m][n] = __builtin_amdgcn_mfma_f32_16x16x32_bf16(Bt[n][k], At[m][k], acc[ai][bj][m][n], 0, 0, 0); __builtin_amdgcn_s_setprio(0); } while (0)
; #define PG8_WAIT_V(n) asm volatile("s_waitcnt vmcnt(" #n ")" ::: "memory")
; #define PG8_WAIT_L(n) asm volatile("s_waitcnt lgkmcnt(" #n ")" ::: "memory")
; #define PG8_BAR __builtin_amdgcn_s_barrier()
; #define PG8_SCHED __builtin_amdgcn_sched_barrier(0)
; template <class Epi, class Sched, bool ALIGN_EPI = false, bool SP2 = false>
; __device__ __forceinline__ void gemm_phase(PG8_LAS unsigned char* lds, const Gemm g, const Sched& S, const Epi& E) {
;     ...
;             PG8_LDB(B0, 0, 0); PG8_LDB(B1, 0, 1); PG8_SCHED; PG8_LDA(At, 0, 0); PG8_STAGE(PG8_SA(1, 1), a1 + hstep, voffA);
;             PG8_WAIT_V(8); PG8_WAIT_L(0); PG8_BAR; PG8_MMA(0, 0, At, B0); PG8_MMA(0, 1, At, B1); PG8_BAR; PG8_SCHED;
;             PG8_LDA(At, 0, 1); PG8_STAGE(PG8_SB(0, 0), b2, voffB); PG8_STAGE(PG8_SB(0, 1), b2 + hstep, voffB); PG8_STAGE(PG8_SA(0, 0), a2, voffA);
;             PG8_WAIT_V(8); PG8_WAIT_L(0); PG8_BAR; PG8_MMA(1, 0, At, B0); PG8_MMA(1, 1, At, B1); PG8_BAR; PG8_SCHED;
	s_waitcnt lgkmcnt(0)
	v_mfma_f32_16x16x32_bf16 v[124:127], v[128:131], v[160:163], v[124:127]
	v_mfma_f32_16x16x32_bf16 v[120:123], v[136:139], v[160:163], v[120:123]
	v_mfma_f32_16x16x32_bf16 v[116:119], v[128:131], v[186:189], v[116:119]
	v_mfma_f32_16x16x32_bf16 v[112:115], v[136:139], v[186:189], v[112:115]
	v_mfma_f32_16x16x32_bf16 v[100:103], v[128:131], v[222:225], v[100:103]
	v_mfma_f32_16x16x32_bf16 v[96:99], v[136:139], v[222:225], v[96:99]
	v_mfma_f32_16x16x32_bf16 v[84:87], v[128:131], v[236:239], v[84:87]
	v_mfma_f32_16x16x32_bf16 v[80:83], v[136:139], v[236:239], v[80:83]
	v_mfma_f32_16x16x32_bf16 v[124:127], v[132:135], v[182:185], v[124:127]
	v_mfma_f32_16x16x32_bf16 v[120:123], v[140:143], v[182:185], v[120:123]
	v_mfma_f32_16x16x32_bf16 v[116:119], v[132:135], v[190:193], v[116:119]
	v_mfma_f32_16x16x32_bf16 v[112:115], v[140:143], v[190:193], v[112:115]
	v_mfma_f32_16x16x32_bf16 v[100:103], v[132:135], v[232:235], v[100:103]
	v_mfma_f32_16x16x32_bf16 v[96:99], v[140:143], v[232:235], v[96:99]
	v_mfma_f32_16x16x32_bf16 v[84:87], v[132:135], v[240:243], v[84:87]
	v_mfma_f32_16x16x32_bf16 v[80:83], v[140:143], v[240:243], v[80:83]
	v_mfma_f32_16x16x32_bf16 v[108:111], v[144:147], v[160:163], v[108:111]
	v_mfma_f32_16x16x32_bf16 v[104:107], v[152:155], v[160:163], v[104:107]
	v_mfma_f32_16x16x32_bf16 v[92:95], v[144:147], v[186:189], v[92:95]
	v_mfma_f32_16x16x32_bf16 v[88:91], v[152:155], v[186:189], v[88:91]
	v_mfma_f32_16x16x32_bf16 v[76:79], v[144:147], v[222:225], v[76:79]
	v_mfma_f32_16x16x32_bf16 v[72:75], v[152:155], v[222:225], v[72:75]
	v_mfma_f32_16x16x32_bf16 v[68:71], v[144:147], v[236:239], v[68:71]
	v_mfma_f32_16x16x32_bf16 v[64:67], v[152:155], v[236:239], v[64:67]
	v_mfma_f32_16x16x32_bf16 v[108:111], v[148:151], v[182:185], v[108:111]
	v_mfma_f32_16x16x32_bf16 v[104:107], v[156:159], v[182:185], v[104:107]
	v_mfma_f32_16x16x32_bf16 v[92:95], v[148:151], v[190:193], v[92:95]
	v_mfma_f32_16x16x32_bf16 v[88:91], v[156:159], v[190:193], v[88:91]
	v_mfma_f32_16x16x32_bf16 v[76:79], v[148:151], v[232:235], v[76:79]
	v_mfma_f32_16x16x32_bf16 v[72:75], v[156:159], v[232:235], v[72:75]
	v_mfma_f32_16x16x32_bf16 v[68:71], v[148:151], v[240:243], v[68:71]
	v_mfma_f32_16x16x32_bf16 v[64:67], v[156:159], v[240:243], v[64:67]
	s_barrier
	s_add_i32 s58, s34, s24
	v_lshl_add_u64 v[194:195], s[86:87], 0, v[168:169]
	s_mov_b32 m0, s58
	ds_read_b128 v[160:163], v216 offset:16384
	ds_read_b128 v[182:185], v216 offset:17408
	ds_read_b128 v[186:189], v216 offset:18432
	ds_read_b128 v[190:193], v216 offset:19456
	ds_read_b128 v[222:225], v216 offset:20480
	ds_read_b128 v[232:235], v216 offset:21504
	ds_read_b128 v[236:239], v216 offset:22528
	ds_read_b128 v[240:243], v216 offset:23552
	global_load_lds_dwordx4 v168, s[86:87]
	s_add_i32 m0, s58, 0x2000
	s_add_u32 s58, s86, 0x80000
	v_lshl_add_u64 v[230:231], s[86:87], 0, v[164:165]
	s_addc_u32 s59, s87, 0
	s_add_i32 s48, s35, s24
	global_load_lds_dwordx4 v164, s[86:87]
	s_mov_b32 m0, s48
	v_lshl_add_u64 v[246:247], s[88:89], 0, v[166:167]
	global_load_lds_dwordx4 v168, s[58:59]
	s_add_i32 m0, s48, 0x2000
	s_nop 0
	global_load_lds_dwordx4 v164, s[58:59]
	v_lshl_add_u64 v[244:245], s[88:89], 0, v[170:171]
	s_mov_b32 m0, s7
	s_nop 0
	global_load_lds_dwordx4 v170, s[88:89]
	s_mov_b32 m0, s8
	s_nop 0
	global_load_lds_dwordx4 v166, s[88:89]
	s_waitcnt vmcnt(8)
	s_waitcnt lgkmcnt(0)
	s_barrier
	s_waitcnt lgkmcnt(0)
	v_mfma_f32_16x16x32_bf16 v[60:63], v[128:131], v[160:163], v[60:63]
	v_mfma_f32_16x16x32_bf16 v[56:59], v[136:139], v[160:163], v[56:59]
	v_mfma_f32_16x16x32_bf16 v[52:55], v[128:131], v[186:189], v[52:55]
	v_mfma_f32_16x16x32_bf16 v[48:51], v[136:139], v[186:189], v[48:51]
	v_mfma_f32_16x16x32_bf16 v[36:39], v[128:131], v[222:225], v[36:39]
	v_mfma_f32_16x16x32_bf16 v[32:35], v[136:139], v[222:225], v[32:35]
	v_mfma_f32_16x16x32_bf16 v[20:23], v[128:131], v[236:239], v[20:23]
	v_mfma_f32_16x16x32_bf16 v[16:19], v[136:139], v[236:239], v[16:19]
	v_mfma_f32_16x16x32_bf16 v[60:63], v[132:135], v[182:185], v[60:63]
	v_mfma_f32_16x16x32_bf16 v[56:59], v[140:143], v[182:185], v[56:59]
	v_mfma_f32_16x16x32_bf16 v[52:55], v[132:135], v[190:193], v[52:55]
	v_mfma_f32_16x16x32_bf16 v[48:51], v[140:143], v[190:193], v[48:51]
	v_mfma_f32_16x16x32_bf16 v[36:39], v[132:135], v[232:235], v[36:39]
	v_mfma_f32_16x16x32_bf16 v[32:35], v[140:143], v[232:235], v[32:35]
	v_mfma_f32_16x16x32_bf16 v[20:23], v[132:135], v[240:243], v[20:23]
	v_mfma_f32_16x16x32_bf16 v[16:19], v[140:143], v[240:243], v[16:19]
	v_mfma_f32_16x16x32_bf16 v[44:47], v[144:147], v[160:163], v[44:47]
	v_mfma_f32_16x16x32_bf16 v[40:43], v[152:155], v[160:163], v[40:43]
	v_mfma_f32_16x16x32_bf16 v[28:31], v[144:147], v[186:189], v[28:31]
	v_mfma_f32_16x16x32_bf16 v[24:27], v[152:155], v[186:189], v[24:27]
	v_mfma_f32_16x16x32_bf16 v[12:15], v[144:147], v[222:225], v[12:15]
	v_mfma_f32_16x16x32_bf16 v[8:11], v[152:155], v[222:225], v[8:11]
	v_mfma_f32_16x16x32_bf16 v[4:7], v[144:147], v[236:239], v[4:7]
	v_mfma_f32_16x16x32_bf16 v[0:3], v[152:155], v[236:239], v[0:3]
	v_mfma_f32_16x16x32_bf16 v[44:47], v[148:151], v[182:185], v[44:47]
	v_mfma_f32_16x16x32_bf16 v[40:43], v[156:159], v[182:185], v[40:43]
	v_mfma_f32_16x16x32_bf16 v[28:31], v[148:151], v[190:193], v[28:31]
	v_mfma_f32_16x16x32_bf16 v[24:27], v[156:159], v[190:193], v[24:27]
	v_mfma_f32_16x16x32_bf16 v[12:15], v[148:151], v[232:235], v[12:15]
	v_mfma_f32_16x16x32_bf16 v[8:11], v[156:159], v[232:235], v[8:11]
	v_mfma_f32_16x16x32_bf16 v[4:7], v[148:151], v[240:243], v[4:7]
	v_mfma_f32_16x16x32_bf16 v[0:3], v[156:159], v[240:243], v[0:3]
	s_barrier
; #define PG8_STAGE(bufoff, gbase, voff) do { _Pragma("unroll") for (int _i = 0; _i < 2; ++_i) \
;         __builtin_amdgcn_global_load_lds((const unsigned*)((const char*)(gbase) + (voff)[_i]), (PG8_LAS unsigned*)(lds + (bufoff) + ldsw + _i * 8192), 16, 0, 0); } while (0)
; #define PG8_LDA(dst, b, h) do { _Pragma("unroll") for (int m = 0; m < 4; ++m) _Pragma("unroll") for (int k = 0; k < 2; ++k) dst[m][k] = *(const PG8_LAS bf16x8*)(lds + PG8_SA(b, h) + aoff + m * 2048 + k * 1024); } while (0)
; #define PG8_LDB(dst, b, h) do { _Pragma("unroll") for (int n = 0; n < 2; ++n) _Pragma("unroll") for (int k = 0; k < 2; ++k) dst[n][k] = *(const PG8_LAS bf16x8*)(lds + PG8_SB(b, h) + boff + n * 2048 + k * 1024); } while (0)
; #define PG8_MMA(ai, bj, At, Bt) do { __builtin_amdgcn_s_setprio(1); _Pragma("unroll") for (int m = 0; m < 4; ++m) _Pragma("unroll") for (int n = 0; n < 2; ++n) _Pragma("unroll") for (int k = 0; k < 2; ++k) \
;         acc[ai][bj][m][n] = __builtin_amdgcn_mfma_f32_16x16x32_bf16(Bt[n][k], At[m][k], acc[ai][bj][m][n], 0, 0, 0); __builtin_amdgcn_s_setprio(0); } while (0)
; #define PG8_WAIT_V(n) asm volatile("s_waitcnt vmcnt(" #n ")" ::: "memory")
; #define PG8_WAIT_L(n) asm volatile("s_waitcnt lgkmcnt(" #n ")" ::: "memory")
; #define PG8_BAR __builtin_amdgcn_s_barrier()
; #define PG8_SCHED __builtin_amdgcn_sched_barrier(0)
; template <class Epi, class Sched, bool ALIGN_EPI = false, bool SP2 = false>
; __device__ __forceinline__ void gemm_phase(PG8_LAS unsigned char* lds, const Gemm g, const Sched& S, const Epi& E) {
;     ...
;             PG8_LDB(B0, 1, 0); PG8_LDB(B1, 1, 1); PG8_SCHED; PG8_LDA(At, 1, 0); PG8_STAGE(PG8_SA(0, 1), a2 + hstep, voffA);
;             PG8_WAIT_V(8); PG8_WAIT_L(0); PG8_BAR; PG8_MMA(0, 0, At, B0); PG8_MMA(0, 1, At, B1); PG8_BAR; PG8_SCHED;
;             PG8_LDA(At, 1, 1); PG8_STAGE(PG8_SB(1, 0), b3, voffB); PG8_STAGE(PG8_SB(1, 1), b3 + hstep, voffB); PG8_STAGE(PG8_SA(1, 0), a3, voffA);
;             PG8_WAIT_V(8); PG8_WAIT_L(0); PG8_BAR; PG8_MMA(1, 0, At, B0); PG8_MMA(1, 1, At, B1); PG8_BAR; PG8_SCHED;
	s_add_i32 s48, 0, 0x18000
	s_add_i32 s60, 0, 0x1c000
	v_add_u32_e32 v140, s48, v197
	v_add_u32_e32 v156, s60, v197
	ds_read_b128 v[128:131], v140
	ds_read_b128 v[132:135], v140 offset:1024
	ds_read_b128 v[136:139], v140 offset:2048
	ds_read_b128 v[140:143], v140 offset:3072
	ds_read_b128 v[144:147], v156
	ds_read_b128 v[148:151], v156 offset:1024
	ds_read_b128 v[152:155], v156 offset:2048
	ds_read_b128 v[156:159], v156 offset:3072
	s_add_u32 s58, s88, 0x80000
	s_addc_u32 s59, s89, 0
	s_mov_b32 m0, s9
	ds_read_b128 v[160:163], v216 offset:32768
	ds_read_b128 v[182:185], v216 offset:33792
	ds_read_b128 v[186:189], v216 offset:34816
	ds_read_b128 v[190:193], v216 offset:35840
	ds_read_b128 v[222:225], v216 offset:36864
	ds_read_b128 v[232:235], v216 offset:37888
	ds_read_b128 v[236:239], v216 offset:38912
	ds_read_b128 v[240:243], v216 offset:39936
	global_load_lds_dwordx4 v170, s[58:59]
	s_mov_b32 m0, s26
	s_nop 0
	global_load_lds_dwordx4 v166, s[58:59]
	s_waitcnt vmcnt(8)
	s_waitcnt lgkmcnt(0)
	s_barrier
	s_waitcnt lgkmcnt(0)
	v_mfma_f32_16x16x32_bf16 v[124:127], v[128:131], v[160:163], v[124:127]
	v_mfma_f32_16x16x32_bf16 v[120:123], v[136:139], v[160:163], v[120:123]
	v_mfma_f32_16x16x32_bf16 v[116:119], v[128:131], v[186:189], v[116:119]
	v_mfma_f32_16x16x32_bf16 v[112:115], v[136:139], v[186:189], v[112:115]
	v_mfma_f32_16x16x32_bf16 v[100:103], v[128:131], v[222:225], v[100:103]
	v_mfma_f32_16x16x32_bf16 v[96:99], v[136:139], v[222:225], v[96:99]
	v_mfma_f32_16x16x32_bf16 v[84:87], v[128:131], v[236:239], v[84:87]
	v_mfma_f32_16x16x32_bf16 v[80:83], v[136:139], v[236:239], v[80:83]
	v_mfma_f32_16x16x32_bf16 v[124:127], v[132:135], v[182:185], v[124:127]
	v_mfma_f32_16x16x32_bf16 v[120:123], v[140:143], v[182:185], v[120:123]
	v_mfma_f32_16x16x32_bf16 v[116:119], v[132:135], v[190:193], v[116:119]
	v_mfma_f32_16x16x32_bf16 v[112:115], v[140:143], v[190:193], v[112:115]
	v_mfma_f32_16x16x32_bf16 v[100:103], v[132:135], v[232:235], v[100:103]
	v_mfma_f32_16x16x32_bf16 v[96:99], v[140:143], v[232:235], v[96:99]
	v_mfma_f32_16x16x32_bf16 v[84:87], v[132:135], v[240:243], v[84:87]
	v_mfma_f32_16x16x32_bf16 v[80:83], v[140:143], v[240:243], v[80:83]
	v_mfma_f32_16x16x32_bf16 v[108:111], v[144:147], v[160:163], v[108:111]
	v_mfma_f32_16x16x32_bf16 v[104:107], v[152:155], v[160:163], v[104:107]
	v_mfma_f32_16x16x32_bf16 v[92:95], v[144:147], v[186:189], v[92:95]
	v_mfma_f32_16x16x32_bf16 v[88:91], v[152:155], v[186:189], v[88:91]
	v_mfma_f32_16x16x32_bf16 v[76:79], v[144:147], v[222:225], v[76:79]
	v_mfma_f32_16x16x32_bf16 v[72:75], v[152:155], v[222:225], v[72:75]
	v_mfma_f32_16x16x32_bf16 v[68:71], v[144:147], v[236:239], v[68:71]
	v_mfma_f32_16x16x32_bf16 v[64:67], v[152:155], v[236:239], v[64:67]
	v_mfma_f32_16x16x32_bf16 v[108:111], v[148:151], v[182:185], v[108:111]
	v_mfma_f32_16x16x32_bf16 v[104:107], v[156:159], v[182:185], v[104:107]
	v_mfma_f32_16x16x32_bf16 v[92:95], v[148:151], v[190:193], v[92:95]
	v_mfma_f32_16x16x32_bf16 v[88:91], v[156:159], v[190:193], v[88:91]
	v_mfma_f32_16x16x32_bf16 v[76:79], v[148:151], v[232:235], v[76:79]
	v_mfma_f32_16x16x32_bf16 v[72:75], v[156:159], v[232:235], v[72:75]
	v_mfma_f32_16x16x32_bf16 v[68:71], v[148:151], v[240:243], v[68:71]
	v_mfma_f32_16x16x32_bf16 v[64:67], v[156:159], v[240:243], v[64:67]
	s_barrier
	s_add_i32 s48, s48, s24
	v_lshl_add_u64 v[194:195], v[194:195], 0, s[54:55]
	s_mov_b32 m0, s48
	ds_read_b128 v[160:163], v216 offset:49152
	ds_read_b128 v[182:185], v216 offset:50176
	ds_read_b128 v[186:189], v216 offset:51200
	ds_read_b128 v[190:193], v216 offset:52224
	ds_read_b128 v[222:225], v216 offset:53248
	ds_read_b128 v[232:235], v216 offset:54272
	ds_read_b128 v[236:239], v216 offset:55296
	ds_read_b128 v[240:243], v216 offset:56320
	global_load_lds_dwordx4 v[194:195], off
	s_add_i32 m0, s48, 0x2000
	s_add_u32 s58, s86, 0x80080
	v_lshl_add_u64 v[194:195], v[230:231], 0, s[54:55]
	s_addc_u32 s59, s87, 0
	s_add_i32 s48, s60, s24
	global_load_lds_dwordx4 v[194:195], off
	s_mov_b32 m0, s48
	s_nop 0
	global_load_lds_dwordx4 v168, s[58:59]
	s_add_i32 m0, s48, 0x2000
	s_nop 0
	global_load_lds_dwordx4 v164, s[58:59]
	v_lshl_add_u64 v[194:195], v[244:245], 0, s[54:55]
	s_mov_b32 m0, s36
	s_nop 0
	global_load_lds_dwordx4 v[194:195], off
	v_lshl_add_u64 v[194:195], v[246:247], 0, s[54:55]
	s_mov_b32 m0, s37
	s_nop 0
	global_load_lds_dwordx4 v[194:195], off
	s_waitcnt vmcnt(8)
	s_waitcnt lgkmcnt(0)
	s_barrier
	s_waitcnt lgkmcnt(0)
	v_mfma_f32_16x16x32_bf16 v[60:63], v[128:131], v[160:163], v[60:63]
	v_mfma_f32_16x16x32_bf16 v[56:59], v[136:139], v[160:163], v[56:59]
	v_mfma_f32_16x16x32_bf16 v[52:55], v[128:131], v[186:189], v[52:55]
	v_mfma_f32_16x16x32_bf16 v[48:51], v[136:139], v[186:189], v[48:51]
	v_mfma_f32_16x16x32_bf16 v[36:39], v[128:131], v[222:225], v[36:39]
	v_mfma_f32_16x16x32_bf16 v[32:35], v[136:139], v[222:225], v[32:35]
	v_mfma_f32_16x16x32_bf16 v[20:23], v[128:131], v[236:239], v[20:23]
	v_mfma_f32_16x16x32_bf16 v[16:19], v[136:139], v[236:239], v[16:19]
	v_mfma_f32_16x16x32_bf16 v[60:63], v[132:135], v[182:185], v[60:63]
	v_mfma_f32_16x16x32_bf16 v[56:59], v[140:143], v[182:185], v[56:59]
	v_mfma_f32_16x16x32_bf16 v[52:55], v[132:135], v[190:193], v[52:55]
	v_mfma_f32_16x16x32_bf16 v[48:51], v[140:143], v[190:193], v[48:51]
	v_mfma_f32_16x16x32_bf16 v[36:39], v[132:135], v[232:235], v[36:39]
	v_mfma_f32_16x16x32_bf16 v[32:35], v[140:143], v[232:235], v[32:35]
	v_mfma_f32_16x16x32_bf16 v[20:23], v[132:135], v[240:243], v[20:23]
	v_mfma_f32_16x16x32_bf16 v[16:19], v[140:143], v[240:243], v[16:19]
	v_mfma_f32_16x16x32_bf16 v[44:47], v[144:147], v[160:163], v[44:47]
	v_mfma_f32_16x16x32_bf16 v[40:43], v[152:155], v[160:163], v[40:43]
	v_mfma_f32_16x16x32_bf16 v[28:31], v[144:147], v[186:189], v[28:31]
	v_mfma_f32_16x16x32_bf16 v[24:27], v[152:155], v[186:189], v[24:27]
	v_mfma_f32_16x16x32_bf16 v[12:15], v[144:147], v[222:225], v[12:15]
	v_mfma_f32_16x16x32_bf16 v[8:11], v[152:155], v[222:225], v[8:11]
	v_mfma_f32_16x16x32_bf16 v[4:7], v[144:147], v[236:239], v[4:7]
	v_mfma_f32_16x16x32_bf16 v[0:3], v[152:155], v[236:239], v[0:3]
	v_mfma_f32_16x16x32_bf16 v[44:47], v[148:151], v[182:185], v[44:47]
	v_mfma_f32_16x16x32_bf16 v[40:43], v[156:159], v[182:185], v[40:43]
	v_mfma_f32_16x16x32_bf16 v[28:31], v[148:151], v[190:193], v[28:31]
	v_mfma_f32_16x16x32_bf16 v[24:27], v[156:159], v[190:193], v[24:27]
	v_mfma_f32_16x16x32_bf16 v[12:15], v[148:151], v[232:235], v[12:15]
	v_mfma_f32_16x16x32_bf16 v[8:11], v[156:159], v[232:235], v[8:11]
	v_mfma_f32_16x16x32_bf16 v[4:7], v[148:151], v[240:243], v[4:7]
	v_mfma_f32_16x16x32_bf16 v[0:3], v[156:159], v[240:243], v[0:3]
	s_add_i32 s39, s39, 2
	s_add_u32 s84, s84, 0x100
	s_addc_u32 s85, s85, 0
	s_add_u32 vcc_hi, vcc_hi, 0x100
	s_addc_u32 s38, s38, 0
	s_cmp_gt_u32 s39, 29
	s_barrier
; __device__ __forceinline__ float fsigmoid(float v) { return __builtin_amdgcn_rcpf(1.0f + __builtin_amdgcn_exp2f(-LOG2E * v)); }
; __device__ __forceinline__ float fsilu(float v) { return v * fsigmoid(v); }
; __device__ __forceinline__ u32x4 pack8(const f32x4 a, const f32x4 b) { u32x4 w; w.x = cvt_pk_bf16(a[0], a[1]); w.y = cvt_pk_bf16(a[2], a[3]); w.z = cvt_pk_bf16(b[0], b[1]); w.w = cvt_pk_bf16(b[2], b[3]); return w; }
;     template <int ACT> __device__ __forceinline__ void ew(const f32x4 (&acc)[2][2][4][2], bf16_t* D, int ld, int row0, int col0) const {
; #pragma unroll
;         for (int ai = 0; ai < 2; ++ai)
; #pragma unroll
;             for (int m = 0; m < 4; ++m) { bf16_t* rowp = D + (size_t)(row0 + ai * HALF + m * 16) * ld + col0;
; #pragma unroll
;                 for (int bj = 0; bj < 2; ++bj) { f32x4 v0 = acc[ai][bj][m][0], v1 = acc[ai][bj][m][1];
;                     if (ACT == 1) {
; #pragma unroll
;                         for (int j = 0; j < 4; ++j) { v0[j] = fsilu(v0[j]); v1[j] = fsilu(v1[j]); } }
;                     if (ACT == 2) {
; #pragma unroll
;                         for (int j = 0; j < 4; ++j) { v0[j] = fsigmoid(v0[j]); v1[j] = fsigmoid(v1[j]); } }
;                     *(u32x4*)(rowp + bj * HALF) = pack8(v0, v1); } }
;     }
;     __device__ __forceinline__ void operator()(const f32x4 (&acc)[2][2][4][2], const Unit& u, int wr, int wc, int fr, int fq) const {
;         const int pn = u.pn, row0 = u.pm * BM + wr * 64 + fr, cl = wc * 32 + 8 * fq;
;         if (pn < 4) ew<0>(acc, HQ, 1024, row0, pn * 256 + cl);
;     ...
;         else if (pn < 28) ew<0>(acc, DV, 1024, row0, (pn - 24) * 256 + cl);
;         else if (pn < 36) ew<2>(acc, SGA, 2048, row0, (pn - 28) * 256 + cl);
;         else ew<2>(acc, SGB, 2048, row0, (pn - 36) * 256 + cl);
	s_cbranch_scc0 .LBB0_364
	v_lshl_add_u32 v182, s82, 8, v196
	s_cmp_gt_i32 s23, 3
	s_mov_b64 s[82:83], -1
	s_cbranch_scc0 .LBB0_391
	s_cmp_gt_u32 s23, 7
	s_cbranch_scc0 .LBB0_388
	s_cmp_gt_u32 s23, 11
	s_cbranch_scc0 .LBB0_385
	s_cmp_gt_u32 s23, 15
	s_cbranch_scc0 .LBB0_382
	s_cmp_gt_u32 s23, 23
	s_cbranch_scc0 .LBB0_379
	s_lshl_b32 s75, s23, 8
	s_cmp_gt_u32 s23, 27
	s_cbranch_scc0 .LBB0_376
	v_mul_f32_e32 v129, 0xbfb8aa3b, v120
	v_exp_f32_e32 v129, v129
	v_mul_f32_e32 v130, 0xbfb8aa3b, v125
	v_mul_f32_e32 v131, 0xbfb8aa3b, v121
	v_exp_f32_e32 v130, v130
	v_exp_f32_e32 v131, v131
	v_add_f32_e32 v129, 1.0, v129
	v_mul_f32_e32 v128, 0xbfb8aa3b, v124
	v_rcp_f32_e32 v132, v129
	v_add_f32_e32 v129, 1.0, v130
	v_add_f32_e32 v130, 1.0, v131
	v_mul_f32_e32 v131, 0xbfb8aa3b, v126
	v_mul_f32_e32 v134, 0xbfb8aa3b, v127
	v_exp_f32_e32 v128, v128
	v_exp_f32_e32 v131, v131
	v_exp_f32_e32 v134, v134
	v_rcp_f32_e32 v129, v129
	v_add_f32_e32 v128, 1.0, v128
	v_add_f32_e32 v131, 1.0, v131
	v_add_f32_e32 v134, 1.0, v134
	v_rcp_f32_e32 v128, v128
	v_mul_f32_e32 v133, 0xbfb8aa3b, v122
	v_rcp_f32_e32 v131, v131
	v_mul_f32_e32 v135, 0xbfb8aa3b, v123
	v_rcp_f32_e32 v134, v134
	v_exp_f32_e32 v133, v133
	v_rcp_f32_e32 v130, v130
	v_exp_f32_e32 v135, v135
	v_cvt_pk_bf16_f32 v128, v128, v129
	v_cvt_pk_bf16_f32 v129, v131, v134
	v_mul_f32_e32 v131, 0xbfb8aa3b, v108
	v_add_f32_e32 v133, 1.0, v133
	v_add_f32_e32 v135, 1.0, v135
	v_cvt_pk_bf16_f32 v130, v132, v130
	v_exp_f32_e32 v132, v131
	v_mul_f32_e32 v131, 0xbfb8aa3b, v104
	v_rcp_f32_e32 v133, v133
	v_rcp_f32_e32 v135, v135
	v_exp_f32_e32 v134, v131
	v_mul_f32_e32 v137, 0xbfb8aa3b, v106
	v_mul_f32_e32 v138, 0xbfb8aa3b, v111
	v_cvt_pk_bf16_f32 v131, v133, v135
	v_add_f32_e32 v133, 1.0, v134
	v_mul_f32_e32 v134, 0xbfb8aa3b, v109
	v_mul_f32_e32 v135, 0xbfb8aa3b, v105
	v_exp_f32_e32 v134, v134
	v_exp_f32_e32 v135, v135
	v_rcp_f32_e32 v136, v133
	v_mul_f32_e32 v139, 0xbfb8aa3b, v107
	v_add_f32_e32 v133, 1.0, v134
	v_add_f32_e32 v134, 1.0, v135
	v_mul_f32_e32 v135, 0xbfb8aa3b, v110
	v_exp_f32_e32 v135, v135
	v_exp_f32_e32 v137, v137
	v_exp_f32_e32 v138, v138
	v_exp_f32_e32 v139, v139
	v_add_f32_e32 v132, 1.0, v132
	v_add_f32_e32 v135, 1.0, v135
	v_add_f32_e32 v137, 1.0, v137
	v_add_f32_e32 v138, 1.0, v138
	v_add_f32_e32 v139, 1.0, v139
	v_rcp_f32_e32 v132, v132
	v_rcp_f32_e32 v133, v133
	v_rcp_f32_e32 v135, v135
	v_rcp_f32_e32 v137, v137
	v_rcp_f32_e32 v138, v138
	v_rcp_f32_e32 v139, v139
	v_rcp_f32_e32 v134, v134
	v_cvt_pk_bf16_f32 v132, v132, v133
	v_cvt_pk_bf16_f32 v133, v135, v138
	v_cvt_pk_bf16_f32 v135, v137, v139
	v_mul_f32_e32 v138, 0xbfb8aa3b, v116
	v_mul_f32_e32 v139, 0xbfb8aa3b, v112
	v_exp_f32_e32 v138, v138
	v_exp_f32_e32 v139, v139
	v_cvt_pk_bf16_f32 v134, v136, v134
	v_or_b32_e32 v136, 16, v182
	v_ashrrev_i32_e32 v137, 31, v136
	v_lshlrev_b64 v[186:187], 12, v[136:137]
	v_add_f32_e32 v136, 1.0, v138
	v_add_f32_e32 v137, 1.0, v139
	v_mul_f32_e32 v138, 0xbfb8aa3b, v117
	v_mul_f32_e32 v139, 0xbfb8aa3b, v113
	v_exp_f32_e32 v138, v138
	v_exp_f32_e32 v139, v139
	v_rcp_f32_e32 v140, v137
	v_mul_f32_e32 v142, 0xbfb8aa3b, v119
	v_add_f32_e32 v137, 1.0, v138
	v_add_f32_e32 v138, 1.0, v139
	v_mul_f32_e32 v139, 0xbfb8aa3b, v118
	v_exp_f32_e32 v139, v139
	v_exp_f32_e32 v142, v142
	v_rcp_f32_e32 v136, v136
	v_rcp_f32_e32 v137, v137
	v_add_f32_e32 v139, 1.0, v139
	v_add_f32_e32 v142, 1.0, v142
	v_mul_f32_e32 v141, 0xbfb8aa3b, v114
	v_rcp_f32_e32 v139, v139
	v_mul_f32_e32 v143, 0xbfb8aa3b, v115
	v_rcp_f32_e32 v142, v142
	v_exp_f32_e32 v141, v141
	v_rcp_f32_e32 v138, v138
	v_exp_f32_e32 v143, v143
	v_cvt_pk_bf16_f32 v136, v136, v137
	v_cvt_pk_bf16_f32 v137, v139, v142
	v_mul_f32_e32 v139, 0xbfb8aa3b, v92
	v_add_f32_e32 v141, 1.0, v141
	v_add_f32_e32 v143, 1.0, v143
	v_cvt_pk_bf16_f32 v138, v140, v138
	v_exp_f32_e32 v140, v139
	v_mul_f32_e32 v139, 0xbfb8aa3b, v88
	v_rcp_f32_e32 v141, v141
	v_rcp_f32_e32 v143, v143
	v_exp_f32_e32 v142, v139
	v_mul_f32_e32 v145, 0xbfb8aa3b, v90
	v_mul_f32_e32 v146, 0xbfb8aa3b, v95
	v_cvt_pk_bf16_f32 v139, v141, v143
	v_add_f32_e32 v141, 1.0, v142
	v_mul_f32_e32 v142, 0xbfb8aa3b, v93
	v_mul_f32_e32 v143, 0xbfb8aa3b, v89
	v_exp_f32_e32 v142, v142
	v_exp_f32_e32 v143, v143
	v_rcp_f32_e32 v144, v141
	v_mul_f32_e32 v147, 0xbfb8aa3b, v91
	v_add_f32_e32 v141, 1.0, v142
	v_add_f32_e32 v142, 1.0, v143
	v_mul_f32_e32 v143, 0xbfb8aa3b, v94
	v_exp_f32_e32 v143, v143
	v_exp_f32_e32 v145, v145
	v_exp_f32_e32 v146, v146
	v_exp_f32_e32 v147, v147
	v_add_f32_e32 v140, 1.0, v140
	v_add_f32_e32 v143, 1.0, v143
	v_add_f32_e32 v145, 1.0, v145
	v_add_f32_e32 v146, 1.0, v146
	v_add_f32_e32 v147, 1.0, v147
	v_rcp_f32_e32 v140, v140
	v_rcp_f32_e32 v141, v141
	v_rcp_f32_e32 v143, v143
	v_rcp_f32_e32 v145, v145
	v_rcp_f32_e32 v146, v146
	v_rcp_f32_e32 v147, v147
	v_rcp_f32_e32 v142, v142
	v_cvt_pk_bf16_f32 v140, v140, v141
	v_cvt_pk_bf16_f32 v141, v143, v146
	v_cvt_pk_bf16_f32 v143, v145, v147
	v_mul_f32_e32 v146, 0xbfb8aa3b, v100
	v_mul_f32_e32 v147, 0xbfb8aa3b, v96
	v_exp_f32_e32 v146, v146
	v_exp_f32_e32 v147, v147
	v_cvt_pk_bf16_f32 v142, v144, v142
	v_or_b32_e32 v144, 32, v182
	v_ashrrev_i32_e32 v145, 31, v144
	v_lshlrev_b64 v[188:189], 12, v[144:145]
	v_add_f32_e32 v144, 1.0, v146
	v_add_f32_e32 v145, 1.0, v147
	v_mul_f32_e32 v146, 0xbfb8aa3b, v101
	v_mul_f32_e32 v147, 0xbfb8aa3b, v97
	v_exp_f32_e32 v146, v146
	v_exp_f32_e32 v147, v147
	v_rcp_f32_e32 v148, v145
	v_mul_f32_e32 v150, 0xbfb8aa3b, v103
	v_add_f32_e32 v145, 1.0, v146
	v_add_f32_e32 v146, 1.0, v147
	v_mul_f32_e32 v147, 0xbfb8aa3b, v102
	v_exp_f32_e32 v147, v147
	v_exp_f32_e32 v150, v150
	v_rcp_f32_e32 v144, v144
	v_rcp_f32_e32 v145, v145
; __device__ __forceinline__ float fsigmoid(float v) { return __builtin_amdgcn_rcpf(1.0f + __builtin_amdgcn_exp2f(-LOG2E * v)); }
; __device__ __forceinline__ float fsilu(float v) { return v * fsigmoid(v); }
; __device__ __forceinline__ u32x4 pack8(const f32x4 a, const f32x4 b) { u32x4 w; w.x = cvt_pk_bf16(a[0], a[1]); w.y = cvt_pk_bf16(a[2], a[3]); w.z = cvt_pk_bf16(b[0], b[1]); w.w = cvt_pk_bf16(b[2], b[3]); return w; }
;     template <int ACT> __device__ __forceinline__ void ew(const f32x4 (&acc)[2][2][4][2], bf16_t* D, int ld, int row0, int col0) const {
; #pragma unroll
;         for (int ai = 0; ai < 2; ++ai)
; #pragma unroll
;             for (int m = 0; m < 4; ++m) { bf16_t* rowp = D + (size_t)(row0 + ai * HALF + m * 16) * ld + col0;
; #pragma unroll
;                 for (int bj = 0; bj < 2; ++bj) { f32x4 v0 = acc[ai][bj][m][0], v1 = acc[ai][bj][m][1];
;                     if (ACT == 1) {
; #pragma unroll
;                         for (int j = 0; j < 4; ++j) { v0[j] = fsilu(v0[j]); v1[j] = fsilu(v1[j]); } }
;                     if (ACT == 2) {
; #pragma unroll
;                         for (int j = 0; j < 4; ++j) { v0[j] = fsigmoid(v0[j]); v1[j] = fsigmoid(v1[j]); } }
;                     *(u32x4*)(rowp + bj * HALF) = pack8(v0, v1); } }
;     }
;     __device__ __forceinline__ void operator()(const f32x4 (&acc)[2][2][4][2], const Unit& u, int wr, int wc, int fr, int fq) const {
;     ...
;         else if (pn < 36) ew<2>(acc, SGA, 2048, row0, (pn - 28) * 256 + cl);
;         else ew<2>(acc, SGB, 2048, row0, (pn - 36) * 256 + cl);
	v_add_f32_e32 v147, 1.0, v147
	v_add_f32_e32 v150, 1.0, v150
	v_mul_f32_e32 v149, 0xbfb8aa3b, v98
	v_rcp_f32_e32 v147, v147
	v_mul_f32_e32 v151, 0xbfb8aa3b, v99
	v_rcp_f32_e32 v150, v150
	v_exp_f32_e32 v149, v149
	v_rcp_f32_e32 v146, v146
	v_exp_f32_e32 v151, v151
	v_cvt_pk_bf16_f32 v144, v144, v145
	v_cvt_pk_bf16_f32 v145, v147, v150
	v_mul_f32_e32 v147, 0xbfb8aa3b, v76
	v_add_f32_e32 v149, 1.0, v149
	v_add_f32_e32 v151, 1.0, v151
	v_cvt_pk_bf16_f32 v146, v148, v146
	v_exp_f32_e32 v148, v147
	v_mul_f32_e32 v147, 0xbfb8aa3b, v72
	v_rcp_f32_e32 v149, v149
	v_rcp_f32_e32 v151, v151
	v_exp_f32_e32 v150, v147
	v_mul_f32_e32 v153, 0xbfb8aa3b, v74
	v_mul_f32_e32 v154, 0xbfb8aa3b, v79
	v_cvt_pk_bf16_f32 v147, v149, v151
	v_add_f32_e32 v149, 1.0, v150
	v_mul_f32_e32 v150, 0xbfb8aa3b, v77
	v_mul_f32_e32 v151, 0xbfb8aa3b, v73
	v_exp_f32_e32 v150, v150
	v_exp_f32_e32 v151, v151
	v_rcp_f32_e32 v152, v149
	v_mul_f32_e32 v155, 0xbfb8aa3b, v75
	v_add_f32_e32 v149, 1.0, v150
	v_add_f32_e32 v150, 1.0, v151
	v_mul_f32_e32 v151, 0xbfb8aa3b, v78
	v_exp_f32_e32 v151, v151
	v_exp_f32_e32 v153, v153
	v_exp_f32_e32 v154, v154
	v_exp_f32_e32 v155, v155
	v_add_f32_e32 v148, 1.0, v148
	v_add_f32_e32 v151, 1.0, v151
	v_add_f32_e32 v153, 1.0, v153
	v_add_f32_e32 v154, 1.0, v154
	v_add_f32_e32 v155, 1.0, v155
	v_rcp_f32_e32 v148, v148
	v_rcp_f32_e32 v149, v149
	v_rcp_f32_e32 v151, v151
	v_rcp_f32_e32 v153, v153
	v_rcp_f32_e32 v154, v154
	v_rcp_f32_e32 v155, v155
	v_rcp_f32_e32 v150, v150
	v_cvt_pk_bf16_f32 v148, v148, v149
	v_cvt_pk_bf16_f32 v149, v151, v154
	v_cvt_pk_bf16_f32 v151, v153, v155
	v_mul_f32_e32 v154, 0xbfb8aa3b, v84
	v_mul_f32_e32 v155, 0xbfb8aa3b, v80
	v_exp_f32_e32 v154, v154
	v_exp_f32_e32 v155, v155
	v_cvt_pk_bf16_f32 v150, v152, v150
	v_or_b32_e32 v152, 48, v182
	v_ashrrev_i32_e32 v153, 31, v152
	v_lshlrev_b64 v[190:191], 12, v[152:153]
	v_add_f32_e32 v152, 1.0, v154
	v_add_f32_e32 v153, 1.0, v155
	v_mul_f32_e32 v154, 0xbfb8aa3b, v85
	v_mul_f32_e32 v155, 0xbfb8aa3b, v81
	v_exp_f32_e32 v154, v154
	v_exp_f32_e32 v155, v155
	v_rcp_f32_e32 v156, v153
	v_mul_f32_e32 v158, 0xbfb8aa3b, v87
	v_add_f32_e32 v153, 1.0, v154
	v_add_f32_e32 v154, 1.0, v155
	v_mul_f32_e32 v155, 0xbfb8aa3b, v86
	v_exp_f32_e32 v155, v155
	v_exp_f32_e32 v158, v158
	v_rcp_f32_e32 v152, v152
	v_rcp_f32_e32 v153, v153
	v_add_f32_e32 v155, 1.0, v155
	v_add_f32_e32 v158, 1.0, v158
	v_mul_f32_e32 v157, 0xbfb8aa3b, v82
	v_rcp_f32_e32 v155, v155
	v_mul_f32_e32 v159, 0xbfb8aa3b, v83
	v_rcp_f32_e32 v158, v158
	v_exp_f32_e32 v157, v157
	v_rcp_f32_e32 v154, v154
	v_exp_f32_e32 v159, v159
	v_cvt_pk_bf16_f32 v152, v152, v153
	v_cvt_pk_bf16_f32 v153, v155, v158
	v_mul_f32_e32 v155, 0xbfb8aa3b, v68
	v_add_f32_e32 v157, 1.0, v157
	v_add_f32_e32 v159, 1.0, v159
	v_cvt_pk_bf16_f32 v154, v156, v154
	v_exp_f32_e32 v156, v155
	v_mul_f32_e32 v155, 0xbfb8aa3b, v64
	v_rcp_f32_e32 v157, v157
	v_rcp_f32_e32 v159, v159
	v_exp_f32_e32 v158, v155
	v_mul_f32_e32 v161, 0xbfb8aa3b, v66
	v_mul_f32_e32 v162, 0xbfb8aa3b, v71
	v_cvt_pk_bf16_f32 v155, v157, v159
	v_add_f32_e32 v157, 1.0, v158
	v_mul_f32_e32 v158, 0xbfb8aa3b, v69
	v_mul_f32_e32 v159, 0xbfb8aa3b, v65
	v_exp_f32_e32 v158, v158
	v_exp_f32_e32 v159, v159
	v_rcp_f32_e32 v160, v157
	v_mul_f32_e32 v163, 0xbfb8aa3b, v67
	v_add_f32_e32 v157, 1.0, v158
	v_add_f32_e32 v158, 1.0, v159
	v_mul_f32_e32 v159, 0xbfb8aa3b, v70
	v_exp_f32_e32 v159, v159
	v_exp_f32_e32 v161, v161
	v_exp_f32_e32 v162, v162
	v_exp_f32_e32 v163, v163
	v_add_f32_e32 v156, 1.0, v156
	v_add_f32_e32 v159, 1.0, v159
	v_add_f32_e32 v161, 1.0, v161
	v_add_f32_e32 v162, 1.0, v162
	v_add_f32_e32 v163, 1.0, v163
	v_rcp_f32_e32 v156, v156
	v_rcp_f32_e32 v157, v157
	v_rcp_f32_e32 v159, v159
	v_rcp_f32_e32 v161, v161
	v_rcp_f32_e32 v162, v162
	v_rcp_f32_e32 v163, v163
	v_cvt_pk_bf16_f32 v156, v156, v157
	v_rcp_f32_e32 v158, v158
	v_cvt_pk_bf16_f32 v157, v159, v162
	v_cvt_pk_bf16_f32 v159, v161, v163
	v_mul_f32_e32 v161, 0xbfb8aa3b, v56
	v_exp_f32_e32 v161, v161
	v_mul_f32_e32 v162, 0xbfb8aa3b, v61
	v_mul_f32_e32 v163, 0xbfb8aa3b, v57
	v_exp_f32_e32 v162, v162
	v_exp_f32_e32 v163, v163
	v_add_f32_e32 v161, 1.0, v161
	v_cvt_pk_bf16_f32 v158, v160, v158
	v_mul_f32_e32 v160, 0xbfb8aa3b, v60
	v_rcp_f32_e32 v172, v161
	v_add_f32_e32 v161, 1.0, v162
	v_add_f32_e32 v162, 1.0, v163
	v_mul_f32_e32 v163, 0xbfb8aa3b, v62
	v_mul_f32_e32 v194, 0xbfb8aa3b, v58
	v_mul_f32_e32 v195, 0xbfb8aa3b, v63
	v_mul_f32_e32 v212, 0xbfb8aa3b, v59
	v_exp_f32_e32 v160, v160
	v_exp_f32_e32 v163, v163
	v_exp_f32_e32 v194, v194
	v_exp_f32_e32 v195, v195
	v_exp_f32_e32 v212, v212
	v_add_f32_e32 v160, 1.0, v160
	v_add_f32_e32 v163, 1.0, v163
	v_add_f32_e32 v194, 1.0, v194
	v_add_f32_e32 v195, 1.0, v195
	v_add_f32_e32 v212, 1.0, v212
	v_rcp_f32_e32 v160, v160
	v_rcp_f32_e32 v161, v161
	v_rcp_f32_e32 v162, v162
	v_rcp_f32_e32 v163, v163
	v_rcp_f32_e32 v194, v194
	v_rcp_f32_e32 v195, v195
	v_rcp_f32_e32 v212, v212
	v_ashrrev_i32_e32 v183, 31, v182
	v_lshlrev_b64 v[184:185], 12, v[182:183]
	s_mov_b64 s[38:39], 0x80000
	s_cmp_gt_u32 s23, 35
	v_lshl_add_u64 v[192:193], v[184:185], 0, s[38:39]
	v_cvt_pk_bf16_f32 v160, v160, v161
	v_cvt_pk_bf16_f32 v161, v163, v195
	v_cvt_pk_bf16_f32 v162, v172, v162
	v_cvt_pk_bf16_f32 v163, v194, v212
	s_cbranch_scc0 .LBB0_373
; __device__ __forceinline__ float fsigmoid(float v) { return __builtin_amdgcn_rcpf(1.0f + __builtin_amdgcn_exp2f(-LOG2E * v)); }
; __device__ __forceinline__ float fsilu(float v) { return v * fsigmoid(v); }
; __device__ __forceinline__ u32x4 pack8(const f32x4 a, const f32x4 b) { u32x4 w; w.x = cvt_pk_bf16(a[0], a[1]); w.y = cvt_pk_bf16(a[2], a[3]); w.z = cvt_pk_bf16(b[0], b[1]); w.w = cvt_pk_bf16(b[2], b[3]); return w; }
;     template <int ACT> __device__ __forceinline__ void ew(const f32x4 (&acc)[2][2][4][2], bf16_t* D, int ld, int row0, int col0) const {
; #pragma unroll
;         for (int ai = 0; ai < 2; ++ai)
; #pragma unroll
;             for (int m = 0; m < 4; ++m) { bf16_t* rowp = D + (size_t)(row0 + ai * HALF + m * 16) * ld + col0;
; #pragma unroll
;                 for (int bj = 0; bj < 2; ++bj) { f32x4 v0 = acc[ai][bj][m][0], v1 = acc[ai][bj][m][1];
;                     if (ACT == 1) {
; #pragma unroll
;                         for (int j = 0; j < 4; ++j) { v0[j] = fsilu(v0[j]); v1[j] = fsilu(v1[j]); } }
;                     if (ACT == 2) {
; #pragma unroll
;                         for (int j = 0; j < 4; ++j) { v0[j] = fsigmoid(v0[j]); v1[j] = fsigmoid(v1[j]); } }
;                     *(u32x4*)(rowp + bj * HALF) = pack8(v0, v1); } }
;     }
	v_readlane_b32 s38, v255, 23
	v_add_u32_e32 v172, s75, v199
	v_readlane_b32 s39, v255, 24
	v_mul_f32_e32 v212, 0xbfb8aa3b, v40
	v_mul_f32_e32 v220, 0xbfb8aa3b, v45
	v_lshl_add_u64 v[222:223], v[172:173], 1, s[38:39]
	v_lshl_add_u64 v[194:195], v[222:223], 0, v[184:185]
	v_lshl_add_u64 v[224:225], v[222:223], 0, v[186:187]
	global_store_dwordx4 v[194:195], v[128:131], off
	global_store_dwordx4 v[194:195], v[132:135], off offset:256
	global_store_dwordx4 v[224:225], v[136:139], off
	global_store_dwordx4 v[224:225], v[140:143], off offset:256
	v_lshl_add_u64 v[224:225], v[222:223], 0, v[188:189]
	global_store_dwordx4 v[224:225], v[144:147], off
	global_store_dwordx4 v[224:225], v[148:151], off offset:256
	v_lshl_add_u64 v[224:225], v[222:223], 0, v[190:191]
	v_lshl_add_u64 v[230:231], v[222:223], 0, v[192:193]
	v_mul_f32_e32 v222, 0xbfb8aa3b, v41
	v_exp_f32_e32 v222, v222
	v_mul_f32_e32 v223, 0xbfb8aa3b, v46
	global_store_dwordx4 v[224:225], v[152:155], off
	global_store_dwordx4 v[224:225], v[156:159], off offset:256
	v_exp_f32_e32 v223, v223
	v_mul_f32_e32 v224, 0xbfb8aa3b, v42
	v_exp_f32_e32 v224, v224
	v_add_f32_e32 v222, 1.0, v222
	v_rcp_f32_e32 v225, v222
	v_add_f32_e32 v222, 1.0, v223
	v_rcp_f32_e32 v223, v222
	v_add_f32_e32 v222, 1.0, v224
	v_mul_f32_e32 v224, 0xbfb8aa3b, v47
	v_mul_f32_e32 v172, 0xbfb8aa3b, v44
	v_exp_f32_e32 v224, v224
	v_mul_f32_e32 v232, 0xbfb8aa3b, v43
	v_exp_f32_e32 v172, v172
	v_exp_f32_e32 v212, v212
	v_exp_f32_e32 v220, v220
	v_exp_f32_e32 v232, v232
	v_rcp_f32_e32 v233, v222
	v_add_f32_e32 v222, 1.0, v224
	v_add_f32_e32 v172, 1.0, v172
	v_add_f32_e32 v212, 1.0, v212
	v_add_f32_e32 v220, 1.0, v220
	v_rcp_f32_e32 v224, v222
	v_add_f32_e32 v222, 1.0, v232
	v_rcp_f32_e32 v172, v172
	v_rcp_f32_e32 v212, v212
	v_rcp_f32_e32 v220, v220
	v_rcp_f32_e32 v232, v222
	v_cvt_pk_bf16_f32 v223, v223, v224
	v_cvt_pk_bf16_f32 v224, v212, v225
	v_cvt_pk_bf16_f32 v222, v172, v220
	v_cvt_pk_bf16_f32 v225, v233, v232
	global_store_dwordx4 v[230:231], v[222:225], off offset:256
	v_mul_f32_e32 v212, 0xbfb8aa3b, v48
	v_mul_f32_e32 v232, 0xbfb8aa3b, v51
	v_mul_f32_e32 v222, 0xbfb8aa3b, v49
	v_exp_f32_e32 v222, v222
	v_mul_f32_e32 v223, 0xbfb8aa3b, v54
	v_exp_f32_e32 v223, v223
	v_mul_f32_e32 v224, 0xbfb8aa3b, v50
	v_exp_f32_e32 v224, v224
	v_add_f32_e32 v222, 1.0, v222
	v_rcp_f32_e32 v225, v222
	v_add_f32_e32 v222, 1.0, v223
	v_rcp_f32_e32 v223, v222
	v_add_f32_e32 v222, 1.0, v224
	v_mul_f32_e32 v224, 0xbfb8aa3b, v55
	v_exp_f32_e32 v224, v224
	v_mul_f32_e32 v172, 0xbfb8aa3b, v52
	v_exp_f32_e32 v212, v212
	v_mul_f32_e32 v220, 0xbfb8aa3b, v53
	v_exp_f32_e32 v232, v232
	v_exp_f32_e32 v172, v172
	v_exp_f32_e32 v220, v220
	v_rcp_f32_e32 v233, v222
	v_add_f32_e32 v222, 1.0, v224
	v_add_f32_e32 v212, 1.0, v212
	v_rcp_f32_e32 v224, v222
	v_add_f32_e32 v222, 1.0, v232
	v_add_f32_e32 v172, 1.0, v172
	v_rcp_f32_e32 v212, v212
	v_add_f32_e32 v220, 1.0, v220
	v_rcp_f32_e32 v232, v222
	v_rcp_f32_e32 v172, v172
	v_rcp_f32_e32 v220, v220
	s_mov_b64 s[38:39], 0x90000
	global_store_dwordx4 v[230:231], v[160:163], off
	v_lshl_add_u64 v[230:231], v[194:195], 0, s[38:39]
	s_mov_b32 s38, 0x90000
	v_cvt_pk_bf16_f32 v223, v223, v224
	v_cvt_pk_bf16_f32 v224, v212, v225
	v_cvt_pk_bf16_f32 v225, v233, v232
	v_add_co_u32_e32 v232, vcc, s38, v194
	v_cvt_pk_bf16_f32 v222, v172, v220
	s_nop 0
	v_addc_co_u32_e32 v233, vcc, 0, v195, vcc
	global_store_dwordx4 v[232:233], v[222:225], off
	v_mul_f32_e32 v172, 0xbfb8aa3b, v28
	v_mul_f32_e32 v212, 0xbfb8aa3b, v24
	v_mul_f32_e32 v222, 0xbfb8aa3b, v25
	v_exp_f32_e32 v222, v222
	v_mul_f32_e32 v223, 0xbfb8aa3b, v30
	v_exp_f32_e32 v223, v223
	v_mul_f32_e32 v224, 0xbfb8aa3b, v26
	v_exp_f32_e32 v224, v224
	v_add_f32_e32 v222, 1.0, v222
	v_rcp_f32_e32 v225, v222
	v_add_f32_e32 v222, 1.0, v223
	v_rcp_f32_e32 v223, v222
	v_add_f32_e32 v222, 1.0, v224
	v_mul_f32_e32 v224, 0xbfb8aa3b, v31
	v_mul_f32_e32 v220, 0xbfb8aa3b, v29
	v_exp_f32_e32 v224, v224
	v_mul_f32_e32 v232, 0xbfb8aa3b, v27
	v_exp_f32_e32 v172, v172
	v_exp_f32_e32 v212, v212
	v_exp_f32_e32 v220, v220
	v_exp_f32_e32 v232, v232
	v_rcp_f32_e32 v233, v222
	v_add_f32_e32 v222, 1.0, v224
	v_add_f32_e32 v172, 1.0, v172
	v_add_f32_e32 v212, 1.0, v212
	v_add_f32_e32 v220, 1.0, v220
	v_rcp_f32_e32 v224, v222
	v_add_f32_e32 v222, 1.0, v232
	v_rcp_f32_e32 v172, v172
	v_rcp_f32_e32 v212, v212
	v_rcp_f32_e32 v220, v220
	v_rcp_f32_e32 v232, v222
	v_cvt_pk_bf16_f32 v223, v223, v224
	v_cvt_pk_bf16_f32 v224, v212, v225
	v_cvt_pk_bf16_f32 v222, v172, v220
	v_cvt_pk_bf16_f32 v225, v233, v232
	global_store_dwordx4 v[230:231], v[222:225], off offset:256
	v_mul_f32_e32 v212, 0xbfb8aa3b, v32
	v_mul_f32_e32 v232, 0xbfb8aa3b, v35
	v_mul_f32_e32 v222, 0xbfb8aa3b, v33
	v_exp_f32_e32 v222, v222
	v_mul_f32_e32 v223, 0xbfb8aa3b, v38
; __device__ __forceinline__ float fsigmoid(float v) { return __builtin_amdgcn_rcpf(1.0f + __builtin_amdgcn_exp2f(-LOG2E * v)); }
; __device__ __forceinline__ float fsilu(float v) { return v * fsigmoid(v); }
; __device__ __forceinline__ u32x4 pack8(const f32x4 a, const f32x4 b) { u32x4 w; w.x = cvt_pk_bf16(a[0], a[1]); w.y = cvt_pk_bf16(a[2], a[3]); w.z = cvt_pk_bf16(b[0], b[1]); w.w = cvt_pk_bf16(b[2], b[3]); return w; }
;     template <int ACT> __device__ __forceinline__ void ew(const f32x4 (&acc)[2][2][4][2], bf16_t* D, int ld, int row0, int col0) const {
; #pragma unroll
;         for (int ai = 0; ai < 2; ++ai)
; #pragma unroll
;             for (int m = 0; m < 4; ++m) { bf16_t* rowp = D + (size_t)(row0 + ai * HALF + m * 16) * ld + col0;
; #pragma unroll
;                 for (int bj = 0; bj < 2; ++bj) { f32x4 v0 = acc[ai][bj][m][0], v1 = acc[ai][bj][m][1];
;                     if (ACT == 1) {
; #pragma unroll
;                         for (int j = 0; j < 4; ++j) { v0[j] = fsilu(v0[j]); v1[j] = fsilu(v1[j]); } }
;                     if (ACT == 2) {
; #pragma unroll
;                         for (int j = 0; j < 4; ++j) { v0[j] = fsigmoid(v0[j]); v1[j] = fsigmoid(v1[j]); } }
;                     *(u32x4*)(rowp + bj * HALF) = pack8(v0, v1); } }
;     }
	v_exp_f32_e32 v223, v223
	v_mul_f32_e32 v224, 0xbfb8aa3b, v34
	v_exp_f32_e32 v224, v224
	v_add_f32_e32 v222, 1.0, v222
	v_rcp_f32_e32 v225, v222
	v_add_f32_e32 v222, 1.0, v223
	v_rcp_f32_e32 v223, v222
	v_add_f32_e32 v222, 1.0, v224
	v_mul_f32_e32 v224, 0xbfb8aa3b, v39
	v_exp_f32_e32 v224, v224
	v_mul_f32_e32 v172, 0xbfb8aa3b, v36
	v_exp_f32_e32 v212, v212
	v_mul_f32_e32 v220, 0xbfb8aa3b, v37
	v_exp_f32_e32 v232, v232
	v_exp_f32_e32 v172, v172
	v_exp_f32_e32 v220, v220
	v_rcp_f32_e32 v233, v222
	v_add_f32_e32 v222, 1.0, v224
	v_add_f32_e32 v212, 1.0, v212
	v_rcp_f32_e32 v224, v222
	v_add_f32_e32 v222, 1.0, v232
	v_add_f32_e32 v172, 1.0, v172
	v_rcp_f32_e32 v212, v212
	v_add_f32_e32 v220, 1.0, v220
	v_rcp_f32_e32 v232, v222
	v_rcp_f32_e32 v172, v172
	v_rcp_f32_e32 v220, v220
	v_cvt_pk_bf16_f32 v223, v223, v224
	v_cvt_pk_bf16_f32 v224, v212, v225
	v_cvt_pk_bf16_f32 v225, v233, v232
	v_add_co_u32_e32 v232, vcc, s49, v194
	v_cvt_pk_bf16_f32 v222, v172, v220
	s_nop 0
	v_addc_co_u32_e32 v233, vcc, 0, v195, vcc
	global_store_dwordx4 v[232:233], v[222:225], off
	v_mul_f32_e32 v172, 0xbfb8aa3b, v12
	v_mul_f32_e32 v212, 0xbfb8aa3b, v8
	v_mul_f32_e32 v222, 0xbfb8aa3b, v9
	v_exp_f32_e32 v222, v222
	v_mul_f32_e32 v223, 0xbfb8aa3b, v14
	v_exp_f32_e32 v223, v223
	v_mul_f32_e32 v224, 0xbfb8aa3b, v10
	v_exp_f32_e32 v224, v224
	v_add_f32_e32 v222, 1.0, v222
	v_rcp_f32_e32 v225, v222
	v_add_f32_e32 v222, 1.0, v223
	v_rcp_f32_e32 v223, v222
	v_add_f32_e32 v222, 1.0, v224
	v_mul_f32_e32 v224, 0xbfb8aa3b, v15
	v_mul_f32_e32 v220, 0xbfb8aa3b, v13
	v_exp_f32_e32 v224, v224
	v_mul_f32_e32 v232, 0xbfb8aa3b, v11
	v_exp_f32_e32 v172, v172
	v_exp_f32_e32 v212, v212
	v_exp_f32_e32 v220, v220
	v_exp_f32_e32 v232, v232
	v_rcp_f32_e32 v233, v222
	v_add_f32_e32 v222, 1.0, v224
	v_add_f32_e32 v172, 1.0, v172
	v_add_f32_e32 v212, 1.0, v212
	v_add_f32_e32 v220, 1.0, v220
	v_rcp_f32_e32 v224, v222
	v_add_f32_e32 v222, 1.0, v232
	v_rcp_f32_e32 v172, v172
	v_rcp_f32_e32 v212, v212
	v_rcp_f32_e32 v220, v220
	v_rcp_f32_e32 v232, v222
	s_mov_b64 s[38:39], 0xa0000
	v_lshl_add_u64 v[230:231], v[194:195], 0, s[38:39]
	v_cvt_pk_bf16_f32 v222, v172, v220
	v_cvt_pk_bf16_f32 v223, v223, v224
	v_cvt_pk_bf16_f32 v224, v212, v225
	v_cvt_pk_bf16_f32 v225, v233, v232
	global_store_dwordx4 v[230:231], v[222:225], off offset:256
	v_mul_f32_e32 v212, 0xbfb8aa3b, v16
	v_exp_f32_e32 v212, v212
	v_mul_f32_e32 v222, 0xbfb8aa3b, v17
	v_exp_f32_e32 v222, v222
	v_mul_f32_e32 v223, 0xbfb8aa3b, v22
	v_exp_f32_e32 v223, v223
	v_mul_f32_e32 v224, 0xbfb8aa3b, v18
	v_exp_f32_e32 v224, v224
	v_add_f32_e32 v222, 1.0, v222
	v_rcp_f32_e32 v225, v222
	v_add_f32_e32 v222, 1.0, v223
	v_rcp_f32_e32 v223, v222
	v_add_f32_e32 v222, 1.0, v224
	v_mul_f32_e32 v224, 0xbfb8aa3b, v23
	v_exp_f32_e32 v224, v224
	v_mul_f32_e32 v172, 0xbfb8aa3b, v20
	v_mul_f32_e32 v220, 0xbfb8aa3b, v21
	v_mul_f32_e32 v232, 0xbfb8aa3b, v19
	v_exp_f32_e32 v172, v172
	v_exp_f32_e32 v220, v220
	v_exp_f32_e32 v232, v232
	v_add_f32_e32 v212, 1.0, v212
	v_rcp_f32_e32 v233, v222
	v_add_f32_e32 v222, 1.0, v224
	v_rcp_f32_e32 v212, v212
	v_rcp_f32_e32 v224, v222
	v_add_f32_e32 v172, 1.0, v172
	v_add_f32_e32 v220, 1.0, v220
	v_add_f32_e32 v222, 1.0, v232
	v_rcp_f32_e32 v172, v172
	v_rcp_f32_e32 v220, v220
	v_rcp_f32_e32 v232, v222
	v_cvt_pk_bf16_f32 v223, v223, v224
	v_cvt_pk_bf16_f32 v224, v212, v225
	v_mul_f32_e32 v212, 0xbfb8aa3b, v0
	v_lshl_add_u64 v[230:231], v[194:195], 0, s[62:63]
	v_add_co_u32_e32 v194, vcc, s50, v194
	v_exp_f32_e32 v212, v212
	v_cvt_pk_bf16_f32 v222, v172, v220
	v_cvt_pk_bf16_f32 v225, v233, v232
	v_addc_co_u32_e32 v195, vcc, 0, v195, vcc
	global_store_dwordx4 v[194:195], v[222:225], off
	v_mul_f32_e32 v172, 0xbfb8aa3b, v4
	v_add_f32_e32 v194, 1.0, v212
	v_mul_f32_e32 v222, 0xbfb8aa3b, v2
	v_exp_f32_e32 v222, v222
	v_mul_f32_e32 v223, 0xbfb8aa3b, v7
	v_mul_f32_e32 v195, 0xbfb8aa3b, v5
	v_mul_f32_e32 v212, 0xbfb8aa3b, v1
	v_mul_f32_e32 v220, 0xbfb8aa3b, v6
	v_exp_f32_e32 v223, v223
	v_mul_f32_e32 v224, 0xbfb8aa3b, v3
	v_exp_f32_e32 v172, v172
	v_exp_f32_e32 v195, v195
	v_exp_f32_e32 v212, v212
	v_exp_f32_e32 v220, v220
	v_exp_f32_e32 v224, v224
	v_add_f32_e32 v222, 1.0, v222
	v_rcp_f32_e32 v225, v222
	v_add_f32_e32 v222, 1.0, v223
	v_add_f32_e32 v172, 1.0, v172
	v_add_f32_e32 v195, 1.0, v195
	v_add_f32_e32 v212, 1.0, v212
	v_add_f32_e32 v220, 1.0, v220
	v_rcp_f32_e32 v223, v222
	v_add_f32_e32 v222, 1.0, v224
	v_rcp_f32_e32 v172, v172
	v_rcp_f32_e32 v194, v194
	v_rcp_f32_e32 v195, v195
	v_rcp_f32_e32 v212, v212
	v_rcp_f32_e32 v220, v220
	v_rcp_f32_e32 v232, v222
	v_cvt_pk_bf16_f32 v222, v172, v195
	v_cvt_pk_bf16_f32 v224, v194, v212
	v_cvt_pk_bf16_f32 v223, v220, v223
	v_cvt_pk_bf16_f32 v225, v225, v232
	global_store_dwordx4 v[230:231], v[222:225], off offset:256
	s_mov_b64 s[82:83], 0

; #define PG8_STAGE(bufoff, gbase, voff) do { _Pragma("unroll") for (int _i = 0; _i < 2; ++_i) \
;         __builtin_amdgcn_global_load_lds((const unsigned*)((const char*)(gbase) + (voff)[_i]), (PG8_LAS unsigned*)(lds + (bufoff) + ldsw + _i * 8192), 16, 0, 0); } while (0)
; #define PG8_LDA(dst, b, h) do { _Pragma("unroll") for (int m = 0; m < 4; ++m) _Pragma("unroll") for (int k = 0; k < 2; ++k) dst[m][k] = *(const PG8_LAS bf16x8*)(lds + PG8_SA(b, h) + aoff + m * 2048 + k * 1024); } while (0)
; #define PG8_LDB(dst, b, h) do { _Pragma("unroll") for (int n = 0; n < 2; ++n) _Pragma("unroll") for (int k = 0; k < 2; ++k) dst[n][k] = *(const PG8_LAS bf16x8*)(lds + PG8_SB(b, h) + boff + n * 2048 + k * 1024); } while (0)
; #define PG8_WAIT_V(n) asm volatile("s_waitcnt vmcnt(" #n ")" ::: "memory")
; #define PG8_WAIT_L(n) asm volatile("s_waitcnt lgkmcnt(" #n ")" ::: "memory")
; #define PG8_BAR __builtin_amdgcn_s_barrier()
; #define PG8_SCHED __builtin_amdgcn_sched_barrier(0)
; template <class Epi, class Sched, bool ALIGN_EPI = false, bool SP2 = false>
; __device__ __forceinline__ void gemm_phase(PG8_LAS unsigned char* lds, const Gemm g, const Sched& S, const Epi& E) {
;     ...
;         const bool has_next = S.next(ui + 1, nxt);
;         const char* nA = has_next ? (const char*)g.A + (size_t)nxt.pm * tstep : cA; const char* nB = has_next ? (const char*)g.Bt + (size_t)nxt.pn * tstep : cB;
;         for (int t = 0; t < nt; t += 2) {
;             const bool last = (t == nt - 2);
;             const char* a1 = cA + (size_t)(t + 1) * kstep;
;             const char* a2 = last ? nA : cA + (size_t)(t + 2) * kstep; const char* b2 = last ? nB : cB + (size_t)(t + 2) * kstep;
;             const char* a3 = a2 + kstep; const char* b3 = b2 + kstep;
;             if (last && has_next) S.a_ready(nxt);
;             if constexpr (SP2) {
;             PG8_LDB(B0, 0, 0); PG8_LDB(B1, 0, 1); PG8_SCHED; PG8_LDA(At, 0, 0); PG8_STAGE(PG8_SA(1, 1), a1 + hstep, voffA);
;             PG8_WAIT_V(8); PG8_WAIT_L(0); PG8_BAR; PG8_MMA(0, 0, At, B0); PG8_MMA(0, 1, At, B1); PG8_BAR; PG8_SCHED;
;             PG8_LDA(At, 0, 1); PG8_STAGE(PG8_SB(0, 0), b2, voffB); PG8_STAGE(PG8_SB(0, 1), b2 + hstep, voffB); PG8_STAGE(PG8_SA(0, 0), a2, voffA);
;             PG8_WAIT_V(8); PG8_WAIT_L(0); PG8_BAR; PG8_MMA(1, 0, At, B0); PG8_MMA(1, 1, At, B1); PG8_BAR; PG8_SCHED;
.LBB0_734:
	s_ashr_i32 s39, s38, 31
	v_cmp_lt_i64_e32 vcc, s[40:41], v[140:141]
	s_lshl_b64 s[40:41], s[38:39], 19
	s_add_u32 s40, s9, s40
	s_addc_u32 s41, s22, s41
	s_and_b64 s[42:43], vcc, exec
	s_cselect_b32 s39, s41, s47
	s_cselect_b32 s65, s40, s46
	s_ashr_i32 s37, s36, 31
	s_lshl_b64 s[42:43], s[36:37], 19
	s_add_u32 s42, s23, s42
	s_addc_u32 s43, s52, s43
	s_and_b64 s[50:51], vcc, exec
	s_cselect_b32 s37, s43, s49
	s_cselect_b32 s66, s42, s48
	s_add_u32 s46, s46, 0x40080
	s_addc_u32 s47, s47, 0
	s_add_u32 s67, s48, 0x100
	s_addc_u32 s68, s49, 0
	s_mov_b32 s69, -2
	ds_read_b128 v[144:147], v155
	ds_read_b128 v[148:151], v155 offset:1024
	ds_read_b128 v[158:161], v155 offset:2048
	ds_read_b128 v[162:165], v155 offset:3072
	ds_read_b128 v[166:169], v156
	ds_read_b128 v[170:173], v156 offset:1024
	ds_read_b128 v[174:177], v156 offset:2048
	ds_read_b128 v[178:181], v156 offset:3072
	s_add_u32 s48, s46, 0xfffc0080
	s_addc_u32 s49, s47, -1
	s_cmp_eq_u32 s69, 12
	s_cselect_b32 s51, s39, s49
	s_cselect_b32 s50, s65, s48
	s_cselect_b32 s49, s37, s68
	s_cselect_b32 s48, s66, s67
	s_add_i32 m0, s45, 0xc000
	ds_read_b128 v[182:185], v157
	ds_read_b128 v[186:189], v157 offset:1024
	ds_read_b128 v[190:193], v157 offset:2048
	ds_read_b128 v[194:197], v157 offset:3072
	ds_read_b128 v[198:201], v157 offset:4096
	ds_read_b128 v[202:205], v157 offset:5120
	ds_read_b128 v[206:209], v157 offset:6144
	ds_read_b128 v[214:217], v157 offset:7168
	global_load_lds_dwordx4 v136, s[46:47]
	s_add_i32 m0, s45, 0xe000
	s_nop 0
	global_load_lds_dwordx4 v138, s[46:47]
	s_waitcnt vmcnt(8)
	s_waitcnt lgkmcnt(0)
	s_barrier
	s_waitcnt lgkmcnt(0)
	v_mfma_f32_16x16x32_bf16 v[124:127], v[144:147], v[182:185], 0
	v_mfma_f32_16x16x32_bf16 v[120:123], v[158:161], v[182:185], 0
	v_mfma_f32_16x16x32_bf16 v[116:119], v[144:147], v[190:193], 0
	v_mfma_f32_16x16x32_bf16 v[112:115], v[158:161], v[190:193], 0
	v_mfma_f32_16x16x32_bf16 v[96:99], v[144:147], v[198:201], 0
	v_mfma_f32_16x16x32_bf16 v[88:91], v[158:161], v[198:201], 0
	v_mfma_f32_16x16x32_bf16 v[80:83], v[144:147], v[206:209], 0
	v_mfma_f32_16x16x32_bf16 v[72:75], v[158:161], v[206:209], 0
	v_mfma_f32_16x16x32_bf16 v[124:127], v[148:151], v[186:189], v[124:127]
	v_mfma_f32_16x16x32_bf16 v[120:123], v[162:165], v[186:189], v[120:123]
	v_mfma_f32_16x16x32_bf16 v[116:119], v[148:151], v[194:197], v[116:119]
	v_mfma_f32_16x16x32_bf16 v[112:115], v[162:165], v[194:197], v[112:115]
	v_mfma_f32_16x16x32_bf16 v[96:99], v[148:151], v[202:205], v[96:99]
	v_mfma_f32_16x16x32_bf16 v[88:91], v[162:165], v[202:205], v[88:91]
	v_mfma_f32_16x16x32_bf16 v[80:83], v[148:151], v[214:217], v[80:83]
	v_mfma_f32_16x16x32_bf16 v[72:75], v[162:165], v[214:217], v[72:75]
	v_mfma_f32_16x16x32_bf16 v[108:111], v[166:169], v[182:185], 0
	v_mfma_f32_16x16x32_bf16 v[104:107], v[174:177], v[182:185], 0
	v_mfma_f32_16x16x32_bf16 v[100:103], v[166:169], v[190:193], 0
	v_mfma_f32_16x16x32_bf16 v[92:95], v[174:177], v[190:193], 0
	v_mfma_f32_16x16x32_bf16 v[84:87], v[166:169], v[198:201], 0
	v_mfma_f32_16x16x32_bf16 v[76:79], v[174:177], v[198:201], 0
	v_mfma_f32_16x16x32_bf16 v[68:71], v[166:169], v[206:209], 0
	v_mfma_f32_16x16x32_bf16 v[64:67], v[174:177], v[206:209], 0
	v_mfma_f32_16x16x32_bf16 v[108:111], v[170:173], v[186:189], v[108:111]
	v_mfma_f32_16x16x32_bf16 v[104:107], v[178:181], v[186:189], v[104:107]
	v_mfma_f32_16x16x32_bf16 v[100:103], v[170:173], v[194:197], v[100:103]
	v_mfma_f32_16x16x32_bf16 v[92:95], v[178:181], v[194:197], v[92:95]
	v_mfma_f32_16x16x32_bf16 v[84:87], v[170:173], v[202:205], v[84:87]
	v_mfma_f32_16x16x32_bf16 v[76:79], v[178:181], v[202:205], v[76:79]
	v_mfma_f32_16x16x32_bf16 v[68:71], v[170:173], v[214:217], v[68:71]
	v_mfma_f32_16x16x32_bf16 v[64:67], v[178:181], v[214:217], v[64:67]
	s_barrier
	s_add_i32 s70, s62, s53
	s_mov_b32 m0, s70
	ds_read_b128 v[182:185], v157 offset:16384
	ds_read_b128 v[186:189], v157 offset:17408
	ds_read_b128 v[190:193], v157 offset:18432
	ds_read_b128 v[194:197], v157 offset:19456
	ds_read_b128 v[198:201], v157 offset:20480
	ds_read_b128 v[202:205], v157 offset:21504
	ds_read_b128 v[206:209], v157 offset:22528
	ds_read_b128 v[214:217], v157 offset:23552
	global_load_lds_dwordx4 v130, s[48:49]
	s_add_i32 m0, s70, 0x2000
	s_add_u32 s70, s48, 0x40000
	s_addc_u32 s71, s49, 0
	s_add_i32 s72, s63, s53
	global_load_lds_dwordx4 v134, s[48:49]
	s_mov_b32 m0, s72
	s_nop 0
	global_load_lds_dwordx4 v130, s[70:71]
	s_add_i32 m0, s72, 0x2000
	s_nop 0
	global_load_lds_dwordx4 v134, s[70:71]
	s_mov_b32 m0, s45
	s_nop 0
	global_load_lds_dwordx4 v128, s[50:51]
	s_mov_b32 m0, s54
	s_nop 0
	global_load_lds_dwordx4 v132, s[50:51]
	s_waitcnt vmcnt(8)
	s_waitcnt lgkmcnt(0)
	s_barrier
; #define PG8_STAGE(bufoff, gbase, voff) do { _Pragma("unroll") for (int _i = 0; _i < 2; ++_i) \
;         __builtin_amdgcn_global_load_lds((const unsigned*)((const char*)(gbase) + (voff)[_i]), (PG8_LAS unsigned*)(lds + (bufoff) + ldsw + _i * 8192), 16, 0, 0); } while (0)
; #define PG8_LDA(dst, b, h) do { _Pragma("unroll") for (int m = 0; m < 4; ++m) _Pragma("unroll") for (int k = 0; k < 2; ++k) dst[m][k] = *(const PG8_LAS bf16x8*)(lds + PG8_SA(b, h) + aoff + m * 2048 + k * 1024); } while (0)
; #define PG8_LDB(dst, b, h) do { _Pragma("unroll") for (int n = 0; n < 2; ++n) _Pragma("unroll") for (int k = 0; k < 2; ++k) dst[n][k] = *(const PG8_LAS bf16x8*)(lds + PG8_SB(b, h) + boff + n * 2048 + k * 1024); } while (0)
; #define PG8_MMA(ai, bj, At, Bt) do { __builtin_amdgcn_s_setprio(1); _Pragma("unroll") for (int m = 0; m < 4; ++m) _Pragma("unroll") for (int n = 0; n < 2; ++n) _Pragma("unroll") for (int k = 0; k < 2; ++k) \
;         acc[ai][bj][m][n] = __builtin_amdgcn_mfma_f32_16x16x32_bf16(Bt[n][k], At[m][k], acc[ai][bj][m][n], 0, 0, 0); __builtin_amdgcn_s_setprio(0); } while (0)
; #define PG8_WAIT_V(n) asm volatile("s_waitcnt vmcnt(" #n ")" ::: "memory")
; #define PG8_WAIT_L(n) asm volatile("s_waitcnt lgkmcnt(" #n ")" ::: "memory")
; #define PG8_BAR __builtin_amdgcn_s_barrier()
; #define PG8_SCHED __builtin_amdgcn_sched_barrier(0)
; template <class Epi, class Sched, bool ALIGN_EPI = false, bool SP2 = false>
; __device__ __forceinline__ void gemm_phase(PG8_LAS unsigned char* lds, const Gemm g, const Sched& S, const Epi& E) {
;     ...
;             PG8_WAIT_V(8); PG8_WAIT_L(0); PG8_BAR; PG8_MMA(1, 0, At, B0); PG8_MMA(1, 1, At, B1); PG8_BAR; PG8_SCHED;
;             PG8_LDB(B0, 1, 0); PG8_LDB(B1, 1, 1); PG8_SCHED; PG8_LDA(At, 1, 0); PG8_STAGE(PG8_SA(0, 1), a2 + hstep, voffA);
;             PG8_WAIT_V(8); PG8_WAIT_L(0); PG8_BAR; PG8_MMA(0, 0, At, B0); PG8_MMA(0, 1, At, B1); PG8_BAR; PG8_SCHED;
	s_waitcnt lgkmcnt(0)
	v_mfma_f32_16x16x32_bf16 v[60:63], v[144:147], v[182:185], 0
	v_mfma_f32_16x16x32_bf16 v[56:59], v[158:161], v[182:185], 0
	v_mfma_f32_16x16x32_bf16 v[48:51], v[144:147], v[190:193], 0
	v_mfma_f32_16x16x32_bf16 v[40:43], v[158:161], v[190:193], 0
	v_mfma_f32_16x16x32_bf16 v[32:35], v[144:147], v[198:201], 0
	v_mfma_f32_16x16x32_bf16 v[24:27], v[158:161], v[198:201], 0
	v_mfma_f32_16x16x32_bf16 v[16:19], v[144:147], v[206:209], 0
	v_mfma_f32_16x16x32_bf16 v[8:11], v[158:161], v[206:209], 0
	v_mfma_f32_16x16x32_bf16 v[60:63], v[148:151], v[186:189], v[60:63]
	v_mfma_f32_16x16x32_bf16 v[56:59], v[162:165], v[186:189], v[56:59]
	v_mfma_f32_16x16x32_bf16 v[48:51], v[148:151], v[194:197], v[48:51]
	v_mfma_f32_16x16x32_bf16 v[40:43], v[162:165], v[194:197], v[40:43]
	v_mfma_f32_16x16x32_bf16 v[32:35], v[148:151], v[202:205], v[32:35]
	v_mfma_f32_16x16x32_bf16 v[24:27], v[162:165], v[202:205], v[24:27]
	v_mfma_f32_16x16x32_bf16 v[16:19], v[148:151], v[214:217], v[16:19]
	v_mfma_f32_16x16x32_bf16 v[8:11], v[162:165], v[214:217], v[8:11]
	v_mfma_f32_16x16x32_bf16 v[52:55], v[166:169], v[182:185], 0
	v_mfma_f32_16x16x32_bf16 v[44:47], v[174:177], v[182:185], 0
	v_mfma_f32_16x16x32_bf16 v[36:39], v[166:169], v[190:193], 0
	v_mfma_f32_16x16x32_bf16 v[28:31], v[174:177], v[190:193], 0
	v_mfma_f32_16x16x32_bf16 v[20:23], v[166:169], v[198:201], 0
	v_mfma_f32_16x16x32_bf16 v[12:15], v[174:177], v[198:201], 0
	v_mfma_f32_16x16x32_bf16 v[4:7], v[166:169], v[206:209], 0
	v_mfma_f32_16x16x32_bf16 v[0:3], v[174:177], v[206:209], 0
	v_mfma_f32_16x16x32_bf16 v[52:55], v[170:173], v[186:189], v[52:55]
	v_mfma_f32_16x16x32_bf16 v[44:47], v[178:181], v[186:189], v[44:47]
	v_mfma_f32_16x16x32_bf16 v[36:39], v[170:173], v[194:197], v[36:39]
	v_mfma_f32_16x16x32_bf16 v[28:31], v[178:181], v[194:197], v[28:31]
	v_mfma_f32_16x16x32_bf16 v[20:23], v[170:173], v[202:205], v[20:23]
	v_mfma_f32_16x16x32_bf16 v[12:15], v[178:181], v[202:205], v[12:15]
	v_mfma_f32_16x16x32_bf16 v[4:7], v[170:173], v[214:217], v[4:7]
	v_mfma_f32_16x16x32_bf16 v[0:3], v[178:181], v[214:217], v[0:3]
	s_barrier
	s_add_i32 s70, 0, 0x18000
	s_add_i32 s71, 0, 0x1c000
	v_add_u32_e32 v162, s70, v153
	v_add_u32_e32 v178, s71, v153
	ds_read_b128 v[144:147], v162
	ds_read_b128 v[148:151], v162 offset:1024
	ds_read_b128 v[158:161], v162 offset:2048
	ds_read_b128 v[162:165], v162 offset:3072
	ds_read_b128 v[166:169], v178
	ds_read_b128 v[170:173], v178 offset:1024
	ds_read_b128 v[174:177], v178 offset:2048
	ds_read_b128 v[178:181], v178 offset:3072
	s_add_u32 s80, s50, 0x80
	s_addc_u32 s81, s51, 0
	s_add_u32 s50, s50, 0x40000
	s_addc_u32 s51, s51, 0
	s_mov_b32 m0, s55
	ds_read_b128 v[182:185], v157 offset:32768
	ds_read_b128 v[186:189], v157 offset:33792
	ds_read_b128 v[190:193], v157 offset:34816
	ds_read_b128 v[194:197], v157 offset:35840
	ds_read_b128 v[198:201], v157 offset:36864
	ds_read_b128 v[202:205], v157 offset:37888
	ds_read_b128 v[206:209], v157 offset:38912
	ds_read_b128 v[214:217], v157 offset:39936
	global_load_lds_dwordx4 v128, s[50:51]
	s_mov_b32 m0, s56
	s_nop 0
	global_load_lds_dwordx4 v132, s[50:51]
	s_waitcnt vmcnt(8)
	s_waitcnt lgkmcnt(0)
	s_barrier
	s_waitcnt lgkmcnt(0)
	v_mfma_f32_16x16x32_bf16 v[124:127], v[144:147], v[182:185], v[124:127]
	v_mfma_f32_16x16x32_bf16 v[120:123], v[158:161], v[182:185], v[120:123]
	v_mfma_f32_16x16x32_bf16 v[116:119], v[144:147], v[190:193], v[116:119]
	v_mfma_f32_16x16x32_bf16 v[112:115], v[158:161], v[190:193], v[112:115]
	v_mfma_f32_16x16x32_bf16 v[96:99], v[144:147], v[198:201], v[96:99]
	v_mfma_f32_16x16x32_bf16 v[88:91], v[158:161], v[198:201], v[88:91]
	v_mfma_f32_16x16x32_bf16 v[80:83], v[144:147], v[206:209], v[80:83]
	v_mfma_f32_16x16x32_bf16 v[72:75], v[158:161], v[206:209], v[72:75]
	v_mfma_f32_16x16x32_bf16 v[124:127], v[148:151], v[186:189], v[124:127]
	v_mfma_f32_16x16x32_bf16 v[120:123], v[162:165], v[186:189], v[120:123]
	v_mfma_f32_16x16x32_bf16 v[116:119], v[148:151], v[194:197], v[116:119]
	v_mfma_f32_16x16x32_bf16 v[112:115], v[162:165], v[194:197], v[112:115]
	v_mfma_f32_16x16x32_bf16 v[96:99], v[148:151], v[202:205], v[96:99]
	v_mfma_f32_16x16x32_bf16 v[88:91], v[162:165], v[202:205], v[88:91]
	v_mfma_f32_16x16x32_bf16 v[80:83], v[148:151], v[214:217], v[80:83]
	v_mfma_f32_16x16x32_bf16 v[72:75], v[162:165], v[214:217], v[72:75]
	v_mfma_f32_16x16x32_bf16 v[108:111], v[166:169], v[182:185], v[108:111]
	v_mfma_f32_16x16x32_bf16 v[104:107], v[174:177], v[182:185], v[104:107]
	v_mfma_f32_16x16x32_bf16 v[100:103], v[166:169], v[190:193], v[100:103]
	v_mfma_f32_16x16x32_bf16 v[92:95], v[174:177], v[190:193], v[92:95]
	v_mfma_f32_16x16x32_bf16 v[84:87], v[166:169], v[198:201], v[84:87]
	v_mfma_f32_16x16x32_bf16 v[76:79], v[174:177], v[198:201], v[76:79]
	v_mfma_f32_16x16x32_bf16 v[68:71], v[166:169], v[206:209], v[68:71]
	v_mfma_f32_16x16x32_bf16 v[64:67], v[174:177], v[206:209], v[64:67]
	v_mfma_f32_16x16x32_bf16 v[108:111], v[170:173], v[186:189], v[108:111]
	v_mfma_f32_16x16x32_bf16 v[104:107], v[178:181], v[186:189], v[104:107]
	v_mfma_f32_16x16x32_bf16 v[100:103], v[170:173], v[194:197], v[100:103]
	v_mfma_f32_16x16x32_bf16 v[92:95], v[178:181], v[194:197], v[92:95]
	v_mfma_f32_16x16x32_bf16 v[84:87], v[170:173], v[202:205], v[84:87]
	v_mfma_f32_16x16x32_bf16 v[76:79], v[178:181], v[202:205], v[76:79]
	v_mfma_f32_16x16x32_bf16 v[68:71], v[170:173], v[214:217], v[68:71]
	v_mfma_f32_16x16x32_bf16 v[64:67], v[178:181], v[214:217], v[64:67]
	s_barrier
; #define PG8_STAGE(bufoff, gbase, voff) do { _Pragma("unroll") for (int _i = 0; _i < 2; ++_i) \
;         __builtin_amdgcn_global_load_lds((const unsigned*)((const char*)(gbase) + (voff)[_i]), (PG8_LAS unsigned*)(lds + (bufoff) + ldsw + _i * 8192), 16, 0, 0); } while (0)
; #define PG8_LDA(dst, b, h) do { _Pragma("unroll") for (int m = 0; m < 4; ++m) _Pragma("unroll") for (int k = 0; k < 2; ++k) dst[m][k] = *(const PG8_LAS bf16x8*)(lds + PG8_SA(b, h) + aoff + m * 2048 + k * 1024); } while (0)
; #define PG8_LDB(dst, b, h) do { _Pragma("unroll") for (int n = 0; n < 2; ++n) _Pragma("unroll") for (int k = 0; k < 2; ++k) dst[n][k] = *(const PG8_LAS bf16x8*)(lds + PG8_SB(b, h) + boff + n * 2048 + k * 1024); } while (0)
; #define PG8_MMA(ai, bj, At, Bt) do { __builtin_amdgcn_s_setprio(1); _Pragma("unroll") for (int m = 0; m < 4; ++m) _Pragma("unroll") for (int n = 0; n < 2; ++n) _Pragma("unroll") for (int k = 0; k < 2; ++k) \
;         acc[ai][bj][m][n] = __builtin_amdgcn_mfma_f32_16x16x32_bf16(Bt[n][k], At[m][k], acc[ai][bj][m][n], 0, 0, 0); __builtin_amdgcn_s_setprio(0); } while (0)
; #define PG8_WAIT_V(n) asm volatile("s_waitcnt vmcnt(" #n ")" ::: "memory")
; #define PG8_WAIT_L(n) asm volatile("s_waitcnt lgkmcnt(" #n ")" ::: "memory")
; #define PG8_BAR __builtin_amdgcn_s_barrier()
; #define PG8_SCHED __builtin_amdgcn_sched_barrier(0)
; template <class Epi, class Sched, bool ALIGN_EPI = false, bool SP2 = false>
; __device__ __forceinline__ void gemm_phase(PG8_LAS unsigned char* lds, const Gemm g, const Sched& S, const Epi& E) {
;     ...
;             PG8_LDB(B0, 0, 0); PG8_LDB(B1, 0, 1); PG8_SCHED; PG8_LDA(At, 0, 0); PG8_STAGE(PG8_SA(1, 1), a1 + hstep, voffA);
;             PG8_WAIT_V(8); PG8_WAIT_L(0); PG8_BAR; PG8_MMA(0, 0, At, B0); PG8_MMA(0, 1, At, B1); PG8_BAR; PG8_SCHED;
;     ...
;             PG8_LDA(At, 1, 1); PG8_STAGE(PG8_SB(1, 0), b3, voffB); PG8_STAGE(PG8_SB(1, 1), b3 + hstep, voffB); PG8_STAGE(PG8_SA(1, 0), a3, voffA);
;             PG8_WAIT_V(8); PG8_WAIT_L(0); PG8_BAR; PG8_MMA(1, 0, At, B0); PG8_MMA(1, 1, At, B1); PG8_BAR; PG8_SCHED;
	s_add_i32 s50, s70, s53
	s_add_u32 s82, s48, 0x80
	s_addc_u32 s83, s49, 0
	s_mov_b32 m0, s50
	ds_read_b128 v[182:185], v157 offset:49152
	ds_read_b128 v[186:189], v157 offset:50176
	ds_read_b128 v[190:193], v157 offset:51200
	ds_read_b128 v[194:197], v157 offset:52224
	ds_read_b128 v[198:201], v157 offset:53248
	ds_read_b128 v[202:205], v157 offset:54272
	ds_read_b128 v[206:209], v157 offset:55296
	ds_read_b128 v[214:217], v157 offset:56320
	global_load_lds_dwordx4 v130, s[82:83]
	s_add_i32 m0, s50, 0x2000
	s_add_u32 s48, s48, 0x40080
	s_addc_u32 s49, s49, 0
	s_add_i32 s50, s71, s53
	global_load_lds_dwordx4 v134, s[82:83]
	s_mov_b32 m0, s50
	s_nop 0
	global_load_lds_dwordx4 v130, s[48:49]
	s_add_i32 m0, s50, 0x2000
	s_nop 0
	global_load_lds_dwordx4 v134, s[48:49]
	s_mov_b32 m0, s58
	s_nop 0
	global_load_lds_dwordx4 v128, s[80:81]
	s_mov_b32 m0, s59
	s_nop 0
	global_load_lds_dwordx4 v132, s[80:81]
	s_waitcnt vmcnt(8)
	s_waitcnt lgkmcnt(0)
	s_barrier
	s_waitcnt lgkmcnt(0)
	v_mfma_f32_16x16x32_bf16 v[60:63], v[144:147], v[182:185], v[60:63]
	v_mfma_f32_16x16x32_bf16 v[56:59], v[158:161], v[182:185], v[56:59]
	v_mfma_f32_16x16x32_bf16 v[48:51], v[144:147], v[190:193], v[48:51]
	v_mfma_f32_16x16x32_bf16 v[40:43], v[158:161], v[190:193], v[40:43]
	v_mfma_f32_16x16x32_bf16 v[32:35], v[144:147], v[198:201], v[32:35]
	v_mfma_f32_16x16x32_bf16 v[24:27], v[158:161], v[198:201], v[24:27]
	v_mfma_f32_16x16x32_bf16 v[16:19], v[144:147], v[206:209], v[16:19]
	v_mfma_f32_16x16x32_bf16 v[8:11], v[158:161], v[206:209], v[8:11]
	v_mfma_f32_16x16x32_bf16 v[60:63], v[148:151], v[186:189], v[60:63]
	v_mfma_f32_16x16x32_bf16 v[56:59], v[162:165], v[186:189], v[56:59]
	v_mfma_f32_16x16x32_bf16 v[48:51], v[148:151], v[194:197], v[48:51]
	v_mfma_f32_16x16x32_bf16 v[40:43], v[162:165], v[194:197], v[40:43]
	v_mfma_f32_16x16x32_bf16 v[32:35], v[148:151], v[202:205], v[32:35]
	v_mfma_f32_16x16x32_bf16 v[24:27], v[162:165], v[202:205], v[24:27]
	v_mfma_f32_16x16x32_bf16 v[16:19], v[148:151], v[214:217], v[16:19]
	v_mfma_f32_16x16x32_bf16 v[8:11], v[162:165], v[214:217], v[8:11]
	v_mfma_f32_16x16x32_bf16 v[52:55], v[166:169], v[182:185], v[52:55]
	v_mfma_f32_16x16x32_bf16 v[44:47], v[174:177], v[182:185], v[44:47]
	v_mfma_f32_16x16x32_bf16 v[36:39], v[166:169], v[190:193], v[36:39]
	v_mfma_f32_16x16x32_bf16 v[28:31], v[174:177], v[190:193], v[28:31]
	v_mfma_f32_16x16x32_bf16 v[20:23], v[166:169], v[198:201], v[20:23]
	v_mfma_f32_16x16x32_bf16 v[12:15], v[174:177], v[198:201], v[12:15]
	v_mfma_f32_16x16x32_bf16 v[4:7], v[166:169], v[206:209], v[4:7]
	v_mfma_f32_16x16x32_bf16 v[0:3], v[174:177], v[206:209], v[0:3]
	v_mfma_f32_16x16x32_bf16 v[52:55], v[170:173], v[186:189], v[52:55]
	v_mfma_f32_16x16x32_bf16 v[44:47], v[178:181], v[186:189], v[44:47]
	v_mfma_f32_16x16x32_bf16 v[36:39], v[170:173], v[194:197], v[36:39]
	v_mfma_f32_16x16x32_bf16 v[28:31], v[178:181], v[194:197], v[28:31]
	v_mfma_f32_16x16x32_bf16 v[20:23], v[170:173], v[202:205], v[20:23]
	v_mfma_f32_16x16x32_bf16 v[12:15], v[178:181], v[202:205], v[12:15]
	v_mfma_f32_16x16x32_bf16 v[4:7], v[170:173], v[214:217], v[4:7]
	v_mfma_f32_16x16x32_bf16 v[0:3], v[178:181], v[214:217], v[0:3]
	s_add_i32 s69, s69, 2
	s_add_u32 s46, s46, 0x100
	s_addc_u32 s47, s47, 0
	s_add_u32 s67, s67, 0x100
	s_addc_u32 s68, s68, 0
	s_cmp_gt_u32 s69, 13
	s_barrier
.LBB0_735:
	ds_read_b128 v[144:147], v155
	ds_read_b128 v[148:151], v155 offset:1024
	ds_read_b128 v[158:161], v155 offset:2048
	ds_read_b128 v[162:165], v155 offset:3072
	ds_read_b128 v[166:169], v156
	ds_read_b128 v[170:173], v156 offset:1024
	ds_read_b128 v[174:177], v156 offset:2048
	ds_read_b128 v[178:181], v156 offset:3072
	s_add_u32 s48, s46, 0xfffc0080
	s_addc_u32 s49, s47, -1
	s_cmp_eq_u32 s69, 12
	s_cselect_b32 s51, s39, s49
	s_cselect_b32 s50, s65, s48
	s_cselect_b32 s49, s37, s68
	s_cselect_b32 s48, s66, s67
	s_add_i32 m0, s45, 0xc000
	ds_read_b128 v[182:185], v157
	ds_read_b128 v[186:189], v157 offset:1024
	ds_read_b128 v[190:193], v157 offset:2048
	ds_read_b128 v[194:197], v157 offset:3072
	ds_read_b128 v[198:201], v157 offset:4096
	ds_read_b128 v[202:205], v157 offset:5120
	ds_read_b128 v[206:209], v157 offset:6144
	ds_read_b128 v[214:217], v157 offset:7168
	global_load_lds_dwordx4 v136, s[46:47]
	s_add_i32 m0, s45, 0xe000
	s_nop 0
	global_load_lds_dwordx4 v138, s[46:47]
	s_waitcnt vmcnt(8)
	s_waitcnt lgkmcnt(0)
	s_barrier
	s_waitcnt lgkmcnt(0)
	v_mfma_f32_16x16x32_bf16 v[124:127], v[144:147], v[182:185], v[124:127]
	v_mfma_f32_16x16x32_bf16 v[120:123], v[158:161], v[182:185], v[120:123]
	v_mfma_f32_16x16x32_bf16 v[116:119], v[144:147], v[190:193], v[116:119]
	v_mfma_f32_16x16x32_bf16 v[112:115], v[158:161], v[190:193], v[112:115]
	v_mfma_f32_16x16x32_bf16 v[96:99], v[144:147], v[198:201], v[96:99]
	v_mfma_f32_16x16x32_bf16 v[88:91], v[158:161], v[198:201], v[88:91]
	v_mfma_f32_16x16x32_bf16 v[80:83], v[144:147], v[206:209], v[80:83]
	v_mfma_f32_16x16x32_bf16 v[72:75], v[158:161], v[206:209], v[72:75]
	v_mfma_f32_16x16x32_bf16 v[124:127], v[148:151], v[186:189], v[124:127]
	v_mfma_f32_16x16x32_bf16 v[120:123], v[162:165], v[186:189], v[120:123]
	v_mfma_f32_16x16x32_bf16 v[116:119], v[148:151], v[194:197], v[116:119]
	v_mfma_f32_16x16x32_bf16 v[112:115], v[162:165], v[194:197], v[112:115]
	v_mfma_f32_16x16x32_bf16 v[96:99], v[148:151], v[202:205], v[96:99]
	v_mfma_f32_16x16x32_bf16 v[88:91], v[162:165], v[202:205], v[88:91]
	v_mfma_f32_16x16x32_bf16 v[80:83], v[148:151], v[214:217], v[80:83]
	v_mfma_f32_16x16x32_bf16 v[72:75], v[162:165], v[214:217], v[72:75]
	v_mfma_f32_16x16x32_bf16 v[108:111], v[166:169], v[182:185], v[108:111]
	v_mfma_f32_16x16x32_bf16 v[104:107], v[174:177], v[182:185], v[104:107]
	v_mfma_f32_16x16x32_bf16 v[100:103], v[166:169], v[190:193], v[100:103]
	v_mfma_f32_16x16x32_bf16 v[92:95], v[174:177], v[190:193], v[92:95]
	v_mfma_f32_16x16x32_bf16 v[84:87], v[166:169], v[198:201], v[84:87]
	v_mfma_f32_16x16x32_bf16 v[76:79], v[174:177], v[198:201], v[76:79]
	v_mfma_f32_16x16x32_bf16 v[68:71], v[166:169], v[206:209], v[68:71]
	v_mfma_f32_16x16x32_bf16 v[64:67], v[174:177], v[206:209], v[64:67]
	v_mfma_f32_16x16x32_bf16 v[108:111], v[170:173], v[186:189], v[108:111]
	v_mfma_f32_16x16x32_bf16 v[104:107], v[178:181], v[186:189], v[104:107]
	v_mfma_f32_16x16x32_bf16 v[100:103], v[170:173], v[194:197], v[100:103]
	v_mfma_f32_16x16x32_bf16 v[92:95], v[178:181], v[194:197], v[92:95]
	v_mfma_f32_16x16x32_bf16 v[84:87], v[170:173], v[202:205], v[84:87]
	v_mfma_f32_16x16x32_bf16 v[76:79], v[178:181], v[202:205], v[76:79]
	v_mfma_f32_16x16x32_bf16 v[68:71], v[170:173], v[214:217], v[68:71]
	v_mfma_f32_16x16x32_bf16 v[64:67], v[178:181], v[214:217], v[64:67]
	s_barrier
; #define PG8_STAGE(bufoff, gbase, voff) do { _Pragma("unroll") for (int _i = 0; _i < 2; ++_i) \
;         __builtin_amdgcn_global_load_lds((const unsigned*)((const char*)(gbase) + (voff)[_i]), (PG8_LAS unsigned*)(lds + (bufoff) + ldsw + _i * 8192), 16, 0, 0); } while (0)
; #define PG8_LDA(dst, b, h) do { _Pragma("unroll") for (int m = 0; m < 4; ++m) _Pragma("unroll") for (int k = 0; k < 2; ++k) dst[m][k] = *(const PG8_LAS bf16x8*)(lds + PG8_SA(b, h) + aoff + m * 2048 + k * 1024); } while (0)
; #define PG8_LDB(dst, b, h) do { _Pragma("unroll") for (int n = 0; n < 2; ++n) _Pragma("unroll") for (int k = 0; k < 2; ++k) dst[n][k] = *(const PG8_LAS bf16x8*)(lds + PG8_SB(b, h) + boff + n * 2048 + k * 1024); } while (0)
; #define PG8_MMA(ai, bj, At, Bt) do { __builtin_amdgcn_s_setprio(1); _Pragma("unroll") for (int m = 0; m < 4; ++m) _Pragma("unroll") for (int n = 0; n < 2; ++n) _Pragma("unroll") for (int k = 0; k < 2; ++k) \
;         acc[ai][bj][m][n] = __builtin_amdgcn_mfma_f32_16x16x32_bf16(Bt[n][k], At[m][k], acc[ai][bj][m][n], 0, 0, 0); __builtin_amdgcn_s_setprio(0); } while (0)
; #define PG8_WAIT_V(n) asm volatile("s_waitcnt vmcnt(" #n ")" ::: "memory")
; #define PG8_WAIT_L(n) asm volatile("s_waitcnt lgkmcnt(" #n ")" ::: "memory")
; #define PG8_BAR __builtin_amdgcn_s_barrier()
; #define PG8_SCHED __builtin_amdgcn_sched_barrier(0)
; template <class Epi, class Sched, bool ALIGN_EPI = false, bool SP2 = false>
; __device__ __forceinline__ void gemm_phase(PG8_LAS unsigned char* lds, const Gemm g, const Sched& S, const Epi& E) {
;     ...
;             PG8_LDA(At, 0, 1); PG8_STAGE(PG8_SB(0, 0), b2, voffB); PG8_STAGE(PG8_SB(0, 1), b2 + hstep, voffB); PG8_STAGE(PG8_SA(0, 0), a2, voffA);
;             PG8_WAIT_V(8); PG8_WAIT_L(0); PG8_BAR; PG8_MMA(1, 0, At, B0); PG8_MMA(1, 1, At, B1); PG8_BAR; PG8_SCHED;
;             PG8_LDB(B0, 1, 0); PG8_LDB(B1, 1, 1); PG8_SCHED; PG8_LDA(At, 1, 0); PG8_STAGE(PG8_SA(0, 1), a2 + hstep, voffA);
;             PG8_WAIT_V(8); PG8_WAIT_L(0); PG8_BAR; PG8_MMA(0, 0, At, B0); PG8_MMA(0, 1, At, B1); PG8_BAR; PG8_SCHED;
	s_add_i32 s70, s62, s53
	s_mov_b32 m0, s70
	ds_read_b128 v[182:185], v157 offset:16384
	ds_read_b128 v[186:189], v157 offset:17408
	ds_read_b128 v[190:193], v157 offset:18432
	ds_read_b128 v[194:197], v157 offset:19456
	ds_read_b128 v[198:201], v157 offset:20480
	ds_read_b128 v[202:205], v157 offset:21504
	ds_read_b128 v[206:209], v157 offset:22528
	ds_read_b128 v[214:217], v157 offset:23552
	global_load_lds_dwordx4 v130, s[48:49]
	s_add_i32 m0, s70, 0x2000
	s_add_u32 s70, s48, 0x40000
	s_addc_u32 s71, s49, 0
	s_add_i32 s72, s63, s53
	global_load_lds_dwordx4 v134, s[48:49]
	s_mov_b32 m0, s72
	s_nop 0
	global_load_lds_dwordx4 v130, s[70:71]
	s_add_i32 m0, s72, 0x2000
	s_nop 0
	global_load_lds_dwordx4 v134, s[70:71]
	s_mov_b32 m0, s45
	s_nop 0
	global_load_lds_dwordx4 v128, s[50:51]
	s_mov_b32 m0, s54
	s_nop 0
	global_load_lds_dwordx4 v132, s[50:51]
	s_waitcnt vmcnt(8)
	s_waitcnt lgkmcnt(0)
	s_barrier
	s_waitcnt lgkmcnt(0)
	v_mfma_f32_16x16x32_bf16 v[60:63], v[144:147], v[182:185], v[60:63]
	v_mfma_f32_16x16x32_bf16 v[56:59], v[158:161], v[182:185], v[56:59]
	v_mfma_f32_16x16x32_bf16 v[48:51], v[144:147], v[190:193], v[48:51]
	v_mfma_f32_16x16x32_bf16 v[40:43], v[158:161], v[190:193], v[40:43]
	v_mfma_f32_16x16x32_bf16 v[32:35], v[144:147], v[198:201], v[32:35]
	v_mfma_f32_16x16x32_bf16 v[24:27], v[158:161], v[198:201], v[24:27]
	v_mfma_f32_16x16x32_bf16 v[16:19], v[144:147], v[206:209], v[16:19]
	v_mfma_f32_16x16x32_bf16 v[8:11], v[158:161], v[206:209], v[8:11]
	v_mfma_f32_16x16x32_bf16 v[60:63], v[148:151], v[186:189], v[60:63]
	v_mfma_f32_16x16x32_bf16 v[56:59], v[162:165], v[186:189], v[56:59]
	v_mfma_f32_16x16x32_bf16 v[48:51], v[148:151], v[194:197], v[48:51]
	v_mfma_f32_16x16x32_bf16 v[40:43], v[162:165], v[194:197], v[40:43]
	v_mfma_f32_16x16x32_bf16 v[32:35], v[148:151], v[202:205], v[32:35]
	v_mfma_f32_16x16x32_bf16 v[24:27], v[162:165], v[202:205], v[24:27]
	v_mfma_f32_16x16x32_bf16 v[16:19], v[148:151], v[214:217], v[16:19]
	v_mfma_f32_16x16x32_bf16 v[8:11], v[162:165], v[214:217], v[8:11]
	v_mfma_f32_16x16x32_bf16 v[52:55], v[166:169], v[182:185], v[52:55]
	v_mfma_f32_16x16x32_bf16 v[44:47], v[174:177], v[182:185], v[44:47]
	v_mfma_f32_16x16x32_bf16 v[36:39], v[166:169], v[190:193], v[36:39]
	v_mfma_f32_16x16x32_bf16 v[28:31], v[174:177], v[190:193], v[28:31]
	v_mfma_f32_16x16x32_bf16 v[20:23], v[166:169], v[198:201], v[20:23]
	v_mfma_f32_16x16x32_bf16 v[12:15], v[174:177], v[198:201], v[12:15]
	v_mfma_f32_16x16x32_bf16 v[4:7], v[166:169], v[206:209], v[4:7]
	v_mfma_f32_16x16x32_bf16 v[0:3], v[174:177], v[206:209], v[0:3]
	v_mfma_f32_16x16x32_bf16 v[52:55], v[170:173], v[186:189], v[52:55]
	v_mfma_f32_16x16x32_bf16 v[44:47], v[178:181], v[186:189], v[44:47]
	v_mfma_f32_16x16x32_bf16 v[36:39], v[170:173], v[194:197], v[36:39]
	v_mfma_f32_16x16x32_bf16 v[28:31], v[178:181], v[194:197], v[28:31]
	v_mfma_f32_16x16x32_bf16 v[20:23], v[170:173], v[202:205], v[20:23]
	v_mfma_f32_16x16x32_bf16 v[12:15], v[178:181], v[202:205], v[12:15]
	v_mfma_f32_16x16x32_bf16 v[4:7], v[170:173], v[214:217], v[4:7]
	v_mfma_f32_16x16x32_bf16 v[0:3], v[178:181], v[214:217], v[0:3]
	s_barrier
	s_add_i32 s70, 0, 0x18000
	s_add_i32 s71, 0, 0x1c000
	v_add_u32_e32 v162, s70, v153
	v_add_u32_e32 v178, s71, v153
	ds_read_b128 v[144:147], v162
	ds_read_b128 v[148:151], v162 offset:1024
	ds_read_b128 v[158:161], v162 offset:2048
	ds_read_b128 v[162:165], v162 offset:3072
	ds_read_b128 v[166:169], v178
	ds_read_b128 v[170:173], v178 offset:1024
	ds_read_b128 v[174:177], v178 offset:2048
	ds_read_b128 v[178:181], v178 offset:3072
	s_add_u32 s80, s50, 0x80
	s_addc_u32 s81, s51, 0
	s_add_u32 s50, s50, 0x40000
	s_addc_u32 s51, s51, 0
	s_mov_b32 m0, s55
	ds_read_b128 v[182:185], v157 offset:32768
	ds_read_b128 v[186:189], v157 offset:33792
	ds_read_b128 v[190:193], v157 offset:34816
	ds_read_b128 v[194:197], v157 offset:35840
	ds_read_b128 v[198:201], v157 offset:36864
	ds_read_b128 v[202:205], v157 offset:37888
	ds_read_b128 v[206:209], v157 offset:38912
	ds_read_b128 v[214:217], v157 offset:39936
	global_load_lds_dwordx4 v128, s[50:51]
	s_mov_b32 m0, s56
	s_nop 0
	global_load_lds_dwordx4 v132, s[50:51]
	s_waitcnt vmcnt(8)
	s_waitcnt lgkmcnt(0)
	s_barrier
	s_waitcnt lgkmcnt(0)
	v_mfma_f32_16x16x32_bf16 v[124:127], v[144:147], v[182:185], v[124:127]
	v_mfma_f32_16x16x32_bf16 v[120:123], v[158:161], v[182:185], v[120:123]
	v_mfma_f32_16x16x32_bf16 v[116:119], v[144:147], v[190:193], v[116:119]
	v_mfma_f32_16x16x32_bf16 v[112:115], v[158:161], v[190:193], v[112:115]
	v_mfma_f32_16x16x32_bf16 v[96:99], v[144:147], v[198:201], v[96:99]
	v_mfma_f32_16x16x32_bf16 v[88:91], v[158:161], v[198:201], v[88:91]
	v_mfma_f32_16x16x32_bf16 v[80:83], v[144:147], v[206:209], v[80:83]
	v_mfma_f32_16x16x32_bf16 v[72:75], v[158:161], v[206:209], v[72:75]
	v_mfma_f32_16x16x32_bf16 v[124:127], v[148:151], v[186:189], v[124:127]
	v_mfma_f32_16x16x32_bf16 v[120:123], v[162:165], v[186:189], v[120:123]
	v_mfma_f32_16x16x32_bf16 v[116:119], v[148:151], v[194:197], v[116:119]
	v_mfma_f32_16x16x32_bf16 v[112:115], v[162:165], v[194:197], v[112:115]
	v_mfma_f32_16x16x32_bf16 v[96:99], v[148:151], v[202:205], v[96:99]
	v_mfma_f32_16x16x32_bf16 v[88:91], v[162:165], v[202:205], v[88:91]
	v_mfma_f32_16x16x32_bf16 v[80:83], v[148:151], v[214:217], v[80:83]
	v_mfma_f32_16x16x32_bf16 v[72:75], v[162:165], v[214:217], v[72:75]
	v_mfma_f32_16x16x32_bf16 v[108:111], v[166:169], v[182:185], v[108:111]
	v_mfma_f32_16x16x32_bf16 v[104:107], v[174:177], v[182:185], v[104:107]
	v_mfma_f32_16x16x32_bf16 v[100:103], v[166:169], v[190:193], v[100:103]
	v_mfma_f32_16x16x32_bf16 v[92:95], v[174:177], v[190:193], v[92:95]
	v_mfma_f32_16x16x32_bf16 v[84:87], v[166:169], v[198:201], v[84:87]
	v_mfma_f32_16x16x32_bf16 v[76:79], v[174:177], v[198:201], v[76:79]
	v_mfma_f32_16x16x32_bf16 v[68:71], v[166:169], v[206:209], v[68:71]
	v_mfma_f32_16x16x32_bf16 v[64:67], v[174:177], v[206:209], v[64:67]
	v_mfma_f32_16x16x32_bf16 v[108:111], v[170:173], v[186:189], v[108:111]
	v_mfma_f32_16x16x32_bf16 v[104:107], v[178:181], v[186:189], v[104:107]
	v_mfma_f32_16x16x32_bf16 v[100:103], v[170:173], v[194:197], v[100:103]
	v_mfma_f32_16x16x32_bf16 v[92:95], v[178:181], v[194:197], v[92:95]
	v_mfma_f32_16x16x32_bf16 v[84:87], v[170:173], v[202:205], v[84:87]
	v_mfma_f32_16x16x32_bf16 v[76:79], v[178:181], v[202:205], v[76:79]
	v_mfma_f32_16x16x32_bf16 v[68:71], v[170:173], v[214:217], v[68:71]
	v_mfma_f32_16x16x32_bf16 v[64:67], v[178:181], v[214:217], v[64:67]
	s_barrier
; #define PG8_STAGE(bufoff, gbase, voff) do { _Pragma("unroll") for (int _i = 0; _i < 2; ++_i) \
;         __builtin_amdgcn_global_load_lds((const unsigned*)((const char*)(gbase) + (voff)[_i]), (PG8_LAS unsigned*)(lds + (bufoff) + ldsw + _i * 8192), 16, 0, 0); } while (0)
; #define PG8_LDA(dst, b, h) do { _Pragma("unroll") for (int m = 0; m < 4; ++m) _Pragma("unroll") for (int k = 0; k < 2; ++k) dst[m][k] = *(const PG8_LAS bf16x8*)(lds + PG8_SA(b, h) + aoff + m * 2048 + k * 1024); } while (0)
; #define PG8_MMA(ai, bj, At, Bt) do { __builtin_amdgcn_s_setprio(1); _Pragma("unroll") for (int m = 0; m < 4; ++m) _Pragma("unroll") for (int n = 0; n < 2; ++n) _Pragma("unroll") for (int k = 0; k < 2; ++k) \
;         acc[ai][bj][m][n] = __builtin_amdgcn_mfma_f32_16x16x32_bf16(Bt[n][k], At[m][k], acc[ai][bj][m][n], 0, 0, 0); __builtin_amdgcn_s_setprio(0); } while (0)
; #define PG8_WAIT_V(n) asm volatile("s_waitcnt vmcnt(" #n ")" ::: "memory")
; #define PG8_WAIT_L(n) asm volatile("s_waitcnt lgkmcnt(" #n ")" ::: "memory")
; #define PG8_BAR __builtin_amdgcn_s_barrier()
; #define PG8_SCHED __builtin_amdgcn_sched_barrier(0)
;     __device__ __forceinline__ void operator()(const f32x4 (&acc)[2][2][4][2], const Unit& u, int wr, int wc, int fr, int fq) const {
;     ...
;         for (int ai = 0; ai < 2; ++ai) { u32x4 gw[4][2], pw[4][2];
; #pragma unroll
;             for (int m = 0; m < 4; ++m) { const size_t off = (size_t)(row0 + ai * HALF + m * 16) * 2048 + col0;
; #pragma unroll
;                 for (int bj = 0; bj < 2; ++bj) { gw[m][bj] = *(const u32x4*)(G + off + bj * HALF); if (PASS == 1) pw[m][bj] = *(const u32x4*)(MIX + off + bj * HALF); } }
; template <class Epi, class Sched, bool ALIGN_EPI = false, bool SP2 = false>
; __device__ __forceinline__ void gemm_phase(PG8_LAS unsigned char* lds, const Gemm g, const Sched& S, const Epi& E) {
;     ...
;             PG8_LDA(At, 1, 1); PG8_STAGE(PG8_SB(1, 0), b3, voffB); PG8_STAGE(PG8_SB(1, 1), b3 + hstep, voffB); PG8_STAGE(PG8_SA(1, 0), a3, voffA);
;             PG8_WAIT_V(8); PG8_WAIT_L(0); PG8_BAR; PG8_MMA(1, 0, At, B0); PG8_MMA(1, 1, At, B1); PG8_BAR; PG8_SCHED;
	s_add_i32 s50, s70, s53
	s_add_u32 s82, s48, 0x80
	s_addc_u32 s83, s49, 0
	s_mov_b32 m0, s50
	ds_read_b128 v[182:185], v157 offset:49152
	ds_read_b128 v[186:189], v157 offset:50176
	ds_read_b128 v[190:193], v157 offset:51200
	ds_read_b128 v[194:197], v157 offset:52224
	ds_read_b128 v[198:201], v157 offset:53248
	ds_read_b128 v[202:205], v157 offset:54272
	ds_read_b128 v[206:209], v157 offset:55296
	ds_read_b128 v[214:217], v157 offset:56320
	global_load_lds_dwordx4 v130, s[82:83]
	s_add_i32 m0, s50, 0x2000
	s_add_u32 s48, s48, 0x40080
	s_addc_u32 s49, s49, 0
	s_add_i32 s50, s71, s53
	global_load_lds_dwordx4 v134, s[82:83]
	s_mov_b32 m0, s50
	s_nop 0
	global_load_lds_dwordx4 v130, s[48:49]
	s_add_i32 m0, s50, 0x2000
	s_nop 0
	global_load_lds_dwordx4 v134, s[48:49]
	s_mov_b32 m0, s58
	s_nop 0
	global_load_lds_dwordx4 v128, s[80:81]
	s_mov_b32 m0, s59
	s_nop 0
	global_load_lds_dwordx4 v132, s[80:81]
	s_waitcnt vmcnt(8)
	s_waitcnt lgkmcnt(0)
	s_barrier
	s_waitcnt lgkmcnt(0)
	v_mfma_f32_16x16x32_bf16 v[60:63], v[144:147], v[182:185], v[60:63]
	v_mfma_f32_16x16x32_bf16 v[56:59], v[158:161], v[182:185], v[56:59]
	v_mfma_f32_16x16x32_bf16 v[48:51], v[144:147], v[190:193], v[48:51]
	v_mfma_f32_16x16x32_bf16 v[40:43], v[158:161], v[190:193], v[40:43]
	v_mfma_f32_16x16x32_bf16 v[32:35], v[144:147], v[198:201], v[32:35]
	v_mfma_f32_16x16x32_bf16 v[24:27], v[158:161], v[198:201], v[24:27]
	v_mfma_f32_16x16x32_bf16 v[16:19], v[144:147], v[206:209], v[16:19]
	v_mfma_f32_16x16x32_bf16 v[8:11], v[158:161], v[206:209], v[8:11]
	v_mfma_f32_16x16x32_bf16 v[60:63], v[148:151], v[186:189], v[60:63]
	v_mfma_f32_16x16x32_bf16 v[56:59], v[162:165], v[186:189], v[56:59]
	v_mfma_f32_16x16x32_bf16 v[48:51], v[148:151], v[194:197], v[48:51]
	v_mfma_f32_16x16x32_bf16 v[40:43], v[162:165], v[194:197], v[40:43]
	v_mfma_f32_16x16x32_bf16 v[32:35], v[148:151], v[202:205], v[32:35]
	v_mfma_f32_16x16x32_bf16 v[24:27], v[162:165], v[202:205], v[24:27]
	v_mfma_f32_16x16x32_bf16 v[16:19], v[148:151], v[214:217], v[16:19]
	v_mfma_f32_16x16x32_bf16 v[8:11], v[162:165], v[214:217], v[8:11]
	v_mfma_f32_16x16x32_bf16 v[52:55], v[166:169], v[182:185], v[52:55]
	v_mfma_f32_16x16x32_bf16 v[44:47], v[174:177], v[182:185], v[44:47]
	v_mfma_f32_16x16x32_bf16 v[36:39], v[166:169], v[190:193], v[36:39]
	v_mfma_f32_16x16x32_bf16 v[28:31], v[174:177], v[190:193], v[28:31]
	v_mfma_f32_16x16x32_bf16 v[20:23], v[166:169], v[198:201], v[20:23]
	v_mfma_f32_16x16x32_bf16 v[12:15], v[174:177], v[198:201], v[12:15]
	v_mfma_f32_16x16x32_bf16 v[4:7], v[166:169], v[206:209], v[4:7]
	v_mfma_f32_16x16x32_bf16 v[0:3], v[174:177], v[206:209], v[0:3]
	v_mfma_f32_16x16x32_bf16 v[52:55], v[170:173], v[186:189], v[52:55]
	v_mfma_f32_16x16x32_bf16 v[44:47], v[178:181], v[186:189], v[44:47]
	v_mfma_f32_16x16x32_bf16 v[36:39], v[170:173], v[194:197], v[36:39]
	v_mfma_f32_16x16x32_bf16 v[28:31], v[178:181], v[194:197], v[28:31]
	v_mfma_f32_16x16x32_bf16 v[20:23], v[170:173], v[202:205], v[20:23]
	v_mfma_f32_16x16x32_bf16 v[12:15], v[178:181], v[202:205], v[12:15]
	v_mfma_f32_16x16x32_bf16 v[4:7], v[170:173], v[214:217], v[4:7]
	v_mfma_f32_16x16x32_bf16 v[0:3], v[178:181], v[214:217], v[0:3]
	s_add_i32 s69, s69, 2
	s_add_u32 s46, s46, 0x100
	s_addc_u32 s47, s47, 0
	s_add_u32 s67, s67, 0x100
	s_addc_u32 s68, s68, 0
	s_cmp_gt_u32 s69, 13
	s_barrier
	s_cbranch_scc0 .LBB0_735
	v_lshl_add_u32 v150, s44, 8, v152
	v_lshl_or_b32 v144, s64, 8, v154
	v_ashrrev_i32_e32 v145, 31, v144
	v_or_b32_e32 v166, 16, v150
	v_lshlrev_b64 v[144:145], 1, v[144:145]
	v_ashrrev_i32_e32 v151, 31, v150
	v_ashrrev_i32_e32 v167, 31, v166
	v_lshl_add_u64 v[146:147], s[12:13], 0, v[144:145]
	v_lshlrev_b64 v[148:149], 12, v[150:151]
	v_lshlrev_b64 v[178:179], 12, v[166:167]
	v_lshl_add_u64 v[162:163], v[146:147], 0, v[148:149]
	v_lshl_add_u64 v[170:171], v[146:147], 0, v[178:179]
	global_load_dwordx4 v[158:161], v[162:163], off
	s_nop 0
	global_load_dwordx4 v[162:165], v[162:163], off offset:256
	s_nop 0
	global_load_dwordx4 v[166:169], v[170:171], off
	s_nop 0
	global_load_dwordx4 v[170:173], v[170:171], off offset:256
	v_or_b32_e32 v174, 32, v150
	v_ashrrev_i32_e32 v175, 31, v174
	v_lshlrev_b64 v[190:191], 12, v[174:175]
	v_lshl_add_u64 v[180:181], v[146:147], 0, v[190:191]
	global_load_dwordx4 v[174:177], v[180:181], off
	v_or_b32_e32 v150, 48, v150
	v_ashrrev_i32_e32 v151, 31, v150
	v_lshlrev_b64 v[150:151], 12, v[150:151]
	v_lshl_add_u64 v[182:183], s[14:15], 0, v[148:149]
	v_lshl_add_u64 v[186:187], v[146:147], 0, v[150:151]
	v_lshl_add_u64 v[192:193], v[182:183], 0, v[144:145]
	v_lshl_add_u64 v[194:195], s[14:15], 0, v[178:179]
	global_load_dwordx4 v[178:181], v[180:181], off offset:256
	s_nop 0
	global_load_dwordx4 v[182:185], v[186:187], off
	s_nop 0
	global_load_dwordx4 v[186:189], v[186:187], off offset:256
	v_lshl_add_u64 v[194:195], v[194:195], 0, v[144:145]
	s_and_b64 vcc, exec, s[10:11]
	s_mov_b32 s64, s36
	s_mov_b32 s44, s38
	s_mov_b64 s[48:49], s[42:43]
	s_mov_b64 s[46:47], s[40:41]
	s_waitcnt vmcnt(0)
; __device__ __forceinline__ float bf_lo(unsigned w) { return __uint_as_float(w << 16); }
; __device__ __forceinline__ float bf_hi(unsigned w) { return __uint_as_float(w & 0xffff0000u); }
; __device__ __forceinline__ u32x4 pack8(const f32x4 a, const f32x4 b) { u32x4 w; w.x = cvt_pk_bf16(a[0], a[1]); w.y = cvt_pk_bf16(a[2], a[3]); w.z = cvt_pk_bf16(b[0], b[1]); w.w = cvt_pk_bf16(b[2], b[3]); return w; }
;     __device__ __forceinline__ void operator()(const f32x4 (&acc)[2][2][4][2], const Unit& u, int wr, int wc, int fr, int fq) const {
;     ...
;         for (int ai = 0; ai < 2; ++ai) { u32x4 gw[4][2], pw[4][2];
; #pragma unroll
;             for (int m = 0; m < 4; ++m) { const size_t off = (size_t)(row0 + ai * HALF + m * 16) * 2048 + col0;
; #pragma unroll
;                 for (int bj = 0; bj < 2; ++bj) { gw[m][bj] = *(const u32x4*)(G + off + bj * HALF); if (PASS == 1) pw[m][bj] = *(const u32x4*)(MIX + off + bj * HALF); } }
; #pragma unroll
;             for (int m = 0; m < 4; ++m) { const size_t off = (size_t)(row0 + ai * HALF + m * 16) * 2048 + col0;
; #pragma unroll
;                 for (int bj = 0; bj < 2; ++bj) { const u32x4 g4 = gw[m][bj];
;                     f32x4 v0 = (f32x4){bf_lo(g4.x), bf_hi(g4.x), bf_lo(g4.y), bf_hi(g4.y)} * acc[ai][bj][m][0], v1 = (f32x4){bf_lo(g4.z), bf_hi(g4.z), bf_lo(g4.w), bf_hi(g4.w)} * acc[ai][bj][m][1];
;                     if (PASS == 1) { const u32x4 p4 = pw[m][bj]; v0 += (f32x4){bf_lo(p4.x), bf_hi(p4.x), bf_lo(p4.y), bf_hi(p4.y)}; v1 += (f32x4){bf_lo(p4.z), bf_hi(p4.z), bf_lo(p4.w), bf_hi(p4.w)}; }
;                     *(u32x4*)(MIX + off + bj * HALF) = pack8(v0, v1); } } }
	v_lshlrev_b32_e32 v196, 16, v158
	v_and_b32_e32 v197, 0xffff0000, v158
	v_lshlrev_b32_e32 v158, 16, v159
	v_and_b32_e32 v159, 0xffff0000, v159
	v_lshlrev_b32_e32 v198, 16, v160
	v_and_b32_e32 v199, 0xffff0000, v160
	v_lshlrev_b32_e32 v160, 16, v161
	v_and_b32_e32 v161, 0xffff0000, v161
	v_lshlrev_b32_e32 v200, 16, v162
	v_and_b32_e32 v201, 0xffff0000, v162
	v_lshlrev_b32_e32 v162, 16, v163
	v_and_b32_e32 v163, 0xffff0000, v163
	v_lshlrev_b32_e32 v202, 16, v164
	v_and_b32_e32 v203, 0xffff0000, v164
	v_lshlrev_b32_e32 v164, 16, v165
	v_and_b32_e32 v165, 0xffff0000, v165
	v_lshlrev_b32_e32 v204, 16, v166
	v_and_b32_e32 v205, 0xffff0000, v166
	v_lshlrev_b32_e32 v166, 16, v167
	v_and_b32_e32 v167, 0xffff0000, v167
	v_lshlrev_b32_e32 v206, 16, v168
	v_and_b32_e32 v207, 0xffff0000, v168
	v_lshlrev_b32_e32 v168, 16, v169
	v_and_b32_e32 v169, 0xffff0000, v169
	v_lshlrev_b32_e32 v208, 16, v170
	v_and_b32_e32 v209, 0xffff0000, v170
	v_lshlrev_b32_e32 v170, 16, v171
	v_and_b32_e32 v171, 0xffff0000, v171
	v_pk_mul_f32 v[126:127], v[126:127], v[158:159]
	v_pk_mul_f32 v[124:125], v[124:125], v[196:197]
	v_pk_mul_f32 v[122:123], v[122:123], v[160:161]
	v_pk_mul_f32 v[120:121], v[120:121], v[198:199]
	v_pk_mul_f32 v[110:111], v[110:111], v[162:163]
	v_pk_mul_f32 v[108:109], v[108:109], v[200:201]
	v_pk_mul_f32 v[158:159], v[106:107], v[164:165]
	v_pk_mul_f32 v[106:107], v[104:105], v[202:203]
	v_pk_mul_f32 v[118:119], v[118:119], v[166:167]
	v_pk_mul_f32 v[116:117], v[116:117], v[204:205]
	v_pk_mul_f32 v[114:115], v[114:115], v[168:169]
	v_pk_mul_f32 v[112:113], v[112:113], v[206:207]
	v_pk_mul_f32 v[160:161], v[102:103], v[170:171]
	v_pk_mul_f32 v[162:163], v[100:101], v[208:209]
	v_cvt_pk_bf16_f32 v100, v124, v125
	v_cvt_pk_bf16_f32 v101, v126, v127
	v_cvt_pk_bf16_f32 v102, v120, v121
	v_cvt_pk_bf16_f32 v103, v122, v123
	v_cvt_pk_bf16_f32 v104, v108, v109
	v_cvt_pk_bf16_f32 v105, v110, v111
	v_cvt_pk_bf16_f32 v106, v106, v107
	v_cvt_pk_bf16_f32 v107, v158, v159
	v_cvt_pk_bf16_f32 v108, v116, v117
	v_cvt_pk_bf16_f32 v109, v118, v119
	v_cvt_pk_bf16_f32 v110, v112, v113
	v_cvt_pk_bf16_f32 v111, v114, v115
	global_store_dwordx4 v[192:193], v[100:103], off
	global_store_dwordx4 v[192:193], v[104:107], off offset:256
	global_store_dwordx4 v[194:195], v[108:111], off
	v_lshlrev_b32_e32 v100, 16, v172
	v_and_b32_e32 v101, 0xffff0000, v172
	v_lshlrev_b32_e32 v102, 16, v173
	v_and_b32_e32 v103, 0xffff0000, v173
	v_pk_mul_f32 v[102:103], v[94:95], v[102:103]
	v_pk_mul_f32 v[94:95], v[92:93], v[100:101]
	v_cvt_pk_bf16_f32 v92, v162, v163
	v_cvt_pk_bf16_f32 v93, v160, v161
	v_cvt_pk_bf16_f32 v94, v94, v95
	v_cvt_pk_bf16_f32 v95, v102, v103
	global_store_dwordx4 v[194:195], v[92:95], off offset:256
	v_lshl_add_u64 v[100:101], v[148:149], 0, s[30:31]
	v_lshl_add_u64 v[102:103], v[148:149], 0, s[34:35]
	v_lshlrev_b32_e32 v92, 16, v174
	v_and_b32_e32 v93, 0xffff0000, v174
	v_lshlrev_b32_e32 v94, 16, v175
	v_and_b32_e32 v95, 0xffff0000, v175
	v_pk_mul_f32 v[94:95], v[98:99], v[94:95]
	v_pk_mul_f32 v[92:93], v[96:97], v[92:93]
	v_lshlrev_b32_e32 v96, 16, v176
	v_and_b32_e32 v97, 0xffff0000, v176
	v_lshlrev_b32_e32 v98, 16, v177
	v_and_b32_e32 v99, 0xffff0000, v177
	v_pk_mul_f32 v[98:99], v[90:91], v[98:99]
	v_pk_mul_f32 v[90:91], v[88:89], v[96:97]
	v_cvt_pk_bf16_f32 v88, v92, v93
	v_lshl_add_u64 v[92:93], s[14:15], 0, v[190:191]
	v_cvt_pk_bf16_f32 v89, v94, v95
	v_cvt_pk_bf16_f32 v90, v90, v91
	v_cvt_pk_bf16_f32 v91, v98, v99
	v_lshl_add_u64 v[92:93], v[92:93], 0, v[144:145]
	global_store_dwordx4 v[92:93], v[88:91], off
	v_lshl_add_u64 v[96:97], v[148:149], 0, s[26:27]
	v_lshl_add_u64 v[98:99], v[148:149], 0, s[28:29]
	v_lshlrev_b32_e32 v88, 16, v178
	v_and_b32_e32 v89, 0xffff0000, v178
	v_lshlrev_b32_e32 v90, 16, v179
	v_and_b32_e32 v91, 0xffff0000, v179
	v_pk_mul_f32 v[86:87], v[86:87], v[90:91]
	v_pk_mul_f32 v[84:85], v[84:85], v[88:89]
	v_lshlrev_b32_e32 v88, 16, v180
	v_and_b32_e32 v89, 0xffff0000, v180
	v_lshlrev_b32_e32 v90, 16, v181
	v_and_b32_e32 v91, 0xffff0000, v181
	v_pk_mul_f32 v[90:91], v[78:79], v[90:91]
	v_pk_mul_f32 v[78:79], v[76:77], v[88:89]
	v_cvt_pk_bf16_f32 v76, v84, v85
	v_cvt_pk_bf16_f32 v77, v86, v87
	v_cvt_pk_bf16_f32 v78, v78, v79
	v_cvt_pk_bf16_f32 v79, v90, v91
	global_store_dwordx4 v[92:93], v[76:79], off offset:256
	s_nop 1
	v_lshlrev_b32_e32 v76, 16, v182
	v_and_b32_e32 v77, 0xffff0000, v182
	v_lshlrev_b32_e32 v78, 16, v183
	v_and_b32_e32 v79, 0xffff0000, v183
	v_pk_mul_f32 v[78:79], v[82:83], v[78:79]
	v_pk_mul_f32 v[76:77], v[80:81], v[76:77]
	v_lshlrev_b32_e32 v80, 16, v184
	v_and_b32_e32 v81, 0xffff0000, v184
	v_lshlrev_b32_e32 v82, 16, v185
	v_and_b32_e32 v83, 0xffff0000, v185
	v_pk_mul_f32 v[82:83], v[74:75], v[82:83]
	v_pk_mul_f32 v[74:75], v[72:73], v[80:81]
	v_cvt_pk_bf16_f32 v72, v76, v77
	v_lshl_add_u64 v[76:77], s[14:15], 0, v[150:151]
	v_cvt_pk_bf16_f32 v73, v78, v79
	v_cvt_pk_bf16_f32 v74, v74, v75
	v_cvt_pk_bf16_f32 v75, v82, v83
	v_lshl_add_u64 v[76:77], v[76:77], 0, v[144:145]
	global_store_dwordx4 v[76:77], v[72:75], off
	s_nop 1
	v_lshlrev_b32_e32 v72, 16, v186
	v_and_b32_e32 v73, 0xffff0000, v186
	v_lshlrev_b32_e32 v74, 16, v187
	v_and_b32_e32 v75, 0xffff0000, v187
	v_pk_mul_f32 v[70:71], v[70:71], v[74:75]
	v_pk_mul_f32 v[68:69], v[68:69], v[72:73]
	v_lshlrev_b32_e32 v72, 16, v188
	v_and_b32_e32 v73, 0xffff0000, v188
	v_lshlrev_b32_e32 v74, 16, v189
	v_and_b32_e32 v75, 0xffff0000, v189
	v_pk_mul_f32 v[74:75], v[66:67], v[74:75]
	v_pk_mul_f32 v[66:67], v[64:65], v[72:73]
	v_cvt_pk_bf16_f32 v64, v68, v69
	v_cvt_pk_bf16_f32 v65, v70, v71
	v_cvt_pk_bf16_f32 v66, v66, v67
	v_cvt_pk_bf16_f32 v67, v74, v75
	global_store_dwordx4 v[76:77], v[64:67], off offset:256
	s_nop 1
	v_lshl_add_u64 v[64:65], v[146:147], 0, v[96:97]
	global_load_dwordx4 v[68:71], v[64:65], off
	global_load_dwordx4 v[72:75], v[64:65], off offset:256
	v_lshl_add_u64 v[64:65], v[146:147], 0, v[98:99]
	global_load_dwordx4 v[76:79], v[64:65], off
	global_load_dwordx4 v[80:83], v[64:65], off offset:256
	v_lshl_add_u64 v[64:65], v[146:147], 0, v[100:101]
	global_load_dwordx4 v[84:87], v[64:65], off
	global_load_dwordx4 v[88:91], v[64:65], off offset:256
	v_lshl_add_u64 v[64:65], v[146:147], 0, v[102:103]
	global_load_dwordx4 v[92:95], v[64:65], off
	s_nop 0
	global_load_dwordx4 v[64:67], v[64:65], off offset:256
	s_waitcnt vmcnt(7)
; __device__ __forceinline__ float bf_lo(unsigned w) { return __uint_as_float(w << 16); }
; __device__ __forceinline__ float bf_hi(unsigned w) { return __uint_as_float(w & 0xffff0000u); }
; __device__ __forceinline__ u32x4 pack8(const f32x4 a, const f32x4 b) { u32x4 w; w.x = cvt_pk_bf16(a[0], a[1]); w.y = cvt_pk_bf16(a[2], a[3]); w.z = cvt_pk_bf16(b[0], b[1]); w.w = cvt_pk_bf16(b[2], b[3]); return w; }
; #define PG8_WAIT_V(n) asm volatile("s_waitcnt vmcnt(" #n ")" ::: "memory")
; #define PG8_BAR __builtin_amdgcn_s_barrier()
;     __device__ __forceinline__ void operator()(const f32x4 (&acc)[2][2][4][2], const Unit& u, int wr, int wc, int fr, int fq) const {
;     ...
;             for (int m = 0; m < 4; ++m) { const size_t off = (size_t)(row0 + ai * HALF + m * 16) * 2048 + col0;
; #pragma unroll
;                 for (int bj = 0; bj < 2; ++bj) { const u32x4 g4 = gw[m][bj];
;                     f32x4 v0 = (f32x4){bf_lo(g4.x), bf_hi(g4.x), bf_lo(g4.y), bf_hi(g4.y)} * acc[ai][bj][m][0], v1 = (f32x4){bf_lo(g4.z), bf_hi(g4.z), bf_lo(g4.w), bf_hi(g4.w)} * acc[ai][bj][m][1];
;                     if (PASS == 1) { const u32x4 p4 = pw[m][bj]; v0 += (f32x4){bf_lo(p4.x), bf_hi(p4.x), bf_lo(p4.y), bf_hi(p4.y)}; v1 += (f32x4){bf_lo(p4.z), bf_hi(p4.z), bf_lo(p4.w), bf_hi(p4.w)}; }
;                     *(u32x4*)(MIX + off + bj * HALF) = pack8(v0, v1); } } }
; template <class Epi, class Sched, bool ALIGN_EPI = false, bool SP2 = false>
; __device__ __forceinline__ void gemm_phase(PG8_LAS unsigned char* lds, const Gemm g, const Sched& S, const Epi& E) {
;     ...
;     PG8_WAIT_V(0);
;     if constexpr (!ALIGN_EPI) { if (wr == 0) PG8_BAR; }
;     PG8_BAR;
	v_lshlrev_b32_e32 v104, 16, v68
	v_and_b32_e32 v105, 0xffff0000, v68
	v_lshlrev_b32_e32 v68, 16, v69
	v_and_b32_e32 v69, 0xffff0000, v69
	v_pk_mul_f32 v[62:63], v[62:63], v[68:69]
	v_pk_mul_f32 v[60:61], v[60:61], v[104:105]
	v_lshlrev_b32_e32 v68, 16, v70
	v_and_b32_e32 v69, 0xffff0000, v70
	v_lshlrev_b32_e32 v70, 16, v71
	v_and_b32_e32 v71, 0xffff0000, v71
	v_pk_mul_f32 v[70:71], v[58:59], v[70:71]
	v_pk_mul_f32 v[58:59], v[56:57], v[68:69]
	v_cvt_pk_bf16_f32 v56, v60, v61
	v_lshl_add_u64 v[60:61], s[14:15], 0, v[96:97]
	v_cvt_pk_bf16_f32 v57, v62, v63
	v_cvt_pk_bf16_f32 v58, v58, v59
	v_cvt_pk_bf16_f32 v59, v70, v71
	v_lshl_add_u64 v[60:61], v[60:61], 0, v[144:145]
	global_store_dwordx4 v[60:61], v[56:59], off
	s_waitcnt vmcnt(7)
	s_nop 0
	v_lshlrev_b32_e32 v56, 16, v72
	v_and_b32_e32 v57, 0xffff0000, v72
	v_lshlrev_b32_e32 v58, 16, v73
	v_and_b32_e32 v59, 0xffff0000, v73
	v_pk_mul_f32 v[54:55], v[54:55], v[58:59]
	v_pk_mul_f32 v[52:53], v[52:53], v[56:57]
	v_lshlrev_b32_e32 v56, 16, v74
	v_and_b32_e32 v57, 0xffff0000, v74
	v_lshlrev_b32_e32 v58, 16, v75
	v_and_b32_e32 v59, 0xffff0000, v75
	v_pk_mul_f32 v[58:59], v[46:47], v[58:59]
	v_pk_mul_f32 v[46:47], v[44:45], v[56:57]
	v_cvt_pk_bf16_f32 v44, v52, v53
	v_cvt_pk_bf16_f32 v45, v54, v55
	v_cvt_pk_bf16_f32 v46, v46, v47
	v_cvt_pk_bf16_f32 v47, v58, v59
	global_store_dwordx4 v[60:61], v[44:47], off offset:256
	s_waitcnt vmcnt(7)
	s_nop 0
	v_lshlrev_b32_e32 v44, 16, v76
	v_and_b32_e32 v45, 0xffff0000, v76
	v_lshlrev_b32_e32 v46, 16, v77
	v_and_b32_e32 v47, 0xffff0000, v77
	v_pk_mul_f32 v[46:47], v[50:51], v[46:47]
	v_pk_mul_f32 v[44:45], v[48:49], v[44:45]
	v_lshlrev_b32_e32 v48, 16, v78
	v_and_b32_e32 v49, 0xffff0000, v78
	v_lshlrev_b32_e32 v50, 16, v79
	v_and_b32_e32 v51, 0xffff0000, v79
	v_pk_mul_f32 v[50:51], v[42:43], v[50:51]
	v_pk_mul_f32 v[42:43], v[40:41], v[48:49]
	v_cvt_pk_bf16_f32 v40, v44, v45
	v_lshl_add_u64 v[44:45], s[14:15], 0, v[98:99]
	v_cvt_pk_bf16_f32 v41, v46, v47
	v_cvt_pk_bf16_f32 v42, v42, v43
	v_cvt_pk_bf16_f32 v43, v50, v51
	v_lshl_add_u64 v[44:45], v[44:45], 0, v[144:145]
	global_store_dwordx4 v[44:45], v[40:43], off
	s_waitcnt vmcnt(7)
	s_nop 0
	v_lshlrev_b32_e32 v40, 16, v80
	v_and_b32_e32 v41, 0xffff0000, v80
	v_lshlrev_b32_e32 v42, 16, v81
	v_and_b32_e32 v43, 0xffff0000, v81
	v_pk_mul_f32 v[38:39], v[38:39], v[42:43]
	v_pk_mul_f32 v[36:37], v[36:37], v[40:41]
	v_lshlrev_b32_e32 v40, 16, v82
	v_and_b32_e32 v41, 0xffff0000, v82
	v_lshlrev_b32_e32 v42, 16, v83
	v_and_b32_e32 v43, 0xffff0000, v83
	v_pk_mul_f32 v[42:43], v[30:31], v[42:43]
	v_pk_mul_f32 v[30:31], v[28:29], v[40:41]
	v_cvt_pk_bf16_f32 v28, v36, v37
	v_cvt_pk_bf16_f32 v29, v38, v39
	v_cvt_pk_bf16_f32 v30, v30, v31
	v_cvt_pk_bf16_f32 v31, v42, v43
	global_store_dwordx4 v[44:45], v[28:31], off offset:256
	s_waitcnt vmcnt(7)
	s_nop 0
	v_lshlrev_b32_e32 v28, 16, v84
	v_and_b32_e32 v29, 0xffff0000, v84
	v_lshlrev_b32_e32 v30, 16, v85
	v_and_b32_e32 v31, 0xffff0000, v85
	v_pk_mul_f32 v[30:31], v[34:35], v[30:31]
	v_pk_mul_f32 v[28:29], v[32:33], v[28:29]
	v_lshlrev_b32_e32 v32, 16, v86
	v_and_b32_e32 v33, 0xffff0000, v86
	v_lshlrev_b32_e32 v34, 16, v87
	v_and_b32_e32 v35, 0xffff0000, v87
	v_pk_mul_f32 v[34:35], v[26:27], v[34:35]
	v_pk_mul_f32 v[26:27], v[24:25], v[32:33]
	v_cvt_pk_bf16_f32 v24, v28, v29
	v_lshl_add_u64 v[28:29], s[14:15], 0, v[100:101]
	v_cvt_pk_bf16_f32 v25, v30, v31
	v_cvt_pk_bf16_f32 v26, v26, v27
	v_cvt_pk_bf16_f32 v27, v34, v35
	v_lshl_add_u64 v[28:29], v[28:29], 0, v[144:145]
	global_store_dwordx4 v[28:29], v[24:27], off
	s_waitcnt vmcnt(7)
	s_nop 0
	v_lshlrev_b32_e32 v24, 16, v88
	v_and_b32_e32 v25, 0xffff0000, v88
	v_lshlrev_b32_e32 v26, 16, v89
	v_and_b32_e32 v27, 0xffff0000, v89
	v_pk_mul_f32 v[22:23], v[22:23], v[26:27]
	v_pk_mul_f32 v[20:21], v[20:21], v[24:25]
	v_lshlrev_b32_e32 v24, 16, v90
	v_and_b32_e32 v25, 0xffff0000, v90
	v_lshlrev_b32_e32 v26, 16, v91
	v_and_b32_e32 v27, 0xffff0000, v91
	v_pk_mul_f32 v[26:27], v[14:15], v[26:27]
	v_pk_mul_f32 v[14:15], v[12:13], v[24:25]
	v_cvt_pk_bf16_f32 v12, v20, v21
	v_cvt_pk_bf16_f32 v13, v22, v23
	v_cvt_pk_bf16_f32 v14, v14, v15
	v_cvt_pk_bf16_f32 v15, v26, v27
	global_store_dwordx4 v[28:29], v[12:15], off offset:256
	s_waitcnt vmcnt(7)
	s_nop 0
	v_lshlrev_b32_e32 v12, 16, v92
	v_and_b32_e32 v13, 0xffff0000, v92
	v_lshlrev_b32_e32 v14, 16, v93
	v_and_b32_e32 v15, 0xffff0000, v93
	v_pk_mul_f32 v[14:15], v[18:19], v[14:15]
	v_pk_mul_f32 v[12:13], v[16:17], v[12:13]
	v_lshlrev_b32_e32 v16, 16, v94
	v_and_b32_e32 v17, 0xffff0000, v94
	v_lshlrev_b32_e32 v18, 16, v95
	v_and_b32_e32 v19, 0xffff0000, v95
	v_pk_mul_f32 v[18:19], v[10:11], v[18:19]
	v_pk_mul_f32 v[10:11], v[8:9], v[16:17]
	v_cvt_pk_bf16_f32 v8, v12, v13
	v_lshl_add_u64 v[12:13], s[14:15], 0, v[102:103]
	v_cvt_pk_bf16_f32 v9, v14, v15
	v_cvt_pk_bf16_f32 v10, v10, v11
	v_cvt_pk_bf16_f32 v11, v18, v19
	v_lshl_add_u64 v[12:13], v[12:13], 0, v[144:145]
	global_store_dwordx4 v[12:13], v[8:11], off
	s_waitcnt vmcnt(7)
	s_nop 0
	v_lshlrev_b32_e32 v8, 16, v64
	v_and_b32_e32 v9, 0xffff0000, v64
	v_lshlrev_b32_e32 v10, 16, v65
	v_and_b32_e32 v11, 0xffff0000, v65
	v_pk_mul_f32 v[6:7], v[6:7], v[10:11]
	v_pk_mul_f32 v[4:5], v[4:5], v[8:9]
	v_lshlrev_b32_e32 v8, 16, v66
	v_and_b32_e32 v9, 0xffff0000, v66
	v_lshlrev_b32_e32 v10, 16, v67
	v_and_b32_e32 v11, 0xffff0000, v67
	v_pk_mul_f32 v[10:11], v[2:3], v[10:11]
	v_pk_mul_f32 v[2:3], v[0:1], v[8:9]
	v_cvt_pk_bf16_f32 v0, v4, v5
	v_cvt_pk_bf16_f32 v1, v6, v7
	v_cvt_pk_bf16_f32 v2, v2, v3
	v_cvt_pk_bf16_f32 v3, v10, v11
	global_store_dwordx4 v[12:13], v[0:3], off offset:256
	s_cbranch_vccz .LBB0_728
	s_waitcnt vmcnt(0)
	s_cmpk_gt_u32 s3, 0xff
	s_cbranch_scc1 .LBB0_739
	s_barrier

; #define PG8_STAGE(bufoff, gbase, voff) do { _Pragma("unroll") for (int _i = 0; _i < 2; ++_i) \
;         __builtin_amdgcn_global_load_lds((const unsigned*)((const char*)(gbase) + (voff)[_i]), (PG8_LAS unsigned*)(lds + (bufoff) + ldsw + _i * 8192), 16, 0, 0); } while (0)
; #define PG8_LDA(dst, b, h) do { _Pragma("unroll") for (int m = 0; m < 4; ++m) _Pragma("unroll") for (int k = 0; k < 2; ++k) dst[m][k] = *(const PG8_LAS bf16x8*)(lds + PG8_SA(b, h) + aoff + m * 2048 + k * 1024); } while (0)
; #define PG8_LDB(dst, b, h) do { _Pragma("unroll") for (int n = 0; n < 2; ++n) _Pragma("unroll") for (int k = 0; k < 2; ++k) dst[n][k] = *(const PG8_LAS bf16x8*)(lds + PG8_SB(b, h) + boff + n * 2048 + k * 1024); } while (0)
; #define PG8_WAIT_V(n) asm volatile("s_waitcnt vmcnt(" #n ")" ::: "memory")
; #define PG8_WAIT_L(n) asm volatile("s_waitcnt lgkmcnt(" #n ")" ::: "memory")
; #define PG8_BAR __builtin_amdgcn_s_barrier()
; #define PG8_SCHED __builtin_amdgcn_sched_barrier(0)
; template <class Epi, class Sched, bool ALIGN_EPI = false, bool SP2 = false>
; __device__ __forceinline__ void gemm_phase(PG8_LAS unsigned char* lds, const Gemm g, const Sched& S, const Epi& E) {
;     ...
;         const bool has_next = S.next(ui + 1, nxt);
;         const char* nA = has_next ? (const char*)g.A + (size_t)nxt.pm * tstep : cA; const char* nB = has_next ? (const char*)g.Bt + (size_t)nxt.pn * tstep : cB;
;         for (int t = 0; t < nt; t += 2) {
;             const bool last = (t == nt - 2);
;             const char* a1 = cA + (size_t)(t + 1) * kstep;
;             const char* a2 = last ? nA : cA + (size_t)(t + 2) * kstep; const char* b2 = last ? nB : cB + (size_t)(t + 2) * kstep;
;             const char* a3 = a2 + kstep; const char* b3 = b2 + kstep;
;             if (last && has_next) S.a_ready(nxt);
;             if constexpr (SP2) {
;             PG8_LDB(B0, 0, 0); PG8_LDB(B1, 0, 1); PG8_SCHED; PG8_LDA(At, 0, 0); PG8_STAGE(PG8_SA(1, 1), a1 + hstep, voffA);
;             PG8_WAIT_V(8); PG8_WAIT_L(0); PG8_BAR; PG8_MMA(0, 0, At, B0); PG8_MMA(0, 1, At, B1); PG8_BAR; PG8_SCHED;
;             PG8_LDA(At, 0, 1); PG8_STAGE(PG8_SB(0, 0), b2, voffB); PG8_STAGE(PG8_SB(0, 1), b2 + hstep, voffB); PG8_STAGE(PG8_SA(0, 0), a2, voffA);
;             PG8_WAIT_V(8); PG8_WAIT_L(0); PG8_BAR; PG8_MMA(1, 0, At, B0); PG8_MMA(1, 1, At, B1); PG8_BAR; PG8_SCHED;
.LBB0_754:
	s_ashr_i32 s29, s28, 31
	v_cmp_lt_i64_e32 vcc, s[30:31], v[160:161]
	s_lshl_b64 s[30:31], s[28:29], 19
	s_add_u32 s30, s9, s30
	s_addc_u32 s31, s22, s31
	s_and_b64 s[34:35], vcc, exec
	s_cselect_b32 s29, s31, s39
	s_cselect_b32 s57, s30, s38
	s_ashr_i32 s27, s26, 31
	s_lshl_b64 s[34:35], s[26:27], 19
	s_add_u32 s34, s23, s34
	s_addc_u32 s35, s44, s35
	s_and_b64 s[42:43], vcc, exec
	s_cselect_b32 s27, s35, s41
	s_cselect_b32 s58, s34, s40
	s_add_u32 s38, s38, 0x40080
	s_addc_u32 s39, s39, 0
	s_add_u32 s59, s40, 0x100
	s_addc_u32 s60, s41, 0
	s_mov_b32 s61, -2
	ds_read_b128 v[128:131], v177
	ds_read_b128 v[132:135], v177 offset:1024
	ds_read_b128 v[136:139], v177 offset:2048
	ds_read_b128 v[140:143], v177 offset:3072
	ds_read_b128 v[144:147], v178
	ds_read_b128 v[164:167], v178 offset:1024
	ds_read_b128 v[168:171], v178 offset:2048
	ds_read_b128 v[180:183], v178 offset:3072
	s_add_u32 s40, s38, 0xfffc0080
	s_addc_u32 s41, s39, -1
	s_cmp_eq_u32 s61, 12
	s_cselect_b32 s43, s29, s41
	s_cselect_b32 s42, s57, s40
	s_cselect_b32 s41, s27, s60
	s_cselect_b32 s40, s58, s59
	s_add_i32 m0, s37, 0xc000
	ds_read_b128 v[184:187], v179
	ds_read_b128 v[188:191], v179 offset:1024
	ds_read_b128 v[192:195], v179 offset:2048
	ds_read_b128 v[196:199], v179 offset:3072
	ds_read_b128 v[200:203], v179 offset:4096
	ds_read_b128 v[204:207], v179 offset:5120
	ds_read_b128 v[208:211], v179 offset:6144
	ds_read_b128 v[214:217], v179 offset:7168
	global_load_lds_dwordx4 v156, s[38:39]
	s_add_i32 m0, s37, 0xe000
	s_nop 0
	global_load_lds_dwordx4 v158, s[38:39]
	s_waitcnt vmcnt(8)
	s_waitcnt lgkmcnt(0)
	s_barrier
	s_waitcnt lgkmcnt(0)
	v_mfma_f32_16x16x32_bf16 v[124:127], v[128:131], v[184:187], 0
	v_mfma_f32_16x16x32_bf16 v[120:123], v[136:139], v[184:187], 0
	v_mfma_f32_16x16x32_bf16 v[108:111], v[128:131], v[192:195], 0
	v_mfma_f32_16x16x32_bf16 v[104:107], v[136:139], v[192:195], 0
	v_mfma_f32_16x16x32_bf16 v[92:95], v[128:131], v[200:203], 0
	v_mfma_f32_16x16x32_bf16 v[88:91], v[136:139], v[200:203], 0
	v_mfma_f32_16x16x32_bf16 v[76:79], v[128:131], v[208:211], 0
	v_mfma_f32_16x16x32_bf16 v[72:75], v[136:139], v[208:211], 0
	v_mfma_f32_16x16x32_bf16 v[124:127], v[132:135], v[188:191], v[124:127]
	v_mfma_f32_16x16x32_bf16 v[120:123], v[140:143], v[188:191], v[120:123]
	v_mfma_f32_16x16x32_bf16 v[108:111], v[132:135], v[196:199], v[108:111]
	v_mfma_f32_16x16x32_bf16 v[104:107], v[140:143], v[196:199], v[104:107]
	v_mfma_f32_16x16x32_bf16 v[92:95], v[132:135], v[204:207], v[92:95]
	v_mfma_f32_16x16x32_bf16 v[88:91], v[140:143], v[204:207], v[88:91]
	v_mfma_f32_16x16x32_bf16 v[76:79], v[132:135], v[214:217], v[76:79]
	v_mfma_f32_16x16x32_bf16 v[72:75], v[140:143], v[214:217], v[72:75]
	v_mfma_f32_16x16x32_bf16 v[116:119], v[144:147], v[184:187], 0
	v_mfma_f32_16x16x32_bf16 v[112:115], v[168:171], v[184:187], 0
	v_mfma_f32_16x16x32_bf16 v[100:103], v[144:147], v[192:195], 0
	v_mfma_f32_16x16x32_bf16 v[96:99], v[168:171], v[192:195], 0
	v_mfma_f32_16x16x32_bf16 v[84:87], v[144:147], v[200:203], 0
	v_mfma_f32_16x16x32_bf16 v[80:83], v[168:171], v[200:203], 0
	v_mfma_f32_16x16x32_bf16 v[68:71], v[144:147], v[208:211], 0
	v_mfma_f32_16x16x32_bf16 v[64:67], v[168:171], v[208:211], 0
	v_mfma_f32_16x16x32_bf16 v[116:119], v[164:167], v[188:191], v[116:119]
	v_mfma_f32_16x16x32_bf16 v[112:115], v[180:183], v[188:191], v[112:115]
	v_mfma_f32_16x16x32_bf16 v[100:103], v[164:167], v[196:199], v[100:103]
	v_mfma_f32_16x16x32_bf16 v[96:99], v[180:183], v[196:199], v[96:99]
	v_mfma_f32_16x16x32_bf16 v[84:87], v[164:167], v[204:207], v[84:87]
	v_mfma_f32_16x16x32_bf16 v[80:83], v[180:183], v[204:207], v[80:83]
	v_mfma_f32_16x16x32_bf16 v[68:71], v[164:167], v[214:217], v[68:71]
	v_mfma_f32_16x16x32_bf16 v[64:67], v[180:183], v[214:217], v[64:67]
	s_barrier
	s_add_i32 s62, s54, s45
	s_mov_b32 m0, s62
	ds_read_b128 v[184:187], v179 offset:16384
	ds_read_b128 v[188:191], v179 offset:17408
	ds_read_b128 v[192:195], v179 offset:18432
	ds_read_b128 v[196:199], v179 offset:19456
	ds_read_b128 v[200:203], v179 offset:20480
	ds_read_b128 v[204:207], v179 offset:21504
	ds_read_b128 v[208:211], v179 offset:22528
	ds_read_b128 v[214:217], v179 offset:23552
	global_load_lds_dwordx4 v150, s[40:41]
	s_add_i32 m0, s62, 0x2000
	s_add_u32 s62, s40, 0x40000
	s_addc_u32 s63, s41, 0
	s_add_i32 s64, s55, s45
	global_load_lds_dwordx4 v154, s[40:41]
	s_mov_b32 m0, s64
	s_nop 0
	global_load_lds_dwordx4 v150, s[62:63]
	s_add_i32 m0, s64, 0x2000
	s_nop 0
	global_load_lds_dwordx4 v154, s[62:63]
	s_mov_b32 m0, s37
	s_nop 0
	global_load_lds_dwordx4 v148, s[42:43]
	s_mov_b32 m0, s46
	s_nop 0
	global_load_lds_dwordx4 v152, s[42:43]
	s_waitcnt vmcnt(8)
	s_waitcnt lgkmcnt(0)
	s_barrier
; #define PG8_STAGE(bufoff, gbase, voff) do { _Pragma("unroll") for (int _i = 0; _i < 2; ++_i) \
;         __builtin_amdgcn_global_load_lds((const unsigned*)((const char*)(gbase) + (voff)[_i]), (PG8_LAS unsigned*)(lds + (bufoff) + ldsw + _i * 8192), 16, 0, 0); } while (0)
; #define PG8_LDA(dst, b, h) do { _Pragma("unroll") for (int m = 0; m < 4; ++m) _Pragma("unroll") for (int k = 0; k < 2; ++k) dst[m][k] = *(const PG8_LAS bf16x8*)(lds + PG8_SA(b, h) + aoff + m * 2048 + k * 1024); } while (0)
; #define PG8_LDB(dst, b, h) do { _Pragma("unroll") for (int n = 0; n < 2; ++n) _Pragma("unroll") for (int k = 0; k < 2; ++k) dst[n][k] = *(const PG8_LAS bf16x8*)(lds + PG8_SB(b, h) + boff + n * 2048 + k * 1024); } while (0)
; #define PG8_MMA(ai, bj, At, Bt) do { __builtin_amdgcn_s_setprio(1); _Pragma("unroll") for (int m = 0; m < 4; ++m) _Pragma("unroll") for (int n = 0; n < 2; ++n) _Pragma("unroll") for (int k = 0; k < 2; ++k) \
;         acc[ai][bj][m][n] = __builtin_amdgcn_mfma_f32_16x16x32_bf16(Bt[n][k], At[m][k], acc[ai][bj][m][n], 0, 0, 0); __builtin_amdgcn_s_setprio(0); } while (0)
; #define PG8_WAIT_V(n) asm volatile("s_waitcnt vmcnt(" #n ")" ::: "memory")
; #define PG8_WAIT_L(n) asm volatile("s_waitcnt lgkmcnt(" #n ")" ::: "memory")
; #define PG8_BAR __builtin_amdgcn_s_barrier()
; #define PG8_SCHED __builtin_amdgcn_sched_barrier(0)
; template <class Epi, class Sched, bool ALIGN_EPI = false, bool SP2 = false>
; __device__ __forceinline__ void gemm_phase(PG8_LAS unsigned char* lds, const Gemm g, const Sched& S, const Epi& E) {
;     ...
;             PG8_WAIT_V(8); PG8_WAIT_L(0); PG8_BAR; PG8_MMA(1, 0, At, B0); PG8_MMA(1, 1, At, B1); PG8_BAR; PG8_SCHED;
;             PG8_LDB(B0, 1, 0); PG8_LDB(B1, 1, 1); PG8_SCHED; PG8_LDA(At, 1, 0); PG8_STAGE(PG8_SA(0, 1), a2 + hstep, voffA);
;             PG8_WAIT_V(8); PG8_WAIT_L(0); PG8_BAR; PG8_MMA(0, 0, At, B0); PG8_MMA(0, 1, At, B1); PG8_BAR; PG8_SCHED;
	s_waitcnt lgkmcnt(0)
	v_mfma_f32_16x16x32_bf16 v[60:63], v[128:131], v[184:187], 0
	v_mfma_f32_16x16x32_bf16 v[56:59], v[136:139], v[184:187], 0
	v_mfma_f32_16x16x32_bf16 v[44:47], v[128:131], v[192:195], 0
	v_mfma_f32_16x16x32_bf16 v[40:43], v[136:139], v[192:195], 0
	v_mfma_f32_16x16x32_bf16 v[28:31], v[128:131], v[200:203], 0
	v_mfma_f32_16x16x32_bf16 v[24:27], v[136:139], v[200:203], 0
	v_mfma_f32_16x16x32_bf16 v[12:15], v[128:131], v[208:211], 0
	v_mfma_f32_16x16x32_bf16 v[8:11], v[136:139], v[208:211], 0
	v_mfma_f32_16x16x32_bf16 v[60:63], v[132:135], v[188:191], v[60:63]
	v_mfma_f32_16x16x32_bf16 v[56:59], v[140:143], v[188:191], v[56:59]
	v_mfma_f32_16x16x32_bf16 v[44:47], v[132:135], v[196:199], v[44:47]
	v_mfma_f32_16x16x32_bf16 v[40:43], v[140:143], v[196:199], v[40:43]
	v_mfma_f32_16x16x32_bf16 v[28:31], v[132:135], v[204:207], v[28:31]
	v_mfma_f32_16x16x32_bf16 v[24:27], v[140:143], v[204:207], v[24:27]
	v_mfma_f32_16x16x32_bf16 v[12:15], v[132:135], v[214:217], v[12:15]
	v_mfma_f32_16x16x32_bf16 v[8:11], v[140:143], v[214:217], v[8:11]
	v_mfma_f32_16x16x32_bf16 v[52:55], v[144:147], v[184:187], 0
	v_mfma_f32_16x16x32_bf16 v[48:51], v[168:171], v[184:187], 0
	v_mfma_f32_16x16x32_bf16 v[36:39], v[144:147], v[192:195], 0
	v_mfma_f32_16x16x32_bf16 v[32:35], v[168:171], v[192:195], 0
	v_mfma_f32_16x16x32_bf16 v[20:23], v[144:147], v[200:203], 0
	v_mfma_f32_16x16x32_bf16 v[16:19], v[168:171], v[200:203], 0
	v_mfma_f32_16x16x32_bf16 v[4:7], v[144:147], v[208:211], 0
	v_mfma_f32_16x16x32_bf16 v[0:3], v[168:171], v[208:211], 0
	v_mfma_f32_16x16x32_bf16 v[52:55], v[164:167], v[188:191], v[52:55]
	v_mfma_f32_16x16x32_bf16 v[48:51], v[180:183], v[188:191], v[48:51]
	v_mfma_f32_16x16x32_bf16 v[36:39], v[164:167], v[196:199], v[36:39]
	v_mfma_f32_16x16x32_bf16 v[32:35], v[180:183], v[196:199], v[32:35]
	v_mfma_f32_16x16x32_bf16 v[20:23], v[164:167], v[204:207], v[20:23]
	v_mfma_f32_16x16x32_bf16 v[16:19], v[180:183], v[204:207], v[16:19]
	v_mfma_f32_16x16x32_bf16 v[4:7], v[164:167], v[214:217], v[4:7]
	v_mfma_f32_16x16x32_bf16 v[0:3], v[180:183], v[214:217], v[0:3]
	s_barrier
	s_add_i32 s62, 0, 0x18000
	s_add_i32 s63, 0, 0x1c000
	v_add_u32_e32 v140, s62, v175
	v_add_u32_e32 v180, s63, v175
	ds_read_b128 v[128:131], v140
	ds_read_b128 v[132:135], v140 offset:1024
	ds_read_b128 v[136:139], v140 offset:2048
	ds_read_b128 v[140:143], v140 offset:3072
	ds_read_b128 v[144:147], v180
	ds_read_b128 v[164:167], v180 offset:1024
	ds_read_b128 v[168:171], v180 offset:2048
	ds_read_b128 v[180:183], v180 offset:3072
	s_add_u32 s84, s42, 0x80
	s_addc_u32 s85, s43, 0
	s_add_u32 s42, s42, 0x40000
	s_addc_u32 s43, s43, 0
	s_mov_b32 m0, s47
	ds_read_b128 v[184:187], v179 offset:32768
	ds_read_b128 v[188:191], v179 offset:33792
	ds_read_b128 v[192:195], v179 offset:34816
	ds_read_b128 v[196:199], v179 offset:35840
	ds_read_b128 v[200:203], v179 offset:36864
	ds_read_b128 v[204:207], v179 offset:37888
	ds_read_b128 v[208:211], v179 offset:38912
	ds_read_b128 v[214:217], v179 offset:39936
	global_load_lds_dwordx4 v148, s[42:43]
	s_mov_b32 m0, s48
	s_nop 0
	global_load_lds_dwordx4 v152, s[42:43]
	s_waitcnt vmcnt(8)
	s_waitcnt lgkmcnt(0)
	s_barrier
	s_waitcnt lgkmcnt(0)
	v_mfma_f32_16x16x32_bf16 v[124:127], v[128:131], v[184:187], v[124:127]
	v_mfma_f32_16x16x32_bf16 v[120:123], v[136:139], v[184:187], v[120:123]
	v_mfma_f32_16x16x32_bf16 v[108:111], v[128:131], v[192:195], v[108:111]
	v_mfma_f32_16x16x32_bf16 v[104:107], v[136:139], v[192:195], v[104:107]
	v_mfma_f32_16x16x32_bf16 v[92:95], v[128:131], v[200:203], v[92:95]
	v_mfma_f32_16x16x32_bf16 v[88:91], v[136:139], v[200:203], v[88:91]
	v_mfma_f32_16x16x32_bf16 v[76:79], v[128:131], v[208:211], v[76:79]
	v_mfma_f32_16x16x32_bf16 v[72:75], v[136:139], v[208:211], v[72:75]
	v_mfma_f32_16x16x32_bf16 v[124:127], v[132:135], v[188:191], v[124:127]
	v_mfma_f32_16x16x32_bf16 v[120:123], v[140:143], v[188:191], v[120:123]
	v_mfma_f32_16x16x32_bf16 v[108:111], v[132:135], v[196:199], v[108:111]
	v_mfma_f32_16x16x32_bf16 v[104:107], v[140:143], v[196:199], v[104:107]
	v_mfma_f32_16x16x32_bf16 v[92:95], v[132:135], v[204:207], v[92:95]
	v_mfma_f32_16x16x32_bf16 v[88:91], v[140:143], v[204:207], v[88:91]
	v_mfma_f32_16x16x32_bf16 v[76:79], v[132:135], v[214:217], v[76:79]
	v_mfma_f32_16x16x32_bf16 v[72:75], v[140:143], v[214:217], v[72:75]
	v_mfma_f32_16x16x32_bf16 v[116:119], v[144:147], v[184:187], v[116:119]
	v_mfma_f32_16x16x32_bf16 v[112:115], v[168:171], v[184:187], v[112:115]
	v_mfma_f32_16x16x32_bf16 v[100:103], v[144:147], v[192:195], v[100:103]
	v_mfma_f32_16x16x32_bf16 v[96:99], v[168:171], v[192:195], v[96:99]
	v_mfma_f32_16x16x32_bf16 v[84:87], v[144:147], v[200:203], v[84:87]
	v_mfma_f32_16x16x32_bf16 v[80:83], v[168:171], v[200:203], v[80:83]
	v_mfma_f32_16x16x32_bf16 v[68:71], v[144:147], v[208:211], v[68:71]
	v_mfma_f32_16x16x32_bf16 v[64:67], v[168:171], v[208:211], v[64:67]
	v_mfma_f32_16x16x32_bf16 v[116:119], v[164:167], v[188:191], v[116:119]
	v_mfma_f32_16x16x32_bf16 v[112:115], v[180:183], v[188:191], v[112:115]
	v_mfma_f32_16x16x32_bf16 v[100:103], v[164:167], v[196:199], v[100:103]
	v_mfma_f32_16x16x32_bf16 v[96:99], v[180:183], v[196:199], v[96:99]
	v_mfma_f32_16x16x32_bf16 v[84:87], v[164:167], v[204:207], v[84:87]
	v_mfma_f32_16x16x32_bf16 v[80:83], v[180:183], v[204:207], v[80:83]
	v_mfma_f32_16x16x32_bf16 v[68:71], v[164:167], v[214:217], v[68:71]
	v_mfma_f32_16x16x32_bf16 v[64:67], v[180:183], v[214:217], v[64:67]
	s_barrier
; #define PG8_STAGE(bufoff, gbase, voff) do { _Pragma("unroll") for (int _i = 0; _i < 2; ++_i) \
;         __builtin_amdgcn_global_load_lds((const unsigned*)((const char*)(gbase) + (voff)[_i]), (PG8_LAS unsigned*)(lds + (bufoff) + ldsw + _i * 8192), 16, 0, 0); } while (0)
; #define PG8_LDA(dst, b, h) do { _Pragma("unroll") for (int m = 0; m < 4; ++m) _Pragma("unroll") for (int k = 0; k < 2; ++k) dst[m][k] = *(const PG8_LAS bf16x8*)(lds + PG8_SA(b, h) + aoff + m * 2048 + k * 1024); } while (0)
; #define PG8_LDB(dst, b, h) do { _Pragma("unroll") for (int n = 0; n < 2; ++n) _Pragma("unroll") for (int k = 0; k < 2; ++k) dst[n][k] = *(const PG8_LAS bf16x8*)(lds + PG8_SB(b, h) + boff + n * 2048 + k * 1024); } while (0)
; #define PG8_MMA(ai, bj, At, Bt) do { __builtin_amdgcn_s_setprio(1); _Pragma("unroll") for (int m = 0; m < 4; ++m) _Pragma("unroll") for (int n = 0; n < 2; ++n) _Pragma("unroll") for (int k = 0; k < 2; ++k) \
;         acc[ai][bj][m][n] = __builtin_amdgcn_mfma_f32_16x16x32_bf16(Bt[n][k], At[m][k], acc[ai][bj][m][n], 0, 0, 0); __builtin_amdgcn_s_setprio(0); } while (0)
; #define PG8_WAIT_V(n) asm volatile("s_waitcnt vmcnt(" #n ")" ::: "memory")
; #define PG8_WAIT_L(n) asm volatile("s_waitcnt lgkmcnt(" #n ")" ::: "memory")
; #define PG8_BAR __builtin_amdgcn_s_barrier()
; #define PG8_SCHED __builtin_amdgcn_sched_barrier(0)
; template <class Epi, class Sched, bool ALIGN_EPI = false, bool SP2 = false>
; __device__ __forceinline__ void gemm_phase(PG8_LAS unsigned char* lds, const Gemm g, const Sched& S, const Epi& E) {
;     ...
;             PG8_LDB(B0, 0, 0); PG8_LDB(B1, 0, 1); PG8_SCHED; PG8_LDA(At, 0, 0); PG8_STAGE(PG8_SA(1, 1), a1 + hstep, voffA);
;             PG8_WAIT_V(8); PG8_WAIT_L(0); PG8_BAR; PG8_MMA(0, 0, At, B0); PG8_MMA(0, 1, At, B1); PG8_BAR; PG8_SCHED;
;     ...
;             PG8_LDA(At, 1, 1); PG8_STAGE(PG8_SB(1, 0), b3, voffB); PG8_STAGE(PG8_SB(1, 1), b3 + hstep, voffB); PG8_STAGE(PG8_SA(1, 0), a3, voffA);
;             PG8_WAIT_V(8); PG8_WAIT_L(0); PG8_BAR; PG8_MMA(1, 0, At, B0); PG8_MMA(1, 1, At, B1); PG8_BAR; PG8_SCHED;
	s_add_i32 s42, s62, s45
	s_add_u32 s86, s40, 0x80
	s_addc_u32 s87, s41, 0
	s_mov_b32 m0, s42
	ds_read_b128 v[184:187], v179 offset:49152
	ds_read_b128 v[188:191], v179 offset:50176
	ds_read_b128 v[192:195], v179 offset:51200
	ds_read_b128 v[196:199], v179 offset:52224
	ds_read_b128 v[200:203], v179 offset:53248
	ds_read_b128 v[204:207], v179 offset:54272
	ds_read_b128 v[208:211], v179 offset:55296
	ds_read_b128 v[214:217], v179 offset:56320
	global_load_lds_dwordx4 v150, s[86:87]
	s_add_i32 m0, s42, 0x2000
	s_add_u32 s40, s40, 0x40080
	s_addc_u32 s41, s41, 0
	s_add_i32 s42, s63, s45
	global_load_lds_dwordx4 v154, s[86:87]
	s_mov_b32 m0, s42
	s_nop 0
	global_load_lds_dwordx4 v150, s[40:41]
	s_add_i32 m0, s42, 0x2000
	s_nop 0
	global_load_lds_dwordx4 v154, s[40:41]
	s_mov_b32 m0, s50
	s_nop 0
	global_load_lds_dwordx4 v148, s[84:85]
	s_mov_b32 m0, s51
	s_nop 0
	global_load_lds_dwordx4 v152, s[84:85]
	s_waitcnt vmcnt(8)
	s_waitcnt lgkmcnt(0)
	s_barrier
	s_waitcnt lgkmcnt(0)
	v_mfma_f32_16x16x32_bf16 v[60:63], v[128:131], v[184:187], v[60:63]
	v_mfma_f32_16x16x32_bf16 v[56:59], v[136:139], v[184:187], v[56:59]
	v_mfma_f32_16x16x32_bf16 v[44:47], v[128:131], v[192:195], v[44:47]
	v_mfma_f32_16x16x32_bf16 v[40:43], v[136:139], v[192:195], v[40:43]
	v_mfma_f32_16x16x32_bf16 v[28:31], v[128:131], v[200:203], v[28:31]
	v_mfma_f32_16x16x32_bf16 v[24:27], v[136:139], v[200:203], v[24:27]
	v_mfma_f32_16x16x32_bf16 v[12:15], v[128:131], v[208:211], v[12:15]
	v_mfma_f32_16x16x32_bf16 v[8:11], v[136:139], v[208:211], v[8:11]
	v_mfma_f32_16x16x32_bf16 v[60:63], v[132:135], v[188:191], v[60:63]
	v_mfma_f32_16x16x32_bf16 v[56:59], v[140:143], v[188:191], v[56:59]
	v_mfma_f32_16x16x32_bf16 v[44:47], v[132:135], v[196:199], v[44:47]
	v_mfma_f32_16x16x32_bf16 v[40:43], v[140:143], v[196:199], v[40:43]
	v_mfma_f32_16x16x32_bf16 v[28:31], v[132:135], v[204:207], v[28:31]
	v_mfma_f32_16x16x32_bf16 v[24:27], v[140:143], v[204:207], v[24:27]
	v_mfma_f32_16x16x32_bf16 v[12:15], v[132:135], v[214:217], v[12:15]
	v_mfma_f32_16x16x32_bf16 v[8:11], v[140:143], v[214:217], v[8:11]
	v_mfma_f32_16x16x32_bf16 v[52:55], v[144:147], v[184:187], v[52:55]
	v_mfma_f32_16x16x32_bf16 v[48:51], v[168:171], v[184:187], v[48:51]
	v_mfma_f32_16x16x32_bf16 v[36:39], v[144:147], v[192:195], v[36:39]
	v_mfma_f32_16x16x32_bf16 v[32:35], v[168:171], v[192:195], v[32:35]
	v_mfma_f32_16x16x32_bf16 v[20:23], v[144:147], v[200:203], v[20:23]
	v_mfma_f32_16x16x32_bf16 v[16:19], v[168:171], v[200:203], v[16:19]
	v_mfma_f32_16x16x32_bf16 v[4:7], v[144:147], v[208:211], v[4:7]
	v_mfma_f32_16x16x32_bf16 v[0:3], v[168:171], v[208:211], v[0:3]
	v_mfma_f32_16x16x32_bf16 v[52:55], v[164:167], v[188:191], v[52:55]
	v_mfma_f32_16x16x32_bf16 v[48:51], v[180:183], v[188:191], v[48:51]
	v_mfma_f32_16x16x32_bf16 v[36:39], v[164:167], v[196:199], v[36:39]
	v_mfma_f32_16x16x32_bf16 v[32:35], v[180:183], v[196:199], v[32:35]
	v_mfma_f32_16x16x32_bf16 v[20:23], v[164:167], v[204:207], v[20:23]
	v_mfma_f32_16x16x32_bf16 v[16:19], v[180:183], v[204:207], v[16:19]
	v_mfma_f32_16x16x32_bf16 v[4:7], v[164:167], v[214:217], v[4:7]
	v_mfma_f32_16x16x32_bf16 v[0:3], v[180:183], v[214:217], v[0:3]
	s_add_i32 s61, s61, 2
	s_add_u32 s38, s38, 0x100
	s_addc_u32 s39, s39, 0
	s_add_u32 s59, s59, 0x100
	s_addc_u32 s60, s60, 0
	s_cmp_gt_u32 s61, 13
	s_barrier
.LBB0_755:
	ds_read_b128 v[128:131], v177
	ds_read_b128 v[132:135], v177 offset:1024
	ds_read_b128 v[136:139], v177 offset:2048
	ds_read_b128 v[140:143], v177 offset:3072
	ds_read_b128 v[144:147], v178
	ds_read_b128 v[164:167], v178 offset:1024
	ds_read_b128 v[168:171], v178 offset:2048
	ds_read_b128 v[180:183], v178 offset:3072
	s_add_u32 s40, s38, 0xfffc0080
	s_addc_u32 s41, s39, -1
	s_cmp_eq_u32 s61, 12
	s_cselect_b32 s43, s29, s41
	s_cselect_b32 s42, s57, s40
	s_cselect_b32 s41, s27, s60
	s_cselect_b32 s40, s58, s59
	s_add_i32 m0, s37, 0xc000
	ds_read_b128 v[184:187], v179
	ds_read_b128 v[188:191], v179 offset:1024
	ds_read_b128 v[192:195], v179 offset:2048
	ds_read_b128 v[196:199], v179 offset:3072
	ds_read_b128 v[200:203], v179 offset:4096
	ds_read_b128 v[204:207], v179 offset:5120
	ds_read_b128 v[208:211], v179 offset:6144
	ds_read_b128 v[214:217], v179 offset:7168
	global_load_lds_dwordx4 v156, s[38:39]
	s_add_i32 m0, s37, 0xe000
	s_nop 0
	global_load_lds_dwordx4 v158, s[38:39]
	s_waitcnt vmcnt(8)
	s_waitcnt lgkmcnt(0)
	s_barrier
	s_waitcnt lgkmcnt(0)
	v_mfma_f32_16x16x32_bf16 v[124:127], v[128:131], v[184:187], v[124:127]
	v_mfma_f32_16x16x32_bf16 v[120:123], v[136:139], v[184:187], v[120:123]
	v_mfma_f32_16x16x32_bf16 v[108:111], v[128:131], v[192:195], v[108:111]
	v_mfma_f32_16x16x32_bf16 v[104:107], v[136:139], v[192:195], v[104:107]
	v_mfma_f32_16x16x32_bf16 v[92:95], v[128:131], v[200:203], v[92:95]
	v_mfma_f32_16x16x32_bf16 v[88:91], v[136:139], v[200:203], v[88:91]
	v_mfma_f32_16x16x32_bf16 v[76:79], v[128:131], v[208:211], v[76:79]
	v_mfma_f32_16x16x32_bf16 v[72:75], v[136:139], v[208:211], v[72:75]
	v_mfma_f32_16x16x32_bf16 v[124:127], v[132:135], v[188:191], v[124:127]
	v_mfma_f32_16x16x32_bf16 v[120:123], v[140:143], v[188:191], v[120:123]
	v_mfma_f32_16x16x32_bf16 v[108:111], v[132:135], v[196:199], v[108:111]
	v_mfma_f32_16x16x32_bf16 v[104:107], v[140:143], v[196:199], v[104:107]
	v_mfma_f32_16x16x32_bf16 v[92:95], v[132:135], v[204:207], v[92:95]
	v_mfma_f32_16x16x32_bf16 v[88:91], v[140:143], v[204:207], v[88:91]
	v_mfma_f32_16x16x32_bf16 v[76:79], v[132:135], v[214:217], v[76:79]
	v_mfma_f32_16x16x32_bf16 v[72:75], v[140:143], v[214:217], v[72:75]
	v_mfma_f32_16x16x32_bf16 v[116:119], v[144:147], v[184:187], v[116:119]
	v_mfma_f32_16x16x32_bf16 v[112:115], v[168:171], v[184:187], v[112:115]
	v_mfma_f32_16x16x32_bf16 v[100:103], v[144:147], v[192:195], v[100:103]
	v_mfma_f32_16x16x32_bf16 v[96:99], v[168:171], v[192:195], v[96:99]
	v_mfma_f32_16x16x32_bf16 v[84:87], v[144:147], v[200:203], v[84:87]
	v_mfma_f32_16x16x32_bf16 v[80:83], v[168:171], v[200:203], v[80:83]
	v_mfma_f32_16x16x32_bf16 v[68:71], v[144:147], v[208:211], v[68:71]
	v_mfma_f32_16x16x32_bf16 v[64:67], v[168:171], v[208:211], v[64:67]
	v_mfma_f32_16x16x32_bf16 v[116:119], v[164:167], v[188:191], v[116:119]
	v_mfma_f32_16x16x32_bf16 v[112:115], v[180:183], v[188:191], v[112:115]
	v_mfma_f32_16x16x32_bf16 v[100:103], v[164:167], v[196:199], v[100:103]
	v_mfma_f32_16x16x32_bf16 v[96:99], v[180:183], v[196:199], v[96:99]
	v_mfma_f32_16x16x32_bf16 v[84:87], v[164:167], v[204:207], v[84:87]
	v_mfma_f32_16x16x32_bf16 v[80:83], v[180:183], v[204:207], v[80:83]
	v_mfma_f32_16x16x32_bf16 v[68:71], v[164:167], v[214:217], v[68:71]
	v_mfma_f32_16x16x32_bf16 v[64:67], v[180:183], v[214:217], v[64:67]
	s_barrier
; #define PG8_STAGE(bufoff, gbase, voff) do { _Pragma("unroll") for (int _i = 0; _i < 2; ++_i) \
;         __builtin_amdgcn_global_load_lds((const unsigned*)((const char*)(gbase) + (voff)[_i]), (PG8_LAS unsigned*)(lds + (bufoff) + ldsw + _i * 8192), 16, 0, 0); } while (0)
; #define PG8_LDA(dst, b, h) do { _Pragma("unroll") for (int m = 0; m < 4; ++m) _Pragma("unroll") for (int k = 0; k < 2; ++k) dst[m][k] = *(const PG8_LAS bf16x8*)(lds + PG8_SA(b, h) + aoff + m * 2048 + k * 1024); } while (0)
; #define PG8_LDB(dst, b, h) do { _Pragma("unroll") for (int n = 0; n < 2; ++n) _Pragma("unroll") for (int k = 0; k < 2; ++k) dst[n][k] = *(const PG8_LAS bf16x8*)(lds + PG8_SB(b, h) + boff + n * 2048 + k * 1024); } while (0)
; #define PG8_MMA(ai, bj, At, Bt) do { __builtin_amdgcn_s_setprio(1); _Pragma("unroll") for (int m = 0; m < 4; ++m) _Pragma("unroll") for (int n = 0; n < 2; ++n) _Pragma("unroll") for (int k = 0; k < 2; ++k) \
;         acc[ai][bj][m][n] = __builtin_amdgcn_mfma_f32_16x16x32_bf16(Bt[n][k], At[m][k], acc[ai][bj][m][n], 0, 0, 0); __builtin_amdgcn_s_setprio(0); } while (0)
; #define PG8_WAIT_V(n) asm volatile("s_waitcnt vmcnt(" #n ")" ::: "memory")
; #define PG8_WAIT_L(n) asm volatile("s_waitcnt lgkmcnt(" #n ")" ::: "memory")
; #define PG8_BAR __builtin_amdgcn_s_barrier()
; #define PG8_SCHED __builtin_amdgcn_sched_barrier(0)
; template <class Epi, class Sched, bool ALIGN_EPI = false, bool SP2 = false>
; __device__ __forceinline__ void gemm_phase(PG8_LAS unsigned char* lds, const Gemm g, const Sched& S, const Epi& E) {
;     ...
;             PG8_LDA(At, 0, 1); PG8_STAGE(PG8_SB(0, 0), b2, voffB); PG8_STAGE(PG8_SB(0, 1), b2 + hstep, voffB); PG8_STAGE(PG8_SA(0, 0), a2, voffA);
;             PG8_WAIT_V(8); PG8_WAIT_L(0); PG8_BAR; PG8_MMA(1, 0, At, B0); PG8_MMA(1, 1, At, B1); PG8_BAR; PG8_SCHED;
;             PG8_LDB(B0, 1, 0); PG8_LDB(B1, 1, 1); PG8_SCHED; PG8_LDA(At, 1, 0); PG8_STAGE(PG8_SA(0, 1), a2 + hstep, voffA);
;             PG8_WAIT_V(8); PG8_WAIT_L(0); PG8_BAR; PG8_MMA(0, 0, At, B0); PG8_MMA(0, 1, At, B1); PG8_BAR; PG8_SCHED;
	s_add_i32 s62, s54, s45
	s_mov_b32 m0, s62
	ds_read_b128 v[184:187], v179 offset:16384
	ds_read_b128 v[188:191], v179 offset:17408
	ds_read_b128 v[192:195], v179 offset:18432
	ds_read_b128 v[196:199], v179 offset:19456
	ds_read_b128 v[200:203], v179 offset:20480
	ds_read_b128 v[204:207], v179 offset:21504
	ds_read_b128 v[208:211], v179 offset:22528
	ds_read_b128 v[214:217], v179 offset:23552
	global_load_lds_dwordx4 v150, s[40:41]
	s_add_i32 m0, s62, 0x2000
	s_add_u32 s62, s40, 0x40000
	s_addc_u32 s63, s41, 0
	s_add_i32 s64, s55, s45
	global_load_lds_dwordx4 v154, s[40:41]
	s_mov_b32 m0, s64
	s_nop 0
	global_load_lds_dwordx4 v150, s[62:63]
	s_add_i32 m0, s64, 0x2000
	s_nop 0
	global_load_lds_dwordx4 v154, s[62:63]
	s_mov_b32 m0, s37
	s_nop 0
	global_load_lds_dwordx4 v148, s[42:43]
	s_mov_b32 m0, s46
	s_nop 0
	global_load_lds_dwordx4 v152, s[42:43]
	s_waitcnt vmcnt(8)
	s_waitcnt lgkmcnt(0)
	s_barrier
	s_waitcnt lgkmcnt(0)
	v_mfma_f32_16x16x32_bf16 v[60:63], v[128:131], v[184:187], v[60:63]
	v_mfma_f32_16x16x32_bf16 v[56:59], v[136:139], v[184:187], v[56:59]
	v_mfma_f32_16x16x32_bf16 v[44:47], v[128:131], v[192:195], v[44:47]
	v_mfma_f32_16x16x32_bf16 v[40:43], v[136:139], v[192:195], v[40:43]
	v_mfma_f32_16x16x32_bf16 v[28:31], v[128:131], v[200:203], v[28:31]
	v_mfma_f32_16x16x32_bf16 v[24:27], v[136:139], v[200:203], v[24:27]
	v_mfma_f32_16x16x32_bf16 v[12:15], v[128:131], v[208:211], v[12:15]
	v_mfma_f32_16x16x32_bf16 v[8:11], v[136:139], v[208:211], v[8:11]
	v_mfma_f32_16x16x32_bf16 v[60:63], v[132:135], v[188:191], v[60:63]
	v_mfma_f32_16x16x32_bf16 v[56:59], v[140:143], v[188:191], v[56:59]
	v_mfma_f32_16x16x32_bf16 v[44:47], v[132:135], v[196:199], v[44:47]
	v_mfma_f32_16x16x32_bf16 v[40:43], v[140:143], v[196:199], v[40:43]
	v_mfma_f32_16x16x32_bf16 v[28:31], v[132:135], v[204:207], v[28:31]
	v_mfma_f32_16x16x32_bf16 v[24:27], v[140:143], v[204:207], v[24:27]
	v_mfma_f32_16x16x32_bf16 v[12:15], v[132:135], v[214:217], v[12:15]
	v_mfma_f32_16x16x32_bf16 v[8:11], v[140:143], v[214:217], v[8:11]
	v_mfma_f32_16x16x32_bf16 v[52:55], v[144:147], v[184:187], v[52:55]
	v_mfma_f32_16x16x32_bf16 v[48:51], v[168:171], v[184:187], v[48:51]
	v_mfma_f32_16x16x32_bf16 v[36:39], v[144:147], v[192:195], v[36:39]
	v_mfma_f32_16x16x32_bf16 v[32:35], v[168:171], v[192:195], v[32:35]
	v_mfma_f32_16x16x32_bf16 v[20:23], v[144:147], v[200:203], v[20:23]
	v_mfma_f32_16x16x32_bf16 v[16:19], v[168:171], v[200:203], v[16:19]
	v_mfma_f32_16x16x32_bf16 v[4:7], v[144:147], v[208:211], v[4:7]
	v_mfma_f32_16x16x32_bf16 v[0:3], v[168:171], v[208:211], v[0:3]
	v_mfma_f32_16x16x32_bf16 v[52:55], v[164:167], v[188:191], v[52:55]
	v_mfma_f32_16x16x32_bf16 v[48:51], v[180:183], v[188:191], v[48:51]
	v_mfma_f32_16x16x32_bf16 v[36:39], v[164:167], v[196:199], v[36:39]
	v_mfma_f32_16x16x32_bf16 v[32:35], v[180:183], v[196:199], v[32:35]
	v_mfma_f32_16x16x32_bf16 v[20:23], v[164:167], v[204:207], v[20:23]
	v_mfma_f32_16x16x32_bf16 v[16:19], v[180:183], v[204:207], v[16:19]
	v_mfma_f32_16x16x32_bf16 v[4:7], v[164:167], v[214:217], v[4:7]
	v_mfma_f32_16x16x32_bf16 v[0:3], v[180:183], v[214:217], v[0:3]
	s_barrier
	s_add_i32 s62, 0, 0x18000
	s_add_i32 s63, 0, 0x1c000
	v_add_u32_e32 v140, s62, v175
	v_add_u32_e32 v180, s63, v175
	ds_read_b128 v[128:131], v140
	ds_read_b128 v[132:135], v140 offset:1024
	ds_read_b128 v[136:139], v140 offset:2048
	ds_read_b128 v[140:143], v140 offset:3072
	ds_read_b128 v[144:147], v180
	ds_read_b128 v[164:167], v180 offset:1024
	ds_read_b128 v[168:171], v180 offset:2048
	ds_read_b128 v[180:183], v180 offset:3072
	s_add_u32 s84, s42, 0x80
	s_addc_u32 s85, s43, 0
	s_add_u32 s42, s42, 0x40000
	s_addc_u32 s43, s43, 0
	s_mov_b32 m0, s47
	ds_read_b128 v[184:187], v179 offset:32768
	ds_read_b128 v[188:191], v179 offset:33792
	ds_read_b128 v[192:195], v179 offset:34816
	ds_read_b128 v[196:199], v179 offset:35840
	ds_read_b128 v[200:203], v179 offset:36864
	ds_read_b128 v[204:207], v179 offset:37888
	ds_read_b128 v[208:211], v179 offset:38912
	ds_read_b128 v[214:217], v179 offset:39936
	global_load_lds_dwordx4 v148, s[42:43]
	s_mov_b32 m0, s48
	s_nop 0
	global_load_lds_dwordx4 v152, s[42:43]
	s_waitcnt vmcnt(8)
	s_waitcnt lgkmcnt(0)
	s_barrier
	s_waitcnt lgkmcnt(0)
	v_mfma_f32_16x16x32_bf16 v[124:127], v[128:131], v[184:187], v[124:127]
	v_mfma_f32_16x16x32_bf16 v[120:123], v[136:139], v[184:187], v[120:123]
	v_mfma_f32_16x16x32_bf16 v[108:111], v[128:131], v[192:195], v[108:111]
	v_mfma_f32_16x16x32_bf16 v[104:107], v[136:139], v[192:195], v[104:107]
	v_mfma_f32_16x16x32_bf16 v[92:95], v[128:131], v[200:203], v[92:95]
	v_mfma_f32_16x16x32_bf16 v[88:91], v[136:139], v[200:203], v[88:91]
	v_mfma_f32_16x16x32_bf16 v[76:79], v[128:131], v[208:211], v[76:79]
	v_mfma_f32_16x16x32_bf16 v[72:75], v[136:139], v[208:211], v[72:75]
	v_mfma_f32_16x16x32_bf16 v[124:127], v[132:135], v[188:191], v[124:127]
	v_mfma_f32_16x16x32_bf16 v[120:123], v[140:143], v[188:191], v[120:123]
	v_mfma_f32_16x16x32_bf16 v[108:111], v[132:135], v[196:199], v[108:111]
	v_mfma_f32_16x16x32_bf16 v[104:107], v[140:143], v[196:199], v[104:107]
	v_mfma_f32_16x16x32_bf16 v[92:95], v[132:135], v[204:207], v[92:95]
	v_mfma_f32_16x16x32_bf16 v[88:91], v[140:143], v[204:207], v[88:91]
	v_mfma_f32_16x16x32_bf16 v[76:79], v[132:135], v[214:217], v[76:79]
	v_mfma_f32_16x16x32_bf16 v[72:75], v[140:143], v[214:217], v[72:75]
	v_mfma_f32_16x16x32_bf16 v[116:119], v[144:147], v[184:187], v[116:119]
	v_mfma_f32_16x16x32_bf16 v[112:115], v[168:171], v[184:187], v[112:115]
	v_mfma_f32_16x16x32_bf16 v[100:103], v[144:147], v[192:195], v[100:103]
	v_mfma_f32_16x16x32_bf16 v[96:99], v[168:171], v[192:195], v[96:99]
	v_mfma_f32_16x16x32_bf16 v[84:87], v[144:147], v[200:203], v[84:87]
	v_mfma_f32_16x16x32_bf16 v[80:83], v[168:171], v[200:203], v[80:83]
	v_mfma_f32_16x16x32_bf16 v[68:71], v[144:147], v[208:211], v[68:71]
	v_mfma_f32_16x16x32_bf16 v[64:67], v[168:171], v[208:211], v[64:67]
	v_mfma_f32_16x16x32_bf16 v[116:119], v[164:167], v[188:191], v[116:119]
	v_mfma_f32_16x16x32_bf16 v[112:115], v[180:183], v[188:191], v[112:115]
	v_mfma_f32_16x16x32_bf16 v[100:103], v[164:167], v[196:199], v[100:103]
	v_mfma_f32_16x16x32_bf16 v[96:99], v[180:183], v[196:199], v[96:99]
	v_mfma_f32_16x16x32_bf16 v[84:87], v[164:167], v[204:207], v[84:87]
	v_mfma_f32_16x16x32_bf16 v[80:83], v[180:183], v[204:207], v[80:83]
	v_mfma_f32_16x16x32_bf16 v[68:71], v[164:167], v[214:217], v[68:71]
	v_mfma_f32_16x16x32_bf16 v[64:67], v[180:183], v[214:217], v[64:67]
	s_barrier
; #define PG8_STAGE(bufoff, gbase, voff) do { _Pragma("unroll") for (int _i = 0; _i < 2; ++_i) \
;         __builtin_amdgcn_global_load_lds((const unsigned*)((const char*)(gbase) + (voff)[_i]), (PG8_LAS unsigned*)(lds + (bufoff) + ldsw + _i * 8192), 16, 0, 0); } while (0)
; #define PG8_LDA(dst, b, h) do { _Pragma("unroll") for (int m = 0; m < 4; ++m) _Pragma("unroll") for (int k = 0; k < 2; ++k) dst[m][k] = *(const PG8_LAS bf16x8*)(lds + PG8_SA(b, h) + aoff + m * 2048 + k * 1024); } while (0)
; #define PG8_MMA(ai, bj, At, Bt) do { __builtin_amdgcn_s_setprio(1); _Pragma("unroll") for (int m = 0; m < 4; ++m) _Pragma("unroll") for (int n = 0; n < 2; ++n) _Pragma("unroll") for (int k = 0; k < 2; ++k) \
;         acc[ai][bj][m][n] = __builtin_amdgcn_mfma_f32_16x16x32_bf16(Bt[n][k], At[m][k], acc[ai][bj][m][n], 0, 0, 0); __builtin_amdgcn_s_setprio(0); } while (0)
; #define PG8_WAIT_V(n) asm volatile("s_waitcnt vmcnt(" #n ")" ::: "memory")
; #define PG8_WAIT_L(n) asm volatile("s_waitcnt lgkmcnt(" #n ")" ::: "memory")
; #define PG8_BAR __builtin_amdgcn_s_barrier()
; #define PG8_SCHED __builtin_amdgcn_sched_barrier(0)
;     __device__ __forceinline__ void operator()(const f32x4 (&acc)[2][2][4][2], const Unit& u, int wr, int wc, int fr, int fq) const {
;     ...
;         for (int ai = 0; ai < 2; ++ai) { u32x4 gw[4][2], pw[4][2];
; #pragma unroll
;             for (int m = 0; m < 4; ++m) { const size_t off = (size_t)(row0 + ai * HALF + m * 16) * 2048 + col0;
; #pragma unroll
;                 for (int bj = 0; bj < 2; ++bj) { gw[m][bj] = *(const u32x4*)(G + off + bj * HALF); if (PASS == 1) pw[m][bj] = *(const u32x4*)(MIX + off + bj * HALF); } }
; template <class Epi, class Sched, bool ALIGN_EPI = false, bool SP2 = false>
; __device__ __forceinline__ void gemm_phase(PG8_LAS unsigned char* lds, const Gemm g, const Sched& S, const Epi& E) {
;     ...
;             PG8_LDA(At, 1, 1); PG8_STAGE(PG8_SB(1, 0), b3, voffB); PG8_STAGE(PG8_SB(1, 1), b3 + hstep, voffB); PG8_STAGE(PG8_SA(1, 0), a3, voffA);
;             PG8_WAIT_V(8); PG8_WAIT_L(0); PG8_BAR; PG8_MMA(1, 0, At, B0); PG8_MMA(1, 1, At, B1); PG8_BAR; PG8_SCHED;
	s_add_i32 s42, s62, s45
	s_add_u32 s86, s40, 0x80
	s_addc_u32 s87, s41, 0
	s_mov_b32 m0, s42
	ds_read_b128 v[184:187], v179 offset:49152
	ds_read_b128 v[188:191], v179 offset:50176
	ds_read_b128 v[192:195], v179 offset:51200
	ds_read_b128 v[196:199], v179 offset:52224
	ds_read_b128 v[200:203], v179 offset:53248
	ds_read_b128 v[204:207], v179 offset:54272
	ds_read_b128 v[208:211], v179 offset:55296
	ds_read_b128 v[214:217], v179 offset:56320
	global_load_lds_dwordx4 v150, s[86:87]
	s_add_i32 m0, s42, 0x2000
	s_add_u32 s40, s40, 0x40080
	s_addc_u32 s41, s41, 0
	s_add_i32 s42, s63, s45
	global_load_lds_dwordx4 v154, s[86:87]
	s_mov_b32 m0, s42
	s_nop 0
	global_load_lds_dwordx4 v150, s[40:41]
	s_add_i32 m0, s42, 0x2000
	s_nop 0
	global_load_lds_dwordx4 v154, s[40:41]
	s_mov_b32 m0, s50
	s_nop 0
	global_load_lds_dwordx4 v148, s[84:85]
	s_mov_b32 m0, s51
	s_nop 0
	global_load_lds_dwordx4 v152, s[84:85]
	s_waitcnt vmcnt(8)
	s_waitcnt lgkmcnt(0)
	s_barrier
	s_waitcnt lgkmcnt(0)
	v_mfma_f32_16x16x32_bf16 v[60:63], v[128:131], v[184:187], v[60:63]
	v_mfma_f32_16x16x32_bf16 v[56:59], v[136:139], v[184:187], v[56:59]
	v_mfma_f32_16x16x32_bf16 v[44:47], v[128:131], v[192:195], v[44:47]
	v_mfma_f32_16x16x32_bf16 v[40:43], v[136:139], v[192:195], v[40:43]
	v_mfma_f32_16x16x32_bf16 v[28:31], v[128:131], v[200:203], v[28:31]
	v_mfma_f32_16x16x32_bf16 v[24:27], v[136:139], v[200:203], v[24:27]
	v_mfma_f32_16x16x32_bf16 v[12:15], v[128:131], v[208:211], v[12:15]
	v_mfma_f32_16x16x32_bf16 v[8:11], v[136:139], v[208:211], v[8:11]
	v_mfma_f32_16x16x32_bf16 v[60:63], v[132:135], v[188:191], v[60:63]
	v_mfma_f32_16x16x32_bf16 v[56:59], v[140:143], v[188:191], v[56:59]
	v_mfma_f32_16x16x32_bf16 v[44:47], v[132:135], v[196:199], v[44:47]
	v_mfma_f32_16x16x32_bf16 v[40:43], v[140:143], v[196:199], v[40:43]
	v_mfma_f32_16x16x32_bf16 v[28:31], v[132:135], v[204:207], v[28:31]
	v_mfma_f32_16x16x32_bf16 v[24:27], v[140:143], v[204:207], v[24:27]
	v_mfma_f32_16x16x32_bf16 v[12:15], v[132:135], v[214:217], v[12:15]
	v_mfma_f32_16x16x32_bf16 v[8:11], v[140:143], v[214:217], v[8:11]
	v_mfma_f32_16x16x32_bf16 v[52:55], v[144:147], v[184:187], v[52:55]
	v_mfma_f32_16x16x32_bf16 v[48:51], v[168:171], v[184:187], v[48:51]
	v_mfma_f32_16x16x32_bf16 v[36:39], v[144:147], v[192:195], v[36:39]
	v_mfma_f32_16x16x32_bf16 v[32:35], v[168:171], v[192:195], v[32:35]
	v_mfma_f32_16x16x32_bf16 v[20:23], v[144:147], v[200:203], v[20:23]
	v_mfma_f32_16x16x32_bf16 v[16:19], v[168:171], v[200:203], v[16:19]
	v_mfma_f32_16x16x32_bf16 v[4:7], v[144:147], v[208:211], v[4:7]
	v_mfma_f32_16x16x32_bf16 v[0:3], v[168:171], v[208:211], v[0:3]
	v_mfma_f32_16x16x32_bf16 v[52:55], v[164:167], v[188:191], v[52:55]
	v_mfma_f32_16x16x32_bf16 v[48:51], v[180:183], v[188:191], v[48:51]
	v_mfma_f32_16x16x32_bf16 v[36:39], v[164:167], v[196:199], v[36:39]
	v_mfma_f32_16x16x32_bf16 v[32:35], v[180:183], v[196:199], v[32:35]
	v_mfma_f32_16x16x32_bf16 v[20:23], v[164:167], v[204:207], v[20:23]
	v_mfma_f32_16x16x32_bf16 v[16:19], v[180:183], v[204:207], v[16:19]
	v_mfma_f32_16x16x32_bf16 v[4:7], v[164:167], v[214:217], v[4:7]
	v_mfma_f32_16x16x32_bf16 v[0:3], v[180:183], v[214:217], v[0:3]
	s_add_i32 s61, s61, 2
	s_add_u32 s38, s38, 0x100
	s_addc_u32 s39, s39, 0
	s_add_u32 s59, s59, 0x100
	s_addc_u32 s60, s60, 0
	s_cmp_gt_u32 s61, 13
	s_barrier
	s_cbranch_scc0 .LBB0_755
	v_lshl_add_u32 v168, s36, 8, v174
	v_lshl_or_b32 v166, s56, 8, v176
	v_ashrrev_i32_e32 v169, 31, v168
	v_ashrrev_i32_e32 v167, 31, v166
	v_lshlrev_b64 v[128:129], 11, v[168:169]
	v_lshl_add_u64 v[128:129], v[128:129], 0, v[166:167]
	v_lshlrev_b64 v[128:129], 1, v[128:129]
	v_lshl_add_u64 v[130:131], s[12:13], 0, v[128:129]
	global_load_dwordx4 v[180:183], v[130:131], off
	v_lshl_add_u64 v[128:129], s[14:15], 0, v[128:129]
	v_or_b32_e32 v212, 16, v168
	global_load_dwordx4 v[184:187], v[128:129], off
	global_load_dwordx4 v[188:191], v[130:131], off offset:256
	global_load_dwordx4 v[192:195], v[128:129], off offset:256
	v_ashrrev_i32_e32 v213, 31, v212
	v_lshlrev_b64 v[128:129], 11, v[212:213]
	v_lshl_add_u64 v[128:129], v[128:129], 0, v[166:167]
	v_lshlrev_b64 v[128:129], 1, v[128:129]
	v_lshl_add_u64 v[130:131], s[12:13], 0, v[128:129]
	v_lshl_add_u64 v[128:129], s[14:15], 0, v[128:129]
	global_load_dwordx4 v[196:199], v[130:131], off
	global_load_dwordx4 v[200:203], v[128:129], off
	v_or_b32_e32 v172, 32, v168
	v_or_b32_e32 v170, 48, v168
	v_ashrrev_i32_e32 v173, 31, v172
	v_ashrrev_i32_e32 v171, 31, v170
	v_lshlrev_b64 v[132:133], 12, v[168:169]
	v_lshlrev_b64 v[134:135], 11, v[172:173]
	v_lshlrev_b64 v[136:137], 11, v[170:171]
	v_lshlrev_b64 v[164:165], 1, v[166:167]
	v_lshl_add_u64 v[132:133], s[14:15], 0, v[132:133]
	v_lshl_add_u64 v[134:135], v[134:135], 0, v[166:167]
	v_lshl_add_u64 v[136:137], v[136:137], 0, v[166:167]
	v_lshl_add_u64 v[218:219], v[132:133], 0, v[164:165]
	v_lshlrev_b64 v[132:133], 1, v[134:135]
	v_lshlrev_b64 v[134:135], 1, v[136:137]
	v_lshl_add_u64 v[136:137], s[12:13], 0, v[132:133]
	v_lshl_add_u64 v[132:133], s[14:15], 0, v[132:133]
	v_lshl_add_u64 v[138:139], s[12:13], 0, v[134:135]
	v_lshl_add_u64 v[230:231], s[14:15], 0, v[134:135]
	global_load_dwordx4 v[204:207], v[130:131], off offset:256
	global_load_dwordx4 v[208:211], v[128:129], off offset:256
	global_load_dwordx4 v[214:217], v[136:137], off
	global_load_dwordx4 v[222:225], v[136:137], off offset:256
	global_load_dwordx4 v[232:235], v[132:133], off
	global_load_dwordx4 v[144:147], v[132:133], off offset:256
	global_load_dwordx4 v[140:143], v[138:139], off
	s_nop 0
	global_load_dwordx4 v[132:135], v[138:139], off offset:256
	s_nop 0
	global_load_dwordx4 v[136:139], v[230:231], off
	global_load_dwordx4 v[128:131], v[230:231], off offset:256
	s_and_b64 vcc, exec, s[10:11]
	s_mov_b32 s56, s26
	s_mov_b32 s36, s28
	s_mov_b64 s[40:41], s[34:35]
	s_mov_b64 s[38:39], s[30:31]
	s_waitcnt vmcnt(0)
; __device__ __forceinline__ float bf_lo(unsigned w) { return __uint_as_float(w << 16); }
; __device__ __forceinline__ float bf_hi(unsigned w) { return __uint_as_float(w & 0xffff0000u); }
; __device__ __forceinline__ u32x4 pack8(const f32x4 a, const f32x4 b) { u32x4 w; w.x = cvt_pk_bf16(a[0], a[1]); w.y = cvt_pk_bf16(a[2], a[3]); w.z = cvt_pk_bf16(b[0], b[1]); w.w = cvt_pk_bf16(b[2], b[3]); return w; }
;     __device__ __forceinline__ void operator()(const f32x4 (&acc)[2][2][4][2], const Unit& u, int wr, int wc, int fr, int fq) const {
;     ...
;             for (int m = 0; m < 4; ++m) { const size_t off = (size_t)(row0 + ai * HALF + m * 16) * 2048 + col0;
; #pragma unroll
;                 for (int bj = 0; bj < 2; ++bj) { const u32x4 g4 = gw[m][bj];
;                     f32x4 v0 = (f32x4){bf_lo(g4.x), bf_hi(g4.x), bf_lo(g4.y), bf_hi(g4.y)} * acc[ai][bj][m][0], v1 = (f32x4){bf_lo(g4.z), bf_hi(g4.z), bf_lo(g4.w), bf_hi(g4.w)} * acc[ai][bj][m][1];
;                     if (PASS == 1) { const u32x4 p4 = pw[m][bj]; v0 += (f32x4){bf_lo(p4.x), bf_hi(p4.x), bf_lo(p4.y), bf_hi(p4.y)}; v1 += (f32x4){bf_lo(p4.z), bf_hi(p4.z), bf_lo(p4.w), bf_hi(p4.w)}; }
;                     *(u32x4*)(MIX + off + bj * HALF) = pack8(v0, v1); } } }
	v_lshlrev_b32_e32 v230, 16, v180
	v_and_b32_e32 v231, 0xffff0000, v180
	v_lshlrev_b32_e32 v180, 16, v181
	v_and_b32_e32 v181, 0xffff0000, v181
	v_lshlrev_b32_e32 v236, 16, v182
	v_and_b32_e32 v237, 0xffff0000, v182
	v_lshlrev_b32_e32 v182, 16, v183
	v_and_b32_e32 v183, 0xffff0000, v183
	v_lshlrev_b32_e32 v238, 16, v184
	v_and_b32_e32 v239, 0xffff0000, v184
	v_lshlrev_b32_e32 v184, 16, v185
	v_and_b32_e32 v185, 0xffff0000, v185
	v_lshlrev_b32_e32 v240, 16, v186
	v_and_b32_e32 v241, 0xffff0000, v186
	v_lshlrev_b32_e32 v186, 16, v187
	v_and_b32_e32 v187, 0xffff0000, v187
	v_lshlrev_b32_e32 v242, 16, v188
	v_and_b32_e32 v243, 0xffff0000, v188
	v_lshlrev_b32_e32 v188, 16, v189
	v_and_b32_e32 v189, 0xffff0000, v189
	v_lshlrev_b32_e32 v246, 16, v192
	v_and_b32_e32 v247, 0xffff0000, v192
	v_lshlrev_b32_e32 v192, 16, v193
	v_and_b32_e32 v193, 0xffff0000, v193
	v_pk_fma_f32 v[126:127], v[126:127], v[180:181], v[184:185]
	v_pk_fma_f32 v[124:125], v[124:125], v[230:231], v[238:239]
	v_pk_fma_f32 v[122:123], v[122:123], v[182:183], v[186:187]
	v_pk_fma_f32 v[120:121], v[120:121], v[236:237], v[240:241]
	v_pk_fma_f32 v[180:181], v[118:119], v[188:189], v[192:193]
	v_pk_fma_f32 v[182:183], v[116:117], v[242:243], v[246:247]
	v_cvt_pk_bf16_f32 v116, v124, v125
	v_cvt_pk_bf16_f32 v117, v126, v127
	v_cvt_pk_bf16_f32 v118, v120, v121
	v_cvt_pk_bf16_f32 v119, v122, v123
	v_lshlrev_b32_e32 v244, 16, v190
	v_and_b32_e32 v245, 0xffff0000, v190
	v_lshlrev_b32_e32 v190, 16, v191
	v_and_b32_e32 v191, 0xffff0000, v191
	v_lshlrev_b32_e32 v248, 16, v194
	global_store_dwordx4 v[218:219], v[116:119], off
	v_and_b32_e32 v249, 0xffff0000, v194
	v_lshlrev_b32_e32 v122, 16, v200
	v_lshlrev_b32_e32 v116, 16, v195
	v_and_b32_e32 v117, 0xffff0000, v195
	v_pk_fma_f32 v[116:117], v[114:115], v[190:191], v[116:117]
	v_pk_fma_f32 v[114:115], v[112:113], v[244:245], v[248:249]
	v_cvt_pk_bf16_f32 v112, v182, v183
	v_cvt_pk_bf16_f32 v113, v180, v181
	v_cvt_pk_bf16_f32 v114, v114, v115
	v_cvt_pk_bf16_f32 v115, v116, v117
	global_store_dwordx4 v[218:219], v[112:115], off offset:256
	v_lshlrev_b32_e32 v116, 16, v197
	v_and_b32_e32 v117, 0xffff0000, v197
	v_lshlrev_b32_e32 v114, 16, v196
	v_and_b32_e32 v115, 0xffff0000, v196
	v_and_b32_e32 v123, 0xffff0000, v200
	v_lshlrev_b32_e32 v124, 16, v201
	v_and_b32_e32 v125, 0xffff0000, v201
	v_lshlrev_b64 v[112:113], 12, v[212:213]
	v_lshlrev_b32_e32 v118, 16, v198
	v_and_b32_e32 v119, 0xffff0000, v198
	v_lshlrev_b32_e32 v120, 16, v199
	v_and_b32_e32 v121, 0xffff0000, v199
	v_pk_fma_f32 v[110:111], v[110:111], v[116:117], v[124:125]
	v_pk_fma_f32 v[108:109], v[108:109], v[114:115], v[122:123]
	v_lshlrev_b32_e32 v114, 16, v202
	v_and_b32_e32 v115, 0xffff0000, v202
	v_lshlrev_b32_e32 v116, 16, v203
	v_and_b32_e32 v117, 0xffff0000, v203
	v_pk_fma_f32 v[116:117], v[106:107], v[120:121], v[116:117]
	v_pk_fma_f32 v[106:107], v[104:105], v[118:119], v[114:115]
	v_cvt_pk_bf16_f32 v104, v108, v109
	v_lshl_add_u64 v[108:109], s[14:15], 0, v[112:113]
	v_cvt_pk_bf16_f32 v105, v110, v111
	v_cvt_pk_bf16_f32 v106, v106, v107
	v_cvt_pk_bf16_f32 v107, v116, v117
	v_lshl_add_u64 v[108:109], v[108:109], 0, v[164:165]
	global_store_dwordx4 v[108:109], v[104:107], off
	v_lshlrev_b32_e32 v114, 16, v208
	v_and_b32_e32 v115, 0xffff0000, v208
	v_lshlrev_b32_e32 v104, 16, v204
	v_and_b32_e32 v105, 0xffff0000, v204
	v_lshlrev_b32_e32 v106, 16, v205
	v_and_b32_e32 v107, 0xffff0000, v205
	v_lshlrev_b32_e32 v116, 16, v209
	v_and_b32_e32 v117, 0xffff0000, v209
	v_lshlrev_b32_e32 v110, 16, v206
	v_and_b32_e32 v111, 0xffff0000, v206
	v_lshlrev_b32_e32 v112, 16, v207
	v_and_b32_e32 v113, 0xffff0000, v207
	v_pk_fma_f32 v[102:103], v[102:103], v[106:107], v[116:117]
	v_pk_fma_f32 v[100:101], v[100:101], v[104:105], v[114:115]
	v_lshlrev_b32_e32 v104, 16, v210
	v_and_b32_e32 v105, 0xffff0000, v210
	v_lshlrev_b32_e32 v106, 16, v211
	v_and_b32_e32 v107, 0xffff0000, v211
	v_pk_fma_f32 v[106:107], v[98:99], v[112:113], v[106:107]
	v_pk_fma_f32 v[98:99], v[96:97], v[110:111], v[104:105]
	v_cvt_pk_bf16_f32 v96, v100, v101
	v_cvt_pk_bf16_f32 v97, v102, v103
	v_cvt_pk_bf16_f32 v98, v98, v99
	v_cvt_pk_bf16_f32 v99, v106, v107
	global_store_dwordx4 v[108:109], v[96:99], off offset:256
	v_lshlrev_b32_e32 v100, 16, v215
	v_and_b32_e32 v101, 0xffff0000, v215
	v_lshlrev_b32_e32 v98, 16, v214
	v_and_b32_e32 v99, 0xffff0000, v214
	v_lshlrev_b32_e32 v106, 16, v232
	v_and_b32_e32 v107, 0xffff0000, v232
	v_lshlrev_b32_e32 v108, 16, v233
	v_and_b32_e32 v109, 0xffff0000, v233
	v_lshlrev_b64 v[96:97], 12, v[172:173]
	v_lshlrev_b32_e32 v102, 16, v216
	v_and_b32_e32 v103, 0xffff0000, v216
	v_lshlrev_b32_e32 v104, 16, v217
	v_and_b32_e32 v105, 0xffff0000, v217
	v_pk_fma_f32 v[94:95], v[94:95], v[100:101], v[108:109]
	v_pk_fma_f32 v[92:93], v[92:93], v[98:99], v[106:107]
	v_lshlrev_b32_e32 v98, 16, v234
	v_and_b32_e32 v99, 0xffff0000, v234
	v_lshlrev_b32_e32 v100, 16, v235
	v_and_b32_e32 v101, 0xffff0000, v235
	v_pk_fma_f32 v[100:101], v[90:91], v[104:105], v[100:101]
	v_pk_fma_f32 v[90:91], v[88:89], v[102:103], v[98:99]
	v_cvt_pk_bf16_f32 v88, v92, v93
	v_lshl_add_u64 v[92:93], s[14:15], 0, v[96:97]
	v_cvt_pk_bf16_f32 v89, v94, v95
	v_cvt_pk_bf16_f32 v90, v90, v91
	v_cvt_pk_bf16_f32 v91, v100, v101
	v_lshl_add_u64 v[92:93], v[92:93], 0, v[164:165]
	global_store_dwordx4 v[92:93], v[88:91], off
	v_lshlrev_b32_e32 v98, 16, v144
	v_and_b32_e32 v99, 0xffff0000, v144
	v_lshlrev_b32_e32 v88, 16, v222
	v_and_b32_e32 v89, 0xffff0000, v222
	v_lshlrev_b32_e32 v90, 16, v223
	v_and_b32_e32 v91, 0xffff0000, v223
	v_lshlrev_b32_e32 v100, 16, v145
	v_and_b32_e32 v101, 0xffff0000, v145
	v_lshlrev_b32_e32 v94, 16, v224
; __device__ __forceinline__ float bf_lo(unsigned w) { return __uint_as_float(w << 16); }
; __device__ __forceinline__ float bf_hi(unsigned w) { return __uint_as_float(w & 0xffff0000u); }
; __device__ __forceinline__ u32x4 pack8(const f32x4 a, const f32x4 b) { u32x4 w; w.x = cvt_pk_bf16(a[0], a[1]); w.y = cvt_pk_bf16(a[2], a[3]); w.z = cvt_pk_bf16(b[0], b[1]); w.w = cvt_pk_bf16(b[2], b[3]); return w; }
;     __device__ __forceinline__ void operator()(const f32x4 (&acc)[2][2][4][2], const Unit& u, int wr, int wc, int fr, int fq) const {
;     ...
;         for (int ai = 0; ai < 2; ++ai) { u32x4 gw[4][2], pw[4][2];
; #pragma unroll
;             for (int m = 0; m < 4; ++m) { const size_t off = (size_t)(row0 + ai * HALF + m * 16) * 2048 + col0;
; #pragma unroll
;                 for (int bj = 0; bj < 2; ++bj) { gw[m][bj] = *(const u32x4*)(G + off + bj * HALF); if (PASS == 1) pw[m][bj] = *(const u32x4*)(MIX + off + bj * HALF); } }
; #pragma unroll
;             for (int m = 0; m < 4; ++m) { const size_t off = (size_t)(row0 + ai * HALF + m * 16) * 2048 + col0;
; #pragma unroll
;                 for (int bj = 0; bj < 2; ++bj) { const u32x4 g4 = gw[m][bj];
;                     f32x4 v0 = (f32x4){bf_lo(g4.x), bf_hi(g4.x), bf_lo(g4.y), bf_hi(g4.y)} * acc[ai][bj][m][0], v1 = (f32x4){bf_lo(g4.z), bf_hi(g4.z), bf_lo(g4.w), bf_hi(g4.w)} * acc[ai][bj][m][1];
;                     if (PASS == 1) { const u32x4 p4 = pw[m][bj]; v0 += (f32x4){bf_lo(p4.x), bf_hi(p4.x), bf_lo(p4.y), bf_hi(p4.y)}; v1 += (f32x4){bf_lo(p4.z), bf_hi(p4.z), bf_lo(p4.w), bf_hi(p4.w)}; }
;                     *(u32x4*)(MIX + off + bj * HALF) = pack8(v0, v1); } } }
	v_and_b32_e32 v95, 0xffff0000, v224
	v_lshlrev_b32_e32 v96, 16, v225
	v_and_b32_e32 v97, 0xffff0000, v225
	v_pk_fma_f32 v[86:87], v[86:87], v[90:91], v[100:101]
	v_pk_fma_f32 v[84:85], v[84:85], v[88:89], v[98:99]
	v_lshlrev_b32_e32 v88, 16, v146
	v_and_b32_e32 v89, 0xffff0000, v146
	v_lshlrev_b32_e32 v90, 16, v147
	v_and_b32_e32 v91, 0xffff0000, v147
	v_pk_fma_f32 v[90:91], v[82:83], v[96:97], v[90:91]
	v_pk_fma_f32 v[82:83], v[80:81], v[94:95], v[88:89]
	v_cvt_pk_bf16_f32 v80, v84, v85
	v_cvt_pk_bf16_f32 v81, v86, v87
	v_cvt_pk_bf16_f32 v82, v82, v83
	v_cvt_pk_bf16_f32 v83, v90, v91
	global_store_dwordx4 v[92:93], v[80:83], off offset:256
	v_lshlrev_b32_e32 v84, 16, v141
	v_and_b32_e32 v85, 0xffff0000, v141
	v_lshlrev_b32_e32 v82, 16, v140
	v_and_b32_e32 v83, 0xffff0000, v140
	v_lshlrev_b32_e32 v90, 16, v136
	v_and_b32_e32 v91, 0xffff0000, v136
	v_lshlrev_b32_e32 v92, 16, v137
	v_and_b32_e32 v93, 0xffff0000, v137
	v_lshlrev_b64 v[80:81], 12, v[170:171]
	v_lshlrev_b32_e32 v86, 16, v142
	v_and_b32_e32 v87, 0xffff0000, v142
	v_lshlrev_b32_e32 v88, 16, v143
	v_and_b32_e32 v89, 0xffff0000, v143
	v_pk_fma_f32 v[78:79], v[78:79], v[84:85], v[92:93]
	v_pk_fma_f32 v[76:77], v[76:77], v[82:83], v[90:91]
	v_lshlrev_b32_e32 v82, 16, v138
	v_and_b32_e32 v83, 0xffff0000, v138
	v_lshlrev_b32_e32 v84, 16, v139
	v_and_b32_e32 v85, 0xffff0000, v139
	v_pk_fma_f32 v[84:85], v[74:75], v[88:89], v[84:85]
	v_pk_fma_f32 v[74:75], v[72:73], v[86:87], v[82:83]
	v_cvt_pk_bf16_f32 v72, v76, v77
	v_lshl_add_u64 v[76:77], s[14:15], 0, v[80:81]
	v_cvt_pk_bf16_f32 v73, v78, v79
	v_cvt_pk_bf16_f32 v74, v74, v75
	v_cvt_pk_bf16_f32 v75, v84, v85
	v_lshl_add_u64 v[76:77], v[76:77], 0, v[164:165]
	global_store_dwordx4 v[76:77], v[72:75], off
	v_lshlrev_b32_e32 v82, 16, v128
	v_and_b32_e32 v83, 0xffff0000, v128
	v_lshlrev_b32_e32 v72, 16, v132
	v_and_b32_e32 v73, 0xffff0000, v132
	v_lshlrev_b32_e32 v74, 16, v133
	v_and_b32_e32 v75, 0xffff0000, v133
	v_lshlrev_b32_e32 v84, 16, v129
	v_and_b32_e32 v85, 0xffff0000, v129
	v_lshlrev_b32_e32 v78, 16, v134
	v_and_b32_e32 v79, 0xffff0000, v134
	v_lshlrev_b32_e32 v80, 16, v135
	v_and_b32_e32 v81, 0xffff0000, v135
	v_pk_fma_f32 v[70:71], v[70:71], v[74:75], v[84:85]
	v_pk_fma_f32 v[68:69], v[68:69], v[72:73], v[82:83]
	v_lshlrev_b32_e32 v72, 16, v130
	v_and_b32_e32 v73, 0xffff0000, v130
	v_lshlrev_b32_e32 v74, 16, v131
	v_and_b32_e32 v75, 0xffff0000, v131
	v_pk_fma_f32 v[74:75], v[66:67], v[80:81], v[74:75]
	v_pk_fma_f32 v[66:67], v[64:65], v[78:79], v[72:73]
	v_add_u32_e32 v130, 0x80, v168
	v_cvt_pk_bf16_f32 v64, v68, v69
	v_cvt_pk_bf16_f32 v65, v70, v71
	v_cvt_pk_bf16_f32 v66, v66, v67
	v_cvt_pk_bf16_f32 v67, v74, v75
	v_ashrrev_i32_e32 v131, 31, v130
	global_store_dwordx4 v[76:77], v[64:67], off offset:256
	v_add_u32_e32 v132, 0x90, v168
	v_ashrrev_i32_e32 v133, 31, v132
	v_lshlrev_b64 v[64:65], 11, v[130:131]
	v_lshl_add_u64 v[64:65], v[64:65], 0, v[166:167]
	v_lshlrev_b64 v[64:65], 1, v[64:65]
	v_lshl_add_u64 v[66:67], s[12:13], 0, v[64:65]
	global_load_dwordx4 v[90:93], v[66:67], off
	v_lshl_add_u64 v[64:65], s[14:15], 0, v[64:65]
	global_load_dwordx4 v[94:97], v[64:65], off
	global_load_dwordx4 v[98:101], v[66:67], off offset:256
	global_load_dwordx4 v[102:105], v[64:65], off offset:256
	v_lshlrev_b64 v[64:65], 11, v[132:133]
	v_lshl_add_u64 v[64:65], v[64:65], 0, v[166:167]
	v_lshlrev_b64 v[64:65], 1, v[64:65]
	v_lshl_add_u64 v[66:67], s[12:13], 0, v[64:65]
	v_lshl_add_u64 v[64:65], s[14:15], 0, v[64:65]
	global_load_dwordx4 v[106:109], v[66:67], off
	global_load_dwordx4 v[110:113], v[66:67], off offset:256
	global_load_dwordx4 v[114:117], v[64:65], off
	global_load_dwordx4 v[118:121], v[64:65], off offset:256
	v_add_u32_e32 v134, 0xa0, v168
	v_ashrrev_i32_e32 v135, 31, v134
	v_lshlrev_b64 v[64:65], 11, v[134:135]
	v_lshl_add_u64 v[64:65], v[64:65], 0, v[166:167]
	v_lshlrev_b64 v[64:65], 1, v[64:65]
	v_lshl_add_u64 v[66:67], s[12:13], 0, v[64:65]
	v_lshl_add_u64 v[64:65], s[14:15], 0, v[64:65]
	global_load_dwordx4 v[122:125], v[66:67], off
	global_load_dwordx4 v[84:87], v[66:67], off offset:256
	global_load_dwordx4 v[126:129], v[64:65], off
	global_load_dwordx4 v[80:83], v[64:65], off offset:256
	v_add_u32_e32 v88, 0xb0, v168
	v_ashrrev_i32_e32 v89, 31, v88
	v_lshlrev_b64 v[64:65], 11, v[88:89]
	v_lshl_add_u64 v[64:65], v[64:65], 0, v[166:167]
	v_lshlrev_b64 v[64:65], 1, v[64:65]
	v_lshl_add_u64 v[66:67], s[12:13], 0, v[64:65]
	v_lshl_add_u64 v[64:65], s[14:15], 0, v[64:65]
	global_load_dwordx4 v[76:79], v[66:67], off
	global_load_dwordx4 v[68:71], v[66:67], off offset:256
	global_load_dwordx4 v[72:75], v[64:65], off
	s_nop 0
	global_load_dwordx4 v[64:67], v[64:65], off offset:256
	v_lshlrev_b64 v[130:131], 12, v[130:131]
	s_waitcnt vmcnt(15)
	v_lshlrev_b32_e32 v136, 16, v90
	v_and_b32_e32 v137, 0xffff0000, v90
	v_lshlrev_b32_e32 v90, 16, v91
	v_and_b32_e32 v91, 0xffff0000, v91
	s_waitcnt vmcnt(14)
	v_lshlrev_b32_e32 v140, 16, v94
	v_and_b32_e32 v141, 0xffff0000, v94
	v_lshlrev_b32_e32 v94, 16, v95
	v_and_b32_e32 v95, 0xffff0000, v95
	v_lshlrev_b32_e32 v138, 16, v92
	v_and_b32_e32 v139, 0xffff0000, v92
	v_lshlrev_b32_e32 v92, 16, v93
	v_and_b32_e32 v93, 0xffff0000, v93
	v_pk_fma_f32 v[62:63], v[62:63], v[90:91], v[94:95]
	v_pk_fma_f32 v[60:61], v[60:61], v[136:137], v[140:141]
	v_lshlrev_b32_e32 v90, 16, v96
	v_and_b32_e32 v91, 0xffff0000, v96
	v_lshlrev_b32_e32 v94, 16, v97
	v_and_b32_e32 v95, 0xffff0000, v97
	v_pk_fma_f32 v[92:93], v[58:59], v[92:93], v[94:95]
	v_pk_fma_f32 v[58:59], v[56:57], v[138:139], v[90:91]
	v_cvt_pk_bf16_f32 v56, v60, v61
	v_lshl_add_u64 v[60:61], s[14:15], 0, v[130:131]
	v_cvt_pk_bf16_f32 v57, v62, v63
	v_cvt_pk_bf16_f32 v58, v58, v59
	v_cvt_pk_bf16_f32 v59, v92, v93
	v_lshl_add_u64 v[60:61], v[60:61], 0, v[164:165]
	global_store_dwordx4 v[60:61], v[56:59], off
	s_waitcnt vmcnt(13)
; __device__ __forceinline__ float bf_lo(unsigned w) { return __uint_as_float(w << 16); }
; __device__ __forceinline__ float bf_hi(unsigned w) { return __uint_as_float(w & 0xffff0000u); }
; __device__ __forceinline__ u32x4 pack8(const f32x4 a, const f32x4 b) { u32x4 w; w.x = cvt_pk_bf16(a[0], a[1]); w.y = cvt_pk_bf16(a[2], a[3]); w.z = cvt_pk_bf16(b[0], b[1]); w.w = cvt_pk_bf16(b[2], b[3]); return w; }
;     __device__ __forceinline__ void operator()(const f32x4 (&acc)[2][2][4][2], const Unit& u, int wr, int wc, int fr, int fq) const {
;     ...
;             for (int m = 0; m < 4; ++m) { const size_t off = (size_t)(row0 + ai * HALF + m * 16) * 2048 + col0;
; #pragma unroll
;                 for (int bj = 0; bj < 2; ++bj) { const u32x4 g4 = gw[m][bj];
;                     f32x4 v0 = (f32x4){bf_lo(g4.x), bf_hi(g4.x), bf_lo(g4.y), bf_hi(g4.y)} * acc[ai][bj][m][0], v1 = (f32x4){bf_lo(g4.z), bf_hi(g4.z), bf_lo(g4.w), bf_hi(g4.w)} * acc[ai][bj][m][1];
;                     if (PASS == 1) { const u32x4 p4 = pw[m][bj]; v0 += (f32x4){bf_lo(p4.x), bf_hi(p4.x), bf_lo(p4.y), bf_hi(p4.y)}; v1 += (f32x4){bf_lo(p4.z), bf_hi(p4.z), bf_lo(p4.w), bf_hi(p4.w)}; }
;                     *(u32x4*)(MIX + off + bj * HALF) = pack8(v0, v1); } } }
	v_lshlrev_b32_e32 v92, 16, v102
	v_and_b32_e32 v93, 0xffff0000, v102
	v_lshlrev_b32_e32 v56, 16, v98
	v_and_b32_e32 v57, 0xffff0000, v98
	v_lshlrev_b32_e32 v58, 16, v99
	v_and_b32_e32 v59, 0xffff0000, v99
	v_lshlrev_b32_e32 v94, 16, v103
	v_and_b32_e32 v95, 0xffff0000, v103
	v_lshlrev_b32_e32 v62, 16, v100
	v_and_b32_e32 v63, 0xffff0000, v100
	v_lshlrev_b32_e32 v90, 16, v101
	v_and_b32_e32 v91, 0xffff0000, v101
	v_pk_fma_f32 v[54:55], v[54:55], v[58:59], v[94:95]
	v_pk_fma_f32 v[52:53], v[52:53], v[56:57], v[92:93]
	v_lshlrev_b32_e32 v56, 16, v104
	v_and_b32_e32 v57, 0xffff0000, v104
	v_lshlrev_b32_e32 v58, 16, v105
	v_and_b32_e32 v59, 0xffff0000, v105
	v_pk_fma_f32 v[58:59], v[50:51], v[90:91], v[58:59]
	v_pk_fma_f32 v[50:51], v[48:49], v[62:63], v[56:57]
	v_cvt_pk_bf16_f32 v48, v52, v53
	v_cvt_pk_bf16_f32 v49, v54, v55
	v_cvt_pk_bf16_f32 v50, v50, v51
	v_cvt_pk_bf16_f32 v51, v58, v59
	global_store_dwordx4 v[60:61], v[48:51], off offset:256
	s_waitcnt vmcnt(13)
	v_lshlrev_b32_e32 v52, 16, v107
	v_and_b32_e32 v53, 0xffff0000, v107
	v_lshlrev_b32_e32 v50, 16, v106
	v_and_b32_e32 v51, 0xffff0000, v106
	s_waitcnt vmcnt(11)
	v_lshlrev_b32_e32 v58, 16, v114
	v_and_b32_e32 v59, 0xffff0000, v114
	v_lshlrev_b32_e32 v60, 16, v115
	v_and_b32_e32 v61, 0xffff0000, v115
	v_lshlrev_b64 v[48:49], 12, v[132:133]
	v_lshlrev_b32_e32 v54, 16, v108
	v_and_b32_e32 v55, 0xffff0000, v108
	v_lshlrev_b32_e32 v56, 16, v109
	v_and_b32_e32 v57, 0xffff0000, v109
	v_pk_fma_f32 v[46:47], v[46:47], v[52:53], v[60:61]
	v_pk_fma_f32 v[44:45], v[44:45], v[50:51], v[58:59]
	v_lshlrev_b32_e32 v50, 16, v116
	v_and_b32_e32 v51, 0xffff0000, v116
	v_lshlrev_b32_e32 v52, 16, v117
	v_and_b32_e32 v53, 0xffff0000, v117
	v_pk_fma_f32 v[52:53], v[42:43], v[56:57], v[52:53]
	v_pk_fma_f32 v[42:43], v[40:41], v[54:55], v[50:51]
	v_cvt_pk_bf16_f32 v40, v44, v45
	v_lshl_add_u64 v[44:45], s[14:15], 0, v[48:49]
	v_cvt_pk_bf16_f32 v41, v46, v47
	v_cvt_pk_bf16_f32 v42, v42, v43
	v_cvt_pk_bf16_f32 v43, v52, v53
	v_lshl_add_u64 v[44:45], v[44:45], 0, v[164:165]
	global_store_dwordx4 v[44:45], v[40:43], off
	s_waitcnt vmcnt(11)
	v_lshlrev_b32_e32 v50, 16, v118
	v_and_b32_e32 v51, 0xffff0000, v118
	v_lshlrev_b32_e32 v40, 16, v110
	v_and_b32_e32 v41, 0xffff0000, v110
	v_lshlrev_b32_e32 v42, 16, v111
	v_and_b32_e32 v43, 0xffff0000, v111
	v_lshlrev_b32_e32 v52, 16, v119
	v_and_b32_e32 v53, 0xffff0000, v119
	v_lshlrev_b32_e32 v46, 16, v112
	v_and_b32_e32 v47, 0xffff0000, v112
	v_lshlrev_b32_e32 v48, 16, v113
	v_and_b32_e32 v49, 0xffff0000, v113
	v_pk_fma_f32 v[38:39], v[38:39], v[42:43], v[52:53]
	v_pk_fma_f32 v[36:37], v[36:37], v[40:41], v[50:51]
	v_lshlrev_b32_e32 v40, 16, v120
	v_and_b32_e32 v41, 0xffff0000, v120
	v_lshlrev_b32_e32 v42, 16, v121
	v_and_b32_e32 v43, 0xffff0000, v121
	v_pk_fma_f32 v[42:43], v[34:35], v[48:49], v[42:43]
	v_pk_fma_f32 v[34:35], v[32:33], v[46:47], v[40:41]
	v_cvt_pk_bf16_f32 v32, v36, v37
	v_cvt_pk_bf16_f32 v33, v38, v39
	v_cvt_pk_bf16_f32 v34, v34, v35
	v_cvt_pk_bf16_f32 v35, v42, v43
	global_store_dwordx4 v[44:45], v[32:35], off offset:256
	s_waitcnt vmcnt(11)
	v_lshlrev_b32_e32 v36, 16, v123
	v_and_b32_e32 v37, 0xffff0000, v123
	v_lshlrev_b32_e32 v34, 16, v122
	v_and_b32_e32 v35, 0xffff0000, v122
	s_waitcnt vmcnt(9)
; __device__ __forceinline__ float bf_lo(unsigned w) { return __uint_as_float(w << 16); }
; __device__ __forceinline__ float bf_hi(unsigned w) { return __uint_as_float(w & 0xffff0000u); }
; __device__ __forceinline__ u32x4 pack8(const f32x4 a, const f32x4 b) { u32x4 w; w.x = cvt_pk_bf16(a[0], a[1]); w.y = cvt_pk_bf16(a[2], a[3]); w.z = cvt_pk_bf16(b[0], b[1]); w.w = cvt_pk_bf16(b[2], b[3]); return w; }
; #define PG8_WAIT_V(n) asm volatile("s_waitcnt vmcnt(" #n ")" ::: "memory")
; #define PG8_BAR __builtin_amdgcn_s_barrier()
;     __device__ __forceinline__ void operator()(const f32x4 (&acc)[2][2][4][2], const Unit& u, int wr, int wc, int fr, int fq) const {
;     ...
;             for (int m = 0; m < 4; ++m) { const size_t off = (size_t)(row0 + ai * HALF + m * 16) * 2048 + col0;
; #pragma unroll
;                 for (int bj = 0; bj < 2; ++bj) { const u32x4 g4 = gw[m][bj];
;                     f32x4 v0 = (f32x4){bf_lo(g4.x), bf_hi(g4.x), bf_lo(g4.y), bf_hi(g4.y)} * acc[ai][bj][m][0], v1 = (f32x4){bf_lo(g4.z), bf_hi(g4.z), bf_lo(g4.w), bf_hi(g4.w)} * acc[ai][bj][m][1];
;                     if (PASS == 1) { const u32x4 p4 = pw[m][bj]; v0 += (f32x4){bf_lo(p4.x), bf_hi(p4.x), bf_lo(p4.y), bf_hi(p4.y)}; v1 += (f32x4){bf_lo(p4.z), bf_hi(p4.z), bf_lo(p4.w), bf_hi(p4.w)}; }
;                     *(u32x4*)(MIX + off + bj * HALF) = pack8(v0, v1); } } }
; template <class Epi, class Sched, bool ALIGN_EPI = false, bool SP2 = false>
; __device__ __forceinline__ void gemm_phase(PG8_LAS unsigned char* lds, const Gemm g, const Sched& S, const Epi& E) {
;     ...
;     PG8_WAIT_V(0);
;     if constexpr (!ALIGN_EPI) { if (wr == 0) PG8_BAR; }
;     PG8_BAR;
	v_lshlrev_b32_e32 v42, 16, v126
	v_and_b32_e32 v43, 0xffff0000, v126
	v_lshlrev_b32_e32 v44, 16, v127
	v_and_b32_e32 v45, 0xffff0000, v127
	v_lshlrev_b64 v[32:33], 12, v[134:135]
	v_lshlrev_b32_e32 v38, 16, v124
	v_and_b32_e32 v39, 0xffff0000, v124
	v_lshlrev_b32_e32 v40, 16, v125
	v_and_b32_e32 v41, 0xffff0000, v125
	v_pk_fma_f32 v[30:31], v[30:31], v[36:37], v[44:45]
	v_pk_fma_f32 v[28:29], v[28:29], v[34:35], v[42:43]
	v_lshlrev_b32_e32 v34, 16, v128
	v_and_b32_e32 v35, 0xffff0000, v128
	v_lshlrev_b32_e32 v36, 16, v129
	v_and_b32_e32 v37, 0xffff0000, v129
	v_pk_fma_f32 v[36:37], v[26:27], v[40:41], v[36:37]
	v_pk_fma_f32 v[26:27], v[24:25], v[38:39], v[34:35]
	v_cvt_pk_bf16_f32 v24, v28, v29
	v_lshl_add_u64 v[28:29], s[14:15], 0, v[32:33]
	v_cvt_pk_bf16_f32 v25, v30, v31
	v_cvt_pk_bf16_f32 v26, v26, v27
	v_cvt_pk_bf16_f32 v27, v36, v37
	v_lshl_add_u64 v[28:29], v[28:29], 0, v[164:165]
	global_store_dwordx4 v[28:29], v[24:27], off
	s_waitcnt vmcnt(9)
	v_lshlrev_b32_e32 v34, 16, v80
	v_and_b32_e32 v35, 0xffff0000, v80
	v_lshlrev_b32_e32 v24, 16, v84
	v_and_b32_e32 v25, 0xffff0000, v84
	v_lshlrev_b32_e32 v26, 16, v85
	v_and_b32_e32 v27, 0xffff0000, v85
	v_lshlrev_b32_e32 v36, 16, v81
	v_and_b32_e32 v37, 0xffff0000, v81
	v_lshlrev_b32_e32 v30, 16, v86
	v_and_b32_e32 v31, 0xffff0000, v86
	v_lshlrev_b32_e32 v32, 16, v87
	v_and_b32_e32 v33, 0xffff0000, v87
	v_pk_fma_f32 v[22:23], v[22:23], v[26:27], v[36:37]
	v_pk_fma_f32 v[20:21], v[20:21], v[24:25], v[34:35]
	v_lshlrev_b32_e32 v24, 16, v82
	v_and_b32_e32 v25, 0xffff0000, v82
	v_lshlrev_b32_e32 v26, 16, v83
	v_and_b32_e32 v27, 0xffff0000, v83
	v_pk_fma_f32 v[26:27], v[18:19], v[32:33], v[26:27]
	v_pk_fma_f32 v[18:19], v[16:17], v[30:31], v[24:25]
	v_cvt_pk_bf16_f32 v16, v20, v21
	v_cvt_pk_bf16_f32 v17, v22, v23
	v_cvt_pk_bf16_f32 v18, v18, v19
	v_cvt_pk_bf16_f32 v19, v26, v27
	global_store_dwordx4 v[28:29], v[16:19], off offset:256
	s_waitcnt vmcnt(9)
	v_lshlrev_b32_e32 v20, 16, v77
	v_and_b32_e32 v21, 0xffff0000, v77
	v_lshlrev_b32_e32 v18, 16, v76
	v_and_b32_e32 v19, 0xffff0000, v76
	s_waitcnt vmcnt(7)
	v_lshlrev_b32_e32 v26, 16, v72
	v_and_b32_e32 v27, 0xffff0000, v72
	v_lshlrev_b32_e32 v28, 16, v73
	v_and_b32_e32 v29, 0xffff0000, v73
	v_lshlrev_b64 v[16:17], 12, v[88:89]
	v_lshlrev_b32_e32 v22, 16, v78
	v_and_b32_e32 v23, 0xffff0000, v78
	v_lshlrev_b32_e32 v24, 16, v79
	v_and_b32_e32 v25, 0xffff0000, v79
	v_pk_fma_f32 v[14:15], v[14:15], v[20:21], v[28:29]
	v_pk_fma_f32 v[12:13], v[12:13], v[18:19], v[26:27]
	v_lshlrev_b32_e32 v18, 16, v74
	v_and_b32_e32 v19, 0xffff0000, v74
	v_lshlrev_b32_e32 v20, 16, v75
	v_and_b32_e32 v21, 0xffff0000, v75
	v_pk_fma_f32 v[20:21], v[10:11], v[24:25], v[20:21]
	v_pk_fma_f32 v[10:11], v[8:9], v[22:23], v[18:19]
	v_cvt_pk_bf16_f32 v8, v12, v13
	v_lshl_add_u64 v[12:13], s[14:15], 0, v[16:17]
	v_cvt_pk_bf16_f32 v9, v14, v15
	v_cvt_pk_bf16_f32 v10, v10, v11
	v_cvt_pk_bf16_f32 v11, v20, v21
	v_lshl_add_u64 v[12:13], v[12:13], 0, v[164:165]
	global_store_dwordx4 v[12:13], v[8:11], off
	s_waitcnt vmcnt(7)
	v_lshlrev_b32_e32 v18, 16, v64
	v_and_b32_e32 v19, 0xffff0000, v64
	v_lshlrev_b32_e32 v8, 16, v68
	v_and_b32_e32 v9, 0xffff0000, v68
	v_lshlrev_b32_e32 v10, 16, v69
	v_and_b32_e32 v11, 0xffff0000, v69
	v_lshlrev_b32_e32 v20, 16, v65
	v_and_b32_e32 v21, 0xffff0000, v65
	v_lshlrev_b32_e32 v14, 16, v70
	v_and_b32_e32 v15, 0xffff0000, v70
	v_lshlrev_b32_e32 v16, 16, v71
	v_and_b32_e32 v17, 0xffff0000, v71
	v_pk_fma_f32 v[6:7], v[6:7], v[10:11], v[20:21]
	v_pk_fma_f32 v[4:5], v[4:5], v[8:9], v[18:19]
	v_lshlrev_b32_e32 v8, 16, v66
	v_and_b32_e32 v9, 0xffff0000, v66
	v_lshlrev_b32_e32 v10, 16, v67
	v_and_b32_e32 v11, 0xffff0000, v67
	v_pk_fma_f32 v[10:11], v[2:3], v[16:17], v[10:11]
	v_pk_fma_f32 v[2:3], v[0:1], v[14:15], v[8:9]
	v_cvt_pk_bf16_f32 v0, v4, v5
	v_cvt_pk_bf16_f32 v1, v6, v7
	v_cvt_pk_bf16_f32 v2, v2, v3
	v_cvt_pk_bf16_f32 v3, v10, v11
	global_store_dwordx4 v[12:13], v[0:3], off offset:256
	s_cbranch_vccz .LBB0_748
	s_waitcnt vmcnt(0)
	s_cmpk_gt_u32 s3, 0xff
	s_cbranch_scc1 .LBB0_759
	s_barrier

; #define PG8_STAGE(bufoff, gbase, voff) do { _Pragma("unroll") for (int _i = 0; _i < 2; ++_i) \
;         __builtin_amdgcn_global_load_lds((const unsigned*)((const char*)(gbase) + (voff)[_i]), (PG8_LAS unsigned*)(lds + (bufoff) + ldsw + _i * 8192), 16, 0, 0); } while (0)
; #define PG8_LDA(dst, b, h) do { _Pragma("unroll") for (int m = 0; m < 4; ++m) _Pragma("unroll") for (int k = 0; k < 2; ++k) dst[m][k] = *(const PG8_LAS bf16x8*)(lds + PG8_SA(b, h) + aoff + m * 2048 + k * 1024); } while (0)
; #define PG8_LDB(dst, b, h) do { _Pragma("unroll") for (int n = 0; n < 2; ++n) _Pragma("unroll") for (int k = 0; k < 2; ++k) dst[n][k] = *(const PG8_LAS bf16x8*)(lds + PG8_SB(b, h) + boff + n * 2048 + k * 1024); } while (0)
; #define PG8_WAIT_V(n) asm volatile("s_waitcnt vmcnt(" #n ")" ::: "memory")
; #define PG8_WAIT_L(n) asm volatile("s_waitcnt lgkmcnt(" #n ")" ::: "memory")
; #define PG8_BAR __builtin_amdgcn_s_barrier()
; #define PG8_SCHED __builtin_amdgcn_sched_barrier(0)
; template <class Epi, class Sched, bool ALIGN_EPI = false, bool SP2 = false>
; __device__ __forceinline__ void gemm_phase(PG8_LAS unsigned char* lds, const Gemm g, const Sched& S, const Epi& E) {
;     ...
;         const bool has_next = S.next(ui + 1, nxt);
;         const char* nA = has_next ? (const char*)g.A + (size_t)nxt.pm * tstep : cA; const char* nB = has_next ? (const char*)g.Bt + (size_t)nxt.pn * tstep : cB;
;         for (int t = 0; t < nt; t += 2) {
;             const bool last = (t == nt - 2);
;             const char* a1 = cA + (size_t)(t + 1) * kstep;
;             const char* a2 = last ? nA : cA + (size_t)(t + 2) * kstep; const char* b2 = last ? nB : cB + (size_t)(t + 2) * kstep;
;             const char* a3 = a2 + kstep; const char* b3 = b2 + kstep;
;             if (last && has_next) S.a_ready(nxt);
;             if constexpr (SP2) {
;             PG8_LDB(B0, 0, 0); PG8_LDB(B1, 0, 1); PG8_SCHED; PG8_LDA(At, 0, 0); PG8_STAGE(PG8_SA(1, 1), a1 + hstep, voffA);
;             PG8_WAIT_V(8); PG8_WAIT_L(0); PG8_BAR; PG8_MMA(0, 0, At, B0); PG8_MMA(0, 1, At, B1); PG8_BAR; PG8_SCHED;
;             PG8_LDA(At, 0, 1); PG8_STAGE(PG8_SB(0, 0), b2, voffB); PG8_STAGE(PG8_SB(0, 1), b2 + hstep, voffB); PG8_STAGE(PG8_SA(0, 0), a2, voffA);
;             PG8_WAIT_V(8); PG8_WAIT_L(0); PG8_BAR; PG8_MMA(1, 0, At, B0); PG8_MMA(1, 1, At, B1); PG8_BAR; PG8_SCHED;
.LBB0_826:
	s_ashr_i32 s39, s38, 31
	v_cmp_lt_i64_e32 vcc, s[40:41], v[156:157]
	s_lshl_b64 s[40:41], s[38:39], 20
	s_add_u32 s40, s9, s40
	s_addc_u32 s41, s22, s41
	s_and_b64 s[42:43], vcc, exec
	s_cselect_b32 s39, s41, s47
	s_cselect_b32 s67, s40, s46
	s_ashr_i32 s37, s36, 31
	s_lshl_b64 s[42:43], s[36:37], 20
	s_add_u32 s42, s23, s42
	s_addc_u32 s43, s52, s43
	s_and_b64 s[50:51], vcc, exec
	s_cselect_b32 s37, s43, s49
	s_cselect_b32 s68, s42, s48
	s_add_u32 s46, s46, 0x80080
	s_addc_u32 s47, s47, 0
	s_add_u32 s69, s48, 0x100
	s_addc_u32 s70, s49, 0
	s_mov_b32 s71, -2
	ds_read_b128 v[128:131], v169
	ds_read_b128 v[132:135], v169 offset:1024
	ds_read_b128 v[136:139], v169 offset:2048
	ds_read_b128 v[140:143], v169 offset:3072
	ds_read_b128 v[160:163], v170
	ds_read_b128 v[172:175], v170 offset:1024
	ds_read_b128 v[176:179], v170 offset:2048
	ds_read_b128 v[180:183], v170 offset:3072
	s_add_u32 s48, s46, 0xfff80080
	s_addc_u32 s49, s47, -1
	s_cmp_eq_u32 s71, 28
	s_cselect_b32 s51, s39, s49
	s_cselect_b32 s50, s67, s48
	s_cselect_b32 s49, s37, s70
	s_cselect_b32 s48, s68, s69
	s_add_i32 m0, s45, 0xc000
	ds_read_b128 v[184:187], v171
	ds_read_b128 v[188:191], v171 offset:1024
	ds_read_b128 v[192:195], v171 offset:2048
	ds_read_b128 v[196:199], v171 offset:3072
	ds_read_b128 v[200:203], v171 offset:4096
	ds_read_b128 v[204:207], v171 offset:5120
	ds_read_b128 v[208:211], v171 offset:6144
	ds_read_b128 v[214:217], v171 offset:7168
	global_load_lds_dwordx4 v152, s[46:47]
	s_add_i32 m0, s45, 0xe000
	s_nop 0
	global_load_lds_dwordx4 v154, s[46:47]
	s_waitcnt vmcnt(8)
	s_waitcnt lgkmcnt(0)
	s_barrier
	s_waitcnt lgkmcnt(0)
	v_mfma_f32_16x16x32_bf16 v[124:127], v[128:131], v[184:187], 0
	v_mfma_f32_16x16x32_bf16 v[120:123], v[136:139], v[184:187], 0
	v_mfma_f32_16x16x32_bf16 v[116:119], v[128:131], v[192:195], 0
	v_mfma_f32_16x16x32_bf16 v[112:115], v[136:139], v[192:195], 0
	v_mfma_f32_16x16x32_bf16 v[108:111], v[128:131], v[200:203], 0
	v_mfma_f32_16x16x32_bf16 v[96:99], v[136:139], v[200:203], 0
	v_mfma_f32_16x16x32_bf16 v[80:83], v[128:131], v[208:211], 0
	v_mfma_f32_16x16x32_bf16 v[72:75], v[136:139], v[208:211], 0
	v_mfma_f32_16x16x32_bf16 v[124:127], v[132:135], v[188:191], v[124:127]
	v_mfma_f32_16x16x32_bf16 v[120:123], v[140:143], v[188:191], v[120:123]
	v_mfma_f32_16x16x32_bf16 v[116:119], v[132:135], v[196:199], v[116:119]
	v_mfma_f32_16x16x32_bf16 v[112:115], v[140:143], v[196:199], v[112:115]
	v_mfma_f32_16x16x32_bf16 v[108:111], v[132:135], v[204:207], v[108:111]
	v_mfma_f32_16x16x32_bf16 v[96:99], v[140:143], v[204:207], v[96:99]
	v_mfma_f32_16x16x32_bf16 v[80:83], v[132:135], v[214:217], v[80:83]
	v_mfma_f32_16x16x32_bf16 v[72:75], v[140:143], v[214:217], v[72:75]
	v_mfma_f32_16x16x32_bf16 v[104:107], v[160:163], v[184:187], 0
	v_mfma_f32_16x16x32_bf16 v[100:103], v[176:179], v[184:187], 0
	v_mfma_f32_16x16x32_bf16 v[92:95], v[160:163], v[192:195], 0
	v_mfma_f32_16x16x32_bf16 v[88:91], v[176:179], v[192:195], 0
	v_mfma_f32_16x16x32_bf16 v[84:87], v[160:163], v[200:203], 0
	v_mfma_f32_16x16x32_bf16 v[76:79], v[176:179], v[200:203], 0
	v_mfma_f32_16x16x32_bf16 v[68:71], v[160:163], v[208:211], 0
	v_mfma_f32_16x16x32_bf16 v[64:67], v[176:179], v[208:211], 0
	v_mfma_f32_16x16x32_bf16 v[104:107], v[172:175], v[188:191], v[104:107]
	v_mfma_f32_16x16x32_bf16 v[100:103], v[180:183], v[188:191], v[100:103]
	v_mfma_f32_16x16x32_bf16 v[92:95], v[172:175], v[196:199], v[92:95]
	v_mfma_f32_16x16x32_bf16 v[88:91], v[180:183], v[196:199], v[88:91]
	v_mfma_f32_16x16x32_bf16 v[84:87], v[172:175], v[204:207], v[84:87]
	v_mfma_f32_16x16x32_bf16 v[76:79], v[180:183], v[204:207], v[76:79]
	v_mfma_f32_16x16x32_bf16 v[68:71], v[172:175], v[214:217], v[68:71]
	v_mfma_f32_16x16x32_bf16 v[64:67], v[180:183], v[214:217], v[64:67]
	s_barrier
	s_add_i32 s72, s64, s53
	s_mov_b32 m0, s72
	ds_read_b128 v[184:187], v171 offset:16384
	ds_read_b128 v[188:191], v171 offset:17408
	ds_read_b128 v[192:195], v171 offset:18432
	ds_read_b128 v[196:199], v171 offset:19456
	ds_read_b128 v[200:203], v171 offset:20480
	ds_read_b128 v[204:207], v171 offset:21504
	ds_read_b128 v[208:211], v171 offset:22528
	ds_read_b128 v[214:217], v171 offset:23552
	global_load_lds_dwordx4 v146, s[48:49]
	s_add_i32 m0, s72, 0x2000
	s_add_u32 s72, s48, 0x80000
	s_addc_u32 s73, s49, 0
	s_add_i32 s74, s65, s53
	global_load_lds_dwordx4 v150, s[48:49]
	s_mov_b32 m0, s74
	s_nop 0
	global_load_lds_dwordx4 v146, s[72:73]
	s_add_i32 m0, s74, 0x2000
	s_nop 0
	global_load_lds_dwordx4 v150, s[72:73]
	s_mov_b32 m0, s45
	s_nop 0
	global_load_lds_dwordx4 v144, s[50:51]
	s_mov_b32 m0, s54
	s_nop 0
	global_load_lds_dwordx4 v148, s[50:51]
	s_waitcnt vmcnt(8)
	s_waitcnt lgkmcnt(0)
	s_barrier
; #define PG8_STAGE(bufoff, gbase, voff) do { _Pragma("unroll") for (int _i = 0; _i < 2; ++_i) \
;         __builtin_amdgcn_global_load_lds((const unsigned*)((const char*)(gbase) + (voff)[_i]), (PG8_LAS unsigned*)(lds + (bufoff) + ldsw + _i * 8192), 16, 0, 0); } while (0)
; #define PG8_LDA(dst, b, h) do { _Pragma("unroll") for (int m = 0; m < 4; ++m) _Pragma("unroll") for (int k = 0; k < 2; ++k) dst[m][k] = *(const PG8_LAS bf16x8*)(lds + PG8_SA(b, h) + aoff + m * 2048 + k * 1024); } while (0)
; #define PG8_LDB(dst, b, h) do { _Pragma("unroll") for (int n = 0; n < 2; ++n) _Pragma("unroll") for (int k = 0; k < 2; ++k) dst[n][k] = *(const PG8_LAS bf16x8*)(lds + PG8_SB(b, h) + boff + n * 2048 + k * 1024); } while (0)
; #define PG8_MMA(ai, bj, At, Bt) do { __builtin_amdgcn_s_setprio(1); _Pragma("unroll") for (int m = 0; m < 4; ++m) _Pragma("unroll") for (int n = 0; n < 2; ++n) _Pragma("unroll") for (int k = 0; k < 2; ++k) \
;         acc[ai][bj][m][n] = __builtin_amdgcn_mfma_f32_16x16x32_bf16(Bt[n][k], At[m][k], acc[ai][bj][m][n], 0, 0, 0); __builtin_amdgcn_s_setprio(0); } while (0)
; #define PG8_WAIT_V(n) asm volatile("s_waitcnt vmcnt(" #n ")" ::: "memory")
; #define PG8_WAIT_L(n) asm volatile("s_waitcnt lgkmcnt(" #n ")" ::: "memory")
; #define PG8_BAR __builtin_amdgcn_s_barrier()
; #define PG8_SCHED __builtin_amdgcn_sched_barrier(0)
; template <class Epi, class Sched, bool ALIGN_EPI = false, bool SP2 = false>
; __device__ __forceinline__ void gemm_phase(PG8_LAS unsigned char* lds, const Gemm g, const Sched& S, const Epi& E) {
;     ...
;             PG8_WAIT_V(8); PG8_WAIT_L(0); PG8_BAR; PG8_MMA(1, 0, At, B0); PG8_MMA(1, 1, At, B1); PG8_BAR; PG8_SCHED;
;             PG8_LDB(B0, 1, 0); PG8_LDB(B1, 1, 1); PG8_SCHED; PG8_LDA(At, 1, 0); PG8_STAGE(PG8_SA(0, 1), a2 + hstep, voffA);
;             PG8_WAIT_V(8); PG8_WAIT_L(0); PG8_BAR; PG8_MMA(0, 0, At, B0); PG8_MMA(0, 1, At, B1); PG8_BAR; PG8_SCHED;
	s_waitcnt lgkmcnt(0)
	v_mfma_f32_16x16x32_bf16 v[60:63], v[128:131], v[184:187], 0
	v_mfma_f32_16x16x32_bf16 v[56:59], v[136:139], v[184:187], 0
	v_mfma_f32_16x16x32_bf16 v[52:55], v[128:131], v[192:195], 0
	v_mfma_f32_16x16x32_bf16 v[48:51], v[136:139], v[192:195], 0
	v_mfma_f32_16x16x32_bf16 v[44:47], v[128:131], v[200:203], 0
	v_mfma_f32_16x16x32_bf16 v[32:35], v[136:139], v[200:203], 0
	v_mfma_f32_16x16x32_bf16 v[20:23], v[128:131], v[208:211], 0
	v_mfma_f32_16x16x32_bf16 v[8:11], v[136:139], v[208:211], 0
	v_mfma_f32_16x16x32_bf16 v[60:63], v[132:135], v[188:191], v[60:63]
	v_mfma_f32_16x16x32_bf16 v[56:59], v[140:143], v[188:191], v[56:59]
	v_mfma_f32_16x16x32_bf16 v[52:55], v[132:135], v[196:199], v[52:55]
	v_mfma_f32_16x16x32_bf16 v[48:51], v[140:143], v[196:199], v[48:51]
	v_mfma_f32_16x16x32_bf16 v[44:47], v[132:135], v[204:207], v[44:47]
	v_mfma_f32_16x16x32_bf16 v[32:35], v[140:143], v[204:207], v[32:35]
	v_mfma_f32_16x16x32_bf16 v[20:23], v[132:135], v[214:217], v[20:23]
	v_mfma_f32_16x16x32_bf16 v[8:11], v[140:143], v[214:217], v[8:11]
	v_mfma_f32_16x16x32_bf16 v[40:43], v[160:163], v[184:187], 0
	v_mfma_f32_16x16x32_bf16 v[36:39], v[176:179], v[184:187], 0
	v_mfma_f32_16x16x32_bf16 v[28:31], v[160:163], v[192:195], 0
	v_mfma_f32_16x16x32_bf16 v[24:27], v[176:179], v[192:195], 0
	v_mfma_f32_16x16x32_bf16 v[16:19], v[160:163], v[200:203], 0
	v_mfma_f32_16x16x32_bf16 v[12:15], v[176:179], v[200:203], 0
	v_mfma_f32_16x16x32_bf16 v[4:7], v[160:163], v[208:211], 0
	v_mfma_f32_16x16x32_bf16 v[0:3], v[176:179], v[208:211], 0
	v_mfma_f32_16x16x32_bf16 v[40:43], v[172:175], v[188:191], v[40:43]
	v_mfma_f32_16x16x32_bf16 v[36:39], v[180:183], v[188:191], v[36:39]
	v_mfma_f32_16x16x32_bf16 v[28:31], v[172:175], v[196:199], v[28:31]
	v_mfma_f32_16x16x32_bf16 v[24:27], v[180:183], v[196:199], v[24:27]
	v_mfma_f32_16x16x32_bf16 v[16:19], v[172:175], v[204:207], v[16:19]
	v_mfma_f32_16x16x32_bf16 v[12:15], v[180:183], v[204:207], v[12:15]
	v_mfma_f32_16x16x32_bf16 v[4:7], v[172:175], v[214:217], v[4:7]
	v_mfma_f32_16x16x32_bf16 v[0:3], v[180:183], v[214:217], v[0:3]
	s_barrier
	s_add_i32 s72, 0, 0x18000
	s_add_i32 s73, 0, 0x1c000
	v_add_u32_e32 v140, s72, v167
	v_add_u32_e32 v180, s73, v167
	ds_read_b128 v[128:131], v140
	ds_read_b128 v[132:135], v140 offset:1024
	ds_read_b128 v[136:139], v140 offset:2048
	ds_read_b128 v[140:143], v140 offset:3072
	ds_read_b128 v[160:163], v180
	ds_read_b128 v[172:175], v180 offset:1024
	ds_read_b128 v[176:179], v180 offset:2048
	ds_read_b128 v[180:183], v180 offset:3072
	s_add_u32 s84, s50, 0x80
	s_addc_u32 s85, s51, 0
	s_add_u32 s50, s50, 0x80000
	s_addc_u32 s51, s51, 0
	s_mov_b32 m0, s55
	ds_read_b128 v[184:187], v171 offset:32768
	ds_read_b128 v[188:191], v171 offset:33792
	ds_read_b128 v[192:195], v171 offset:34816
	ds_read_b128 v[196:199], v171 offset:35840
	ds_read_b128 v[200:203], v171 offset:36864
	ds_read_b128 v[204:207], v171 offset:37888
	ds_read_b128 v[208:211], v171 offset:38912
	ds_read_b128 v[214:217], v171 offset:39936
	global_load_lds_dwordx4 v144, s[50:51]
	s_mov_b32 m0, s56
	s_nop 0
	global_load_lds_dwordx4 v148, s[50:51]
	s_waitcnt vmcnt(8)
	s_waitcnt lgkmcnt(0)
	s_barrier
	s_waitcnt lgkmcnt(0)
	v_mfma_f32_16x16x32_bf16 v[124:127], v[128:131], v[184:187], v[124:127]
	v_mfma_f32_16x16x32_bf16 v[120:123], v[136:139], v[184:187], v[120:123]
	v_mfma_f32_16x16x32_bf16 v[116:119], v[128:131], v[192:195], v[116:119]
	v_mfma_f32_16x16x32_bf16 v[112:115], v[136:139], v[192:195], v[112:115]
	v_mfma_f32_16x16x32_bf16 v[108:111], v[128:131], v[200:203], v[108:111]
	v_mfma_f32_16x16x32_bf16 v[96:99], v[136:139], v[200:203], v[96:99]
	v_mfma_f32_16x16x32_bf16 v[80:83], v[128:131], v[208:211], v[80:83]
	v_mfma_f32_16x16x32_bf16 v[72:75], v[136:139], v[208:211], v[72:75]
	v_mfma_f32_16x16x32_bf16 v[124:127], v[132:135], v[188:191], v[124:127]
	v_mfma_f32_16x16x32_bf16 v[120:123], v[140:143], v[188:191], v[120:123]
	v_mfma_f32_16x16x32_bf16 v[116:119], v[132:135], v[196:199], v[116:119]
	v_mfma_f32_16x16x32_bf16 v[112:115], v[140:143], v[196:199], v[112:115]
	v_mfma_f32_16x16x32_bf16 v[108:111], v[132:135], v[204:207], v[108:111]
	v_mfma_f32_16x16x32_bf16 v[96:99], v[140:143], v[204:207], v[96:99]
	v_mfma_f32_16x16x32_bf16 v[80:83], v[132:135], v[214:217], v[80:83]
	v_mfma_f32_16x16x32_bf16 v[72:75], v[140:143], v[214:217], v[72:75]
	v_mfma_f32_16x16x32_bf16 v[104:107], v[160:163], v[184:187], v[104:107]
	v_mfma_f32_16x16x32_bf16 v[100:103], v[176:179], v[184:187], v[100:103]
	v_mfma_f32_16x16x32_bf16 v[92:95], v[160:163], v[192:195], v[92:95]
	v_mfma_f32_16x16x32_bf16 v[88:91], v[176:179], v[192:195], v[88:91]
	v_mfma_f32_16x16x32_bf16 v[84:87], v[160:163], v[200:203], v[84:87]
	v_mfma_f32_16x16x32_bf16 v[76:79], v[176:179], v[200:203], v[76:79]
	v_mfma_f32_16x16x32_bf16 v[68:71], v[160:163], v[208:211], v[68:71]
	v_mfma_f32_16x16x32_bf16 v[64:67], v[176:179], v[208:211], v[64:67]
	v_mfma_f32_16x16x32_bf16 v[104:107], v[172:175], v[188:191], v[104:107]
	v_mfma_f32_16x16x32_bf16 v[100:103], v[180:183], v[188:191], v[100:103]
	v_mfma_f32_16x16x32_bf16 v[92:95], v[172:175], v[196:199], v[92:95]
	v_mfma_f32_16x16x32_bf16 v[88:91], v[180:183], v[196:199], v[88:91]
	v_mfma_f32_16x16x32_bf16 v[84:87], v[172:175], v[204:207], v[84:87]
	v_mfma_f32_16x16x32_bf16 v[76:79], v[180:183], v[204:207], v[76:79]
	v_mfma_f32_16x16x32_bf16 v[68:71], v[172:175], v[214:217], v[68:71]
	v_mfma_f32_16x16x32_bf16 v[64:67], v[180:183], v[214:217], v[64:67]
	s_barrier
; #define PG8_STAGE(bufoff, gbase, voff) do { _Pragma("unroll") for (int _i = 0; _i < 2; ++_i) \
;         __builtin_amdgcn_global_load_lds((const unsigned*)((const char*)(gbase) + (voff)[_i]), (PG8_LAS unsigned*)(lds + (bufoff) + ldsw + _i * 8192), 16, 0, 0); } while (0)
; #define PG8_LDA(dst, b, h) do { _Pragma("unroll") for (int m = 0; m < 4; ++m) _Pragma("unroll") for (int k = 0; k < 2; ++k) dst[m][k] = *(const PG8_LAS bf16x8*)(lds + PG8_SA(b, h) + aoff + m * 2048 + k * 1024); } while (0)
; #define PG8_LDB(dst, b, h) do { _Pragma("unroll") for (int n = 0; n < 2; ++n) _Pragma("unroll") for (int k = 0; k < 2; ++k) dst[n][k] = *(const PG8_LAS bf16x8*)(lds + PG8_SB(b, h) + boff + n * 2048 + k * 1024); } while (0)
; #define PG8_MMA(ai, bj, At, Bt) do { __builtin_amdgcn_s_setprio(1); _Pragma("unroll") for (int m = 0; m < 4; ++m) _Pragma("unroll") for (int n = 0; n < 2; ++n) _Pragma("unroll") for (int k = 0; k < 2; ++k) \
;         acc[ai][bj][m][n] = __builtin_amdgcn_mfma_f32_16x16x32_bf16(Bt[n][k], At[m][k], acc[ai][bj][m][n], 0, 0, 0); __builtin_amdgcn_s_setprio(0); } while (0)
; #define PG8_WAIT_V(n) asm volatile("s_waitcnt vmcnt(" #n ")" ::: "memory")
; #define PG8_WAIT_L(n) asm volatile("s_waitcnt lgkmcnt(" #n ")" ::: "memory")
; #define PG8_BAR __builtin_amdgcn_s_barrier()
; #define PG8_SCHED __builtin_amdgcn_sched_barrier(0)
; template <class Epi, class Sched, bool ALIGN_EPI = false, bool SP2 = false>
; __device__ __forceinline__ void gemm_phase(PG8_LAS unsigned char* lds, const Gemm g, const Sched& S, const Epi& E) {
;     ...
;             PG8_LDB(B0, 0, 0); PG8_LDB(B1, 0, 1); PG8_SCHED; PG8_LDA(At, 0, 0); PG8_STAGE(PG8_SA(1, 1), a1 + hstep, voffA);
;             PG8_WAIT_V(8); PG8_WAIT_L(0); PG8_BAR; PG8_MMA(0, 0, At, B0); PG8_MMA(0, 1, At, B1); PG8_BAR; PG8_SCHED;
;     ...
;             PG8_LDA(At, 1, 1); PG8_STAGE(PG8_SB(1, 0), b3, voffB); PG8_STAGE(PG8_SB(1, 1), b3 + hstep, voffB); PG8_STAGE(PG8_SA(1, 0), a3, voffA);
;             PG8_WAIT_V(8); PG8_WAIT_L(0); PG8_BAR; PG8_MMA(1, 0, At, B0); PG8_MMA(1, 1, At, B1); PG8_BAR; PG8_SCHED;
	s_add_i32 s50, s72, s53
	s_add_u32 s86, s48, 0x80
	s_addc_u32 s87, s49, 0
	s_mov_b32 m0, s50
	ds_read_b128 v[184:187], v171 offset:49152
	ds_read_b128 v[188:191], v171 offset:50176
	ds_read_b128 v[192:195], v171 offset:51200
	ds_read_b128 v[196:199], v171 offset:52224
	ds_read_b128 v[200:203], v171 offset:53248
	ds_read_b128 v[204:207], v171 offset:54272
	ds_read_b128 v[208:211], v171 offset:55296
	ds_read_b128 v[214:217], v171 offset:56320
	global_load_lds_dwordx4 v146, s[86:87]
	s_add_i32 m0, s50, 0x2000
	s_add_u32 s48, s48, 0x80080
	s_addc_u32 s49, s49, 0
	s_add_i32 s50, s73, s53
	global_load_lds_dwordx4 v150, s[86:87]
	s_mov_b32 m0, s50
	s_nop 0
	global_load_lds_dwordx4 v146, s[48:49]
	s_add_i32 m0, s50, 0x2000
	s_nop 0
	global_load_lds_dwordx4 v150, s[48:49]
	s_mov_b32 m0, s60
	s_nop 0
	global_load_lds_dwordx4 v144, s[84:85]
	s_mov_b32 m0, s61
	s_nop 0
	global_load_lds_dwordx4 v148, s[84:85]
	s_waitcnt vmcnt(8)
	s_waitcnt lgkmcnt(0)
	s_barrier
	s_waitcnt lgkmcnt(0)
	v_mfma_f32_16x16x32_bf16 v[60:63], v[128:131], v[184:187], v[60:63]
	v_mfma_f32_16x16x32_bf16 v[56:59], v[136:139], v[184:187], v[56:59]
	v_mfma_f32_16x16x32_bf16 v[52:55], v[128:131], v[192:195], v[52:55]
	v_mfma_f32_16x16x32_bf16 v[48:51], v[136:139], v[192:195], v[48:51]
	v_mfma_f32_16x16x32_bf16 v[44:47], v[128:131], v[200:203], v[44:47]
	v_mfma_f32_16x16x32_bf16 v[32:35], v[136:139], v[200:203], v[32:35]
	v_mfma_f32_16x16x32_bf16 v[20:23], v[128:131], v[208:211], v[20:23]
	v_mfma_f32_16x16x32_bf16 v[8:11], v[136:139], v[208:211], v[8:11]
	v_mfma_f32_16x16x32_bf16 v[60:63], v[132:135], v[188:191], v[60:63]
	v_mfma_f32_16x16x32_bf16 v[56:59], v[140:143], v[188:191], v[56:59]
	v_mfma_f32_16x16x32_bf16 v[52:55], v[132:135], v[196:199], v[52:55]
	v_mfma_f32_16x16x32_bf16 v[48:51], v[140:143], v[196:199], v[48:51]
	v_mfma_f32_16x16x32_bf16 v[44:47], v[132:135], v[204:207], v[44:47]
	v_mfma_f32_16x16x32_bf16 v[32:35], v[140:143], v[204:207], v[32:35]
	v_mfma_f32_16x16x32_bf16 v[20:23], v[132:135], v[214:217], v[20:23]
	v_mfma_f32_16x16x32_bf16 v[8:11], v[140:143], v[214:217], v[8:11]
	v_mfma_f32_16x16x32_bf16 v[40:43], v[160:163], v[184:187], v[40:43]
	v_mfma_f32_16x16x32_bf16 v[36:39], v[176:179], v[184:187], v[36:39]
	v_mfma_f32_16x16x32_bf16 v[28:31], v[160:163], v[192:195], v[28:31]
	v_mfma_f32_16x16x32_bf16 v[24:27], v[176:179], v[192:195], v[24:27]
	v_mfma_f32_16x16x32_bf16 v[16:19], v[160:163], v[200:203], v[16:19]
	v_mfma_f32_16x16x32_bf16 v[12:15], v[176:179], v[200:203], v[12:15]
	v_mfma_f32_16x16x32_bf16 v[4:7], v[160:163], v[208:211], v[4:7]
	v_mfma_f32_16x16x32_bf16 v[0:3], v[176:179], v[208:211], v[0:3]
	v_mfma_f32_16x16x32_bf16 v[40:43], v[172:175], v[188:191], v[40:43]
	v_mfma_f32_16x16x32_bf16 v[36:39], v[180:183], v[188:191], v[36:39]
	v_mfma_f32_16x16x32_bf16 v[28:31], v[172:175], v[196:199], v[28:31]
	v_mfma_f32_16x16x32_bf16 v[24:27], v[180:183], v[196:199], v[24:27]
	v_mfma_f32_16x16x32_bf16 v[16:19], v[172:175], v[204:207], v[16:19]
	v_mfma_f32_16x16x32_bf16 v[12:15], v[180:183], v[204:207], v[12:15]
	v_mfma_f32_16x16x32_bf16 v[4:7], v[172:175], v[214:217], v[4:7]
	v_mfma_f32_16x16x32_bf16 v[0:3], v[180:183], v[214:217], v[0:3]
	s_add_i32 s71, s71, 2
	s_add_u32 s46, s46, 0x100
	s_addc_u32 s47, s47, 0
	s_add_u32 s69, s69, 0x100
	s_addc_u32 s70, s70, 0
	s_cmp_gt_u32 s71, 29
	s_barrier
.LBB0_827:
	ds_read_b128 v[128:131], v169
	ds_read_b128 v[132:135], v169 offset:1024
	ds_read_b128 v[136:139], v169 offset:2048
	ds_read_b128 v[140:143], v169 offset:3072
	ds_read_b128 v[160:163], v170
	ds_read_b128 v[172:175], v170 offset:1024
	ds_read_b128 v[176:179], v170 offset:2048
	ds_read_b128 v[180:183], v170 offset:3072
	s_add_u32 s48, s46, 0xfff80080
	s_addc_u32 s49, s47, -1
	s_cmp_eq_u32 s71, 28
	s_cselect_b32 s51, s39, s49
	s_cselect_b32 s50, s67, s48
	s_cselect_b32 s49, s37, s70
	s_cselect_b32 s48, s68, s69
	s_add_i32 m0, s45, 0xc000
	ds_read_b128 v[184:187], v171
	ds_read_b128 v[188:191], v171 offset:1024
	ds_read_b128 v[192:195], v171 offset:2048
	ds_read_b128 v[196:199], v171 offset:3072
	ds_read_b128 v[200:203], v171 offset:4096
	ds_read_b128 v[204:207], v171 offset:5120
	ds_read_b128 v[208:211], v171 offset:6144
	ds_read_b128 v[214:217], v171 offset:7168
	global_load_lds_dwordx4 v152, s[46:47]
	s_add_i32 m0, s45, 0xe000
	s_nop 0
	global_load_lds_dwordx4 v154, s[46:47]
	s_waitcnt vmcnt(8)
	s_waitcnt lgkmcnt(0)
	s_barrier
	s_waitcnt lgkmcnt(0)
	v_mfma_f32_16x16x32_bf16 v[124:127], v[128:131], v[184:187], v[124:127]
	v_mfma_f32_16x16x32_bf16 v[120:123], v[136:139], v[184:187], v[120:123]
	v_mfma_f32_16x16x32_bf16 v[116:119], v[128:131], v[192:195], v[116:119]
	v_mfma_f32_16x16x32_bf16 v[112:115], v[136:139], v[192:195], v[112:115]
	v_mfma_f32_16x16x32_bf16 v[108:111], v[128:131], v[200:203], v[108:111]
	v_mfma_f32_16x16x32_bf16 v[96:99], v[136:139], v[200:203], v[96:99]
	v_mfma_f32_16x16x32_bf16 v[80:83], v[128:131], v[208:211], v[80:83]
	v_mfma_f32_16x16x32_bf16 v[72:75], v[136:139], v[208:211], v[72:75]
	v_mfma_f32_16x16x32_bf16 v[124:127], v[132:135], v[188:191], v[124:127]
	v_mfma_f32_16x16x32_bf16 v[120:123], v[140:143], v[188:191], v[120:123]
	v_mfma_f32_16x16x32_bf16 v[116:119], v[132:135], v[196:199], v[116:119]
	v_mfma_f32_16x16x32_bf16 v[112:115], v[140:143], v[196:199], v[112:115]
	v_mfma_f32_16x16x32_bf16 v[108:111], v[132:135], v[204:207], v[108:111]
	v_mfma_f32_16x16x32_bf16 v[96:99], v[140:143], v[204:207], v[96:99]
	v_mfma_f32_16x16x32_bf16 v[80:83], v[132:135], v[214:217], v[80:83]
	v_mfma_f32_16x16x32_bf16 v[72:75], v[140:143], v[214:217], v[72:75]
	v_mfma_f32_16x16x32_bf16 v[104:107], v[160:163], v[184:187], v[104:107]
	v_mfma_f32_16x16x32_bf16 v[100:103], v[176:179], v[184:187], v[100:103]
	v_mfma_f32_16x16x32_bf16 v[92:95], v[160:163], v[192:195], v[92:95]
	v_mfma_f32_16x16x32_bf16 v[88:91], v[176:179], v[192:195], v[88:91]
	v_mfma_f32_16x16x32_bf16 v[84:87], v[160:163], v[200:203], v[84:87]
	v_mfma_f32_16x16x32_bf16 v[76:79], v[176:179], v[200:203], v[76:79]
	v_mfma_f32_16x16x32_bf16 v[68:71], v[160:163], v[208:211], v[68:71]
	v_mfma_f32_16x16x32_bf16 v[64:67], v[176:179], v[208:211], v[64:67]
	v_mfma_f32_16x16x32_bf16 v[104:107], v[172:175], v[188:191], v[104:107]
	v_mfma_f32_16x16x32_bf16 v[100:103], v[180:183], v[188:191], v[100:103]
	v_mfma_f32_16x16x32_bf16 v[92:95], v[172:175], v[196:199], v[92:95]
	v_mfma_f32_16x16x32_bf16 v[88:91], v[180:183], v[196:199], v[88:91]
	v_mfma_f32_16x16x32_bf16 v[84:87], v[172:175], v[204:207], v[84:87]
	v_mfma_f32_16x16x32_bf16 v[76:79], v[180:183], v[204:207], v[76:79]
	v_mfma_f32_16x16x32_bf16 v[68:71], v[172:175], v[214:217], v[68:71]
	v_mfma_f32_16x16x32_bf16 v[64:67], v[180:183], v[214:217], v[64:67]
	s_barrier
; #define PG8_STAGE(bufoff, gbase, voff) do { _Pragma("unroll") for (int _i = 0; _i < 2; ++_i) \
;         __builtin_amdgcn_global_load_lds((const unsigned*)((const char*)(gbase) + (voff)[_i]), (PG8_LAS unsigned*)(lds + (bufoff) + ldsw + _i * 8192), 16, 0, 0); } while (0)
; #define PG8_LDA(dst, b, h) do { _Pragma("unroll") for (int m = 0; m < 4; ++m) _Pragma("unroll") for (int k = 0; k < 2; ++k) dst[m][k] = *(const PG8_LAS bf16x8*)(lds + PG8_SA(b, h) + aoff + m * 2048 + k * 1024); } while (0)
; #define PG8_LDB(dst, b, h) do { _Pragma("unroll") for (int n = 0; n < 2; ++n) _Pragma("unroll") for (int k = 0; k < 2; ++k) dst[n][k] = *(const PG8_LAS bf16x8*)(lds + PG8_SB(b, h) + boff + n * 2048 + k * 1024); } while (0)
; #define PG8_MMA(ai, bj, At, Bt) do { __builtin_amdgcn_s_setprio(1); _Pragma("unroll") for (int m = 0; m < 4; ++m) _Pragma("unroll") for (int n = 0; n < 2; ++n) _Pragma("unroll") for (int k = 0; k < 2; ++k) \
;         acc[ai][bj][m][n] = __builtin_amdgcn_mfma_f32_16x16x32_bf16(Bt[n][k], At[m][k], acc[ai][bj][m][n], 0, 0, 0); __builtin_amdgcn_s_setprio(0); } while (0)
; #define PG8_WAIT_V(n) asm volatile("s_waitcnt vmcnt(" #n ")" ::: "memory")
; #define PG8_WAIT_L(n) asm volatile("s_waitcnt lgkmcnt(" #n ")" ::: "memory")
; #define PG8_BAR __builtin_amdgcn_s_barrier()
; #define PG8_SCHED __builtin_amdgcn_sched_barrier(0)
; template <class Epi, class Sched, bool ALIGN_EPI = false, bool SP2 = false>
; __device__ __forceinline__ void gemm_phase(PG8_LAS unsigned char* lds, const Gemm g, const Sched& S, const Epi& E) {
;     ...
;             PG8_LDA(At, 0, 1); PG8_STAGE(PG8_SB(0, 0), b2, voffB); PG8_STAGE(PG8_SB(0, 1), b2 + hstep, voffB); PG8_STAGE(PG8_SA(0, 0), a2, voffA);
;             PG8_WAIT_V(8); PG8_WAIT_L(0); PG8_BAR; PG8_MMA(1, 0, At, B0); PG8_MMA(1, 1, At, B1); PG8_BAR; PG8_SCHED;
;             PG8_LDB(B0, 1, 0); PG8_LDB(B1, 1, 1); PG8_SCHED; PG8_LDA(At, 1, 0); PG8_STAGE(PG8_SA(0, 1), a2 + hstep, voffA);
;             PG8_WAIT_V(8); PG8_WAIT_L(0); PG8_BAR; PG8_MMA(0, 0, At, B0); PG8_MMA(0, 1, At, B1); PG8_BAR; PG8_SCHED;
	s_add_i32 s72, s64, s53
	s_mov_b32 m0, s72
	ds_read_b128 v[184:187], v171 offset:16384
	ds_read_b128 v[188:191], v171 offset:17408
	ds_read_b128 v[192:195], v171 offset:18432
	ds_read_b128 v[196:199], v171 offset:19456
	ds_read_b128 v[200:203], v171 offset:20480
	ds_read_b128 v[204:207], v171 offset:21504
	ds_read_b128 v[208:211], v171 offset:22528
	ds_read_b128 v[214:217], v171 offset:23552
	global_load_lds_dwordx4 v146, s[48:49]
	s_add_i32 m0, s72, 0x2000
	s_add_u32 s72, s48, 0x80000
	s_addc_u32 s73, s49, 0
	s_add_i32 s74, s65, s53
	global_load_lds_dwordx4 v150, s[48:49]
	s_mov_b32 m0, s74
	s_nop 0
	global_load_lds_dwordx4 v146, s[72:73]
	s_add_i32 m0, s74, 0x2000
	s_nop 0
	global_load_lds_dwordx4 v150, s[72:73]
	s_mov_b32 m0, s45
	s_nop 0
	global_load_lds_dwordx4 v144, s[50:51]
	s_mov_b32 m0, s54
	s_nop 0
	global_load_lds_dwordx4 v148, s[50:51]
	s_waitcnt vmcnt(8)
	s_waitcnt lgkmcnt(0)
	s_barrier
	s_waitcnt lgkmcnt(0)
	v_mfma_f32_16x16x32_bf16 v[60:63], v[128:131], v[184:187], v[60:63]
	v_mfma_f32_16x16x32_bf16 v[56:59], v[136:139], v[184:187], v[56:59]
	v_mfma_f32_16x16x32_bf16 v[52:55], v[128:131], v[192:195], v[52:55]
	v_mfma_f32_16x16x32_bf16 v[48:51], v[136:139], v[192:195], v[48:51]
	v_mfma_f32_16x16x32_bf16 v[44:47], v[128:131], v[200:203], v[44:47]
	v_mfma_f32_16x16x32_bf16 v[32:35], v[136:139], v[200:203], v[32:35]
	v_mfma_f32_16x16x32_bf16 v[20:23], v[128:131], v[208:211], v[20:23]
	v_mfma_f32_16x16x32_bf16 v[8:11], v[136:139], v[208:211], v[8:11]
	v_mfma_f32_16x16x32_bf16 v[60:63], v[132:135], v[188:191], v[60:63]
	v_mfma_f32_16x16x32_bf16 v[56:59], v[140:143], v[188:191], v[56:59]
	v_mfma_f32_16x16x32_bf16 v[52:55], v[132:135], v[196:199], v[52:55]
	v_mfma_f32_16x16x32_bf16 v[48:51], v[140:143], v[196:199], v[48:51]
	v_mfma_f32_16x16x32_bf16 v[44:47], v[132:135], v[204:207], v[44:47]
	v_mfma_f32_16x16x32_bf16 v[32:35], v[140:143], v[204:207], v[32:35]
	v_mfma_f32_16x16x32_bf16 v[20:23], v[132:135], v[214:217], v[20:23]
	v_mfma_f32_16x16x32_bf16 v[8:11], v[140:143], v[214:217], v[8:11]
	v_mfma_f32_16x16x32_bf16 v[40:43], v[160:163], v[184:187], v[40:43]
	v_mfma_f32_16x16x32_bf16 v[36:39], v[176:179], v[184:187], v[36:39]
	v_mfma_f32_16x16x32_bf16 v[28:31], v[160:163], v[192:195], v[28:31]
	v_mfma_f32_16x16x32_bf16 v[24:27], v[176:179], v[192:195], v[24:27]
	v_mfma_f32_16x16x32_bf16 v[16:19], v[160:163], v[200:203], v[16:19]
	v_mfma_f32_16x16x32_bf16 v[12:15], v[176:179], v[200:203], v[12:15]
	v_mfma_f32_16x16x32_bf16 v[4:7], v[160:163], v[208:211], v[4:7]
	v_mfma_f32_16x16x32_bf16 v[0:3], v[176:179], v[208:211], v[0:3]
	v_mfma_f32_16x16x32_bf16 v[40:43], v[172:175], v[188:191], v[40:43]
	v_mfma_f32_16x16x32_bf16 v[36:39], v[180:183], v[188:191], v[36:39]
	v_mfma_f32_16x16x32_bf16 v[28:31], v[172:175], v[196:199], v[28:31]
	v_mfma_f32_16x16x32_bf16 v[24:27], v[180:183], v[196:199], v[24:27]
	v_mfma_f32_16x16x32_bf16 v[16:19], v[172:175], v[204:207], v[16:19]
	v_mfma_f32_16x16x32_bf16 v[12:15], v[180:183], v[204:207], v[12:15]
	v_mfma_f32_16x16x32_bf16 v[4:7], v[172:175], v[214:217], v[4:7]
	v_mfma_f32_16x16x32_bf16 v[0:3], v[180:183], v[214:217], v[0:3]
	s_barrier
	s_add_i32 s72, 0, 0x18000
	s_add_i32 s73, 0, 0x1c000
	v_add_u32_e32 v140, s72, v167
	v_add_u32_e32 v180, s73, v167
	ds_read_b128 v[128:131], v140
	ds_read_b128 v[132:135], v140 offset:1024
	ds_read_b128 v[136:139], v140 offset:2048
	ds_read_b128 v[140:143], v140 offset:3072
	ds_read_b128 v[160:163], v180
	ds_read_b128 v[172:175], v180 offset:1024
	ds_read_b128 v[176:179], v180 offset:2048
	ds_read_b128 v[180:183], v180 offset:3072
	s_add_u32 s84, s50, 0x80
	s_addc_u32 s85, s51, 0
	s_add_u32 s50, s50, 0x80000
	s_addc_u32 s51, s51, 0
	s_mov_b32 m0, s55
	ds_read_b128 v[184:187], v171 offset:32768
	ds_read_b128 v[188:191], v171 offset:33792
	ds_read_b128 v[192:195], v171 offset:34816
	ds_read_b128 v[196:199], v171 offset:35840
	ds_read_b128 v[200:203], v171 offset:36864
	ds_read_b128 v[204:207], v171 offset:37888
	ds_read_b128 v[208:211], v171 offset:38912
	ds_read_b128 v[214:217], v171 offset:39936
	global_load_lds_dwordx4 v144, s[50:51]
	s_mov_b32 m0, s56
	s_nop 0
	global_load_lds_dwordx4 v148, s[50:51]
	s_waitcnt vmcnt(8)
	s_waitcnt lgkmcnt(0)
	s_barrier
	s_waitcnt lgkmcnt(0)
	v_mfma_f32_16x16x32_bf16 v[124:127], v[128:131], v[184:187], v[124:127]
	v_mfma_f32_16x16x32_bf16 v[120:123], v[136:139], v[184:187], v[120:123]
	v_mfma_f32_16x16x32_bf16 v[116:119], v[128:131], v[192:195], v[116:119]
	v_mfma_f32_16x16x32_bf16 v[112:115], v[136:139], v[192:195], v[112:115]
	v_mfma_f32_16x16x32_bf16 v[108:111], v[128:131], v[200:203], v[108:111]
	v_mfma_f32_16x16x32_bf16 v[96:99], v[136:139], v[200:203], v[96:99]
	v_mfma_f32_16x16x32_bf16 v[80:83], v[128:131], v[208:211], v[80:83]
	v_mfma_f32_16x16x32_bf16 v[72:75], v[136:139], v[208:211], v[72:75]
	v_mfma_f32_16x16x32_bf16 v[124:127], v[132:135], v[188:191], v[124:127]
	v_mfma_f32_16x16x32_bf16 v[120:123], v[140:143], v[188:191], v[120:123]
	v_mfma_f32_16x16x32_bf16 v[116:119], v[132:135], v[196:199], v[116:119]
	v_mfma_f32_16x16x32_bf16 v[112:115], v[140:143], v[196:199], v[112:115]
	v_mfma_f32_16x16x32_bf16 v[108:111], v[132:135], v[204:207], v[108:111]
	v_mfma_f32_16x16x32_bf16 v[96:99], v[140:143], v[204:207], v[96:99]
	v_mfma_f32_16x16x32_bf16 v[80:83], v[132:135], v[214:217], v[80:83]
	v_mfma_f32_16x16x32_bf16 v[72:75], v[140:143], v[214:217], v[72:75]
	v_mfma_f32_16x16x32_bf16 v[104:107], v[160:163], v[184:187], v[104:107]
	v_mfma_f32_16x16x32_bf16 v[100:103], v[176:179], v[184:187], v[100:103]
	v_mfma_f32_16x16x32_bf16 v[92:95], v[160:163], v[192:195], v[92:95]
	v_mfma_f32_16x16x32_bf16 v[88:91], v[176:179], v[192:195], v[88:91]
	v_mfma_f32_16x16x32_bf16 v[84:87], v[160:163], v[200:203], v[84:87]
	v_mfma_f32_16x16x32_bf16 v[76:79], v[176:179], v[200:203], v[76:79]
	v_mfma_f32_16x16x32_bf16 v[68:71], v[160:163], v[208:211], v[68:71]
	v_mfma_f32_16x16x32_bf16 v[64:67], v[176:179], v[208:211], v[64:67]
	v_mfma_f32_16x16x32_bf16 v[104:107], v[172:175], v[188:191], v[104:107]
	v_mfma_f32_16x16x32_bf16 v[100:103], v[180:183], v[188:191], v[100:103]
	v_mfma_f32_16x16x32_bf16 v[92:95], v[172:175], v[196:199], v[92:95]
	v_mfma_f32_16x16x32_bf16 v[88:91], v[180:183], v[196:199], v[88:91]
	v_mfma_f32_16x16x32_bf16 v[84:87], v[172:175], v[204:207], v[84:87]
	v_mfma_f32_16x16x32_bf16 v[76:79], v[180:183], v[204:207], v[76:79]
	v_mfma_f32_16x16x32_bf16 v[68:71], v[172:175], v[214:217], v[68:71]
	v_mfma_f32_16x16x32_bf16 v[64:67], v[180:183], v[214:217], v[64:67]
	s_barrier
; #define PG8_STAGE(bufoff, gbase, voff) do { _Pragma("unroll") for (int _i = 0; _i < 2; ++_i) \
;         __builtin_amdgcn_global_load_lds((const unsigned*)((const char*)(gbase) + (voff)[_i]), (PG8_LAS unsigned*)(lds + (bufoff) + ldsw + _i * 8192), 16, 0, 0); } while (0)
; #define PG8_LDA(dst, b, h) do { _Pragma("unroll") for (int m = 0; m < 4; ++m) _Pragma("unroll") for (int k = 0; k < 2; ++k) dst[m][k] = *(const PG8_LAS bf16x8*)(lds + PG8_SA(b, h) + aoff + m * 2048 + k * 1024); } while (0)
; #define PG8_MMA(ai, bj, At, Bt) do { __builtin_amdgcn_s_setprio(1); _Pragma("unroll") for (int m = 0; m < 4; ++m) _Pragma("unroll") for (int n = 0; n < 2; ++n) _Pragma("unroll") for (int k = 0; k < 2; ++k) \
;         acc[ai][bj][m][n] = __builtin_amdgcn_mfma_f32_16x16x32_bf16(Bt[n][k], At[m][k], acc[ai][bj][m][n], 0, 0, 0); __builtin_amdgcn_s_setprio(0); } while (0)
; #define PG8_WAIT_V(n) asm volatile("s_waitcnt vmcnt(" #n ")" ::: "memory")
; #define PG8_WAIT_L(n) asm volatile("s_waitcnt lgkmcnt(" #n ")" ::: "memory")
;     __device__ __forceinline__ void operator()(const f32x4 (&acc)[2][2][4][2], const Unit& u, int wr, int wc, int fr, int fq) const {
;         const int row0 = u.pm * BM + wr * 64 + fr, col0 = u.pn * BM + wc * 32 + 8 * fq;
;         const float* gp = gate + (u.pm >> 5) * 18432 + col0;
;         f32x4 gv[2][2];
; #pragma unroll
;         for (int bj = 0; bj < 2; ++bj)
; #pragma unroll
;             for (int n = 0; n < 2; ++n) gv[bj][n] = *(const f32x4*)(gp + bj * HALF + 4 * n) * scale;
; #pragma unroll
;         for (int ai = 0; ai < 2; ++ai) { f32x4 r[4][2][2];
; #pragma unroll
;             for (int m = 0; m < 4; ++m) { const size_t off = (size_t)(row0 + ai * HALF + m * 16) * 2048 + col0;
; #pragma unroll
;                 for (int bj = 0; bj < 2; ++bj)
; #pragma unroll
;                     for (int n = 0; n < 2; ++n) r[m][bj][n] = *(const f32x4*)(res + off + bj * HALF + 4 * n); }
; template <class Epi, class Sched, bool ALIGN_EPI = false, bool SP2 = false>
; __device__ __forceinline__ void gemm_phase(PG8_LAS unsigned char* lds, const Gemm g, const Sched& S, const Epi& E) {
;     ...
;             PG8_LDA(At, 1, 1); PG8_STAGE(PG8_SB(1, 0), b3, voffB); PG8_STAGE(PG8_SB(1, 1), b3 + hstep, voffB); PG8_STAGE(PG8_SA(1, 0), a3, voffA);
;             PG8_WAIT_V(8); PG8_WAIT_L(0); PG8_BAR; PG8_MMA(1, 0, At, B0); PG8_MMA(1, 1, At, B1); PG8_BAR; PG8_SCHED;
	s_add_i32 s50, s72, s53
	s_add_u32 s86, s48, 0x80
	s_addc_u32 s87, s49, 0
	s_mov_b32 m0, s50
	ds_read_b128 v[184:187], v171 offset:49152
	ds_read_b128 v[188:191], v171 offset:50176
	ds_read_b128 v[192:195], v171 offset:51200
	ds_read_b128 v[196:199], v171 offset:52224
	ds_read_b128 v[200:203], v171 offset:53248
	ds_read_b128 v[204:207], v171 offset:54272
	ds_read_b128 v[208:211], v171 offset:55296
	ds_read_b128 v[214:217], v171 offset:56320
	global_load_lds_dwordx4 v146, s[86:87]
	s_add_i32 m0, s50, 0x2000
	s_add_u32 s48, s48, 0x80080
	s_addc_u32 s49, s49, 0
	s_add_i32 s50, s73, s53
	global_load_lds_dwordx4 v150, s[86:87]
	s_mov_b32 m0, s50
	s_nop 0
	global_load_lds_dwordx4 v146, s[48:49]
	s_add_i32 m0, s50, 0x2000
	s_nop 0
	global_load_lds_dwordx4 v150, s[48:49]
	s_mov_b32 m0, s60
	s_nop 0
	global_load_lds_dwordx4 v144, s[84:85]
	s_mov_b32 m0, s61
	s_nop 0
	global_load_lds_dwordx4 v148, s[84:85]
	s_waitcnt vmcnt(8)
	s_waitcnt lgkmcnt(0)
	s_barrier
	s_waitcnt lgkmcnt(0)
	v_mfma_f32_16x16x32_bf16 v[60:63], v[128:131], v[184:187], v[60:63]
	v_mfma_f32_16x16x32_bf16 v[56:59], v[136:139], v[184:187], v[56:59]
	v_mfma_f32_16x16x32_bf16 v[52:55], v[128:131], v[192:195], v[52:55]
	v_mfma_f32_16x16x32_bf16 v[48:51], v[136:139], v[192:195], v[48:51]
	v_mfma_f32_16x16x32_bf16 v[44:47], v[128:131], v[200:203], v[44:47]
	v_mfma_f32_16x16x32_bf16 v[32:35], v[136:139], v[200:203], v[32:35]
	v_mfma_f32_16x16x32_bf16 v[20:23], v[128:131], v[208:211], v[20:23]
	v_mfma_f32_16x16x32_bf16 v[8:11], v[136:139], v[208:211], v[8:11]
	v_mfma_f32_16x16x32_bf16 v[60:63], v[132:135], v[188:191], v[60:63]
	v_mfma_f32_16x16x32_bf16 v[56:59], v[140:143], v[188:191], v[56:59]
	v_mfma_f32_16x16x32_bf16 v[52:55], v[132:135], v[196:199], v[52:55]
	v_mfma_f32_16x16x32_bf16 v[48:51], v[140:143], v[196:199], v[48:51]
	v_mfma_f32_16x16x32_bf16 v[44:47], v[132:135], v[204:207], v[44:47]
	v_mfma_f32_16x16x32_bf16 v[32:35], v[140:143], v[204:207], v[32:35]
	v_mfma_f32_16x16x32_bf16 v[20:23], v[132:135], v[214:217], v[20:23]
	v_mfma_f32_16x16x32_bf16 v[8:11], v[140:143], v[214:217], v[8:11]
	v_mfma_f32_16x16x32_bf16 v[40:43], v[160:163], v[184:187], v[40:43]
	v_mfma_f32_16x16x32_bf16 v[36:39], v[176:179], v[184:187], v[36:39]
	v_mfma_f32_16x16x32_bf16 v[28:31], v[160:163], v[192:195], v[28:31]
	v_mfma_f32_16x16x32_bf16 v[24:27], v[176:179], v[192:195], v[24:27]
	v_mfma_f32_16x16x32_bf16 v[16:19], v[160:163], v[200:203], v[16:19]
	v_mfma_f32_16x16x32_bf16 v[12:15], v[176:179], v[200:203], v[12:15]
	v_mfma_f32_16x16x32_bf16 v[4:7], v[160:163], v[208:211], v[4:7]
	v_mfma_f32_16x16x32_bf16 v[0:3], v[176:179], v[208:211], v[0:3]
	v_mfma_f32_16x16x32_bf16 v[40:43], v[172:175], v[188:191], v[40:43]
	v_mfma_f32_16x16x32_bf16 v[36:39], v[180:183], v[188:191], v[36:39]
	v_mfma_f32_16x16x32_bf16 v[28:31], v[172:175], v[196:199], v[28:31]
	v_mfma_f32_16x16x32_bf16 v[24:27], v[180:183], v[196:199], v[24:27]
	v_mfma_f32_16x16x32_bf16 v[16:19], v[172:175], v[204:207], v[16:19]
	v_mfma_f32_16x16x32_bf16 v[12:15], v[180:183], v[204:207], v[12:15]
	v_mfma_f32_16x16x32_bf16 v[4:7], v[172:175], v[214:217], v[4:7]
	v_mfma_f32_16x16x32_bf16 v[0:3], v[180:183], v[214:217], v[0:3]
	s_add_i32 s71, s71, 2
	s_add_u32 s46, s46, 0x100
	s_addc_u32 s47, s47, 0
	s_add_u32 s69, s69, 0x100
	s_addc_u32 s70, s70, 0
	s_cmp_gt_u32 s71, 29
	s_barrier
	s_cbranch_scc0 .LBB0_827
	s_lshr_b32 s37, s44, 5
	s_mul_i32 s46, s37, 0x4800
	v_lshl_or_b32 v128, s66, 8, v168
	s_ashr_i32 s47, s46, 31
	v_lshl_add_u32 v212, s44, 8, v166
	s_lshl_b64 s[46:47], s[46:47], 2
	v_ashrrev_i32_e32 v129, 31, v128
	v_or_b32_e32 v188, 16, v212
	v_or_b32_e32 v204, 32, v212
	s_add_u32 s46, s58, s46
	v_lshlrev_b64 v[160:161], 2, v[128:129]
	v_ashrrev_i32_e32 v213, 31, v212
	v_ashrrev_i32_e32 v189, 31, v188
	v_ashrrev_i32_e32 v205, 31, v204
	s_addc_u32 s47, s59, s47
	v_lshl_add_u64 v[162:163], s[12:13], 0, v[160:161]
	v_lshlrev_b64 v[164:165], 13, v[212:213]
	v_lshlrev_b64 v[218:219], 13, v[188:189]
	v_lshlrev_b64 v[230:231], 13, v[204:205]
	v_or_b32_e32 v212, 48, v212
	v_lshl_add_u64 v[136:137], s[46:47], 0, v[160:161]
	v_lshl_add_u64 v[184:185], v[162:163], 0, v[164:165]
	v_lshl_add_u64 v[200:201], v[162:163], 0, v[218:219]
	v_lshl_add_u64 v[222:223], v[162:163], 0, v[230:231]
	v_ashrrev_i32_e32 v213, 31, v212
	global_load_dwordx4 v[132:135], v[136:137], off offset:16
	global_load_dwordx4 v[140:143], v[136:137], off
	global_load_dwordx4 v[172:175], v[184:185], off offset:16
	global_load_dwordx4 v[176:179], v[184:185], off
	global_load_dwordx4 v[128:131], v[136:137], off offset:528
	s_nop 0
	global_load_dwordx4 v[136:139], v[136:137], off offset:512
	s_nop 0
	global_load_dwordx4 v[180:183], v[184:185], off offset:528
	s_nop 0
	global_load_dwordx4 v[184:187], v[184:185], off offset:512
	s_nop 0
	global_load_dwordx4 v[188:191], v[200:201], off
	global_load_dwordx4 v[192:195], v[200:201], off offset:16
	global_load_dwordx4 v[196:199], v[200:201], off offset:528
	s_nop 0
	global_load_dwordx4 v[200:203], v[200:201], off offset:512
	s_nop 0
	global_load_dwordx4 v[204:207], v[222:223], off
	global_load_dwordx4 v[208:211], v[222:223], off offset:16
	global_load_dwordx4 v[214:217], v[222:223], off offset:512
	s_nop 0
	global_load_dwordx4 v[222:225], v[222:223], off offset:528
	v_lshlrev_b64 v[212:213], 13, v[212:213]
	v_lshl_add_u64 v[244:245], v[162:163], 0, v[212:213]
	global_load_dwordx4 v[232:235], v[244:245], off
	global_load_dwordx4 v[236:239], v[244:245], off offset:16
	global_load_dwordx4 v[240:243], v[244:245], off offset:512
	s_nop 0
	global_load_dwordx4 v[244:247], v[244:245], off offset:528
	v_lshl_add_u64 v[248:249], s[14:15], 0, v[164:165]
	v_lshl_add_u64 v[248:249], v[248:249], 0, v[160:161]
	v_lshl_add_u64 v[218:219], s[14:15], 0, v[218:219]
	v_lshl_add_u64 v[230:231], s[14:15], 0, v[230:231]
	v_lshl_add_u64 v[218:219], v[218:219], 0, v[160:161]
	v_lshl_add_u64 v[230:231], v[230:231], 0, v[160:161]
	s_and_b64 vcc, exec, s[10:11]
	s_mov_b32 s66, s36
	s_mov_b32 s44, s38
	s_mov_b64 s[48:49], s[42:43]
	s_mov_b64 s[46:47], s[40:41]
	s_waitcnt vmcnt(0)
;     __device__ __forceinline__ void operator()(const f32x4 (&acc)[2][2][4][2], const Unit& u, int wr, int wc, int fr, int fq) const {
;     ...
;         for (int ai = 0; ai < 2; ++ai) { f32x4 r[4][2][2];
; #pragma unroll
;             for (int m = 0; m < 4; ++m) { const size_t off = (size_t)(row0 + ai * HALF + m * 16) * 2048 + col0;
; #pragma unroll
;                 for (int bj = 0; bj < 2; ++bj)
; #pragma unroll
;                     for (int n = 0; n < 2; ++n) r[m][bj][n] = *(const f32x4*)(res + off + bj * HALF + 4 * n); }
; #pragma unroll
;             for (int m = 0; m < 4; ++m) { const size_t off = (size_t)(row0 + ai * HALF + m * 16) * 2048 + col0;
; #pragma unroll
;                 for (int bj = 0; bj < 2; ++bj)
; #pragma unroll
;                     for (int n = 0; n < 2; ++n) *(f32x4*)(out + off + bj * HALF + 4 * n) = r[m][bj][n] + gv[bj][n] * acc[ai][bj][m][n]; } }
	v_pk_fma_f32 v[122:123], v[122:123], v[134:135], v[174:175]
	v_pk_fma_f32 v[126:127], v[126:127], v[142:143], v[178:179]
	v_pk_fma_f32 v[124:125], v[124:125], v[140:141], v[176:177]
	v_pk_fma_f32 v[120:121], v[120:121], v[132:133], v[172:173]
	v_pk_fma_f32 v[76:77], v[76:77], v[128:129], v[222:223]
	v_pk_fma_f32 v[106:107], v[106:107], v[138:139], v[186:187]
	v_pk_fma_f32 v[104:105], v[104:105], v[136:137], v[184:185]
	v_pk_fma_f32 v[102:103], v[102:103], v[130:131], v[182:183]
	v_pk_fma_f32 v[100:101], v[100:101], v[128:129], v[180:181]
	v_pk_fma_f32 v[118:119], v[118:119], v[142:143], v[190:191]
	v_pk_fma_f32 v[116:117], v[116:117], v[140:141], v[188:189]
	v_pk_fma_f32 v[114:115], v[114:115], v[134:135], v[194:195]
	v_pk_fma_f32 v[112:113], v[112:113], v[132:133], v[192:193]
	v_pk_fma_f32 v[94:95], v[94:95], v[138:139], v[202:203]
	v_pk_fma_f32 v[92:93], v[92:93], v[136:137], v[200:201]
	v_pk_fma_f32 v[90:91], v[90:91], v[130:131], v[198:199]
	v_pk_fma_f32 v[88:89], v[88:89], v[128:129], v[196:197]
	v_pk_fma_f32 v[110:111], v[110:111], v[142:143], v[206:207]
	v_pk_fma_f32 v[108:109], v[108:109], v[140:141], v[204:205]
	v_pk_fma_f32 v[98:99], v[98:99], v[134:135], v[210:211]
	v_pk_fma_f32 v[96:97], v[96:97], v[132:133], v[208:209]
	v_pk_fma_f32 v[86:87], v[86:87], v[138:139], v[216:217]
	v_pk_fma_f32 v[84:85], v[84:85], v[136:137], v[214:215]
	v_pk_fma_f32 v[78:79], v[78:79], v[130:131], v[224:225]
	global_store_dwordx4 v[248:249], v[124:127], off
	global_store_dwordx4 v[248:249], v[120:123], off offset:16
	global_store_dwordx4 v[248:249], v[104:107], off offset:512
	global_store_dwordx4 v[248:249], v[100:103], off offset:528
	global_store_dwordx4 v[218:219], v[116:119], off
	global_store_dwordx4 v[218:219], v[112:115], off offset:16
	global_store_dwordx4 v[218:219], v[92:95], off offset:512
	global_store_dwordx4 v[218:219], v[88:91], off offset:528
	global_store_dwordx4 v[230:231], v[108:111], off
	global_store_dwordx4 v[230:231], v[96:99], off offset:16
	global_store_dwordx4 v[230:231], v[84:87], off offset:512
	global_store_dwordx4 v[230:231], v[76:79], off offset:528
	v_pk_fma_f32 v[74:75], v[74:75], v[134:135], v[238:239]
	v_pk_fma_f32 v[72:73], v[72:73], v[132:133], v[236:237]
	v_pk_fma_f32 v[76:77], v[80:81], v[140:141], v[232:233]
	v_lshl_add_u64 v[80:81], s[14:15], 0, v[212:213]
	v_pk_fma_f32 v[78:79], v[82:83], v[142:143], v[234:235]
	v_lshl_add_u64 v[80:81], v[80:81], 0, v[160:161]
	v_pk_fma_f32 v[70:71], v[70:71], v[138:139], v[242:243]
	v_pk_fma_f32 v[68:69], v[68:69], v[136:137], v[240:241]
	v_pk_fma_f32 v[66:67], v[66:67], v[130:131], v[246:247]
	v_pk_fma_f32 v[64:65], v[64:65], v[128:129], v[244:245]
	v_lshl_add_u64 v[172:173], v[164:165], 0, s[26:27]
	v_lshl_add_u64 v[174:175], v[164:165], 0, s[28:29]
	v_lshl_add_u64 v[176:177], v[164:165], 0, s[30:31]
	global_store_dwordx4 v[80:81], v[76:79], off
	global_store_dwordx4 v[80:81], v[72:75], off offset:16
	global_store_dwordx4 v[80:81], v[68:71], off offset:512
	global_store_dwordx4 v[80:81], v[64:67], off offset:528
	v_lshl_add_u64 v[76:77], v[162:163], 0, v[172:173]
	v_lshl_add_u64 v[92:93], v[162:163], 0, v[174:175]
	v_lshl_add_u64 v[108:109], v[162:163], 0, v[176:177]
	global_load_dwordx4 v[64:67], v[76:77], off
	global_load_dwordx4 v[68:71], v[76:77], off offset:16
	global_load_dwordx4 v[72:75], v[76:77], off offset:512
	s_nop 0
	global_load_dwordx4 v[76:79], v[76:77], off offset:528
	s_nop 0
	global_load_dwordx4 v[80:83], v[92:93], off
	global_load_dwordx4 v[84:87], v[92:93], off offset:16
	global_load_dwordx4 v[88:91], v[92:93], off offset:512
	s_nop 0
	global_load_dwordx4 v[92:95], v[92:93], off offset:528
	s_nop 0
	global_load_dwordx4 v[96:99], v[108:109], off
	global_load_dwordx4 v[100:103], v[108:109], off offset:16
	global_load_dwordx4 v[104:107], v[108:109], off offset:512
	s_nop 0
	global_load_dwordx4 v[108:111], v[108:109], off offset:528
	v_lshl_add_u64 v[164:165], v[164:165], 0, s[34:35]
	v_lshl_add_u64 v[124:125], v[162:163], 0, v[164:165]
	global_load_dwordx4 v[112:115], v[124:125], off
	global_load_dwordx4 v[116:119], v[124:125], off offset:16
	global_load_dwordx4 v[120:123], v[124:125], off offset:512
	s_nop 0
	global_load_dwordx4 v[124:127], v[124:125], off offset:528
	v_lshl_add_u64 v[162:163], s[14:15], 0, v[172:173]
	v_lshl_add_u64 v[172:173], s[14:15], 0, v[174:175]
	v_lshl_add_u64 v[174:175], s[14:15], 0, v[176:177]
	v_lshl_add_u64 v[162:163], v[162:163], 0, v[160:161]
	v_lshl_add_u64 v[172:173], v[172:173], 0, v[160:161]
	v_lshl_add_u64 v[174:175], v[174:175], 0, v[160:161]
	s_waitcnt vmcnt(15)
; #define PG8_WAIT_V(n) asm volatile("s_waitcnt vmcnt(" #n ")" ::: "memory")
; #define PG8_BAR __builtin_amdgcn_s_barrier()
;     __device__ __forceinline__ void operator()(const f32x4 (&acc)[2][2][4][2], const Unit& u, int wr, int wc, int fr, int fq) const {
;     ...
;             for (int m = 0; m < 4; ++m) { const size_t off = (size_t)(row0 + ai * HALF + m * 16) * 2048 + col0;
; #pragma unroll
;                 for (int bj = 0; bj < 2; ++bj)
; #pragma unroll
;                     for (int n = 0; n < 2; ++n) *(f32x4*)(out + off + bj * HALF + 4 * n) = r[m][bj][n] + gv[bj][n] * acc[ai][bj][m][n]; } }
; template <class Epi, class Sched, bool ALIGN_EPI = false, bool SP2 = false>
; __device__ __forceinline__ void gemm_phase(PG8_LAS unsigned char* lds, const Gemm g, const Sched& S, const Epi& E) {
;     ...
;     PG8_WAIT_V(0);
;     if constexpr (!ALIGN_EPI) { if (wr == 0) PG8_BAR; }
;     PG8_BAR;
	v_pk_fma_f32 v[62:63], v[62:63], v[142:143], v[66:67]
	v_pk_fma_f32 v[60:61], v[60:61], v[140:141], v[64:65]
	s_waitcnt vmcnt(14)
	v_pk_fma_f32 v[58:59], v[58:59], v[134:135], v[70:71]
	v_pk_fma_f32 v[56:57], v[56:57], v[132:133], v[68:69]
	s_waitcnt vmcnt(13)
	v_pk_fma_f32 v[42:43], v[42:43], v[138:139], v[74:75]
	s_waitcnt vmcnt(4)
	v_pk_fma_f32 v[12:13], v[12:13], v[128:129], v[108:109]
	v_pk_fma_f32 v[40:41], v[40:41], v[136:137], v[72:73]
	v_pk_fma_f32 v[38:39], v[38:39], v[130:131], v[78:79]
	v_pk_fma_f32 v[36:37], v[36:37], v[128:129], v[76:77]
	v_pk_fma_f32 v[54:55], v[54:55], v[142:143], v[82:83]
	v_pk_fma_f32 v[52:53], v[52:53], v[140:141], v[80:81]
	v_pk_fma_f32 v[50:51], v[50:51], v[134:135], v[86:87]
	v_pk_fma_f32 v[48:49], v[48:49], v[132:133], v[84:85]
	v_pk_fma_f32 v[30:31], v[30:31], v[138:139], v[90:91]
	v_pk_fma_f32 v[28:29], v[28:29], v[136:137], v[88:89]
	v_pk_fma_f32 v[26:27], v[26:27], v[130:131], v[94:95]
	v_pk_fma_f32 v[24:25], v[24:25], v[128:129], v[92:93]
	v_pk_fma_f32 v[46:47], v[46:47], v[142:143], v[98:99]
	v_pk_fma_f32 v[44:45], v[44:45], v[140:141], v[96:97]
	v_pk_fma_f32 v[34:35], v[34:35], v[134:135], v[102:103]
	v_pk_fma_f32 v[32:33], v[32:33], v[132:133], v[100:101]
	v_pk_fma_f32 v[18:19], v[18:19], v[138:139], v[106:107]
	v_pk_fma_f32 v[16:17], v[16:17], v[136:137], v[104:105]
	v_pk_fma_f32 v[14:15], v[14:15], v[130:131], v[110:111]
	global_store_dwordx4 v[162:163], v[60:63], off
	global_store_dwordx4 v[162:163], v[56:59], off offset:16
	global_store_dwordx4 v[162:163], v[40:43], off offset:512
	global_store_dwordx4 v[162:163], v[36:39], off offset:528
	global_store_dwordx4 v[172:173], v[52:55], off
	global_store_dwordx4 v[172:173], v[48:51], off offset:16
	global_store_dwordx4 v[172:173], v[28:31], off offset:512
	global_store_dwordx4 v[172:173], v[24:27], off offset:528
	global_store_dwordx4 v[174:175], v[44:47], off
	global_store_dwordx4 v[174:175], v[32:35], off offset:16
	global_store_dwordx4 v[174:175], v[16:19], off offset:512
	global_store_dwordx4 v[174:175], v[12:15], off offset:528
	s_waitcnt vmcnt(15)
	v_pk_fma_f32 v[22:23], v[22:23], v[142:143], v[114:115]
	v_pk_fma_f32 v[20:21], v[20:21], v[140:141], v[112:113]
	v_lshl_add_u64 v[12:13], s[14:15], 0, v[164:165]
	v_lshl_add_u64 v[12:13], v[12:13], 0, v[160:161]
	s_waitcnt vmcnt(14)
	v_pk_fma_f32 v[10:11], v[10:11], v[134:135], v[118:119]
	v_pk_fma_f32 v[8:9], v[8:9], v[132:133], v[116:117]
	s_waitcnt vmcnt(13)
	v_pk_fma_f32 v[6:7], v[6:7], v[138:139], v[122:123]
	v_pk_fma_f32 v[4:5], v[4:5], v[136:137], v[120:121]
	s_waitcnt vmcnt(12)
	v_pk_fma_f32 v[2:3], v[2:3], v[130:131], v[126:127]
	v_pk_fma_f32 v[0:1], v[0:1], v[128:129], v[124:125]
	global_store_dwordx4 v[12:13], v[20:23], off
	global_store_dwordx4 v[12:13], v[8:11], off offset:16
	global_store_dwordx4 v[12:13], v[4:7], off offset:512
	global_store_dwordx4 v[12:13], v[0:3], off offset:528
	s_cbranch_vccz .LBB0_820
	s_waitcnt vmcnt(0)
	s_cmpk_gt_u32 s3, 0xff
	s_cbranch_scc1 .LBB0_831
	s_barrier

; #define PG8_STAGE(bufoff, gbase, voff) do { _Pragma("unroll") for (int _i = 0; _i < 2; ++_i) \
;         __builtin_amdgcn_global_load_lds((const unsigned*)((const char*)(gbase) + (voff)[_i]), (PG8_LAS unsigned*)(lds + (bufoff) + ldsw + _i * 8192), 16, 0, 0); } while (0)
; #define PG8_LDA(dst, b, h) do { _Pragma("unroll") for (int m = 0; m < 4; ++m) _Pragma("unroll") for (int k = 0; k < 2; ++k) dst[m][k] = *(const PG8_LAS bf16x8*)(lds + PG8_SA(b, h) + aoff + m * 2048 + k * 1024); } while (0)
; #define PG8_LDB(dst, b, h) do { _Pragma("unroll") for (int n = 0; n < 2; ++n) _Pragma("unroll") for (int k = 0; k < 2; ++k) dst[n][k] = *(const PG8_LAS bf16x8*)(lds + PG8_SB(b, h) + boff + n * 2048 + k * 1024); } while (0)
; #define PG8_MMA(ai, bj, At, Bt) do { __builtin_amdgcn_s_setprio(1); _Pragma("unroll") for (int m = 0; m < 4; ++m) _Pragma("unroll") for (int n = 0; n < 2; ++n) _Pragma("unroll") for (int k = 0; k < 2; ++k) \
;         acc[ai][bj][m][n] = __builtin_amdgcn_mfma_f32_16x16x32_bf16(Bt[n][k], At[m][k], acc[ai][bj][m][n], 0, 0, 0); __builtin_amdgcn_s_setprio(0); } while (0)
; #define PG8_BAR __builtin_amdgcn_s_barrier()
; template <class Epi, class Sched, bool ALIGN_EPI = false, bool SP2 = false>
; __device__ __forceinline__ void gemm_phase(PG8_LAS unsigned char* lds, const Gemm g, const Sched& S, const Epi& E) {
;     ...
;         const bool has_next = S.next(ui + 1, nxt);
;         const char* nA = has_next ? (const char*)g.A + (size_t)nxt.pm * tstep : cA; const char* nB = has_next ? (const char*)g.Bt + (size_t)nxt.pn * tstep : cB;
;         for (int t = 0; t < nt; t += 2) {
;             const bool last = (t == nt - 2);
;             const char* a1 = cA + (size_t)(t + 1) * kstep;
;             const char* a2 = last ? nA : cA + (size_t)(t + 2) * kstep; const char* b2 = last ? nB : cB + (size_t)(t + 2) * kstep;
;             const char* a3 = a2 + kstep; const char* b3 = b2 + kstep;
;             if (last && has_next) S.a_ready(nxt);
;             if constexpr (SP2) {
;             PG8_LDB(B0, 0, 0); PG8_LDB(B1, 0, 1); PG8_SCHED; PG8_LDA(At, 0, 0); PG8_STAGE(PG8_SA(1, 1), a1 + hstep, voffA);
;             PG8_WAIT_V(8); PG8_WAIT_L(0); PG8_BAR; PG8_MMA(0, 0, At, B0); PG8_MMA(0, 1, At, B1); PG8_BAR; PG8_SCHED;
;             PG8_LDA(At, 0, 1); PG8_STAGE(PG8_SB(0, 0), b2, voffB); PG8_STAGE(PG8_SB(0, 1), b2 + hstep, voffB); PG8_STAGE(PG8_SA(0, 0), a2, voffA);
.LBB0_944:
	s_ashr_i32 s23, s22, 31
	v_cmp_lt_i64_e32 vcc, s[24:25], v[140:141]
	s_lshl_b64 s[24:25], s[22:23], 20
	s_add_u32 s24, s38, s24
	s_addc_u32 s25, s39, s25
	s_and_b64 s[26:27], vcc, exec
	s_cselect_b32 s23, s25, s31
	s_cselect_b32 s57, s24, s30
	s_ashr_i32 s15, s14, 31
	s_lshl_b64 s[26:27], s[14:15], 20
	s_add_u32 s26, s40, s26
	s_addc_u32 s27, s41, s27
	s_and_b64 s[36:37], vcc, exec
	s_cselect_b32 s15, s27, s35
	s_cselect_b32 s58, s26, s34
	s_add_u32 s30, s30, 0x80080
	s_addc_u32 s31, s31, 0
	s_add_u32 s59, s34, 0x100
	s_addc_u32 s60, s35, 0
	s_mov_b32 s61, -2
	ds_read_b128 v[152:155], v149
	ds_read_b128 v[156:159], v149 offset:1024
	ds_read_b128 v[160:163], v149 offset:2048
	ds_read_b128 v[164:167], v149 offset:3072
	ds_read_b128 v[168:171], v150
	ds_read_b128 v[172:175], v150 offset:1024
	ds_read_b128 v[176:179], v150 offset:2048
	ds_read_b128 v[180:183], v150 offset:3072
	s_add_u32 s34, s30, 0xfff80080
	s_addc_u32 s35, s31, -1
	s_cmp_eq_u32 s61, 28
	s_cselect_b32 s37, s23, s35
	s_cselect_b32 s36, s57, s34
	s_cselect_b32 s35, s15, s60
	s_cselect_b32 s34, s58, s59
	s_add_i32 m0, s29, 0xc000
	ds_read_b128 v[184:187], v151
	ds_read_b128 v[188:191], v151 offset:1024
	ds_read_b128 v[192:195], v151 offset:2048
	ds_read_b128 v[196:199], v151 offset:3072
	ds_read_b128 v[200:203], v151 offset:4096
	ds_read_b128 v[204:207], v151 offset:5120
	ds_read_b128 v[208:211], v151 offset:6144
	ds_read_b128 v[212:215], v151 offset:7168
	global_load_lds_dwordx4 v136, s[30:31]
	s_add_i32 m0, s29, 0xe000
	s_nop 0
	global_load_lds_dwordx4 v138, s[30:31]
	s_waitcnt vmcnt(8)
	s_waitcnt lgkmcnt(0)
	s_barrier
	s_waitcnt lgkmcnt(0)
	v_mfma_f32_16x16x32_bf16 v[124:127], v[152:155], v[184:187], 0
	v_mfma_f32_16x16x32_bf16 v[120:123], v[160:163], v[184:187], 0
	v_mfma_f32_16x16x32_bf16 v[108:111], v[152:155], v[192:195], 0
	v_mfma_f32_16x16x32_bf16 v[104:107], v[160:163], v[192:195], 0
	v_mfma_f32_16x16x32_bf16 v[92:95], v[152:155], v[200:203], 0
	v_mfma_f32_16x16x32_bf16 v[88:91], v[160:163], v[200:203], 0
	v_mfma_f32_16x16x32_bf16 v[76:79], v[152:155], v[208:211], 0
	v_mfma_f32_16x16x32_bf16 v[72:75], v[160:163], v[208:211], 0
	v_mfma_f32_16x16x32_bf16 v[124:127], v[156:159], v[188:191], v[124:127]
	v_mfma_f32_16x16x32_bf16 v[120:123], v[164:167], v[188:191], v[120:123]
	v_mfma_f32_16x16x32_bf16 v[108:111], v[156:159], v[196:199], v[108:111]
	v_mfma_f32_16x16x32_bf16 v[104:107], v[164:167], v[196:199], v[104:107]
	v_mfma_f32_16x16x32_bf16 v[92:95], v[156:159], v[204:207], v[92:95]
	v_mfma_f32_16x16x32_bf16 v[88:91], v[164:167], v[204:207], v[88:91]
	v_mfma_f32_16x16x32_bf16 v[76:79], v[156:159], v[212:215], v[76:79]
	v_mfma_f32_16x16x32_bf16 v[72:75], v[164:167], v[212:215], v[72:75]
	v_mfma_f32_16x16x32_bf16 v[116:119], v[168:171], v[184:187], 0
	v_mfma_f32_16x16x32_bf16 v[112:115], v[176:179], v[184:187], 0
	v_mfma_f32_16x16x32_bf16 v[100:103], v[168:171], v[192:195], 0
	v_mfma_f32_16x16x32_bf16 v[96:99], v[176:179], v[192:195], 0
	v_mfma_f32_16x16x32_bf16 v[84:87], v[168:171], v[200:203], 0
	v_mfma_f32_16x16x32_bf16 v[80:83], v[176:179], v[200:203], 0
	v_mfma_f32_16x16x32_bf16 v[68:71], v[168:171], v[208:211], 0
	v_mfma_f32_16x16x32_bf16 v[64:67], v[176:179], v[208:211], 0
	v_mfma_f32_16x16x32_bf16 v[116:119], v[172:175], v[188:191], v[116:119]
	v_mfma_f32_16x16x32_bf16 v[112:115], v[180:183], v[188:191], v[112:115]
	v_mfma_f32_16x16x32_bf16 v[100:103], v[172:175], v[196:199], v[100:103]
	v_mfma_f32_16x16x32_bf16 v[96:99], v[180:183], v[196:199], v[96:99]
	v_mfma_f32_16x16x32_bf16 v[84:87], v[172:175], v[204:207], v[84:87]
	v_mfma_f32_16x16x32_bf16 v[80:83], v[180:183], v[204:207], v[80:83]
	v_mfma_f32_16x16x32_bf16 v[68:71], v[172:175], v[212:215], v[68:71]
	v_mfma_f32_16x16x32_bf16 v[64:67], v[180:183], v[212:215], v[64:67]
	s_barrier
	s_add_i32 s62, s53, s42
	s_mov_b32 m0, s62
	ds_read_b128 v[184:187], v151 offset:16384
	ds_read_b128 v[188:191], v151 offset:17408
	ds_read_b128 v[192:195], v151 offset:18432
	ds_read_b128 v[196:199], v151 offset:19456
	ds_read_b128 v[200:203], v151 offset:20480
	ds_read_b128 v[204:207], v151 offset:21504
	ds_read_b128 v[208:211], v151 offset:22528
	ds_read_b128 v[212:215], v151 offset:23552
	global_load_lds_dwordx4 v132, s[34:35]
	s_add_i32 m0, s62, 0x2000
	s_add_u32 s62, s34, 0x80000
	s_addc_u32 s63, s35, 0
	s_add_i32 s64, s54, s42
	global_load_lds_dwordx4 v128, s[34:35]
	s_mov_b32 m0, s64
	s_nop 0
	global_load_lds_dwordx4 v132, s[62:63]
	s_add_i32 m0, s64, 0x2000
	s_nop 0
	global_load_lds_dwordx4 v128, s[62:63]
	s_mov_b32 m0, s29
	s_nop 0
	global_load_lds_dwordx4 v134, s[36:37]
	s_mov_b32 m0, s45
	s_nop 0
	global_load_lds_dwordx4 v130, s[36:37]
	s_waitcnt vmcnt(8)
	s_waitcnt lgkmcnt(0)
	s_barrier
; #define PG8_STAGE(bufoff, gbase, voff) do { _Pragma("unroll") for (int _i = 0; _i < 2; ++_i) \
;         __builtin_amdgcn_global_load_lds((const unsigned*)((const char*)(gbase) + (voff)[_i]), (PG8_LAS unsigned*)(lds + (bufoff) + ldsw + _i * 8192), 16, 0, 0); } while (0)
; #define PG8_LDA(dst, b, h) do { _Pragma("unroll") for (int m = 0; m < 4; ++m) _Pragma("unroll") for (int k = 0; k < 2; ++k) dst[m][k] = *(const PG8_LAS bf16x8*)(lds + PG8_SA(b, h) + aoff + m * 2048 + k * 1024); } while (0)
; #define PG8_LDB(dst, b, h) do { _Pragma("unroll") for (int n = 0; n < 2; ++n) _Pragma("unroll") for (int k = 0; k < 2; ++k) dst[n][k] = *(const PG8_LAS bf16x8*)(lds + PG8_SB(b, h) + boff + n * 2048 + k * 1024); } while (0)
; #define PG8_MMA(ai, bj, At, Bt) do { __builtin_amdgcn_s_setprio(1); _Pragma("unroll") for (int m = 0; m < 4; ++m) _Pragma("unroll") for (int n = 0; n < 2; ++n) _Pragma("unroll") for (int k = 0; k < 2; ++k) \
;         acc[ai][bj][m][n] = __builtin_amdgcn_mfma_f32_16x16x32_bf16(Bt[n][k], At[m][k], acc[ai][bj][m][n], 0, 0, 0); __builtin_amdgcn_s_setprio(0); } while (0)
; #define PG8_WAIT_V(n) asm volatile("s_waitcnt vmcnt(" #n ")" ::: "memory")
; #define PG8_WAIT_L(n) asm volatile("s_waitcnt lgkmcnt(" #n ")" ::: "memory")
; #define PG8_BAR __builtin_amdgcn_s_barrier()
; #define PG8_SCHED __builtin_amdgcn_sched_barrier(0)
; template <class Epi, class Sched, bool ALIGN_EPI = false, bool SP2 = false>
; __device__ __forceinline__ void gemm_phase(PG8_LAS unsigned char* lds, const Gemm g, const Sched& S, const Epi& E) {
;     ...
;             PG8_WAIT_V(8); PG8_WAIT_L(0); PG8_BAR; PG8_MMA(1, 0, At, B0); PG8_MMA(1, 1, At, B1); PG8_BAR; PG8_SCHED;
;             PG8_LDB(B0, 1, 0); PG8_LDB(B1, 1, 1); PG8_SCHED; PG8_LDA(At, 1, 0); PG8_STAGE(PG8_SA(0, 1), a2 + hstep, voffA);
;             PG8_WAIT_V(8); PG8_WAIT_L(0); PG8_BAR; PG8_MMA(0, 0, At, B0); PG8_MMA(0, 1, At, B1); PG8_BAR; PG8_SCHED;
	s_waitcnt lgkmcnt(0)
	v_mfma_f32_16x16x32_bf16 v[60:63], v[152:155], v[184:187], 0
	v_mfma_f32_16x16x32_bf16 v[56:59], v[160:163], v[184:187], 0
	v_mfma_f32_16x16x32_bf16 v[44:47], v[152:155], v[192:195], 0
	v_mfma_f32_16x16x32_bf16 v[40:43], v[160:163], v[192:195], 0
	v_mfma_f32_16x16x32_bf16 v[28:31], v[152:155], v[200:203], 0
	v_mfma_f32_16x16x32_bf16 v[24:27], v[160:163], v[200:203], 0
	v_mfma_f32_16x16x32_bf16 v[12:15], v[152:155], v[208:211], 0
	v_mfma_f32_16x16x32_bf16 v[8:11], v[160:163], v[208:211], 0
	v_mfma_f32_16x16x32_bf16 v[60:63], v[156:159], v[188:191], v[60:63]
	v_mfma_f32_16x16x32_bf16 v[56:59], v[164:167], v[188:191], v[56:59]
	v_mfma_f32_16x16x32_bf16 v[44:47], v[156:159], v[196:199], v[44:47]
	v_mfma_f32_16x16x32_bf16 v[40:43], v[164:167], v[196:199], v[40:43]
	v_mfma_f32_16x16x32_bf16 v[28:31], v[156:159], v[204:207], v[28:31]
	v_mfma_f32_16x16x32_bf16 v[24:27], v[164:167], v[204:207], v[24:27]
	v_mfma_f32_16x16x32_bf16 v[12:15], v[156:159], v[212:215], v[12:15]
	v_mfma_f32_16x16x32_bf16 v[8:11], v[164:167], v[212:215], v[8:11]
	v_mfma_f32_16x16x32_bf16 v[52:55], v[168:171], v[184:187], 0
	v_mfma_f32_16x16x32_bf16 v[48:51], v[176:179], v[184:187], 0
	v_mfma_f32_16x16x32_bf16 v[36:39], v[168:171], v[192:195], 0
	v_mfma_f32_16x16x32_bf16 v[32:35], v[176:179], v[192:195], 0
	v_mfma_f32_16x16x32_bf16 v[20:23], v[168:171], v[200:203], 0
	v_mfma_f32_16x16x32_bf16 v[16:19], v[176:179], v[200:203], 0
	v_mfma_f32_16x16x32_bf16 v[4:7], v[168:171], v[208:211], 0
	v_mfma_f32_16x16x32_bf16 v[0:3], v[176:179], v[208:211], 0
	v_mfma_f32_16x16x32_bf16 v[52:55], v[172:175], v[188:191], v[52:55]
	v_mfma_f32_16x16x32_bf16 v[48:51], v[180:183], v[188:191], v[48:51]
	v_mfma_f32_16x16x32_bf16 v[36:39], v[172:175], v[196:199], v[36:39]
	v_mfma_f32_16x16x32_bf16 v[32:35], v[180:183], v[196:199], v[32:35]
	v_mfma_f32_16x16x32_bf16 v[20:23], v[172:175], v[204:207], v[20:23]
	v_mfma_f32_16x16x32_bf16 v[16:19], v[180:183], v[204:207], v[16:19]
	v_mfma_f32_16x16x32_bf16 v[4:7], v[172:175], v[212:215], v[4:7]
	v_mfma_f32_16x16x32_bf16 v[0:3], v[180:183], v[212:215], v[0:3]
	s_barrier
	s_add_i32 s62, 0, 0x18000
	s_add_i32 s63, 0, 0x1c000
	v_add_u32_e32 v164, s62, v147
	v_add_u32_e32 v180, s63, v147
	ds_read_b128 v[152:155], v164
	ds_read_b128 v[156:159], v164 offset:1024
	ds_read_b128 v[160:163], v164 offset:2048
	ds_read_b128 v[164:167], v164 offset:3072
	ds_read_b128 v[168:171], v180
	ds_read_b128 v[172:175], v180 offset:1024
	ds_read_b128 v[176:179], v180 offset:2048
	ds_read_b128 v[180:183], v180 offset:3072
	s_add_u32 s84, s36, 0x80
	s_addc_u32 s85, s37, 0
	s_add_u32 s36, s36, 0x80000
	s_addc_u32 s37, s37, 0
	s_mov_b32 m0, s46
	ds_read_b128 v[184:187], v151 offset:32768
	ds_read_b128 v[188:191], v151 offset:33792
	ds_read_b128 v[192:195], v151 offset:34816
	ds_read_b128 v[196:199], v151 offset:35840
	ds_read_b128 v[200:203], v151 offset:36864
	ds_read_b128 v[204:207], v151 offset:37888
	ds_read_b128 v[208:211], v151 offset:38912
	ds_read_b128 v[212:215], v151 offset:39936
	global_load_lds_dwordx4 v134, s[36:37]
	s_mov_b32 m0, s47
	s_nop 0
	global_load_lds_dwordx4 v130, s[36:37]
	s_waitcnt vmcnt(8)
	s_waitcnt lgkmcnt(0)
	s_barrier
	s_waitcnt lgkmcnt(0)
	v_mfma_f32_16x16x32_bf16 v[124:127], v[152:155], v[184:187], v[124:127]
	v_mfma_f32_16x16x32_bf16 v[120:123], v[160:163], v[184:187], v[120:123]
	v_mfma_f32_16x16x32_bf16 v[108:111], v[152:155], v[192:195], v[108:111]
	v_mfma_f32_16x16x32_bf16 v[104:107], v[160:163], v[192:195], v[104:107]
	v_mfma_f32_16x16x32_bf16 v[92:95], v[152:155], v[200:203], v[92:95]
	v_mfma_f32_16x16x32_bf16 v[88:91], v[160:163], v[200:203], v[88:91]
	v_mfma_f32_16x16x32_bf16 v[76:79], v[152:155], v[208:211], v[76:79]
	v_mfma_f32_16x16x32_bf16 v[72:75], v[160:163], v[208:211], v[72:75]
	v_mfma_f32_16x16x32_bf16 v[124:127], v[156:159], v[188:191], v[124:127]
	v_mfma_f32_16x16x32_bf16 v[120:123], v[164:167], v[188:191], v[120:123]
	v_mfma_f32_16x16x32_bf16 v[108:111], v[156:159], v[196:199], v[108:111]
	v_mfma_f32_16x16x32_bf16 v[104:107], v[164:167], v[196:199], v[104:107]
	v_mfma_f32_16x16x32_bf16 v[92:95], v[156:159], v[204:207], v[92:95]
	v_mfma_f32_16x16x32_bf16 v[88:91], v[164:167], v[204:207], v[88:91]
	v_mfma_f32_16x16x32_bf16 v[76:79], v[156:159], v[212:215], v[76:79]
	v_mfma_f32_16x16x32_bf16 v[72:75], v[164:167], v[212:215], v[72:75]
	v_mfma_f32_16x16x32_bf16 v[116:119], v[168:171], v[184:187], v[116:119]
	v_mfma_f32_16x16x32_bf16 v[112:115], v[176:179], v[184:187], v[112:115]
	v_mfma_f32_16x16x32_bf16 v[100:103], v[168:171], v[192:195], v[100:103]
	v_mfma_f32_16x16x32_bf16 v[96:99], v[176:179], v[192:195], v[96:99]
	v_mfma_f32_16x16x32_bf16 v[84:87], v[168:171], v[200:203], v[84:87]
	v_mfma_f32_16x16x32_bf16 v[80:83], v[176:179], v[200:203], v[80:83]
	v_mfma_f32_16x16x32_bf16 v[68:71], v[168:171], v[208:211], v[68:71]
	v_mfma_f32_16x16x32_bf16 v[64:67], v[176:179], v[208:211], v[64:67]
	v_mfma_f32_16x16x32_bf16 v[116:119], v[172:175], v[188:191], v[116:119]
	v_mfma_f32_16x16x32_bf16 v[112:115], v[180:183], v[188:191], v[112:115]
	v_mfma_f32_16x16x32_bf16 v[100:103], v[172:175], v[196:199], v[100:103]
	v_mfma_f32_16x16x32_bf16 v[96:99], v[180:183], v[196:199], v[96:99]
	v_mfma_f32_16x16x32_bf16 v[84:87], v[172:175], v[204:207], v[84:87]
	v_mfma_f32_16x16x32_bf16 v[80:83], v[180:183], v[204:207], v[80:83]
	v_mfma_f32_16x16x32_bf16 v[68:71], v[172:175], v[212:215], v[68:71]
	v_mfma_f32_16x16x32_bf16 v[64:67], v[180:183], v[212:215], v[64:67]
	s_barrier
; #define PG8_STAGE(bufoff, gbase, voff) do { _Pragma("unroll") for (int _i = 0; _i < 2; ++_i) \
;         __builtin_amdgcn_global_load_lds((const unsigned*)((const char*)(gbase) + (voff)[_i]), (PG8_LAS unsigned*)(lds + (bufoff) + ldsw + _i * 8192), 16, 0, 0); } while (0)
; #define PG8_LDA(dst, b, h) do { _Pragma("unroll") for (int m = 0; m < 4; ++m) _Pragma("unroll") for (int k = 0; k < 2; ++k) dst[m][k] = *(const PG8_LAS bf16x8*)(lds + PG8_SA(b, h) + aoff + m * 2048 + k * 1024); } while (0)
; #define PG8_LDB(dst, b, h) do { _Pragma("unroll") for (int n = 0; n < 2; ++n) _Pragma("unroll") for (int k = 0; k < 2; ++k) dst[n][k] = *(const PG8_LAS bf16x8*)(lds + PG8_SB(b, h) + boff + n * 2048 + k * 1024); } while (0)
; #define PG8_MMA(ai, bj, At, Bt) do { __builtin_amdgcn_s_setprio(1); _Pragma("unroll") for (int m = 0; m < 4; ++m) _Pragma("unroll") for (int n = 0; n < 2; ++n) _Pragma("unroll") for (int k = 0; k < 2; ++k) \
;         acc[ai][bj][m][n] = __builtin_amdgcn_mfma_f32_16x16x32_bf16(Bt[n][k], At[m][k], acc[ai][bj][m][n], 0, 0, 0); __builtin_amdgcn_s_setprio(0); } while (0)
; #define PG8_WAIT_V(n) asm volatile("s_waitcnt vmcnt(" #n ")" ::: "memory")
; template <class Epi, class Sched, bool ALIGN_EPI = false, bool SP2 = false>
; __device__ __forceinline__ void gemm_phase(PG8_LAS unsigned char* lds, const Gemm g, const Sched& S, const Epi& E) {
;     ...
;             PG8_LDB(B0, 0, 0); PG8_LDB(B1, 0, 1); PG8_SCHED; PG8_LDA(At, 0, 0); PG8_STAGE(PG8_SA(1, 1), a1 + hstep, voffA);
;             PG8_WAIT_V(8); PG8_WAIT_L(0); PG8_BAR; PG8_MMA(0, 0, At, B0); PG8_MMA(0, 1, At, B1); PG8_BAR; PG8_SCHED;
;             PG8_LDA(At, 0, 1); PG8_STAGE(PG8_SB(0, 0), b2, voffB); PG8_STAGE(PG8_SB(0, 1), b2 + hstep, voffB); PG8_STAGE(PG8_SA(0, 0), a2, voffA);
;             PG8_WAIT_V(8); PG8_WAIT_L(0); PG8_BAR; PG8_MMA(1, 0, At, B0); PG8_MMA(1, 1, At, B1); PG8_BAR; PG8_SCHED;
;             PG8_LDB(B0, 1, 0); PG8_LDB(B1, 1, 1); PG8_SCHED; PG8_LDA(At, 1, 0); PG8_STAGE(PG8_SA(0, 1), a2 + hstep, voffA);
;             PG8_WAIT_V(8); PG8_WAIT_L(0); PG8_BAR; PG8_MMA(0, 0, At, B0); PG8_MMA(0, 1, At, B1); PG8_BAR; PG8_SCHED;
;             PG8_LDA(At, 1, 1); PG8_STAGE(PG8_SB(1, 0), b3, voffB); PG8_STAGE(PG8_SB(1, 1), b3 + hstep, voffB); PG8_STAGE(PG8_SA(1, 0), a3, voffA);
;             PG8_WAIT_V(8); PG8_WAIT_L(0); PG8_BAR; PG8_MMA(1, 0, At, B0); PG8_MMA(1, 1, At, B1); PG8_BAR; PG8_SCHED;
	s_add_i32 s36, s62, s42
	s_add_u32 s86, s34, 0x80
	s_addc_u32 s87, s35, 0
	s_mov_b32 m0, s36
	ds_read_b128 v[184:187], v151 offset:49152
	ds_read_b128 v[188:191], v151 offset:50176
	ds_read_b128 v[192:195], v151 offset:51200
	ds_read_b128 v[196:199], v151 offset:52224
	ds_read_b128 v[200:203], v151 offset:53248
	ds_read_b128 v[204:207], v151 offset:54272
	ds_read_b128 v[208:211], v151 offset:55296
	ds_read_b128 v[212:215], v151 offset:56320
	global_load_lds_dwordx4 v132, s[86:87]
	s_add_i32 m0, s36, 0x2000
	s_add_u32 s34, s34, 0x80080
	s_addc_u32 s35, s35, 0
	s_add_i32 s36, s63, s42
	global_load_lds_dwordx4 v128, s[86:87]
	s_mov_b32 m0, s36
	s_nop 0
	global_load_lds_dwordx4 v132, s[34:35]
	s_add_i32 m0, s36, 0x2000
	s_nop 0
	global_load_lds_dwordx4 v128, s[34:35]
	s_mov_b32 m0, s49
	s_nop 0
	global_load_lds_dwordx4 v134, s[84:85]
	s_mov_b32 m0, s50
	s_nop 0
	global_load_lds_dwordx4 v130, s[84:85]
	s_waitcnt vmcnt(8)
	s_waitcnt lgkmcnt(0)
	s_barrier
	s_waitcnt lgkmcnt(0)
	v_mfma_f32_16x16x32_bf16 v[60:63], v[152:155], v[184:187], v[60:63]
	v_mfma_f32_16x16x32_bf16 v[56:59], v[160:163], v[184:187], v[56:59]
	v_mfma_f32_16x16x32_bf16 v[44:47], v[152:155], v[192:195], v[44:47]
	v_mfma_f32_16x16x32_bf16 v[40:43], v[160:163], v[192:195], v[40:43]
	v_mfma_f32_16x16x32_bf16 v[28:31], v[152:155], v[200:203], v[28:31]
	v_mfma_f32_16x16x32_bf16 v[24:27], v[160:163], v[200:203], v[24:27]
	v_mfma_f32_16x16x32_bf16 v[12:15], v[152:155], v[208:211], v[12:15]
	v_mfma_f32_16x16x32_bf16 v[8:11], v[160:163], v[208:211], v[8:11]
	v_mfma_f32_16x16x32_bf16 v[60:63], v[156:159], v[188:191], v[60:63]
	v_mfma_f32_16x16x32_bf16 v[56:59], v[164:167], v[188:191], v[56:59]
	v_mfma_f32_16x16x32_bf16 v[44:47], v[156:159], v[196:199], v[44:47]
	v_mfma_f32_16x16x32_bf16 v[40:43], v[164:167], v[196:199], v[40:43]
	v_mfma_f32_16x16x32_bf16 v[28:31], v[156:159], v[204:207], v[28:31]
	v_mfma_f32_16x16x32_bf16 v[24:27], v[164:167], v[204:207], v[24:27]
	v_mfma_f32_16x16x32_bf16 v[12:15], v[156:159], v[212:215], v[12:15]
	v_mfma_f32_16x16x32_bf16 v[8:11], v[164:167], v[212:215], v[8:11]
	v_mfma_f32_16x16x32_bf16 v[52:55], v[168:171], v[184:187], v[52:55]
	v_mfma_f32_16x16x32_bf16 v[48:51], v[176:179], v[184:187], v[48:51]
	v_mfma_f32_16x16x32_bf16 v[36:39], v[168:171], v[192:195], v[36:39]
	v_mfma_f32_16x16x32_bf16 v[32:35], v[176:179], v[192:195], v[32:35]
	v_mfma_f32_16x16x32_bf16 v[20:23], v[168:171], v[200:203], v[20:23]
	v_mfma_f32_16x16x32_bf16 v[16:19], v[176:179], v[200:203], v[16:19]
	v_mfma_f32_16x16x32_bf16 v[4:7], v[168:171], v[208:211], v[4:7]
	v_mfma_f32_16x16x32_bf16 v[0:3], v[176:179], v[208:211], v[0:3]
	v_mfma_f32_16x16x32_bf16 v[52:55], v[172:175], v[188:191], v[52:55]
	v_mfma_f32_16x16x32_bf16 v[48:51], v[180:183], v[188:191], v[48:51]
	v_mfma_f32_16x16x32_bf16 v[36:39], v[172:175], v[196:199], v[36:39]
	v_mfma_f32_16x16x32_bf16 v[32:35], v[180:183], v[196:199], v[32:35]
	v_mfma_f32_16x16x32_bf16 v[20:23], v[172:175], v[204:207], v[20:23]
	v_mfma_f32_16x16x32_bf16 v[16:19], v[180:183], v[204:207], v[16:19]
	v_mfma_f32_16x16x32_bf16 v[4:7], v[172:175], v[212:215], v[4:7]
	v_mfma_f32_16x16x32_bf16 v[0:3], v[180:183], v[212:215], v[0:3]
	s_add_i32 s61, s61, 2
	s_add_u32 s30, s30, 0x100
	s_addc_u32 s31, s31, 0
	s_add_u32 s59, s59, 0x100
	s_addc_u32 s60, s60, 0
	s_cmp_gt_u32 s61, 29
	s_barrier
.LBB0_945:
	ds_read_b128 v[152:155], v149
	ds_read_b128 v[156:159], v149 offset:1024
	ds_read_b128 v[160:163], v149 offset:2048
	ds_read_b128 v[164:167], v149 offset:3072
	ds_read_b128 v[168:171], v150
	ds_read_b128 v[172:175], v150 offset:1024
	ds_read_b128 v[176:179], v150 offset:2048
	ds_read_b128 v[180:183], v150 offset:3072
	s_add_u32 s34, s30, 0xfff80080
	s_addc_u32 s35, s31, -1
	s_cmp_eq_u32 s61, 28
	s_cselect_b32 s37, s23, s35
	s_cselect_b32 s36, s57, s34
	s_cselect_b32 s35, s15, s60
	s_cselect_b32 s34, s58, s59
	s_add_i32 m0, s29, 0xc000
	ds_read_b128 v[184:187], v151
	ds_read_b128 v[188:191], v151 offset:1024
	ds_read_b128 v[192:195], v151 offset:2048
	ds_read_b128 v[196:199], v151 offset:3072
	ds_read_b128 v[200:203], v151 offset:4096
	ds_read_b128 v[204:207], v151 offset:5120
	ds_read_b128 v[208:211], v151 offset:6144
	ds_read_b128 v[212:215], v151 offset:7168
	global_load_lds_dwordx4 v136, s[30:31]
	s_add_i32 m0, s29, 0xe000
	s_nop 0
	global_load_lds_dwordx4 v138, s[30:31]
	s_waitcnt vmcnt(8)
	s_waitcnt lgkmcnt(0)
	s_barrier
	s_waitcnt lgkmcnt(0)
	v_mfma_f32_16x16x32_bf16 v[124:127], v[152:155], v[184:187], v[124:127]
	v_mfma_f32_16x16x32_bf16 v[120:123], v[160:163], v[184:187], v[120:123]
	v_mfma_f32_16x16x32_bf16 v[108:111], v[152:155], v[192:195], v[108:111]
	v_mfma_f32_16x16x32_bf16 v[104:107], v[160:163], v[192:195], v[104:107]
	v_mfma_f32_16x16x32_bf16 v[92:95], v[152:155], v[200:203], v[92:95]
	v_mfma_f32_16x16x32_bf16 v[88:91], v[160:163], v[200:203], v[88:91]
	v_mfma_f32_16x16x32_bf16 v[76:79], v[152:155], v[208:211], v[76:79]
	v_mfma_f32_16x16x32_bf16 v[72:75], v[160:163], v[208:211], v[72:75]
	v_mfma_f32_16x16x32_bf16 v[124:127], v[156:159], v[188:191], v[124:127]
	v_mfma_f32_16x16x32_bf16 v[120:123], v[164:167], v[188:191], v[120:123]
	v_mfma_f32_16x16x32_bf16 v[108:111], v[156:159], v[196:199], v[108:111]
	v_mfma_f32_16x16x32_bf16 v[104:107], v[164:167], v[196:199], v[104:107]
	v_mfma_f32_16x16x32_bf16 v[92:95], v[156:159], v[204:207], v[92:95]
	v_mfma_f32_16x16x32_bf16 v[88:91], v[164:167], v[204:207], v[88:91]
	v_mfma_f32_16x16x32_bf16 v[76:79], v[156:159], v[212:215], v[76:79]
	v_mfma_f32_16x16x32_bf16 v[72:75], v[164:167], v[212:215], v[72:75]
	v_mfma_f32_16x16x32_bf16 v[116:119], v[168:171], v[184:187], v[116:119]
	v_mfma_f32_16x16x32_bf16 v[112:115], v[176:179], v[184:187], v[112:115]
	v_mfma_f32_16x16x32_bf16 v[100:103], v[168:171], v[192:195], v[100:103]
	v_mfma_f32_16x16x32_bf16 v[96:99], v[176:179], v[192:195], v[96:99]
	v_mfma_f32_16x16x32_bf16 v[84:87], v[168:171], v[200:203], v[84:87]
	v_mfma_f32_16x16x32_bf16 v[80:83], v[176:179], v[200:203], v[80:83]
	v_mfma_f32_16x16x32_bf16 v[68:71], v[168:171], v[208:211], v[68:71]
	v_mfma_f32_16x16x32_bf16 v[64:67], v[176:179], v[208:211], v[64:67]
	v_mfma_f32_16x16x32_bf16 v[116:119], v[172:175], v[188:191], v[116:119]
	v_mfma_f32_16x16x32_bf16 v[112:115], v[180:183], v[188:191], v[112:115]
	v_mfma_f32_16x16x32_bf16 v[100:103], v[172:175], v[196:199], v[100:103]
	v_mfma_f32_16x16x32_bf16 v[96:99], v[180:183], v[196:199], v[96:99]
	v_mfma_f32_16x16x32_bf16 v[84:87], v[172:175], v[204:207], v[84:87]
	v_mfma_f32_16x16x32_bf16 v[80:83], v[180:183], v[204:207], v[80:83]
	v_mfma_f32_16x16x32_bf16 v[68:71], v[172:175], v[212:215], v[68:71]
	v_mfma_f32_16x16x32_bf16 v[64:67], v[180:183], v[212:215], v[64:67]
	s_barrier
; #define PG8_STAGE(bufoff, gbase, voff) do { _Pragma("unroll") for (int _i = 0; _i < 2; ++_i) \
;         __builtin_amdgcn_global_load_lds((const unsigned*)((const char*)(gbase) + (voff)[_i]), (PG8_LAS unsigned*)(lds + (bufoff) + ldsw + _i * 8192), 16, 0, 0); } while (0)
; #define PG8_LDA(dst, b, h) do { _Pragma("unroll") for (int m = 0; m < 4; ++m) _Pragma("unroll") for (int k = 0; k < 2; ++k) dst[m][k] = *(const PG8_LAS bf16x8*)(lds + PG8_SA(b, h) + aoff + m * 2048 + k * 1024); } while (0)
; #define PG8_LDB(dst, b, h) do { _Pragma("unroll") for (int n = 0; n < 2; ++n) _Pragma("unroll") for (int k = 0; k < 2; ++k) dst[n][k] = *(const PG8_LAS bf16x8*)(lds + PG8_SB(b, h) + boff + n * 2048 + k * 1024); } while (0)
; #define PG8_MMA(ai, bj, At, Bt) do { __builtin_amdgcn_s_setprio(1); _Pragma("unroll") for (int m = 0; m < 4; ++m) _Pragma("unroll") for (int n = 0; n < 2; ++n) _Pragma("unroll") for (int k = 0; k < 2; ++k) \
;         acc[ai][bj][m][n] = __builtin_amdgcn_mfma_f32_16x16x32_bf16(Bt[n][k], At[m][k], acc[ai][bj][m][n], 0, 0, 0); __builtin_amdgcn_s_setprio(0); } while (0)
; #define PG8_WAIT_V(n) asm volatile("s_waitcnt vmcnt(" #n ")" ::: "memory")
; #define PG8_WAIT_L(n) asm volatile("s_waitcnt lgkmcnt(" #n ")" ::: "memory")
; #define PG8_BAR __builtin_amdgcn_s_barrier()
; #define PG8_SCHED __builtin_amdgcn_sched_barrier(0)
; template <class Epi, class Sched, bool ALIGN_EPI = false, bool SP2 = false>
; __device__ __forceinline__ void gemm_phase(PG8_LAS unsigned char* lds, const Gemm g, const Sched& S, const Epi& E) {
;     ...
;             PG8_WAIT_V(8); PG8_WAIT_L(0); PG8_BAR; PG8_MMA(0, 0, At, B0); PG8_MMA(0, 1, At, B1); PG8_BAR; PG8_SCHED;
;             PG8_LDA(At, 0, 1); PG8_STAGE(PG8_SB(0, 0), b2, voffB); PG8_STAGE(PG8_SB(0, 1), b2 + hstep, voffB); PG8_STAGE(PG8_SA(0, 0), a2, voffA);
;             PG8_WAIT_V(8); PG8_WAIT_L(0); PG8_BAR; PG8_MMA(1, 0, At, B0); PG8_MMA(1, 1, At, B1); PG8_BAR; PG8_SCHED;
;             PG8_LDB(B0, 1, 0); PG8_LDB(B1, 1, 1); PG8_SCHED; PG8_LDA(At, 1, 0); PG8_STAGE(PG8_SA(0, 1), a2 + hstep, voffA);
;             PG8_WAIT_V(8); PG8_WAIT_L(0); PG8_BAR; PG8_MMA(0, 0, At, B0); PG8_MMA(0, 1, At, B1); PG8_BAR; PG8_SCHED;
	s_add_i32 s62, s53, s42
	s_mov_b32 m0, s62
	ds_read_b128 v[184:187], v151 offset:16384
	ds_read_b128 v[188:191], v151 offset:17408
	ds_read_b128 v[192:195], v151 offset:18432
	ds_read_b128 v[196:199], v151 offset:19456
	ds_read_b128 v[200:203], v151 offset:20480
	ds_read_b128 v[204:207], v151 offset:21504
	ds_read_b128 v[208:211], v151 offset:22528
	ds_read_b128 v[212:215], v151 offset:23552
	global_load_lds_dwordx4 v132, s[34:35]
	s_add_i32 m0, s62, 0x2000
	s_add_u32 s62, s34, 0x80000
	s_addc_u32 s63, s35, 0
	s_add_i32 s64, s54, s42
	global_load_lds_dwordx4 v128, s[34:35]
	s_mov_b32 m0, s64
	s_nop 0
	global_load_lds_dwordx4 v132, s[62:63]
	s_add_i32 m0, s64, 0x2000
	s_nop 0
	global_load_lds_dwordx4 v128, s[62:63]
	s_mov_b32 m0, s29
	s_nop 0
	global_load_lds_dwordx4 v134, s[36:37]
	s_mov_b32 m0, s45
	s_nop 0
	global_load_lds_dwordx4 v130, s[36:37]
	s_waitcnt vmcnt(8)
	s_waitcnt lgkmcnt(0)
	s_barrier
	s_waitcnt lgkmcnt(0)
	v_mfma_f32_16x16x32_bf16 v[60:63], v[152:155], v[184:187], v[60:63]
	v_mfma_f32_16x16x32_bf16 v[56:59], v[160:163], v[184:187], v[56:59]
	v_mfma_f32_16x16x32_bf16 v[44:47], v[152:155], v[192:195], v[44:47]
	v_mfma_f32_16x16x32_bf16 v[40:43], v[160:163], v[192:195], v[40:43]
	v_mfma_f32_16x16x32_bf16 v[28:31], v[152:155], v[200:203], v[28:31]
	v_mfma_f32_16x16x32_bf16 v[24:27], v[160:163], v[200:203], v[24:27]
	v_mfma_f32_16x16x32_bf16 v[12:15], v[152:155], v[208:211], v[12:15]
	v_mfma_f32_16x16x32_bf16 v[8:11], v[160:163], v[208:211], v[8:11]
	v_mfma_f32_16x16x32_bf16 v[60:63], v[156:159], v[188:191], v[60:63]
	v_mfma_f32_16x16x32_bf16 v[56:59], v[164:167], v[188:191], v[56:59]
	v_mfma_f32_16x16x32_bf16 v[44:47], v[156:159], v[196:199], v[44:47]
	v_mfma_f32_16x16x32_bf16 v[40:43], v[164:167], v[196:199], v[40:43]
	v_mfma_f32_16x16x32_bf16 v[28:31], v[156:159], v[204:207], v[28:31]
	v_mfma_f32_16x16x32_bf16 v[24:27], v[164:167], v[204:207], v[24:27]
	v_mfma_f32_16x16x32_bf16 v[12:15], v[156:159], v[212:215], v[12:15]
	v_mfma_f32_16x16x32_bf16 v[8:11], v[164:167], v[212:215], v[8:11]
	v_mfma_f32_16x16x32_bf16 v[52:55], v[168:171], v[184:187], v[52:55]
	v_mfma_f32_16x16x32_bf16 v[48:51], v[176:179], v[184:187], v[48:51]
	v_mfma_f32_16x16x32_bf16 v[36:39], v[168:171], v[192:195], v[36:39]
	v_mfma_f32_16x16x32_bf16 v[32:35], v[176:179], v[192:195], v[32:35]
	v_mfma_f32_16x16x32_bf16 v[20:23], v[168:171], v[200:203], v[20:23]
	v_mfma_f32_16x16x32_bf16 v[16:19], v[176:179], v[200:203], v[16:19]
	v_mfma_f32_16x16x32_bf16 v[4:7], v[168:171], v[208:211], v[4:7]
	v_mfma_f32_16x16x32_bf16 v[0:3], v[176:179], v[208:211], v[0:3]
	v_mfma_f32_16x16x32_bf16 v[52:55], v[172:175], v[188:191], v[52:55]
	v_mfma_f32_16x16x32_bf16 v[48:51], v[180:183], v[188:191], v[48:51]
	v_mfma_f32_16x16x32_bf16 v[36:39], v[172:175], v[196:199], v[36:39]
	v_mfma_f32_16x16x32_bf16 v[32:35], v[180:183], v[196:199], v[32:35]
	v_mfma_f32_16x16x32_bf16 v[20:23], v[172:175], v[204:207], v[20:23]
	v_mfma_f32_16x16x32_bf16 v[16:19], v[180:183], v[204:207], v[16:19]
	v_mfma_f32_16x16x32_bf16 v[4:7], v[172:175], v[212:215], v[4:7]
	v_mfma_f32_16x16x32_bf16 v[0:3], v[180:183], v[212:215], v[0:3]
	s_barrier
	s_add_i32 s62, 0, 0x18000
	s_add_i32 s63, 0, 0x1c000
	v_add_u32_e32 v164, s62, v147
	v_add_u32_e32 v180, s63, v147
	ds_read_b128 v[152:155], v164
	ds_read_b128 v[156:159], v164 offset:1024
	ds_read_b128 v[160:163], v164 offset:2048
	ds_read_b128 v[164:167], v164 offset:3072
	ds_read_b128 v[168:171], v180
	ds_read_b128 v[172:175], v180 offset:1024
	ds_read_b128 v[176:179], v180 offset:2048
	ds_read_b128 v[180:183], v180 offset:3072
	s_add_u32 s84, s36, 0x80
	s_addc_u32 s85, s37, 0
	s_add_u32 s36, s36, 0x80000
	s_addc_u32 s37, s37, 0
	s_mov_b32 m0, s46
	ds_read_b128 v[184:187], v151 offset:32768
	ds_read_b128 v[188:191], v151 offset:33792
	ds_read_b128 v[192:195], v151 offset:34816
	ds_read_b128 v[196:199], v151 offset:35840
	ds_read_b128 v[200:203], v151 offset:36864
	ds_read_b128 v[204:207], v151 offset:37888
	ds_read_b128 v[208:211], v151 offset:38912
	ds_read_b128 v[212:215], v151 offset:39936
	global_load_lds_dwordx4 v134, s[36:37]
	s_mov_b32 m0, s47
	s_nop 0
	global_load_lds_dwordx4 v130, s[36:37]
	s_waitcnt vmcnt(8)
	s_waitcnt lgkmcnt(0)
	s_barrier
	s_waitcnt lgkmcnt(0)
	v_mfma_f32_16x16x32_bf16 v[124:127], v[152:155], v[184:187], v[124:127]
	v_mfma_f32_16x16x32_bf16 v[120:123], v[160:163], v[184:187], v[120:123]
	v_mfma_f32_16x16x32_bf16 v[108:111], v[152:155], v[192:195], v[108:111]
	v_mfma_f32_16x16x32_bf16 v[104:107], v[160:163], v[192:195], v[104:107]
	v_mfma_f32_16x16x32_bf16 v[92:95], v[152:155], v[200:203], v[92:95]
	v_mfma_f32_16x16x32_bf16 v[88:91], v[160:163], v[200:203], v[88:91]
	v_mfma_f32_16x16x32_bf16 v[76:79], v[152:155], v[208:211], v[76:79]
	v_mfma_f32_16x16x32_bf16 v[72:75], v[160:163], v[208:211], v[72:75]
	v_mfma_f32_16x16x32_bf16 v[124:127], v[156:159], v[188:191], v[124:127]
	v_mfma_f32_16x16x32_bf16 v[120:123], v[164:167], v[188:191], v[120:123]
	v_mfma_f32_16x16x32_bf16 v[108:111], v[156:159], v[196:199], v[108:111]
	v_mfma_f32_16x16x32_bf16 v[104:107], v[164:167], v[196:199], v[104:107]
	v_mfma_f32_16x16x32_bf16 v[92:95], v[156:159], v[204:207], v[92:95]
	v_mfma_f32_16x16x32_bf16 v[88:91], v[164:167], v[204:207], v[88:91]
	v_mfma_f32_16x16x32_bf16 v[76:79], v[156:159], v[212:215], v[76:79]
	v_mfma_f32_16x16x32_bf16 v[72:75], v[164:167], v[212:215], v[72:75]
	v_mfma_f32_16x16x32_bf16 v[116:119], v[168:171], v[184:187], v[116:119]
	v_mfma_f32_16x16x32_bf16 v[112:115], v[176:179], v[184:187], v[112:115]
	v_mfma_f32_16x16x32_bf16 v[100:103], v[168:171], v[192:195], v[100:103]
	v_mfma_f32_16x16x32_bf16 v[96:99], v[176:179], v[192:195], v[96:99]
	v_mfma_f32_16x16x32_bf16 v[84:87], v[168:171], v[200:203], v[84:87]
	v_mfma_f32_16x16x32_bf16 v[80:83], v[176:179], v[200:203], v[80:83]
	v_mfma_f32_16x16x32_bf16 v[68:71], v[168:171], v[208:211], v[68:71]
	v_mfma_f32_16x16x32_bf16 v[64:67], v[176:179], v[208:211], v[64:67]
	v_mfma_f32_16x16x32_bf16 v[116:119], v[172:175], v[188:191], v[116:119]
	v_mfma_f32_16x16x32_bf16 v[112:115], v[180:183], v[188:191], v[112:115]
	v_mfma_f32_16x16x32_bf16 v[100:103], v[172:175], v[196:199], v[100:103]
	v_mfma_f32_16x16x32_bf16 v[96:99], v[180:183], v[196:199], v[96:99]
	v_mfma_f32_16x16x32_bf16 v[84:87], v[172:175], v[204:207], v[84:87]
	v_mfma_f32_16x16x32_bf16 v[80:83], v[180:183], v[204:207], v[80:83]
	v_mfma_f32_16x16x32_bf16 v[68:71], v[172:175], v[212:215], v[68:71]
	v_mfma_f32_16x16x32_bf16 v[64:67], v[180:183], v[212:215], v[64:67]
	s_barrier
; __device__ __forceinline__ float fsilu(float v) { return v * fsigmoid(v); }
; __device__ __forceinline__ u32x4 pack8(const f32x4 a, const f32x4 b) { u32x4 w; w.x = cvt_pk_bf16(a[0], a[1]); w.y = cvt_pk_bf16(a[2], a[3]); w.z = cvt_pk_bf16(b[0], b[1]); w.w = cvt_pk_bf16(b[2], b[3]); return w; }
; #define PG8_STAGE(bufoff, gbase, voff) do { _Pragma("unroll") for (int _i = 0; _i < 2; ++_i) \
;         __builtin_amdgcn_global_load_lds((const unsigned*)((const char*)(gbase) + (voff)[_i]), (PG8_LAS unsigned*)(lds + (bufoff) + ldsw + _i * 8192), 16, 0, 0); } while (0)
; #define PG8_LDA(dst, b, h) do { _Pragma("unroll") for (int m = 0; m < 4; ++m) _Pragma("unroll") for (int k = 0; k < 2; ++k) dst[m][k] = *(const PG8_LAS bf16x8*)(lds + PG8_SA(b, h) + aoff + m * 2048 + k * 1024); } while (0)
; #define PG8_MMA(ai, bj, At, Bt) do { __builtin_amdgcn_s_setprio(1); _Pragma("unroll") for (int m = 0; m < 4; ++m) _Pragma("unroll") for (int n = 0; n < 2; ++n) _Pragma("unroll") for (int k = 0; k < 2; ++k) \
;         acc[ai][bj][m][n] = __builtin_amdgcn_mfma_f32_16x16x32_bf16(Bt[n][k], At[m][k], acc[ai][bj][m][n], 0, 0, 0); __builtin_amdgcn_s_setprio(0); } while (0)
; #define PG8_BAR __builtin_amdgcn_s_barrier()
;     __device__ __forceinline__ void operator()(const f32x4 (&acc)[2][2][4][2], const Unit& u, int wr, int wc, int fr, int fq) const {
;         const int row0 = u.pm * BM + wr * 64 + fr, col0 = u.pn * 128 + wc * 32 + 8 * fq;
; #pragma unroll
;         for (int ai = 0; ai < 2; ++ai)
; #pragma unroll
;             for (int m = 0; m < 4; ++m) {
;                 bf16_t* rowp = O + (size_t)(row0 + ai * HALF + m * 16) * ldc + col0;
;                 f32x4 h0, h1;
; #pragma unroll
;                 for (int j = 0; j < 4; ++j) { h0[j] = fsilu(acc[ai][0][m][0][j]) * acc[ai][1][m][0][j]; h1[j] = fsilu(acc[ai][0][m][1][j]) * acc[ai][1][m][1][j]; }
;                 *(u32x4*)rowp = pack8(h0, h1);
; template <class Epi, class Sched, bool ALIGN_EPI = false, bool SP2 = false>
; __device__ __forceinline__ void gemm_phase(PG8_LAS unsigned char* lds, const Gemm g, const Sched& S, const Epi& E) {
;     ...
;             PG8_LDA(At, 1, 1); PG8_STAGE(PG8_SB(1, 0), b3, voffB); PG8_STAGE(PG8_SB(1, 1), b3 + hstep, voffB); PG8_STAGE(PG8_SA(1, 0), a3, voffA);
;             PG8_WAIT_V(8); PG8_WAIT_L(0); PG8_BAR; PG8_MMA(1, 0, At, B0); PG8_MMA(1, 1, At, B1); PG8_BAR; PG8_SCHED;
	s_add_i32 s36, s62, s42
	s_add_u32 s86, s34, 0x80
	s_addc_u32 s87, s35, 0
	s_mov_b32 m0, s36
	ds_read_b128 v[184:187], v151 offset:49152
	ds_read_b128 v[188:191], v151 offset:50176
	ds_read_b128 v[192:195], v151 offset:51200
	ds_read_b128 v[196:199], v151 offset:52224
	ds_read_b128 v[200:203], v151 offset:53248
	ds_read_b128 v[204:207], v151 offset:54272
	ds_read_b128 v[208:211], v151 offset:55296
	ds_read_b128 v[212:215], v151 offset:56320
	global_load_lds_dwordx4 v132, s[86:87]
	s_add_i32 m0, s36, 0x2000
	s_add_u32 s34, s34, 0x80080
	s_addc_u32 s35, s35, 0
	s_add_i32 s36, s63, s42
	global_load_lds_dwordx4 v128, s[86:87]
	s_mov_b32 m0, s36
	s_nop 0
	global_load_lds_dwordx4 v132, s[34:35]
	s_add_i32 m0, s36, 0x2000
	s_nop 0
	global_load_lds_dwordx4 v128, s[34:35]
	s_mov_b32 m0, s49
	s_nop 0
	global_load_lds_dwordx4 v134, s[84:85]
	s_mov_b32 m0, s50
	s_nop 0
	global_load_lds_dwordx4 v130, s[84:85]
	s_waitcnt vmcnt(8)
	s_waitcnt lgkmcnt(0)
	s_barrier
	s_waitcnt lgkmcnt(0)
	v_mfma_f32_16x16x32_bf16 v[60:63], v[152:155], v[184:187], v[60:63]
	v_mfma_f32_16x16x32_bf16 v[56:59], v[160:163], v[184:187], v[56:59]
	v_mfma_f32_16x16x32_bf16 v[44:47], v[152:155], v[192:195], v[44:47]
	v_mfma_f32_16x16x32_bf16 v[40:43], v[160:163], v[192:195], v[40:43]
	v_mfma_f32_16x16x32_bf16 v[28:31], v[152:155], v[200:203], v[28:31]
	v_mfma_f32_16x16x32_bf16 v[24:27], v[160:163], v[200:203], v[24:27]
	v_mfma_f32_16x16x32_bf16 v[12:15], v[152:155], v[208:211], v[12:15]
	v_mfma_f32_16x16x32_bf16 v[8:11], v[160:163], v[208:211], v[8:11]
	v_mfma_f32_16x16x32_bf16 v[60:63], v[156:159], v[188:191], v[60:63]
	v_mfma_f32_16x16x32_bf16 v[56:59], v[164:167], v[188:191], v[56:59]
	v_mfma_f32_16x16x32_bf16 v[44:47], v[156:159], v[196:199], v[44:47]
	v_mfma_f32_16x16x32_bf16 v[40:43], v[164:167], v[196:199], v[40:43]
	v_mfma_f32_16x16x32_bf16 v[28:31], v[156:159], v[204:207], v[28:31]
	v_mfma_f32_16x16x32_bf16 v[24:27], v[164:167], v[204:207], v[24:27]
	v_mfma_f32_16x16x32_bf16 v[12:15], v[156:159], v[212:215], v[12:15]
	v_mfma_f32_16x16x32_bf16 v[8:11], v[164:167], v[212:215], v[8:11]
	v_mfma_f32_16x16x32_bf16 v[52:55], v[168:171], v[184:187], v[52:55]
	v_mfma_f32_16x16x32_bf16 v[48:51], v[176:179], v[184:187], v[48:51]
	v_mfma_f32_16x16x32_bf16 v[36:39], v[168:171], v[192:195], v[36:39]
	v_mfma_f32_16x16x32_bf16 v[32:35], v[176:179], v[192:195], v[32:35]
	v_mfma_f32_16x16x32_bf16 v[20:23], v[168:171], v[200:203], v[20:23]
	v_mfma_f32_16x16x32_bf16 v[16:19], v[176:179], v[200:203], v[16:19]
	v_mfma_f32_16x16x32_bf16 v[4:7], v[168:171], v[208:211], v[4:7]
	v_mfma_f32_16x16x32_bf16 v[0:3], v[176:179], v[208:211], v[0:3]
	v_mfma_f32_16x16x32_bf16 v[52:55], v[172:175], v[188:191], v[52:55]
	v_mfma_f32_16x16x32_bf16 v[48:51], v[180:183], v[188:191], v[48:51]
	v_mfma_f32_16x16x32_bf16 v[36:39], v[172:175], v[196:199], v[36:39]
	v_mfma_f32_16x16x32_bf16 v[32:35], v[180:183], v[196:199], v[32:35]
	v_mfma_f32_16x16x32_bf16 v[20:23], v[172:175], v[204:207], v[20:23]
	v_mfma_f32_16x16x32_bf16 v[16:19], v[180:183], v[204:207], v[16:19]
	v_mfma_f32_16x16x32_bf16 v[4:7], v[172:175], v[212:215], v[4:7]
	v_mfma_f32_16x16x32_bf16 v[0:3], v[180:183], v[212:215], v[0:3]
	s_add_i32 s61, s61, 2
	s_add_u32 s30, s30, 0x100
	s_addc_u32 s31, s31, 0
	s_add_u32 s59, s59, 0x100
	s_addc_u32 s60, s60, 0
	s_cmp_gt_u32 s61, 29
	s_barrier
	s_cbranch_scc0 .LBB0_945
	v_mul_f32_e32 v153, 0xbfb8aa3b, v124
	v_mul_f32_e32 v158, 0xbfb8aa3b, v120
	v_exp_f32_e32 v153, v153
	v_exp_f32_e32 v159, v158
	v_mul_f32_e32 v158, 0xbfb8aa3b, v125
	v_exp_f32_e32 v160, v158
	v_add_f32_e32 v153, 1.0, v153
	v_rcp_f32_e32 v158, v153
	v_add_f32_e32 v153, 1.0, v159
	v_add_f32_e32 v159, 1.0, v160
	v_rcp_f32_e32 v159, v159
	v_mul_f32_e32 v160, 0xbfb8aa3b, v121
	v_exp_f32_e32 v161, v160
	v_rcp_f32_e32 v160, v153
	v_pk_mul_f32 v[124:125], v[124:125], v[158:159]
	v_mul_f32_e32 v153, 0xbfb8aa3b, v127
	v_pk_mul_f32 v[116:117], v[124:125], v[116:117]
	v_add_f32_e32 v124, 1.0, v161
	v_mul_f32_e32 v125, 0xbfb8aa3b, v122
	v_rcp_f32_e32 v161, v124
	v_mul_f32_e32 v124, 0xbfb8aa3b, v126
	v_exp_f32_e32 v125, v125
	v_exp_f32_e32 v124, v124
	v_exp_f32_e32 v153, v153
	v_mul_f32_e32 v158, 0xbfb8aa3b, v123
	v_exp_f32_e32 v159, v158
	v_add_f32_e32 v125, 1.0, v125
	v_add_f32_e32 v124, 1.0, v124
	v_rcp_f32_e32 v158, v125
	v_add_f32_e32 v125, 1.0, v153
	v_rcp_f32_e32 v124, v124
	v_rcp_f32_e32 v125, v125
	v_add_f32_e32 v153, 1.0, v159
	v_rcp_f32_e32 v159, v153
	v_pk_mul_f32 v[120:121], v[120:121], v[160:161]
	v_lshl_or_b32 v154, s56, 7, v148
	v_pk_mul_f32 v[120:121], v[120:121], v[112:113]
	v_pk_mul_f32 v[112:113], v[126:127], v[124:125]
	v_lshl_add_u32 v152, s28, 8, v146
	v_ashrrev_i32_e32 v155, 31, v154
	v_mov_b64_e32 v[144:145], s[10:11]
	v_pk_mul_f32 v[118:119], v[112:113], v[118:119]
	v_pk_mul_f32 v[112:113], v[122:123], v[158:159]
	v_mad_i64_i32 v[156:157], s[30:31], v152, s55, v[144:145]
	v_pk_mul_f32 v[122:123], v[112:113], v[114:115]
	v_lshlrev_b64 v[112:113], 1, v[154:155]
	v_lshl_add_u64 v[124:125], v[156:157], 0, v[112:113]
	v_cvt_pk_bf16_f32 v114, v116, v117
	v_cvt_pk_bf16_f32 v115, v118, v119
	v_cvt_pk_bf16_f32 v116, v120, v121
	v_cvt_pk_bf16_f32 v117, v122, v123
	global_store_dwordx4 v[124:125], v[114:117], off
	v_mul_f32_e32 v118, 0xbfb8aa3b, v109
	v_exp_f32_e32 v118, v118
	v_mul_f32_e32 v116, 0xbfb8aa3b, v108
	v_mul_f32_e32 v117, 0xbfb8aa3b, v104
	v_exp_f32_e32 v116, v116
	v_exp_f32_e32 v117, v117
	v_or_b32_e32 v114, 16, v152
	v_mad_i64_i32 v[114:115], s[30:31], v114, s55, v[144:145]
	v_add_f32_e32 v116, 1.0, v116
	v_add_f32_e32 v119, 1.0, v117
	v_add_f32_e32 v117, 1.0, v118
	v_rcp_f32_e32 v116, v116
	v_rcp_f32_e32 v117, v117
; __device__ __forceinline__ unsigned cvt_pk_bf16(float lo, float hi) { const f32x2c v = {lo, hi}; const bf16x2c b = __builtin_convertvector(v, bf16x2c); return __builtin_bit_cast(unsigned, b); }
; __device__ __forceinline__ float fsigmoid(float v) { return __builtin_amdgcn_rcpf(1.0f + __builtin_amdgcn_exp2f(-LOG2E * v)); }
; __device__ __forceinline__ float fsilu(float v) { return v * fsigmoid(v); }
; __device__ __forceinline__ float bf_lo(unsigned w) { return __uint_as_float(w << 16); }
; __device__ __forceinline__ float bf_hi(unsigned w) { return __uint_as_float(w & 0xffff0000u); }
; __device__ __forceinline__ u32x4 pack8(const f32x4 a, const f32x4 b) { u32x4 w; w.x = cvt_pk_bf16(a[0], a[1]); w.y = cvt_pk_bf16(a[2], a[3]); w.z = cvt_pk_bf16(b[0], b[1]); w.w = cvt_pk_bf16(b[2], b[3]); return w; }
;     __device__ __forceinline__ void operator()(const f32x4 (&acc)[2][2][4][2], const Unit& u, int wr, int wc, int fr, int fq) const {
;         const int row0 = u.pm * BM + wr * 64 + fr, col0 = u.pn * 128 + wc * 32 + 8 * fq;
; #pragma unroll
;         for (int ai = 0; ai < 2; ++ai)
; #pragma unroll
;             for (int m = 0; m < 4; ++m) {
;                 bf16_t* rowp = O + (size_t)(row0 + ai * HALF + m * 16) * ldc + col0;
;                 f32x4 h0, h1;
; #pragma unroll
;                 for (int j = 0; j < 4; ++j) { h0[j] = fsilu(acc[ai][0][m][0][j]) * acc[ai][1][m][0][j]; h1[j] = fsilu(acc[ai][0][m][1][j]) * acc[ai][1][m][1][j]; }
;                 *(u32x4*)rowp = pack8(h0, h1);
	v_mul_f32_e32 v118, 0xbfb8aa3b, v105
	v_exp_f32_e32 v120, v118
	v_rcp_f32_e32 v118, v119
	v_pk_mul_f32 v[108:109], v[108:109], v[116:117]
	v_mul_f32_e32 v116, 0xbfb8aa3b, v111
	v_pk_mul_f32 v[100:101], v[108:109], v[100:101]
	v_add_f32_e32 v108, 1.0, v120
	v_rcp_f32_e32 v119, v108
	v_mul_f32_e32 v109, 0xbfb8aa3b, v106
	v_mul_f32_e32 v108, 0xbfb8aa3b, v110
	v_exp_f32_e32 v109, v109
	v_exp_f32_e32 v108, v108
	v_exp_f32_e32 v117, v116
	v_mul_f32_e32 v116, 0xbfb8aa3b, v107
	v_pk_mul_f32 v[104:105], v[104:105], v[118:119]
	v_exp_f32_e32 v118, v116
	v_add_f32_e32 v109, 1.0, v109
	v_add_f32_e32 v108, 1.0, v108
	v_rcp_f32_e32 v116, v109
	v_add_f32_e32 v109, 1.0, v117
	v_rcp_f32_e32 v108, v108
	v_rcp_f32_e32 v109, v109
	v_add_f32_e32 v117, 1.0, v118
	v_rcp_f32_e32 v117, v117
	v_pk_mul_f32 v[104:105], v[104:105], v[96:97]
	v_pk_mul_f32 v[96:97], v[110:111], v[108:109]
	v_lshl_add_u64 v[108:109], v[114:115], 0, v[112:113]
	v_pk_mul_f32 v[102:103], v[96:97], v[102:103]
	v_pk_mul_f32 v[96:97], v[106:107], v[116:117]
	s_and_b64 vcc, exec, s[8:9]
	v_pk_mul_f32 v[106:107], v[96:97], v[98:99]
	v_cvt_pk_bf16_f32 v96, v100, v101
	v_cvt_pk_bf16_f32 v97, v102, v103
	v_cvt_pk_bf16_f32 v98, v104, v105
	v_cvt_pk_bf16_f32 v99, v106, v107
	global_store_dwordx4 v[108:109], v[96:99], off
	v_mul_f32_e32 v100, 0xbfb8aa3b, v93
	v_exp_f32_e32 v100, v100
	v_mul_f32_e32 v98, 0xbfb8aa3b, v92
	v_mul_f32_e32 v99, 0xbfb8aa3b, v88
	v_exp_f32_e32 v98, v98
	v_exp_f32_e32 v99, v99
	v_or_b32_e32 v96, 32, v152
	v_mad_i64_i32 v[96:97], s[30:31], v96, s55, v[144:145]
	v_add_f32_e32 v98, 1.0, v98
	v_add_f32_e32 v101, 1.0, v99
	v_add_f32_e32 v99, 1.0, v100
	v_rcp_f32_e32 v98, v98
	v_rcp_f32_e32 v99, v99
	v_mul_f32_e32 v100, 0xbfb8aa3b, v89
	v_exp_f32_e32 v102, v100
	v_rcp_f32_e32 v100, v101
	v_pk_mul_f32 v[92:93], v[92:93], v[98:99]
	v_mul_f32_e32 v98, 0xbfb8aa3b, v95
	v_pk_mul_f32 v[84:85], v[92:93], v[84:85]
	v_add_f32_e32 v92, 1.0, v102
	v_rcp_f32_e32 v101, v92
	v_mul_f32_e32 v93, 0xbfb8aa3b, v90
	v_mul_f32_e32 v92, 0xbfb8aa3b, v94
	v_exp_f32_e32 v93, v93
	v_exp_f32_e32 v92, v92
	v_exp_f32_e32 v99, v98
	v_mul_f32_e32 v98, 0xbfb8aa3b, v91
	v_pk_mul_f32 v[88:89], v[88:89], v[100:101]
	v_exp_f32_e32 v100, v98
	v_add_f32_e32 v93, 1.0, v93
	v_add_f32_e32 v92, 1.0, v92
	v_rcp_f32_e32 v98, v93
	v_add_f32_e32 v93, 1.0, v99
	v_rcp_f32_e32 v92, v92
	v_rcp_f32_e32 v93, v93
	v_add_f32_e32 v99, 1.0, v100
	v_rcp_f32_e32 v99, v99
	v_pk_mul_f32 v[88:89], v[88:89], v[80:81]
	v_pk_mul_f32 v[80:81], v[94:95], v[92:93]
	v_lshl_add_u64 v[92:93], v[96:97], 0, v[112:113]
	v_pk_mul_f32 v[86:87], v[80:81], v[86:87]
	v_pk_mul_f32 v[80:81], v[90:91], v[98:99]
	s_mov_b32 s56, s14
	v_pk_mul_f32 v[90:91], v[80:81], v[82:83]
	v_cvt_pk_bf16_f32 v80, v84, v85
	v_cvt_pk_bf16_f32 v81, v86, v87
	v_cvt_pk_bf16_f32 v82, v88, v89
	v_cvt_pk_bf16_f32 v83, v90, v91
	global_store_dwordx4 v[92:93], v[80:83], off
	v_mul_f32_e32 v84, 0xbfb8aa3b, v77
	v_exp_f32_e32 v84, v84
	v_mul_f32_e32 v82, 0xbfb8aa3b, v76
	v_mul_f32_e32 v83, 0xbfb8aa3b, v72
	v_exp_f32_e32 v82, v82
	v_exp_f32_e32 v83, v83
	v_or_b32_e32 v80, 48, v152
	v_mad_i64_i32 v[80:81], s[30:31], v80, s55, v[144:145]
	v_add_f32_e32 v82, 1.0, v82
	v_add_f32_e32 v85, 1.0, v83
	v_add_f32_e32 v83, 1.0, v84
	v_rcp_f32_e32 v82, v82
	v_rcp_f32_e32 v83, v83
	v_mul_f32_e32 v84, 0xbfb8aa3b, v73
	v_exp_f32_e32 v86, v84
	v_rcp_f32_e32 v84, v85
	v_pk_mul_f32 v[76:77], v[76:77], v[82:83]
	v_mul_f32_e32 v82, 0xbfb8aa3b, v79
	v_pk_mul_f32 v[68:69], v[76:77], v[68:69]
	v_add_f32_e32 v76, 1.0, v86
	v_rcp_f32_e32 v85, v76
	v_mul_f32_e32 v77, 0xbfb8aa3b, v74
	v_mul_f32_e32 v76, 0xbfb8aa3b, v78
	v_exp_f32_e32 v77, v77
	v_exp_f32_e32 v76, v76
	v_exp_f32_e32 v83, v82
	v_mul_f32_e32 v82, 0xbfb8aa3b, v75
	v_pk_mul_f32 v[72:73], v[72:73], v[84:85]
	v_exp_f32_e32 v84, v82
	v_add_f32_e32 v77, 1.0, v77
	v_add_f32_e32 v76, 1.0, v76
	v_rcp_f32_e32 v82, v77
	v_add_f32_e32 v77, 1.0, v83
	v_rcp_f32_e32 v76, v76
	v_rcp_f32_e32 v77, v77
	v_add_f32_e32 v83, 1.0, v84
	v_rcp_f32_e32 v83, v83
	v_pk_mul_f32 v[72:73], v[72:73], v[64:65]
	v_pk_mul_f32 v[64:65], v[78:79], v[76:77]
	v_lshl_add_u64 v[76:77], v[80:81], 0, v[112:113]
	v_pk_mul_f32 v[70:71], v[64:65], v[70:71]
	v_pk_mul_f32 v[64:65], v[74:75], v[82:83]
	s_mov_b32 s28, s22
	v_pk_mul_f32 v[74:75], v[64:65], v[66:67]
	v_cvt_pk_bf16_f32 v64, v68, v69
	v_cvt_pk_bf16_f32 v65, v70, v71
	v_cvt_pk_bf16_f32 v66, v72, v73
	v_cvt_pk_bf16_f32 v67, v74, v75
	global_store_dwordx4 v[76:77], v[64:67], off
	v_mul_f32_e32 v68, 0xbfb8aa3b, v61
	v_exp_f32_e32 v68, v68
	v_mul_f32_e32 v66, 0xbfb8aa3b, v60
	v_mul_f32_e32 v67, 0xbfb8aa3b, v56
	v_exp_f32_e32 v66, v66
	v_exp_f32_e32 v67, v67
	v_add_u32_e32 v64, 0x80, v152
	v_mad_i64_i32 v[64:65], s[30:31], v64, s55, v[144:145]
	v_add_f32_e32 v66, 1.0, v66
	v_add_f32_e32 v69, 1.0, v67
	v_add_f32_e32 v67, 1.0, v68
	v_rcp_f32_e32 v66, v66
	v_rcp_f32_e32 v67, v67
	v_mul_f32_e32 v68, 0xbfb8aa3b, v57
	v_exp_f32_e32 v70, v68
	v_rcp_f32_e32 v68, v69
	v_pk_mul_f32 v[60:61], v[60:61], v[66:67]
	v_mul_f32_e32 v66, 0xbfb8aa3b, v63
	v_pk_mul_f32 v[52:53], v[60:61], v[52:53]
	v_add_f32_e32 v60, 1.0, v70
	v_rcp_f32_e32 v69, v60
	v_mul_f32_e32 v61, 0xbfb8aa3b, v58
	v_mul_f32_e32 v60, 0xbfb8aa3b, v62
	v_exp_f32_e32 v61, v61
	v_exp_f32_e32 v60, v60
	v_exp_f32_e32 v67, v66
	v_mul_f32_e32 v66, 0xbfb8aa3b, v59
	v_pk_mul_f32 v[56:57], v[56:57], v[68:69]
	v_exp_f32_e32 v68, v66
	v_add_f32_e32 v61, 1.0, v61
	v_add_f32_e32 v60, 1.0, v60
; __device__ __forceinline__ float fsilu(float v) { return v * fsigmoid(v); }
; __device__ __forceinline__ u32x4 pack8(const f32x4 a, const f32x4 b) { u32x4 w; w.x = cvt_pk_bf16(a[0], a[1]); w.y = cvt_pk_bf16(a[2], a[3]); w.z = cvt_pk_bf16(b[0], b[1]); w.w = cvt_pk_bf16(b[2], b[3]); return w; }
; #define PG8_WAIT_V(n) asm volatile("s_waitcnt vmcnt(" #n ")" ::: "memory")
; #define PG8_BAR __builtin_amdgcn_s_barrier()
;     __device__ __forceinline__ void operator()(const f32x4 (&acc)[2][2][4][2], const Unit& u, int wr, int wc, int fr, int fq) const {
;         const int row0 = u.pm * BM + wr * 64 + fr, col0 = u.pn * 128 + wc * 32 + 8 * fq;
; #pragma unroll
;         for (int ai = 0; ai < 2; ++ai)
; #pragma unroll
;             for (int m = 0; m < 4; ++m) {
;                 bf16_t* rowp = O + (size_t)(row0 + ai * HALF + m * 16) * ldc + col0;
;                 f32x4 h0, h1;
; #pragma unroll
;                 for (int j = 0; j < 4; ++j) { h0[j] = fsilu(acc[ai][0][m][0][j]) * acc[ai][1][m][0][j]; h1[j] = fsilu(acc[ai][0][m][1][j]) * acc[ai][1][m][1][j]; }
;                 *(u32x4*)rowp = pack8(h0, h1);
; template <class Epi, class Sched, bool ALIGN_EPI = false, bool SP2 = false>
; __device__ __forceinline__ void gemm_phase(PG8_LAS unsigned char* lds, const Gemm g, const Sched& S, const Epi& E) {
;     ...
;     PG8_WAIT_V(0);
;     if constexpr (!ALIGN_EPI) { if (wr == 0) PG8_BAR; }
;     PG8_BAR;
	v_rcp_f32_e32 v66, v61
	v_add_f32_e32 v61, 1.0, v67
	v_rcp_f32_e32 v60, v60
	v_rcp_f32_e32 v61, v61
	v_add_f32_e32 v67, 1.0, v68
	v_rcp_f32_e32 v67, v67
	v_pk_mul_f32 v[56:57], v[56:57], v[48:49]
	v_pk_mul_f32 v[48:49], v[62:63], v[60:61]
	v_lshl_add_u64 v[60:61], v[64:65], 0, v[112:113]
	v_pk_mul_f32 v[54:55], v[48:49], v[54:55]
	v_pk_mul_f32 v[48:49], v[58:59], v[66:67]
	s_mov_b64 s[34:35], s[26:27]
	v_pk_mul_f32 v[58:59], v[48:49], v[50:51]
	v_cvt_pk_bf16_f32 v48, v52, v53
	v_cvt_pk_bf16_f32 v49, v54, v55
	v_cvt_pk_bf16_f32 v50, v56, v57
	v_cvt_pk_bf16_f32 v51, v58, v59
	global_store_dwordx4 v[60:61], v[48:51], off
	v_mul_f32_e32 v52, 0xbfb8aa3b, v45
	v_exp_f32_e32 v52, v52
	v_mul_f32_e32 v50, 0xbfb8aa3b, v44
	v_mul_f32_e32 v51, 0xbfb8aa3b, v40
	v_exp_f32_e32 v50, v50
	v_exp_f32_e32 v51, v51
	v_add_u32_e32 v48, 0x90, v152
	v_mad_i64_i32 v[48:49], s[30:31], v48, s55, v[144:145]
	v_add_f32_e32 v50, 1.0, v50
	v_add_f32_e32 v53, 1.0, v51
	v_add_f32_e32 v51, 1.0, v52
	v_rcp_f32_e32 v50, v50
	v_rcp_f32_e32 v51, v51
	v_mul_f32_e32 v52, 0xbfb8aa3b, v41
	v_exp_f32_e32 v54, v52
	v_rcp_f32_e32 v52, v53
	v_pk_mul_f32 v[44:45], v[44:45], v[50:51]
	v_mul_f32_e32 v50, 0xbfb8aa3b, v47
	v_pk_mul_f32 v[36:37], v[44:45], v[36:37]
	v_add_f32_e32 v44, 1.0, v54
	v_rcp_f32_e32 v53, v44
	v_mul_f32_e32 v45, 0xbfb8aa3b, v42
	v_mul_f32_e32 v44, 0xbfb8aa3b, v46
	v_exp_f32_e32 v45, v45
	v_exp_f32_e32 v44, v44
	v_exp_f32_e32 v51, v50
	v_mul_f32_e32 v50, 0xbfb8aa3b, v43
	v_pk_mul_f32 v[40:41], v[40:41], v[52:53]
	v_exp_f32_e32 v52, v50
	v_add_f32_e32 v45, 1.0, v45
	v_add_f32_e32 v44, 1.0, v44
	v_rcp_f32_e32 v50, v45
	v_add_f32_e32 v45, 1.0, v51
	v_rcp_f32_e32 v44, v44
	v_rcp_f32_e32 v45, v45
	v_add_f32_e32 v51, 1.0, v52
	v_rcp_f32_e32 v51, v51
	v_pk_mul_f32 v[40:41], v[40:41], v[32:33]
	v_pk_mul_f32 v[32:33], v[46:47], v[44:45]
	v_lshl_add_u64 v[44:45], v[48:49], 0, v[112:113]
	v_pk_mul_f32 v[38:39], v[32:33], v[38:39]
	v_pk_mul_f32 v[32:33], v[42:43], v[50:51]
	s_nop 0
	v_pk_mul_f32 v[42:43], v[32:33], v[34:35]
	v_cvt_pk_bf16_f32 v32, v36, v37
	v_cvt_pk_bf16_f32 v33, v38, v39
	v_cvt_pk_bf16_f32 v34, v40, v41
	v_cvt_pk_bf16_f32 v35, v42, v43
	global_store_dwordx4 v[44:45], v[32:35], off
	v_mul_f32_e32 v36, 0xbfb8aa3b, v29
	v_exp_f32_e32 v36, v36
	v_mul_f32_e32 v34, 0xbfb8aa3b, v28
	v_mul_f32_e32 v35, 0xbfb8aa3b, v24
	v_exp_f32_e32 v34, v34
	v_exp_f32_e32 v35, v35
	v_add_u32_e32 v32, 0xa0, v152
	v_mad_i64_i32 v[32:33], s[30:31], v32, s55, v[144:145]
	v_add_f32_e32 v34, 1.0, v34
	v_add_f32_e32 v37, 1.0, v35
	v_add_f32_e32 v35, 1.0, v36
	v_rcp_f32_e32 v34, v34
	v_rcp_f32_e32 v35, v35
	v_mul_f32_e32 v36, 0xbfb8aa3b, v25
	v_exp_f32_e32 v38, v36
	v_rcp_f32_e32 v36, v37
	v_pk_mul_f32 v[28:29], v[28:29], v[34:35]
	v_mul_f32_e32 v34, 0xbfb8aa3b, v31
	v_pk_mul_f32 v[20:21], v[28:29], v[20:21]
	v_add_f32_e32 v28, 1.0, v38
	v_rcp_f32_e32 v37, v28
	v_mul_f32_e32 v29, 0xbfb8aa3b, v26
	v_mul_f32_e32 v28, 0xbfb8aa3b, v30
	v_exp_f32_e32 v29, v29
	v_exp_f32_e32 v28, v28
	v_exp_f32_e32 v35, v34
	v_mul_f32_e32 v34, 0xbfb8aa3b, v27
	v_pk_mul_f32 v[24:25], v[24:25], v[36:37]
	v_exp_f32_e32 v36, v34
	v_add_f32_e32 v29, 1.0, v29
	v_add_f32_e32 v28, 1.0, v28
	v_rcp_f32_e32 v34, v29
	v_add_f32_e32 v29, 1.0, v35
	v_rcp_f32_e32 v28, v28
	v_rcp_f32_e32 v29, v29
	v_add_f32_e32 v35, 1.0, v36
	v_rcp_f32_e32 v35, v35
	v_pk_mul_f32 v[24:25], v[24:25], v[16:17]
	v_pk_mul_f32 v[16:17], v[30:31], v[28:29]
	v_lshl_add_u64 v[28:29], v[32:33], 0, v[112:113]
	v_pk_mul_f32 v[22:23], v[16:17], v[22:23]
	v_pk_mul_f32 v[16:17], v[26:27], v[34:35]
	s_nop 0
	v_pk_mul_f32 v[26:27], v[16:17], v[18:19]
	v_cvt_pk_bf16_f32 v16, v20, v21
	v_cvt_pk_bf16_f32 v17, v22, v23
	v_cvt_pk_bf16_f32 v18, v24, v25
	v_cvt_pk_bf16_f32 v19, v26, v27
	global_store_dwordx4 v[28:29], v[16:19], off
	v_mul_f32_e32 v20, 0xbfb8aa3b, v13
	v_exp_f32_e32 v20, v20
	v_mul_f32_e32 v18, 0xbfb8aa3b, v12
	v_mul_f32_e32 v19, 0xbfb8aa3b, v8
	v_exp_f32_e32 v18, v18
	v_exp_f32_e32 v19, v19
	v_add_u32_e32 v16, 0xb0, v152
	v_mad_i64_i32 v[16:17], s[30:31], v16, s55, v[144:145]
	v_add_f32_e32 v18, 1.0, v18
	v_add_f32_e32 v21, 1.0, v19
	v_add_f32_e32 v19, 1.0, v20
	v_rcp_f32_e32 v18, v18
	v_rcp_f32_e32 v19, v19
	v_mul_f32_e32 v20, 0xbfb8aa3b, v9
	v_exp_f32_e32 v22, v20
	v_rcp_f32_e32 v20, v21
	v_pk_mul_f32 v[12:13], v[12:13], v[18:19]
	v_mul_f32_e32 v18, 0xbfb8aa3b, v15
	v_pk_mul_f32 v[4:5], v[12:13], v[4:5]
	v_add_f32_e32 v12, 1.0, v22
	v_rcp_f32_e32 v21, v12
	v_mul_f32_e32 v13, 0xbfb8aa3b, v10
	v_mul_f32_e32 v12, 0xbfb8aa3b, v14
	v_exp_f32_e32 v13, v13
	v_exp_f32_e32 v12, v12
	v_exp_f32_e32 v19, v18
	v_mul_f32_e32 v18, 0xbfb8aa3b, v11
	v_pk_mul_f32 v[8:9], v[8:9], v[20:21]
	v_exp_f32_e32 v20, v18
	v_add_f32_e32 v13, 1.0, v13
	v_add_f32_e32 v12, 1.0, v12
	v_rcp_f32_e32 v18, v13
	v_add_f32_e32 v13, 1.0, v19
	v_rcp_f32_e32 v12, v12
	v_rcp_f32_e32 v13, v13
	v_add_f32_e32 v19, 1.0, v20
	v_rcp_f32_e32 v19, v19
	v_pk_mul_f32 v[8:9], v[8:9], v[0:1]
	v_pk_mul_f32 v[0:1], v[14:15], v[12:13]
	v_lshl_add_u64 v[12:13], v[16:17], 0, v[112:113]
	v_pk_mul_f32 v[6:7], v[0:1], v[6:7]
	v_pk_mul_f32 v[0:1], v[10:11], v[18:19]
	s_mov_b64 s[30:31], s[24:25]
	v_pk_mul_f32 v[10:11], v[0:1], v[2:3]
	v_cvt_pk_bf16_f32 v0, v4, v5
	v_cvt_pk_bf16_f32 v1, v6, v7
	v_cvt_pk_bf16_f32 v2, v8, v9
	v_cvt_pk_bf16_f32 v3, v10, v11
	global_store_dwordx4 v[12:13], v[0:3], off
	s_cbranch_vccz .LBB0_942
	s_waitcnt vmcnt(0)
	s_cmpk_gt_u32 s3, 0xff
	s_cbranch_scc1 .LBB0_949
	s_barrier

; #define PG8_STAGE(bufoff, gbase, voff) do { _Pragma("unroll") for (int _i = 0; _i < 2; ++_i) \
;         __builtin_amdgcn_global_load_lds((const unsigned*)((const char*)(gbase) + (voff)[_i]), (PG8_LAS unsigned*)(lds + (bufoff) + ldsw + _i * 8192), 16, 0, 0); } while (0)
; #define PG8_LDA(dst, b, h) do { _Pragma("unroll") for (int m = 0; m < 4; ++m) _Pragma("unroll") for (int k = 0; k < 2; ++k) dst[m][k] = *(const PG8_LAS bf16x8*)(lds + PG8_SA(b, h) + aoff + m * 2048 + k * 1024); } while (0)
; #define PG8_LDB(dst, b, h) do { _Pragma("unroll") for (int n = 0; n < 2; ++n) _Pragma("unroll") for (int k = 0; k < 2; ++k) dst[n][k] = *(const PG8_LAS bf16x8*)(lds + PG8_SB(b, h) + boff + n * 2048 + k * 1024); } while (0)
; #define PG8_WAIT_V(n) asm volatile("s_waitcnt vmcnt(" #n ")" ::: "memory")
; #define PG8_WAIT_L(n) asm volatile("s_waitcnt lgkmcnt(" #n ")" ::: "memory")
; #define PG8_BAR __builtin_amdgcn_s_barrier()
; #define PG8_SCHED __builtin_amdgcn_sched_barrier(0)
; template <class Epi, class Sched, bool ALIGN_EPI = false, bool SP2 = false>
; __device__ __forceinline__ void gemm_phase(PG8_LAS unsigned char* lds, const Gemm g, const Sched& S, const Epi& E) {
;     ...
;         const bool has_next = S.next(ui + 1, nxt);
;         const char* nA = has_next ? (const char*)g.A + (size_t)nxt.pm * tstep : cA; const char* nB = has_next ? (const char*)g.Bt + (size_t)nxt.pn * tstep : cB;
;         for (int t = 0; t < nt; t += 2) {
;             const bool last = (t == nt - 2);
;             const char* a1 = cA + (size_t)(t + 1) * kstep;
;             const char* a2 = last ? nA : cA + (size_t)(t + 2) * kstep; const char* b2 = last ? nB : cB + (size_t)(t + 2) * kstep;
;             const char* a3 = a2 + kstep; const char* b3 = b2 + kstep;
;             if (last && has_next) S.a_ready(nxt);
;             if constexpr (SP2) {
;             PG8_LDB(B0, 0, 0); PG8_LDB(B1, 0, 1); PG8_SCHED; PG8_LDA(At, 0, 0); PG8_STAGE(PG8_SA(1, 1), a1 + hstep, voffA);
;             PG8_WAIT_V(8); PG8_WAIT_L(0); PG8_BAR; PG8_MMA(0, 0, At, B0); PG8_MMA(0, 1, At, B1); PG8_BAR; PG8_SCHED;
;             PG8_LDA(At, 0, 1); PG8_STAGE(PG8_SB(0, 0), b2, voffB); PG8_STAGE(PG8_SB(0, 1), b2 + hstep, voffB); PG8_STAGE(PG8_SA(0, 0), a2, voffA);
;             PG8_WAIT_V(8); PG8_WAIT_L(0); PG8_BAR; PG8_MMA(1, 0, At, B0); PG8_MMA(1, 1, At, B1); PG8_BAR; PG8_SCHED;
.LBB0_1020:
	s_add_u32 s54, s26, 0x100
	s_addc_u32 s55, s27, 0
	s_mov_b32 s56, -2
	ds_read_b128 v[144:147], v169
	ds_read_b128 v[148:151], v169 offset:1024
	ds_read_b128 v[152:155], v169 offset:2048
	ds_read_b128 v[156:159], v169 offset:3072
	ds_read_b128 v[160:163], v170
	ds_read_b128 v[172:175], v170 offset:1024
	ds_read_b128 v[176:179], v170 offset:2048
	ds_read_b128 v[180:183], v170 offset:3072
	s_add_u32 s26, s24, 0x100
	s_addc_u32 s27, s25, 0
	s_cmpk_eq_i32 s56, 0x54
	s_cselect_b32 s31, s5, s27
	s_cselect_b32 s30, s4, s26
	s_cselect_b32 s29, s7, s55
	s_cselect_b32 s28, s6, s54
	s_add_i32 m0, s38, 0xc000
	ds_read_b128 v[184:187], v171
	ds_read_b128 v[188:191], v171 offset:1024
	ds_read_b128 v[192:195], v171 offset:2048
	ds_read_b128 v[196:199], v171 offset:3072
	ds_read_b128 v[200:203], v171 offset:4096
	ds_read_b128 v[204:207], v171 offset:5120
	ds_read_b128 v[208:211], v171 offset:6144
	ds_read_b128 v[212:215], v171 offset:7168
	global_load_lds_dwordx4 v136, s[24:25]
	s_add_i32 m0, s38, 0xe000
	s_nop 0
	global_load_lds_dwordx4 v138, s[24:25]
	s_waitcnt vmcnt(8)
	s_waitcnt lgkmcnt(0)
	s_barrier
	s_waitcnt lgkmcnt(0)
	v_mfma_f32_16x16x32_bf16 v[124:127], v[144:147], v[184:187], 0
	v_mfma_f32_16x16x32_bf16 v[120:123], v[152:155], v[184:187], 0
	v_mfma_f32_16x16x32_bf16 v[116:119], v[144:147], v[192:195], 0
	v_mfma_f32_16x16x32_bf16 v[112:115], v[152:155], v[192:195], 0
	v_mfma_f32_16x16x32_bf16 v[108:111], v[144:147], v[200:203], 0
	v_mfma_f32_16x16x32_bf16 v[96:99], v[152:155], v[200:203], 0
	v_mfma_f32_16x16x32_bf16 v[84:87], v[144:147], v[208:211], 0
	v_mfma_f32_16x16x32_bf16 v[76:79], v[152:155], v[208:211], 0
	v_mfma_f32_16x16x32_bf16 v[124:127], v[148:151], v[188:191], v[124:127]
	v_mfma_f32_16x16x32_bf16 v[120:123], v[156:159], v[188:191], v[120:123]
	v_mfma_f32_16x16x32_bf16 v[116:119], v[148:151], v[196:199], v[116:119]
	v_mfma_f32_16x16x32_bf16 v[112:115], v[156:159], v[196:199], v[112:115]
	v_mfma_f32_16x16x32_bf16 v[108:111], v[148:151], v[204:207], v[108:111]
	v_mfma_f32_16x16x32_bf16 v[96:99], v[156:159], v[204:207], v[96:99]
	v_mfma_f32_16x16x32_bf16 v[84:87], v[148:151], v[212:215], v[84:87]
	v_mfma_f32_16x16x32_bf16 v[76:79], v[156:159], v[212:215], v[76:79]
	v_mfma_f32_16x16x32_bf16 v[104:107], v[160:163], v[184:187], 0
	v_mfma_f32_16x16x32_bf16 v[100:103], v[176:179], v[184:187], 0
	v_mfma_f32_16x16x32_bf16 v[92:95], v[160:163], v[192:195], 0
	v_mfma_f32_16x16x32_bf16 v[88:91], v[176:179], v[192:195], 0
	v_mfma_f32_16x16x32_bf16 v[80:83], v[160:163], v[200:203], 0
	v_mfma_f32_16x16x32_bf16 v[72:75], v[176:179], v[200:203], 0
	v_mfma_f32_16x16x32_bf16 v[68:71], v[160:163], v[208:211], 0
	v_mfma_f32_16x16x32_bf16 v[64:67], v[176:179], v[208:211], 0
	v_mfma_f32_16x16x32_bf16 v[104:107], v[172:175], v[188:191], v[104:107]
	v_mfma_f32_16x16x32_bf16 v[100:103], v[180:183], v[188:191], v[100:103]
	v_mfma_f32_16x16x32_bf16 v[92:95], v[172:175], v[196:199], v[92:95]
	v_mfma_f32_16x16x32_bf16 v[88:91], v[180:183], v[196:199], v[88:91]
	v_mfma_f32_16x16x32_bf16 v[80:83], v[172:175], v[204:207], v[80:83]
	v_mfma_f32_16x16x32_bf16 v[72:75], v[180:183], v[204:207], v[72:75]
	v_mfma_f32_16x16x32_bf16 v[68:71], v[172:175], v[212:215], v[68:71]
	v_mfma_f32_16x16x32_bf16 v[64:67], v[180:183], v[212:215], v[64:67]
	s_barrier
	s_add_i32 s24, s48, s37
	s_mov_b32 m0, s24
	ds_read_b128 v[184:187], v171 offset:16384
	ds_read_b128 v[188:191], v171 offset:17408
	ds_read_b128 v[192:195], v171 offset:18432
	ds_read_b128 v[196:199], v171 offset:19456
	ds_read_b128 v[200:203], v171 offset:20480
	ds_read_b128 v[204:207], v171 offset:21504
	ds_read_b128 v[208:211], v171 offset:22528
	ds_read_b128 v[212:215], v171 offset:23552
	global_load_lds_dwordx4 v130, s[28:29]
	s_add_i32 m0, s24, 0x2000
	s_add_u32 s24, s28, 0x160000
	s_addc_u32 s25, s29, 0
	s_add_i32 s57, s49, s37
	global_load_lds_dwordx4 v134, s[28:29]
	s_mov_b32 m0, s57
	s_nop 0
	global_load_lds_dwordx4 v130, s[24:25]
	s_add_i32 m0, s57, 0x2000
	s_nop 0
	global_load_lds_dwordx4 v134, s[24:25]
	s_mov_b32 m0, s38
	s_nop 0
	global_load_lds_dwordx4 v128, s[30:31]
	s_mov_b32 m0, s39
	s_nop 0
	global_load_lds_dwordx4 v132, s[30:31]
	s_waitcnt vmcnt(8)
	s_waitcnt lgkmcnt(0)
	s_barrier
	s_waitcnt lgkmcnt(0)
	v_mfma_f32_16x16x32_bf16 v[60:63], v[144:147], v[184:187], 0
	v_mfma_f32_16x16x32_bf16 v[56:59], v[152:155], v[184:187], 0
	v_mfma_f32_16x16x32_bf16 v[52:55], v[144:147], v[192:195], 0
	v_mfma_f32_16x16x32_bf16 v[48:51], v[152:155], v[192:195], 0
	v_mfma_f32_16x16x32_bf16 v[44:47], v[144:147], v[200:203], 0
	v_mfma_f32_16x16x32_bf16 v[32:35], v[152:155], v[200:203], 0
	v_mfma_f32_16x16x32_bf16 v[20:23], v[144:147], v[208:211], 0
	v_mfma_f32_16x16x32_bf16 v[12:15], v[152:155], v[208:211], 0
	v_mfma_f32_16x16x32_bf16 v[60:63], v[148:151], v[188:191], v[60:63]
	v_mfma_f32_16x16x32_bf16 v[56:59], v[156:159], v[188:191], v[56:59]
	v_mfma_f32_16x16x32_bf16 v[52:55], v[148:151], v[196:199], v[52:55]
	v_mfma_f32_16x16x32_bf16 v[48:51], v[156:159], v[196:199], v[48:51]
	v_mfma_f32_16x16x32_bf16 v[44:47], v[148:151], v[204:207], v[44:47]
	v_mfma_f32_16x16x32_bf16 v[32:35], v[156:159], v[204:207], v[32:35]
	v_mfma_f32_16x16x32_bf16 v[20:23], v[148:151], v[212:215], v[20:23]
	v_mfma_f32_16x16x32_bf16 v[12:15], v[156:159], v[212:215], v[12:15]
	v_mfma_f32_16x16x32_bf16 v[40:43], v[160:163], v[184:187], 0
	v_mfma_f32_16x16x32_bf16 v[36:39], v[176:179], v[184:187], 0
	v_mfma_f32_16x16x32_bf16 v[28:31], v[160:163], v[192:195], 0
	v_mfma_f32_16x16x32_bf16 v[24:27], v[176:179], v[192:195], 0
	v_mfma_f32_16x16x32_bf16 v[16:19], v[160:163], v[200:203], 0
	v_mfma_f32_16x16x32_bf16 v[8:11], v[176:179], v[200:203], 0
	v_mfma_f32_16x16x32_bf16 v[4:7], v[160:163], v[208:211], 0
	v_mfma_f32_16x16x32_bf16 v[0:3], v[176:179], v[208:211], 0
	v_mfma_f32_16x16x32_bf16 v[40:43], v[172:175], v[188:191], v[40:43]
	v_mfma_f32_16x16x32_bf16 v[36:39], v[180:183], v[188:191], v[36:39]
	v_mfma_f32_16x16x32_bf16 v[28:31], v[172:175], v[196:199], v[28:31]
	v_mfma_f32_16x16x32_bf16 v[24:27], v[180:183], v[196:199], v[24:27]
	v_mfma_f32_16x16x32_bf16 v[16:19], v[172:175], v[204:207], v[16:19]
	v_mfma_f32_16x16x32_bf16 v[8:11], v[180:183], v[204:207], v[8:11]
	v_mfma_f32_16x16x32_bf16 v[4:7], v[172:175], v[212:215], v[4:7]
	v_mfma_f32_16x16x32_bf16 v[0:3], v[180:183], v[212:215], v[0:3]
	s_barrier
; #define PG8_STAGE(bufoff, gbase, voff) do { _Pragma("unroll") for (int _i = 0; _i < 2; ++_i) \
;         __builtin_amdgcn_global_load_lds((const unsigned*)((const char*)(gbase) + (voff)[_i]), (PG8_LAS unsigned*)(lds + (bufoff) + ldsw + _i * 8192), 16, 0, 0); } while (0)
; #define PG8_LDA(dst, b, h) do { _Pragma("unroll") for (int m = 0; m < 4; ++m) _Pragma("unroll") for (int k = 0; k < 2; ++k) dst[m][k] = *(const PG8_LAS bf16x8*)(lds + PG8_SA(b, h) + aoff + m * 2048 + k * 1024); } while (0)
; #define PG8_LDB(dst, b, h) do { _Pragma("unroll") for (int n = 0; n < 2; ++n) _Pragma("unroll") for (int k = 0; k < 2; ++k) dst[n][k] = *(const PG8_LAS bf16x8*)(lds + PG8_SB(b, h) + boff + n * 2048 + k * 1024); } while (0)
; #define PG8_MMA(ai, bj, At, Bt) do { __builtin_amdgcn_s_setprio(1); _Pragma("unroll") for (int m = 0; m < 4; ++m) _Pragma("unroll") for (int n = 0; n < 2; ++n) _Pragma("unroll") for (int k = 0; k < 2; ++k) \
;         acc[ai][bj][m][n] = __builtin_amdgcn_mfma_f32_16x16x32_bf16(Bt[n][k], At[m][k], acc[ai][bj][m][n], 0, 0, 0); __builtin_amdgcn_s_setprio(0); } while (0)
; #define PG8_WAIT_V(n) asm volatile("s_waitcnt vmcnt(" #n ")" ::: "memory")
; #define PG8_WAIT_L(n) asm volatile("s_waitcnt lgkmcnt(" #n ")" ::: "memory")
; #define PG8_BAR __builtin_amdgcn_s_barrier()
; #define PG8_SCHED __builtin_amdgcn_sched_barrier(0)
; template <class Epi, class Sched, bool ALIGN_EPI = false, bool SP2 = false>
; __device__ __forceinline__ void gemm_phase(PG8_LAS unsigned char* lds, const Gemm g, const Sched& S, const Epi& E) {
;     ...
;             PG8_WAIT_V(8); PG8_WAIT_L(0); PG8_BAR; PG8_MMA(1, 0, At, B0); PG8_MMA(1, 1, At, B1); PG8_BAR; PG8_SCHED;
;             PG8_LDB(B0, 1, 0); PG8_LDB(B1, 1, 1); PG8_SCHED; PG8_LDA(At, 1, 0); PG8_STAGE(PG8_SA(0, 1), a2 + hstep, voffA);
;             PG8_WAIT_V(8); PG8_WAIT_L(0); PG8_BAR; PG8_MMA(0, 0, At, B0); PG8_MMA(0, 1, At, B1); PG8_BAR; PG8_SCHED;
;             PG8_LDA(At, 1, 1); PG8_STAGE(PG8_SB(1, 0), b3, voffB); PG8_STAGE(PG8_SB(1, 1), b3 + hstep, voffB); PG8_STAGE(PG8_SA(1, 0), a3, voffA);
;             PG8_WAIT_V(8); PG8_WAIT_L(0); PG8_BAR; PG8_MMA(1, 0, At, B0); PG8_MMA(1, 1, At, B1); PG8_BAR; PG8_SCHED;
	s_add_i32 s57, 0, 0x18000
	s_add_i32 s58, 0, 0x1c000
	v_add_u32_e32 v156, s57, v167
	v_add_u32_e32 v180, s58, v167
	ds_read_b128 v[144:147], v156
	ds_read_b128 v[148:151], v156 offset:1024
	ds_read_b128 v[152:155], v156 offset:2048
	ds_read_b128 v[156:159], v156 offset:3072
	ds_read_b128 v[160:163], v180
	ds_read_b128 v[172:175], v180 offset:1024
	ds_read_b128 v[176:179], v180 offset:2048
	ds_read_b128 v[180:183], v180 offset:3072
	s_add_u32 s24, s30, 0x160000
	s_addc_u32 s25, s31, 0
	s_mov_b32 m0, s40
	ds_read_b128 v[184:187], v171 offset:32768
	ds_read_b128 v[188:191], v171 offset:33792
	ds_read_b128 v[192:195], v171 offset:34816
	ds_read_b128 v[196:199], v171 offset:35840
	ds_read_b128 v[200:203], v171 offset:36864
	ds_read_b128 v[204:207], v171 offset:37888
	ds_read_b128 v[208:211], v171 offset:38912
	ds_read_b128 v[212:215], v171 offset:39936
	global_load_lds_dwordx4 v128, s[24:25]
	s_mov_b32 m0, s41
	s_nop 0
	global_load_lds_dwordx4 v132, s[24:25]
	s_waitcnt vmcnt(8)
	s_waitcnt lgkmcnt(0)
	s_barrier
	s_waitcnt lgkmcnt(0)
	v_mfma_f32_16x16x32_bf16 v[124:127], v[144:147], v[184:187], v[124:127]
	v_mfma_f32_16x16x32_bf16 v[120:123], v[152:155], v[184:187], v[120:123]
	v_mfma_f32_16x16x32_bf16 v[116:119], v[144:147], v[192:195], v[116:119]
	v_mfma_f32_16x16x32_bf16 v[112:115], v[152:155], v[192:195], v[112:115]
	v_mfma_f32_16x16x32_bf16 v[108:111], v[144:147], v[200:203], v[108:111]
	v_mfma_f32_16x16x32_bf16 v[96:99], v[152:155], v[200:203], v[96:99]
	v_mfma_f32_16x16x32_bf16 v[84:87], v[144:147], v[208:211], v[84:87]
	v_mfma_f32_16x16x32_bf16 v[76:79], v[152:155], v[208:211], v[76:79]
	v_mfma_f32_16x16x32_bf16 v[124:127], v[148:151], v[188:191], v[124:127]
	v_mfma_f32_16x16x32_bf16 v[120:123], v[156:159], v[188:191], v[120:123]
	v_mfma_f32_16x16x32_bf16 v[116:119], v[148:151], v[196:199], v[116:119]
	v_mfma_f32_16x16x32_bf16 v[112:115], v[156:159], v[196:199], v[112:115]
	v_mfma_f32_16x16x32_bf16 v[108:111], v[148:151], v[204:207], v[108:111]
	v_mfma_f32_16x16x32_bf16 v[96:99], v[156:159], v[204:207], v[96:99]
	v_mfma_f32_16x16x32_bf16 v[84:87], v[148:151], v[212:215], v[84:87]
	v_mfma_f32_16x16x32_bf16 v[76:79], v[156:159], v[212:215], v[76:79]
	v_mfma_f32_16x16x32_bf16 v[104:107], v[160:163], v[184:187], v[104:107]
	v_mfma_f32_16x16x32_bf16 v[100:103], v[176:179], v[184:187], v[100:103]
	v_mfma_f32_16x16x32_bf16 v[92:95], v[160:163], v[192:195], v[92:95]
	v_mfma_f32_16x16x32_bf16 v[88:91], v[176:179], v[192:195], v[88:91]
	v_mfma_f32_16x16x32_bf16 v[80:83], v[160:163], v[200:203], v[80:83]
	v_mfma_f32_16x16x32_bf16 v[72:75], v[176:179], v[200:203], v[72:75]
	v_mfma_f32_16x16x32_bf16 v[68:71], v[160:163], v[208:211], v[68:71]
	v_mfma_f32_16x16x32_bf16 v[64:67], v[176:179], v[208:211], v[64:67]
	v_mfma_f32_16x16x32_bf16 v[104:107], v[172:175], v[188:191], v[104:107]
	v_mfma_f32_16x16x32_bf16 v[100:103], v[180:183], v[188:191], v[100:103]
	v_mfma_f32_16x16x32_bf16 v[92:95], v[172:175], v[196:199], v[92:95]
	v_mfma_f32_16x16x32_bf16 v[88:91], v[180:183], v[196:199], v[88:91]
	v_mfma_f32_16x16x32_bf16 v[80:83], v[172:175], v[204:207], v[80:83]
	v_mfma_f32_16x16x32_bf16 v[72:75], v[180:183], v[204:207], v[72:75]
	v_mfma_f32_16x16x32_bf16 v[68:71], v[172:175], v[212:215], v[68:71]
	v_mfma_f32_16x16x32_bf16 v[64:67], v[180:183], v[212:215], v[64:67]
	s_barrier
	s_add_i32 s24, s57, s37
	s_add_u32 s86, s28, 0x80
	s_addc_u32 s87, s29, 0
	s_mov_b32 m0, s24
	ds_read_b128 v[184:187], v171 offset:49152
	ds_read_b128 v[188:191], v171 offset:50176
	ds_read_b128 v[192:195], v171 offset:51200
	ds_read_b128 v[196:199], v171 offset:52224
	ds_read_b128 v[200:203], v171 offset:53248
	ds_read_b128 v[204:207], v171 offset:54272
	ds_read_b128 v[208:211], v171 offset:55296
	ds_read_b128 v[212:215], v171 offset:56320
	global_load_lds_dwordx4 v130, s[86:87]
	s_add_i32 m0, s24, 0x2000
	s_add_u32 s24, s28, 0x160080
	s_addc_u32 s25, s29, 0
	s_add_i32 s28, s58, s37
	global_load_lds_dwordx4 v134, s[86:87]
	s_mov_b32 m0, s28
	s_nop 0
	global_load_lds_dwordx4 v130, s[24:25]
	s_add_i32 m0, s28, 0x2000
	s_nop 0
	global_load_lds_dwordx4 v134, s[24:25]
	s_add_u32 s84, s30, 0x80
	s_addc_u32 s85, s31, 0
	s_mov_b32 m0, s45
	s_nop 0
	global_load_lds_dwordx4 v128, s[84:85]
	s_mov_b32 m0, s46
	s_nop 0
	global_load_lds_dwordx4 v132, s[84:85]
	s_waitcnt vmcnt(8)
	s_waitcnt lgkmcnt(0)
	s_barrier
	s_waitcnt lgkmcnt(0)
	v_mfma_f32_16x16x32_bf16 v[60:63], v[144:147], v[184:187], v[60:63]
	v_mfma_f32_16x16x32_bf16 v[56:59], v[152:155], v[184:187], v[56:59]
	v_mfma_f32_16x16x32_bf16 v[52:55], v[144:147], v[192:195], v[52:55]
	v_mfma_f32_16x16x32_bf16 v[48:51], v[152:155], v[192:195], v[48:51]
	v_mfma_f32_16x16x32_bf16 v[44:47], v[144:147], v[200:203], v[44:47]
	v_mfma_f32_16x16x32_bf16 v[32:35], v[152:155], v[200:203], v[32:35]
	v_mfma_f32_16x16x32_bf16 v[20:23], v[144:147], v[208:211], v[20:23]
	v_mfma_f32_16x16x32_bf16 v[12:15], v[152:155], v[208:211], v[12:15]
	v_mfma_f32_16x16x32_bf16 v[60:63], v[148:151], v[188:191], v[60:63]
	v_mfma_f32_16x16x32_bf16 v[56:59], v[156:159], v[188:191], v[56:59]
	v_mfma_f32_16x16x32_bf16 v[52:55], v[148:151], v[196:199], v[52:55]
	v_mfma_f32_16x16x32_bf16 v[48:51], v[156:159], v[196:199], v[48:51]
	v_mfma_f32_16x16x32_bf16 v[44:47], v[148:151], v[204:207], v[44:47]
	v_mfma_f32_16x16x32_bf16 v[32:35], v[156:159], v[204:207], v[32:35]
	v_mfma_f32_16x16x32_bf16 v[20:23], v[148:151], v[212:215], v[20:23]
	v_mfma_f32_16x16x32_bf16 v[12:15], v[156:159], v[212:215], v[12:15]
	v_mfma_f32_16x16x32_bf16 v[40:43], v[160:163], v[184:187], v[40:43]
	v_mfma_f32_16x16x32_bf16 v[36:39], v[176:179], v[184:187], v[36:39]
	v_mfma_f32_16x16x32_bf16 v[28:31], v[160:163], v[192:195], v[28:31]
	v_mfma_f32_16x16x32_bf16 v[24:27], v[176:179], v[192:195], v[24:27]
	v_mfma_f32_16x16x32_bf16 v[16:19], v[160:163], v[200:203], v[16:19]
	v_mfma_f32_16x16x32_bf16 v[8:11], v[176:179], v[200:203], v[8:11]
	v_mfma_f32_16x16x32_bf16 v[4:7], v[160:163], v[208:211], v[4:7]
	v_mfma_f32_16x16x32_bf16 v[0:3], v[176:179], v[208:211], v[0:3]
	v_mfma_f32_16x16x32_bf16 v[40:43], v[172:175], v[188:191], v[40:43]
	v_mfma_f32_16x16x32_bf16 v[36:39], v[180:183], v[188:191], v[36:39]
	v_mfma_f32_16x16x32_bf16 v[28:31], v[172:175], v[196:199], v[28:31]
	v_mfma_f32_16x16x32_bf16 v[24:27], v[180:183], v[196:199], v[24:27]
	v_mfma_f32_16x16x32_bf16 v[16:19], v[172:175], v[204:207], v[16:19]
	v_mfma_f32_16x16x32_bf16 v[8:11], v[180:183], v[204:207], v[8:11]
	v_mfma_f32_16x16x32_bf16 v[4:7], v[172:175], v[212:215], v[4:7]
	v_mfma_f32_16x16x32_bf16 v[0:3], v[180:183], v[212:215], v[0:3]
	s_add_i32 s56, s56, 2
	s_add_u32 s54, s54, 0x100
	s_addc_u32 s55, s55, 0
	s_cmpk_gt_u32 s56, 0x55
	s_mov_b64 s[24:25], s[26:27]
	s_barrier
; #define PG8_STAGE(bufoff, gbase, voff) do { _Pragma("unroll") for (int _i = 0; _i < 2; ++_i) \
;         __builtin_amdgcn_global_load_lds((const unsigned*)((const char*)(gbase) + (voff)[_i]), (PG8_LAS unsigned*)(lds + (bufoff) + ldsw + _i * 8192), 16, 0, 0); } while (0)
; #define PG8_LDA(dst, b, h) do { _Pragma("unroll") for (int m = 0; m < 4; ++m) _Pragma("unroll") for (int k = 0; k < 2; ++k) dst[m][k] = *(const PG8_LAS bf16x8*)(lds + PG8_SA(b, h) + aoff + m * 2048 + k * 1024); } while (0)
; #define PG8_LDB(dst, b, h) do { _Pragma("unroll") for (int n = 0; n < 2; ++n) _Pragma("unroll") for (int k = 0; k < 2; ++k) dst[n][k] = *(const PG8_LAS bf16x8*)(lds + PG8_SB(b, h) + boff + n * 2048 + k * 1024); } while (0)
; #define PG8_MMA(ai, bj, At, Bt) do { __builtin_amdgcn_s_setprio(1); _Pragma("unroll") for (int m = 0; m < 4; ++m) _Pragma("unroll") for (int n = 0; n < 2; ++n) _Pragma("unroll") for (int k = 0; k < 2; ++k) \
;         acc[ai][bj][m][n] = __builtin_amdgcn_mfma_f32_16x16x32_bf16(Bt[n][k], At[m][k], acc[ai][bj][m][n], 0, 0, 0); __builtin_amdgcn_s_setprio(0); } while (0)
; #define PG8_WAIT_V(n) asm volatile("s_waitcnt vmcnt(" #n ")" ::: "memory")
; #define PG8_WAIT_L(n) asm volatile("s_waitcnt lgkmcnt(" #n ")" ::: "memory")
; #define PG8_BAR __builtin_amdgcn_s_barrier()
; #define PG8_SCHED __builtin_amdgcn_sched_barrier(0)
; template <class Epi, class Sched, bool ALIGN_EPI = false, bool SP2 = false>
; __device__ __forceinline__ void gemm_phase(PG8_LAS unsigned char* lds, const Gemm g, const Sched& S, const Epi& E) {
;     ...
;             PG8_LDB(B0, 0, 0); PG8_LDB(B1, 0, 1); PG8_SCHED; PG8_LDA(At, 0, 0); PG8_STAGE(PG8_SA(1, 1), a1 + hstep, voffA);
;             PG8_WAIT_V(8); PG8_WAIT_L(0); PG8_BAR; PG8_MMA(0, 0, At, B0); PG8_MMA(0, 1, At, B1); PG8_BAR; PG8_SCHED;
;             PG8_LDA(At, 0, 1); PG8_STAGE(PG8_SB(0, 0), b2, voffB); PG8_STAGE(PG8_SB(0, 1), b2 + hstep, voffB); PG8_STAGE(PG8_SA(0, 0), a2, voffA);
;             PG8_WAIT_V(8); PG8_WAIT_L(0); PG8_BAR; PG8_MMA(1, 0, At, B0); PG8_MMA(1, 1, At, B1); PG8_BAR; PG8_SCHED;
.LBB0_1021:
	ds_read_b128 v[144:147], v169
	ds_read_b128 v[148:151], v169 offset:1024
	ds_read_b128 v[152:155], v169 offset:2048
	ds_read_b128 v[156:159], v169 offset:3072
	ds_read_b128 v[160:163], v170
	ds_read_b128 v[172:175], v170 offset:1024
	ds_read_b128 v[176:179], v170 offset:2048
	ds_read_b128 v[180:183], v170 offset:3072
	s_add_u32 s26, s24, 0x100
	s_addc_u32 s27, s25, 0
	s_cmpk_eq_i32 s56, 0x54
	s_cselect_b32 s31, s5, s27
	s_cselect_b32 s30, s4, s26
	s_cselect_b32 s29, s7, s55
	s_cselect_b32 s28, s6, s54
	s_add_i32 m0, s38, 0xc000
	ds_read_b128 v[184:187], v171
	ds_read_b128 v[188:191], v171 offset:1024
	ds_read_b128 v[192:195], v171 offset:2048
	ds_read_b128 v[196:199], v171 offset:3072
	ds_read_b128 v[200:203], v171 offset:4096
	ds_read_b128 v[204:207], v171 offset:5120
	ds_read_b128 v[208:211], v171 offset:6144
	ds_read_b128 v[212:215], v171 offset:7168
	global_load_lds_dwordx4 v136, s[24:25]
	s_add_i32 m0, s38, 0xe000
	s_nop 0
	global_load_lds_dwordx4 v138, s[24:25]
	s_waitcnt vmcnt(8)
	s_waitcnt lgkmcnt(0)
	s_barrier
	s_waitcnt lgkmcnt(0)
	v_mfma_f32_16x16x32_bf16 v[124:127], v[144:147], v[184:187], v[124:127]
	v_mfma_f32_16x16x32_bf16 v[120:123], v[152:155], v[184:187], v[120:123]
	v_mfma_f32_16x16x32_bf16 v[116:119], v[144:147], v[192:195], v[116:119]
	v_mfma_f32_16x16x32_bf16 v[112:115], v[152:155], v[192:195], v[112:115]
	v_mfma_f32_16x16x32_bf16 v[108:111], v[144:147], v[200:203], v[108:111]
	v_mfma_f32_16x16x32_bf16 v[96:99], v[152:155], v[200:203], v[96:99]
	v_mfma_f32_16x16x32_bf16 v[84:87], v[144:147], v[208:211], v[84:87]
	v_mfma_f32_16x16x32_bf16 v[76:79], v[152:155], v[208:211], v[76:79]
	v_mfma_f32_16x16x32_bf16 v[124:127], v[148:151], v[188:191], v[124:127]
	v_mfma_f32_16x16x32_bf16 v[120:123], v[156:159], v[188:191], v[120:123]
	v_mfma_f32_16x16x32_bf16 v[116:119], v[148:151], v[196:199], v[116:119]
	v_mfma_f32_16x16x32_bf16 v[112:115], v[156:159], v[196:199], v[112:115]
	v_mfma_f32_16x16x32_bf16 v[108:111], v[148:151], v[204:207], v[108:111]
	v_mfma_f32_16x16x32_bf16 v[96:99], v[156:159], v[204:207], v[96:99]
	v_mfma_f32_16x16x32_bf16 v[84:87], v[148:151], v[212:215], v[84:87]
	v_mfma_f32_16x16x32_bf16 v[76:79], v[156:159], v[212:215], v[76:79]
	v_mfma_f32_16x16x32_bf16 v[104:107], v[160:163], v[184:187], v[104:107]
	v_mfma_f32_16x16x32_bf16 v[100:103], v[176:179], v[184:187], v[100:103]
	v_mfma_f32_16x16x32_bf16 v[92:95], v[160:163], v[192:195], v[92:95]
	v_mfma_f32_16x16x32_bf16 v[88:91], v[176:179], v[192:195], v[88:91]
	v_mfma_f32_16x16x32_bf16 v[80:83], v[160:163], v[200:203], v[80:83]
	v_mfma_f32_16x16x32_bf16 v[72:75], v[176:179], v[200:203], v[72:75]
	v_mfma_f32_16x16x32_bf16 v[68:71], v[160:163], v[208:211], v[68:71]
	v_mfma_f32_16x16x32_bf16 v[64:67], v[176:179], v[208:211], v[64:67]
	v_mfma_f32_16x16x32_bf16 v[104:107], v[172:175], v[188:191], v[104:107]
	v_mfma_f32_16x16x32_bf16 v[100:103], v[180:183], v[188:191], v[100:103]
	v_mfma_f32_16x16x32_bf16 v[92:95], v[172:175], v[196:199], v[92:95]
	v_mfma_f32_16x16x32_bf16 v[88:91], v[180:183], v[196:199], v[88:91]
	v_mfma_f32_16x16x32_bf16 v[80:83], v[172:175], v[204:207], v[80:83]
	v_mfma_f32_16x16x32_bf16 v[72:75], v[180:183], v[204:207], v[72:75]
	v_mfma_f32_16x16x32_bf16 v[68:71], v[172:175], v[212:215], v[68:71]
	v_mfma_f32_16x16x32_bf16 v[64:67], v[180:183], v[212:215], v[64:67]
	s_barrier
	s_add_i32 s24, s48, s37
	s_mov_b32 m0, s24
	ds_read_b128 v[184:187], v171 offset:16384
	ds_read_b128 v[188:191], v171 offset:17408
	ds_read_b128 v[192:195], v171 offset:18432
	ds_read_b128 v[196:199], v171 offset:19456
	ds_read_b128 v[200:203], v171 offset:20480
	ds_read_b128 v[204:207], v171 offset:21504
	ds_read_b128 v[208:211], v171 offset:22528
	ds_read_b128 v[212:215], v171 offset:23552
	global_load_lds_dwordx4 v130, s[28:29]
	s_add_i32 m0, s24, 0x2000
	s_add_u32 s24, s28, 0x160000
	s_addc_u32 s25, s29, 0
	s_add_i32 s57, s49, s37
	global_load_lds_dwordx4 v134, s[28:29]
	s_mov_b32 m0, s57
	s_nop 0
	global_load_lds_dwordx4 v130, s[24:25]
	s_add_i32 m0, s57, 0x2000
	s_nop 0
	global_load_lds_dwordx4 v134, s[24:25]
	s_mov_b32 m0, s38
	s_nop 0
	global_load_lds_dwordx4 v128, s[30:31]
	s_mov_b32 m0, s39
	s_nop 0
	global_load_lds_dwordx4 v132, s[30:31]
	s_waitcnt vmcnt(8)
	s_waitcnt lgkmcnt(0)
	s_barrier
	s_waitcnt lgkmcnt(0)
	v_mfma_f32_16x16x32_bf16 v[60:63], v[144:147], v[184:187], v[60:63]
	v_mfma_f32_16x16x32_bf16 v[56:59], v[152:155], v[184:187], v[56:59]
	v_mfma_f32_16x16x32_bf16 v[52:55], v[144:147], v[192:195], v[52:55]
	v_mfma_f32_16x16x32_bf16 v[48:51], v[152:155], v[192:195], v[48:51]
	v_mfma_f32_16x16x32_bf16 v[44:47], v[144:147], v[200:203], v[44:47]
	v_mfma_f32_16x16x32_bf16 v[32:35], v[152:155], v[200:203], v[32:35]
	v_mfma_f32_16x16x32_bf16 v[20:23], v[144:147], v[208:211], v[20:23]
	v_mfma_f32_16x16x32_bf16 v[12:15], v[152:155], v[208:211], v[12:15]
	v_mfma_f32_16x16x32_bf16 v[60:63], v[148:151], v[188:191], v[60:63]
	v_mfma_f32_16x16x32_bf16 v[56:59], v[156:159], v[188:191], v[56:59]
	v_mfma_f32_16x16x32_bf16 v[52:55], v[148:151], v[196:199], v[52:55]
	v_mfma_f32_16x16x32_bf16 v[48:51], v[156:159], v[196:199], v[48:51]
	v_mfma_f32_16x16x32_bf16 v[44:47], v[148:151], v[204:207], v[44:47]
	v_mfma_f32_16x16x32_bf16 v[32:35], v[156:159], v[204:207], v[32:35]
	v_mfma_f32_16x16x32_bf16 v[20:23], v[148:151], v[212:215], v[20:23]
	v_mfma_f32_16x16x32_bf16 v[12:15], v[156:159], v[212:215], v[12:15]
	v_mfma_f32_16x16x32_bf16 v[40:43], v[160:163], v[184:187], v[40:43]
	v_mfma_f32_16x16x32_bf16 v[36:39], v[176:179], v[184:187], v[36:39]
	v_mfma_f32_16x16x32_bf16 v[28:31], v[160:163], v[192:195], v[28:31]
	v_mfma_f32_16x16x32_bf16 v[24:27], v[176:179], v[192:195], v[24:27]
	v_mfma_f32_16x16x32_bf16 v[16:19], v[160:163], v[200:203], v[16:19]
	v_mfma_f32_16x16x32_bf16 v[8:11], v[176:179], v[200:203], v[8:11]
	v_mfma_f32_16x16x32_bf16 v[4:7], v[160:163], v[208:211], v[4:7]
	v_mfma_f32_16x16x32_bf16 v[0:3], v[176:179], v[208:211], v[0:3]
	v_mfma_f32_16x16x32_bf16 v[40:43], v[172:175], v[188:191], v[40:43]
	v_mfma_f32_16x16x32_bf16 v[36:39], v[180:183], v[188:191], v[36:39]
	v_mfma_f32_16x16x32_bf16 v[28:31], v[172:175], v[196:199], v[28:31]
	v_mfma_f32_16x16x32_bf16 v[24:27], v[180:183], v[196:199], v[24:27]
	v_mfma_f32_16x16x32_bf16 v[16:19], v[172:175], v[204:207], v[16:19]
	v_mfma_f32_16x16x32_bf16 v[8:11], v[180:183], v[204:207], v[8:11]
	v_mfma_f32_16x16x32_bf16 v[4:7], v[172:175], v[212:215], v[4:7]
	v_mfma_f32_16x16x32_bf16 v[0:3], v[180:183], v[212:215], v[0:3]
	s_barrier
; #define PG8_STAGE(bufoff, gbase, voff) do { _Pragma("unroll") for (int _i = 0; _i < 2; ++_i) \
;         __builtin_amdgcn_global_load_lds((const unsigned*)((const char*)(gbase) + (voff)[_i]), (PG8_LAS unsigned*)(lds + (bufoff) + ldsw + _i * 8192), 16, 0, 0); } while (0)
; #define PG8_LDA(dst, b, h) do { _Pragma("unroll") for (int m = 0; m < 4; ++m) _Pragma("unroll") for (int k = 0; k < 2; ++k) dst[m][k] = *(const PG8_LAS bf16x8*)(lds + PG8_SA(b, h) + aoff + m * 2048 + k * 1024); } while (0)
; #define PG8_LDB(dst, b, h) do { _Pragma("unroll") for (int n = 0; n < 2; ++n) _Pragma("unroll") for (int k = 0; k < 2; ++k) dst[n][k] = *(const PG8_LAS bf16x8*)(lds + PG8_SB(b, h) + boff + n * 2048 + k * 1024); } while (0)
; #define PG8_MMA(ai, bj, At, Bt) do { __builtin_amdgcn_s_setprio(1); _Pragma("unroll") for (int m = 0; m < 4; ++m) _Pragma("unroll") for (int n = 0; n < 2; ++n) _Pragma("unroll") for (int k = 0; k < 2; ++k) \
;         acc[ai][bj][m][n] = __builtin_amdgcn_mfma_f32_16x16x32_bf16(Bt[n][k], At[m][k], acc[ai][bj][m][n], 0, 0, 0); __builtin_amdgcn_s_setprio(0); } while (0)
; #define PG8_WAIT_V(n) asm volatile("s_waitcnt vmcnt(" #n ")" ::: "memory")
; #define PG8_WAIT_L(n) asm volatile("s_waitcnt lgkmcnt(" #n ")" ::: "memory")
; #define PG8_BAR __builtin_amdgcn_s_barrier()
; #define PG8_SCHED __builtin_amdgcn_sched_barrier(0)
; template <class Epi, class Sched, bool ALIGN_EPI = false, bool SP2 = false>
; __device__ __forceinline__ void gemm_phase(PG8_LAS unsigned char* lds, const Gemm g, const Sched& S, const Epi& E) {
;     ...
;             PG8_WAIT_V(8); PG8_WAIT_L(0); PG8_BAR; PG8_MMA(1, 0, At, B0); PG8_MMA(1, 1, At, B1); PG8_BAR; PG8_SCHED;
;             PG8_LDB(B0, 1, 0); PG8_LDB(B1, 1, 1); PG8_SCHED; PG8_LDA(At, 1, 0); PG8_STAGE(PG8_SA(0, 1), a2 + hstep, voffA);
;             PG8_WAIT_V(8); PG8_WAIT_L(0); PG8_BAR; PG8_MMA(0, 0, At, B0); PG8_MMA(0, 1, At, B1); PG8_BAR; PG8_SCHED;
;             PG8_LDA(At, 1, 1); PG8_STAGE(PG8_SB(1, 0), b3, voffB); PG8_STAGE(PG8_SB(1, 1), b3 + hstep, voffB); PG8_STAGE(PG8_SA(1, 0), a3, voffA);
;             PG8_WAIT_V(8); PG8_WAIT_L(0); PG8_BAR; PG8_MMA(1, 0, At, B0); PG8_MMA(1, 1, At, B1); PG8_BAR; PG8_SCHED;
	s_add_i32 s57, 0, 0x18000
	s_add_i32 s58, 0, 0x1c000
	v_add_u32_e32 v156, s57, v167
	v_add_u32_e32 v180, s58, v167
	ds_read_b128 v[144:147], v156
	ds_read_b128 v[148:151], v156 offset:1024
	ds_read_b128 v[152:155], v156 offset:2048
	ds_read_b128 v[156:159], v156 offset:3072
	ds_read_b128 v[160:163], v180
	ds_read_b128 v[172:175], v180 offset:1024
	ds_read_b128 v[176:179], v180 offset:2048
	ds_read_b128 v[180:183], v180 offset:3072
	s_add_u32 s24, s30, 0x160000
	s_addc_u32 s25, s31, 0
	s_mov_b32 m0, s40
	ds_read_b128 v[184:187], v171 offset:32768
	ds_read_b128 v[188:191], v171 offset:33792
	ds_read_b128 v[192:195], v171 offset:34816
	ds_read_b128 v[196:199], v171 offset:35840
	ds_read_b128 v[200:203], v171 offset:36864
	ds_read_b128 v[204:207], v171 offset:37888
	ds_read_b128 v[208:211], v171 offset:38912
	ds_read_b128 v[212:215], v171 offset:39936
	global_load_lds_dwordx4 v128, s[24:25]
	s_mov_b32 m0, s41
	s_nop 0
	global_load_lds_dwordx4 v132, s[24:25]
	s_waitcnt vmcnt(8)
	s_waitcnt lgkmcnt(0)
	s_barrier
	s_waitcnt lgkmcnt(0)
	v_mfma_f32_16x16x32_bf16 v[124:127], v[144:147], v[184:187], v[124:127]
	v_mfma_f32_16x16x32_bf16 v[120:123], v[152:155], v[184:187], v[120:123]
	v_mfma_f32_16x16x32_bf16 v[116:119], v[144:147], v[192:195], v[116:119]
	v_mfma_f32_16x16x32_bf16 v[112:115], v[152:155], v[192:195], v[112:115]
	v_mfma_f32_16x16x32_bf16 v[108:111], v[144:147], v[200:203], v[108:111]
	v_mfma_f32_16x16x32_bf16 v[96:99], v[152:155], v[200:203], v[96:99]
	v_mfma_f32_16x16x32_bf16 v[84:87], v[144:147], v[208:211], v[84:87]
	v_mfma_f32_16x16x32_bf16 v[76:79], v[152:155], v[208:211], v[76:79]
	v_mfma_f32_16x16x32_bf16 v[124:127], v[148:151], v[188:191], v[124:127]
	v_mfma_f32_16x16x32_bf16 v[120:123], v[156:159], v[188:191], v[120:123]
	v_mfma_f32_16x16x32_bf16 v[116:119], v[148:151], v[196:199], v[116:119]
	v_mfma_f32_16x16x32_bf16 v[112:115], v[156:159], v[196:199], v[112:115]
	v_mfma_f32_16x16x32_bf16 v[108:111], v[148:151], v[204:207], v[108:111]
	v_mfma_f32_16x16x32_bf16 v[96:99], v[156:159], v[204:207], v[96:99]
	v_mfma_f32_16x16x32_bf16 v[84:87], v[148:151], v[212:215], v[84:87]
	v_mfma_f32_16x16x32_bf16 v[76:79], v[156:159], v[212:215], v[76:79]
	v_mfma_f32_16x16x32_bf16 v[104:107], v[160:163], v[184:187], v[104:107]
	v_mfma_f32_16x16x32_bf16 v[100:103], v[176:179], v[184:187], v[100:103]
	v_mfma_f32_16x16x32_bf16 v[92:95], v[160:163], v[192:195], v[92:95]
	v_mfma_f32_16x16x32_bf16 v[88:91], v[176:179], v[192:195], v[88:91]
	v_mfma_f32_16x16x32_bf16 v[80:83], v[160:163], v[200:203], v[80:83]
	v_mfma_f32_16x16x32_bf16 v[72:75], v[176:179], v[200:203], v[72:75]
	v_mfma_f32_16x16x32_bf16 v[68:71], v[160:163], v[208:211], v[68:71]
	v_mfma_f32_16x16x32_bf16 v[64:67], v[176:179], v[208:211], v[64:67]
	v_mfma_f32_16x16x32_bf16 v[104:107], v[172:175], v[188:191], v[104:107]
	v_mfma_f32_16x16x32_bf16 v[100:103], v[180:183], v[188:191], v[100:103]
	v_mfma_f32_16x16x32_bf16 v[92:95], v[172:175], v[196:199], v[92:95]
	v_mfma_f32_16x16x32_bf16 v[88:91], v[180:183], v[196:199], v[88:91]
	v_mfma_f32_16x16x32_bf16 v[80:83], v[172:175], v[204:207], v[80:83]
	v_mfma_f32_16x16x32_bf16 v[72:75], v[180:183], v[204:207], v[72:75]
	v_mfma_f32_16x16x32_bf16 v[68:71], v[172:175], v[212:215], v[68:71]
	v_mfma_f32_16x16x32_bf16 v[64:67], v[180:183], v[212:215], v[64:67]
	s_barrier
	s_add_i32 s24, s57, s37
	s_add_u32 s86, s28, 0x80
	s_addc_u32 s87, s29, 0
	s_mov_b32 m0, s24
	ds_read_b128 v[184:187], v171 offset:49152
	ds_read_b128 v[188:191], v171 offset:50176
	ds_read_b128 v[192:195], v171 offset:51200
	ds_read_b128 v[196:199], v171 offset:52224
	ds_read_b128 v[200:203], v171 offset:53248
	ds_read_b128 v[204:207], v171 offset:54272
	ds_read_b128 v[208:211], v171 offset:55296
	ds_read_b128 v[212:215], v171 offset:56320
	global_load_lds_dwordx4 v130, s[86:87]
	s_add_i32 m0, s24, 0x2000
	s_add_u32 s24, s28, 0x160080
	s_addc_u32 s25, s29, 0
	s_add_i32 s28, s58, s37
	global_load_lds_dwordx4 v134, s[86:87]
	s_mov_b32 m0, s28
	s_nop 0
	global_load_lds_dwordx4 v130, s[24:25]
	s_add_i32 m0, s28, 0x2000
	s_nop 0
	global_load_lds_dwordx4 v134, s[24:25]
	s_add_u32 s84, s30, 0x80
	s_addc_u32 s85, s31, 0
	s_mov_b32 m0, s45
	s_nop 0
	global_load_lds_dwordx4 v128, s[84:85]
	s_mov_b32 m0, s46
	s_nop 0
	global_load_lds_dwordx4 v132, s[84:85]
	s_waitcnt vmcnt(8)
	s_waitcnt lgkmcnt(0)
	s_barrier
	s_waitcnt lgkmcnt(0)
	v_mfma_f32_16x16x32_bf16 v[60:63], v[144:147], v[184:187], v[60:63]
	v_mfma_f32_16x16x32_bf16 v[56:59], v[152:155], v[184:187], v[56:59]
	v_mfma_f32_16x16x32_bf16 v[52:55], v[144:147], v[192:195], v[52:55]
	v_mfma_f32_16x16x32_bf16 v[48:51], v[152:155], v[192:195], v[48:51]
	v_mfma_f32_16x16x32_bf16 v[44:47], v[144:147], v[200:203], v[44:47]
	v_mfma_f32_16x16x32_bf16 v[32:35], v[152:155], v[200:203], v[32:35]
	v_mfma_f32_16x16x32_bf16 v[20:23], v[144:147], v[208:211], v[20:23]
	v_mfma_f32_16x16x32_bf16 v[12:15], v[152:155], v[208:211], v[12:15]
	v_mfma_f32_16x16x32_bf16 v[60:63], v[148:151], v[188:191], v[60:63]
	v_mfma_f32_16x16x32_bf16 v[56:59], v[156:159], v[188:191], v[56:59]
	v_mfma_f32_16x16x32_bf16 v[52:55], v[148:151], v[196:199], v[52:55]
	v_mfma_f32_16x16x32_bf16 v[48:51], v[156:159], v[196:199], v[48:51]
	v_mfma_f32_16x16x32_bf16 v[44:47], v[148:151], v[204:207], v[44:47]
	v_mfma_f32_16x16x32_bf16 v[32:35], v[156:159], v[204:207], v[32:35]
	v_mfma_f32_16x16x32_bf16 v[20:23], v[148:151], v[212:215], v[20:23]
	v_mfma_f32_16x16x32_bf16 v[12:15], v[156:159], v[212:215], v[12:15]
	v_mfma_f32_16x16x32_bf16 v[40:43], v[160:163], v[184:187], v[40:43]
	v_mfma_f32_16x16x32_bf16 v[36:39], v[176:179], v[184:187], v[36:39]
	v_mfma_f32_16x16x32_bf16 v[28:31], v[160:163], v[192:195], v[28:31]
	v_mfma_f32_16x16x32_bf16 v[24:27], v[176:179], v[192:195], v[24:27]
	v_mfma_f32_16x16x32_bf16 v[16:19], v[160:163], v[200:203], v[16:19]
	v_mfma_f32_16x16x32_bf16 v[8:11], v[176:179], v[200:203], v[8:11]
	v_mfma_f32_16x16x32_bf16 v[4:7], v[160:163], v[208:211], v[4:7]
	v_mfma_f32_16x16x32_bf16 v[0:3], v[176:179], v[208:211], v[0:3]
	v_mfma_f32_16x16x32_bf16 v[40:43], v[172:175], v[188:191], v[40:43]
	v_mfma_f32_16x16x32_bf16 v[36:39], v[180:183], v[188:191], v[36:39]
	v_mfma_f32_16x16x32_bf16 v[28:31], v[172:175], v[196:199], v[28:31]
	v_mfma_f32_16x16x32_bf16 v[24:27], v[180:183], v[196:199], v[24:27]
	v_mfma_f32_16x16x32_bf16 v[16:19], v[172:175], v[204:207], v[16:19]
	v_mfma_f32_16x16x32_bf16 v[8:11], v[180:183], v[204:207], v[8:11]
	v_mfma_f32_16x16x32_bf16 v[4:7], v[172:175], v[212:215], v[4:7]
	v_mfma_f32_16x16x32_bf16 v[0:3], v[180:183], v[212:215], v[0:3]
	s_add_i32 s56, s56, 2
	s_add_u32 s54, s54, 0x100
	s_addc_u32 s55, s55, 0
	s_cmpk_gt_u32 s56, 0x55
	s_mov_b64 s[24:25], s[26:27]
	s_barrier
;     __device__ __forceinline__ void operator()(const f32x4 (&acc)[2][2][4][2], const Unit& u, int wr, int wc, int fr, int fq) const {
;         const int row0 = u.pm * BM + wr * 64 + fr, col0 = u.pn * BM + wc * 32 + 8 * fq;
;         const float* gp = gate + (u.pm >> 5) * 18432 + col0;
;         f32x4 gv[2][2];
; #pragma unroll
;         for (int bj = 0; bj < 2; ++bj)
; #pragma unroll
;             for (int n = 0; n < 2; ++n) gv[bj][n] = *(const f32x4*)(gp + bj * HALF + 4 * n) * scale;
; #pragma unroll
;         for (int ai = 0; ai < 2; ++ai) { f32x4 r[4][2][2];
; #pragma unroll
;             for (int m = 0; m < 4; ++m) { const size_t off = (size_t)(row0 + ai * HALF + m * 16) * 2048 + col0;
; #pragma unroll
;                 for (int bj = 0; bj < 2; ++bj)
; #pragma unroll
;                     for (int n = 0; n < 2; ++n) r[m][bj][n] = *(const f32x4*)(res + off + bj * HALF + 4 * n); }
; #pragma unroll
;             for (int m = 0; m < 4; ++m) { const size_t off = (size_t)(row0 + ai * HALF + m * 16) * 2048 + col0;
; #pragma unroll
;                 for (int bj = 0; bj < 2; ++bj)
; #pragma unroll
;                     for (int n = 0; n < 2; ++n) *(f32x4*)(out + off + bj * HALF + 4 * n) = r[m][bj][n] + gv[bj][n] * acc[ai][bj][m][n]; } }
	s_cbranch_scc0 .LBB0_1021
	s_lshr_b32 s24, s52, 5
	s_mulk_i32 s24, 0x4800
	s_ashr_i32 s25, s24, 31
	v_lshl_or_b32 v144, s53, 8, v168
	s_lshl_b64 s[24:25], s[24:25], 2
	s_add_u32 s24, s43, s24
	v_ashrrev_i32_e32 v145, 31, v144
	s_addc_u32 s25, s44, s25
	v_lshlrev_b64 v[144:145], 2, v[144:145]
	v_lshl_add_u64 v[154:155], s[24:25], 0, v[144:145]
	global_load_dwordx4 v[146:149], v[154:155], off offset:16
	global_load_dwordx4 v[150:153], v[154:155], off
	global_load_dwordx4 v[172:175], v[154:155], off offset:528
	global_load_dwordx4 v[176:179], v[154:155], off offset:512
	v_lshl_add_u32 v154, s52, 8, v166
	v_ashrrev_i32_e32 v155, 31, v154
	v_lshl_add_u64 v[162:163], s[8:9], 0, v[144:145]
	v_lshlrev_b64 v[164:165], 13, v[154:155]
	v_lshl_add_u64 v[156:157], v[162:163], 0, v[164:165]
	global_load_dwordx4 v[180:183], v[156:157], off
	global_load_dwordx4 v[184:187], v[156:157], off offset:16
	global_load_dwordx4 v[188:191], v[156:157], off offset:528
	global_load_dwordx4 v[192:195], v[156:157], off offset:512
	v_or_b32_e32 v156, 16, v154
	v_ashrrev_i32_e32 v157, 31, v156
	v_lshlrev_b64 v[156:157], 13, v[156:157]
	v_lshl_add_u64 v[158:159], v[162:163], 0, v[156:157]
	global_load_dwordx4 v[196:199], v[158:159], off
	global_load_dwordx4 v[200:203], v[158:159], off offset:16
	global_load_dwordx4 v[204:207], v[158:159], off offset:528
	global_load_dwordx4 v[208:211], v[158:159], off offset:512
	v_or_b32_e32 v158, 32, v154
	v_ashrrev_i32_e32 v159, 31, v158
	v_lshlrev_b64 v[158:159], 13, v[158:159]
	v_or_b32_e32 v154, 48, v154
	v_lshl_add_u64 v[160:161], v[162:163], 0, v[158:159]
	v_ashrrev_i32_e32 v155, 31, v154
	global_load_dwordx4 v[212:215], v[160:161], off
	global_load_dwordx4 v[216:219], v[160:161], off offset:16
	global_load_dwordx4 v[220:223], v[160:161], off offset:512
	global_load_dwordx4 v[224:227], v[160:161], off offset:528
	v_lshlrev_b64 v[244:245], 13, v[154:155]
	v_lshl_add_u64 v[154:155], v[162:163], 0, v[244:245]
	global_load_dwordx4 v[228:231], v[154:155], off
	global_load_dwordx4 v[232:235], v[154:155], off offset:16
	global_load_dwordx4 v[236:239], v[154:155], off offset:512
	global_load_dwordx4 v[240:243], v[154:155], off offset:528
	v_lshl_add_u64 v[154:155], s[10:11], 0, v[164:165]
	v_lshl_add_u64 v[246:247], v[154:155], 0, v[144:145]
	v_lshl_add_u64 v[154:155], s[10:11], 0, v[156:157]
	v_lshl_add_u64 v[156:157], s[10:11], 0, v[158:159]
	v_lshl_add_u64 v[248:249], v[154:155], 0, v[144:145]
	v_lshl_add_u64 v[250:251], v[156:157], 0, v[144:145]
	s_and_b64 vcc, exec, s[0:1]
	s_mov_b32 s53, s50
	s_mov_b32 s52, s51
	s_mov_b64 s[26:27], s[6:7]
	s_mov_b64 s[24:25], s[4:5]
	s_waitcnt vmcnt(0)
	v_pk_mul_f32 v[154:155], v[148:149], 0.5 op_sel_hi:[1,0]
	v_pk_mul_f32 v[158:159], v[152:153], 0.5 op_sel_hi:[1,0]
	v_pk_mul_f32 v[160:161], v[150:151], 0.5 op_sel_hi:[1,0]
	v_pk_mul_f32 v[150:151], v[178:179], 0.5 op_sel_hi:[1,0]
	v_pk_mul_f32 v[152:153], v[176:177], 0.5 op_sel_hi:[1,0]
	v_pk_mul_f32 v[156:157], v[146:147], 0.5 op_sel_hi:[1,0]
	v_pk_mul_f32 v[146:147], v[174:175], 0.5 op_sel_hi:[1,0]
	v_pk_mul_f32 v[148:149], v[172:173], 0.5 op_sel_hi:[1,0]
	v_pk_fma_f32 v[126:127], v[126:127], v[158:159], v[182:183]
	v_pk_fma_f32 v[124:125], v[124:125], v[160:161], v[180:181]
	v_pk_fma_f32 v[122:123], v[122:123], v[154:155], v[186:187]
	v_pk_fma_f32 v[120:121], v[120:121], v[156:157], v[184:185]
	v_pk_fma_f32 v[106:107], v[106:107], v[150:151], v[194:195]
	v_pk_fma_f32 v[104:105], v[104:105], v[152:153], v[192:193]
	v_pk_fma_f32 v[102:103], v[102:103], v[146:147], v[190:191]
	v_pk_fma_f32 v[100:101], v[100:101], v[148:149], v[188:189]
	v_pk_fma_f32 v[118:119], v[118:119], v[158:159], v[198:199]
	v_pk_fma_f32 v[116:117], v[116:117], v[160:161], v[196:197]
	v_pk_fma_f32 v[114:115], v[114:115], v[154:155], v[202:203]
	v_pk_fma_f32 v[112:113], v[112:113], v[156:157], v[200:201]
	v_pk_fma_f32 v[82:83], v[82:83], v[150:151], v[222:223]
	v_pk_fma_f32 v[80:81], v[80:81], v[152:153], v[220:221]
	v_pk_fma_f32 v[94:95], v[94:95], v[150:151], v[210:211]
	v_pk_fma_f32 v[92:93], v[92:93], v[152:153], v[208:209]
	v_pk_fma_f32 v[90:91], v[90:91], v[146:147], v[206:207]
	v_pk_fma_f32 v[88:89], v[88:89], v[148:149], v[204:205]
	v_pk_fma_f32 v[110:111], v[110:111], v[158:159], v[214:215]
	v_pk_fma_f32 v[108:109], v[108:109], v[160:161], v[212:213]
	v_pk_fma_f32 v[98:99], v[98:99], v[154:155], v[218:219]
	v_pk_fma_f32 v[96:97], v[96:97], v[156:157], v[216:217]
	global_store_dwordx4 v[246:247], v[124:127], off
	global_store_dwordx4 v[246:247], v[120:123], off offset:16
	global_store_dwordx4 v[246:247], v[104:107], off offset:512
	global_store_dwordx4 v[246:247], v[100:103], off offset:528
	global_store_dwordx4 v[248:249], v[116:119], off
	global_store_dwordx4 v[248:249], v[112:115], off offset:16
	global_store_dwordx4 v[248:249], v[92:95], off offset:512
	global_store_dwordx4 v[248:249], v[88:91], off offset:528
	global_store_dwordx4 v[250:251], v[108:111], off
	global_store_dwordx4 v[250:251], v[96:99], off offset:16
	global_store_dwordx4 v[250:251], v[80:83], off offset:512
	v_pk_fma_f32 v[74:75], v[74:75], v[146:147], v[226:227]
	v_pk_fma_f32 v[72:73], v[72:73], v[148:149], v[224:225]
	v_lshl_add_u64 v[80:81], s[10:11], 0, v[244:245]
	global_store_dwordx4 v[250:251], v[72:75], off offset:528
	v_lshl_add_u64 v[80:81], v[80:81], 0, v[144:145]
; #define PG8_WAIT_V(n) asm volatile("s_waitcnt vmcnt(" #n ")" ::: "memory")
; #define PG8_BAR __builtin_amdgcn_s_barrier()
;     __device__ __forceinline__ void operator()(const f32x4 (&acc)[2][2][4][2], const Unit& u, int wr, int wc, int fr, int fq) const {
;     ...
;             for (int m = 0; m < 4; ++m) { const size_t off = (size_t)(row0 + ai * HALF + m * 16) * 2048 + col0;
; #pragma unroll
;                 for (int bj = 0; bj < 2; ++bj)
; #pragma unroll
;                     for (int n = 0; n < 2; ++n) r[m][bj][n] = *(const f32x4*)(res + off + bj * HALF + 4 * n); }
; #pragma unroll
;             for (int m = 0; m < 4; ++m) { const size_t off = (size_t)(row0 + ai * HALF + m * 16) * 2048 + col0;
; #pragma unroll
;                 for (int bj = 0; bj < 2; ++bj)
; #pragma unroll
;                     for (int n = 0; n < 2; ++n) *(f32x4*)(out + off + bj * HALF + 4 * n) = r[m][bj][n] + gv[bj][n] * acc[ai][bj][m][n]; } }
; template <class Epi, class Sched, bool ALIGN_EPI = false, bool SP2 = false>
; __device__ __forceinline__ void gemm_phase(PG8_LAS unsigned char* lds, const Gemm g, const Sched& S, const Epi& E) {
;     ...
;     PG8_WAIT_V(0);
;     if constexpr (!ALIGN_EPI) { if (wr == 0) PG8_BAR; }
;     PG8_BAR;
	v_pk_fma_f32 v[70:71], v[70:71], v[150:151], v[238:239]
	v_pk_fma_f32 v[74:75], v[86:87], v[158:159], v[230:231]
	v_pk_fma_f32 v[72:73], v[84:85], v[160:161], v[228:229]
	global_store_dwordx4 v[80:81], v[72:75], off
	v_pk_fma_f32 v[68:69], v[68:69], v[152:153], v[236:237]
	v_pk_fma_f32 v[66:67], v[66:67], v[146:147], v[242:243]
	v_pk_fma_f32 v[74:75], v[78:79], v[154:155], v[234:235]
	v_pk_fma_f32 v[72:73], v[76:77], v[156:157], v[232:233]
	v_pk_fma_f32 v[64:65], v[64:65], v[148:149], v[240:241]
	v_lshl_add_u64 v[172:173], v[164:165], 0, s[18:19]
	v_lshl_add_u64 v[174:175], v[164:165], 0, s[20:21]
	v_lshl_add_u64 v[176:177], v[164:165], 0, s[22:23]
	global_store_dwordx4 v[80:81], v[72:75], off offset:16
	global_store_dwordx4 v[80:81], v[68:71], off offset:512
	global_store_dwordx4 v[80:81], v[64:67], off offset:528
	v_lshl_add_u64 v[80:81], v[162:163], 0, v[172:173]
	v_lshl_add_u64 v[92:93], v[162:163], 0, v[174:175]
	v_lshl_add_u64 v[108:109], v[162:163], 0, v[176:177]
	global_load_dwordx4 v[64:67], v[80:81], off
	global_load_dwordx4 v[68:71], v[80:81], off offset:16
	global_load_dwordx4 v[72:75], v[80:81], off offset:512
	global_load_dwordx4 v[76:79], v[80:81], off offset:528
	s_nop 0
	global_load_dwordx4 v[80:83], v[92:93], off
	global_load_dwordx4 v[84:87], v[92:93], off offset:16
	global_load_dwordx4 v[88:91], v[92:93], off offset:512
	s_nop 0
	global_load_dwordx4 v[92:95], v[92:93], off offset:528
	s_nop 0
	global_load_dwordx4 v[96:99], v[108:109], off
	global_load_dwordx4 v[100:103], v[108:109], off offset:16
	global_load_dwordx4 v[104:107], v[108:109], off offset:512
	s_nop 0
	global_load_dwordx4 v[108:111], v[108:109], off offset:528
	v_lshl_add_u64 v[164:165], v[164:165], 0, s[12:13]
	v_lshl_add_u64 v[124:125], v[162:163], 0, v[164:165]
	global_load_dwordx4 v[112:115], v[124:125], off
	global_load_dwordx4 v[116:119], v[124:125], off offset:16
	global_load_dwordx4 v[120:123], v[124:125], off offset:512
	s_nop 0
	global_load_dwordx4 v[124:127], v[124:125], off offset:528
	v_lshl_add_u64 v[162:163], s[10:11], 0, v[172:173]
	v_lshl_add_u64 v[172:173], s[10:11], 0, v[174:175]
	v_lshl_add_u64 v[174:175], s[10:11], 0, v[176:177]
	v_lshl_add_u64 v[162:163], v[162:163], 0, v[144:145]
	v_lshl_add_u64 v[174:175], v[174:175], 0, v[144:145]
	v_lshl_add_u64 v[172:173], v[172:173], 0, v[144:145]
	s_waitcnt vmcnt(15)
	v_pk_fma_f32 v[62:63], v[62:63], v[158:159], v[66:67]
	v_pk_fma_f32 v[60:61], v[60:61], v[160:161], v[64:65]
	s_waitcnt vmcnt(14)
	v_pk_fma_f32 v[58:59], v[58:59], v[154:155], v[70:71]
	v_pk_fma_f32 v[56:57], v[56:57], v[156:157], v[68:69]
	s_waitcnt vmcnt(5)
	v_pk_fma_f32 v[18:19], v[18:19], v[150:151], v[106:107]
	v_pk_fma_f32 v[16:17], v[16:17], v[152:153], v[104:105]
	v_pk_fma_f32 v[42:43], v[42:43], v[150:151], v[74:75]
	v_pk_fma_f32 v[40:41], v[40:41], v[152:153], v[72:73]
	v_pk_fma_f32 v[38:39], v[38:39], v[146:147], v[78:79]
	v_pk_fma_f32 v[36:37], v[36:37], v[148:149], v[76:77]
	v_pk_fma_f32 v[54:55], v[54:55], v[158:159], v[82:83]
	v_pk_fma_f32 v[52:53], v[52:53], v[160:161], v[80:81]
	v_pk_fma_f32 v[50:51], v[50:51], v[154:155], v[86:87]
	v_pk_fma_f32 v[48:49], v[48:49], v[156:157], v[84:85]
	v_pk_fma_f32 v[30:31], v[30:31], v[150:151], v[90:91]
	v_pk_fma_f32 v[28:29], v[28:29], v[152:153], v[88:89]
	v_pk_fma_f32 v[26:27], v[26:27], v[146:147], v[94:95]
	v_pk_fma_f32 v[24:25], v[24:25], v[148:149], v[92:93]
	v_pk_fma_f32 v[46:47], v[46:47], v[158:159], v[98:99]
	v_pk_fma_f32 v[44:45], v[44:45], v[160:161], v[96:97]
	v_pk_fma_f32 v[34:35], v[34:35], v[154:155], v[102:103]
	v_pk_fma_f32 v[32:33], v[32:33], v[156:157], v[100:101]
	global_store_dwordx4 v[162:163], v[60:63], off
	global_store_dwordx4 v[162:163], v[56:59], off offset:16
	global_store_dwordx4 v[162:163], v[40:43], off offset:512
	global_store_dwordx4 v[162:163], v[36:39], off offset:528
	global_store_dwordx4 v[172:173], v[52:55], off
	global_store_dwordx4 v[172:173], v[48:51], off offset:16
	global_store_dwordx4 v[172:173], v[28:31], off offset:512
	global_store_dwordx4 v[172:173], v[24:27], off offset:528
	global_store_dwordx4 v[174:175], v[44:47], off
	global_store_dwordx4 v[174:175], v[32:35], off offset:16
	global_store_dwordx4 v[174:175], v[16:19], off offset:512
	s_waitcnt vmcnt(15)
	v_pk_fma_f32 v[10:11], v[10:11], v[146:147], v[110:111]
	v_pk_fma_f32 v[8:9], v[8:9], v[148:149], v[108:109]
	v_lshl_add_u64 v[16:17], s[10:11], 0, v[164:165]
	global_store_dwordx4 v[174:175], v[8:11], off offset:528
	v_lshl_add_u64 v[16:17], v[16:17], 0, v[144:145]
	s_waitcnt vmcnt(13)
	v_pk_fma_f32 v[6:7], v[6:7], v[150:151], v[122:123]
	v_pk_fma_f32 v[10:11], v[22:23], v[158:159], v[114:115]
	v_pk_fma_f32 v[8:9], v[20:21], v[160:161], v[112:113]
	global_store_dwordx4 v[16:17], v[8:11], off
	v_pk_fma_f32 v[4:5], v[4:5], v[152:153], v[120:121]
	s_waitcnt vmcnt(13)
	v_pk_fma_f32 v[2:3], v[2:3], v[146:147], v[126:127]
	v_pk_fma_f32 v[10:11], v[14:15], v[154:155], v[118:119]
	v_pk_fma_f32 v[8:9], v[12:13], v[156:157], v[116:117]
	v_pk_fma_f32 v[0:1], v[0:1], v[148:149], v[124:125]
	global_store_dwordx4 v[16:17], v[8:11], off offset:16
	global_store_dwordx4 v[16:17], v[4:7], off offset:512
	global_store_dwordx4 v[16:17], v[0:3], off offset:528
	s_cbranch_vccz .LBB0_1010
	s_waitcnt vmcnt(0)
	s_cmpk_gt_u32 s3, 0xff
	s_cbranch_scc1 .LBB0_1025
	s_barrier
